# peel + all s_setprio 1/0 flips removed from the 9 GEMM K-loops (216 instructions)
# speedup vs baseline: 1.0103x; 1.0092x over previous
; #define PG8_STAGE(bufoff, gbase, voff) do { _Pragma("unroll") for (int _i = 0; _i < 2; ++_i) \
;         __builtin_amdgcn_global_load_lds((const unsigned*)((const char*)(gbase) + (voff)[_i]), (PG8_LAS unsigned*)(lds + (bufoff) + ldsw + _i * 8192), 16, 0, PG8_LOAD_AUX); } while (0)
; #define PG8_LDA(dst, b, h) do { _Pragma("unroll") for (int m = 0; m < 4; ++m) _Pragma("unroll") for (int k = 0; k < 2; ++k) dst[m][k] = *(const PG8_LAS bf16x8*)(lds + PG8_SA(b, h) + aoff + m * 2048 + k * 1024); } while (0)
; #define PG8_LDB(dst, b, h) do { _Pragma("unroll") for (int n = 0; n < 2; ++n) _Pragma("unroll") for (int k = 0; k < 2; ++k) dst[n][k] = *(const PG8_LAS bf16x8*)(lds + PG8_SB(b, h) + boff + n * 2048 + k * 1024); } while (0)
; #define PG8_WAIT_V(n) asm volatile("s_waitcnt vmcnt(" #n ")" ::: "memory")
; #define PG8_WAIT_L(n) asm volatile("s_waitcnt lgkmcnt(" #n ")" ::: "memory")
; #define PG8_BAR __builtin_amdgcn_s_barrier()
; #define PG8_SCHED __builtin_amdgcn_sched_barrier(0)
; template <class Epi, class Sched, bool ALIGN_EPI = false, bool SP2 = false>
; __device__ __forceinline__ void gemm_phase(PG8_LAS unsigned char* lds, const Gemm g, const Sched& S, const Epi& E) {
;     ...
;         const char* nA = has_next ? (const char*)g.A + (size_t)nxt.pm * tstepA + (size_t)nxt.pn * apn : cA; const char* nB = has_next ? (const char*)g.Bt + (size_t)nxt.pn * tstepB : cB;
;         for (int t = 0; t < nt; t += 2) {
;             const bool last = (t == nt - 2);
;             const char* a1 = cA + (size_t)(t + 1) * kstep;
;             const char* a2 = last ? nA : cA + (size_t)(t + 2) * kstep; const char* b2 = last ? nB : cB + (size_t)(t + 2) * kstep;
;             const char* a3 = a2 + kstep; const char* b3 = b2 + kstep;
;             if (last && has_next) S.a_ready(nxt);
;             if constexpr (SP2) {
;             PG8_LDB(B0, 0, 0); PG8_LDB(B1, 0, 1); PG8_SCHED; PG8_LDA(At, 0, 0); PG8_STAGE(PG8_SA(1, 1), a1 + hstepA, voffA);
;             PG8_WAIT_V(8); PG8_WAIT_L(0); PG8_BAR; PG8_MMA(0, 0, At, B0); PG8_MMA(0, 1, At, B1); PG8_BAR; PG8_SCHED;
;             PG8_LDA(At, 0, 1); PG8_STAGE(PG8_SB(0, 0), b2, voffB); PG8_STAGE(PG8_SB(0, 1), b2 + hstepB, voffB); PG8_STAGE(PG8_SA(0, 0), a2, voffA);
;             PG8_WAIT_V(8); PG8_WAIT_L(0); PG8_BAR; PG8_MMA(1, 0, At, B0); PG8_MMA(1, 1, At, B1); PG8_BAR; PG8_SCHED;
.LBB0_214:
	s_ashr_i32 s17, s16, 31
	s_lshl_b64 s[18:19], s[16:17], 19
	v_readlane_b32 s24, v239, 47
	v_readlane_b32 s25, v239, 48
	s_add_u32 s18, s24, s18
	s_addc_u32 s19, s25, s19
	s_and_b64 s[24:25], s[4:5], exec
	s_cselect_b32 s17, s19, s21
	s_cselect_b32 s24, s18, s20
	s_ashr_i32 s15, s14, 31
	s_lshl_b64 s[26:27], s[14:15], 19
	s_add_u32 s40, s64, s26
	s_addc_u32 s41, s65, s27
	s_and_b64 s[26:27], s[4:5], exec
	s_cselect_b32 s15, s41, s23
	s_cselect_b32 s25, s40, s22
	s_add_u32 s20, s20, 0x40080
	s_addc_u32 s21, s21, 0
	s_add_u32 s26, s22, 0x100
	s_addc_u32 s27, s23, 0
	s_mov_b32 s28, -2
	ds_read_b128 v[162:165], v158
	ds_read_b128 v[166:169], v158 offset:1024
	ds_read_b128 v[170:173], v158 offset:2048
	ds_read_b128 v[174:177], v158 offset:3072
	ds_read_b128 v[178:181], v159
	ds_read_b128 v[182:185], v159 offset:1024
	ds_read_b128 v[186:189], v159 offset:2048
	ds_read_b128 v[190:193], v159 offset:3072
	s_add_u32 s22, s20, 0xfffc0080
	s_addc_u32 s23, s21, -1
	s_cmp_eq_u32 s28, 12
	s_cselect_b32 s35, s17, s23
	s_cselect_b32 s34, s24, s22
	s_cselect_b32 s23, s15, s27
	s_cselect_b32 s22, s25, s26
	v_lshl_add_u64 v[226:227], s[20:21], 0, v[138:139]
	s_add_i32 m0, s42, 0xc000
	ds_read_b128 v[194:197], v160
	ds_read_b128 v[198:201], v160 offset:1024
	ds_read_b128 v[202:205], v160 offset:2048
	ds_read_b128 v[206:209], v160 offset:3072
	ds_read_b128 v[210:213], v160 offset:4096
	ds_read_b128 v[214:217], v160 offset:5120
	ds_read_b128 v[218:221], v160 offset:6144
	ds_read_b128 v[222:225], v160 offset:7168
	global_load_lds_dwordx4 v[226:227], off
	v_lshl_add_u64 v[226:227], s[20:21], 0, v[140:141]
	s_add_i32 m0, s42, 0xe000
	s_nop 0
	global_load_lds_dwordx4 v[226:227], off
	s_waitcnt vmcnt(8)
	s_waitcnt lgkmcnt(0)
	s_barrier
	s_waitcnt lgkmcnt(0)
	v_mfma_f32_16x16x32_bf16 v[124:127], v[162:165], v[194:197], 0
	v_mfma_f32_16x16x32_bf16 v[120:123], v[170:173], v[194:197], 0
	v_mfma_f32_16x16x32_bf16 v[108:111], v[162:165], v[202:205], 0
	v_mfma_f32_16x16x32_bf16 v[104:107], v[170:173], v[202:205], 0
	v_mfma_f32_16x16x32_bf16 v[92:95], v[162:165], v[210:213], 0
	v_mfma_f32_16x16x32_bf16 v[88:91], v[170:173], v[210:213], 0
	v_mfma_f32_16x16x32_bf16 v[76:79], v[162:165], v[218:221], 0
	v_mfma_f32_16x16x32_bf16 v[72:75], v[170:173], v[218:221], 0
	v_mfma_f32_16x16x32_bf16 v[124:127], v[166:169], v[198:201], v[124:127]
	v_mfma_f32_16x16x32_bf16 v[120:123], v[174:177], v[198:201], v[120:123]
	v_mfma_f32_16x16x32_bf16 v[108:111], v[166:169], v[206:209], v[108:111]
	v_mfma_f32_16x16x32_bf16 v[104:107], v[174:177], v[206:209], v[104:107]
	v_mfma_f32_16x16x32_bf16 v[92:95], v[166:169], v[214:217], v[92:95]
	v_mfma_f32_16x16x32_bf16 v[88:91], v[174:177], v[214:217], v[88:91]
	v_mfma_f32_16x16x32_bf16 v[76:79], v[166:169], v[222:225], v[76:79]
	v_mfma_f32_16x16x32_bf16 v[72:75], v[174:177], v[222:225], v[72:75]
	v_mfma_f32_16x16x32_bf16 v[116:119], v[178:181], v[194:197], 0
	v_mfma_f32_16x16x32_bf16 v[112:115], v[186:189], v[194:197], 0
	v_mfma_f32_16x16x32_bf16 v[100:103], v[178:181], v[202:205], 0
	v_mfma_f32_16x16x32_bf16 v[96:99], v[186:189], v[202:205], 0
	v_mfma_f32_16x16x32_bf16 v[84:87], v[178:181], v[210:213], 0
	v_mfma_f32_16x16x32_bf16 v[80:83], v[186:189], v[210:213], 0
	v_mfma_f32_16x16x32_bf16 v[68:71], v[178:181], v[218:221], 0
	v_mfma_f32_16x16x32_bf16 v[64:67], v[186:189], v[218:221], 0
	v_mfma_f32_16x16x32_bf16 v[116:119], v[182:185], v[198:201], v[116:119]
	v_mfma_f32_16x16x32_bf16 v[112:115], v[190:193], v[198:201], v[112:115]
	v_mfma_f32_16x16x32_bf16 v[100:103], v[182:185], v[206:209], v[100:103]
	v_mfma_f32_16x16x32_bf16 v[96:99], v[190:193], v[206:209], v[96:99]
	v_mfma_f32_16x16x32_bf16 v[84:87], v[182:185], v[214:217], v[84:87]
	v_mfma_f32_16x16x32_bf16 v[80:83], v[190:193], v[214:217], v[80:83]
	v_mfma_f32_16x16x32_bf16 v[68:71], v[182:185], v[222:225], v[68:71]
	v_mfma_f32_16x16x32_bf16 v[64:67], v[190:193], v[222:225], v[64:67]
	s_barrier
	s_add_i32 s29, s51, s33
	v_lshl_add_u64 v[226:227], s[22:23], 0, v[130:131]
	s_mov_b32 m0, s29
	ds_read_b128 v[194:197], v160 offset:16384
	ds_read_b128 v[198:201], v160 offset:17408
	ds_read_b128 v[202:205], v160 offset:18432
	ds_read_b128 v[206:209], v160 offset:19456
	ds_read_b128 v[210:213], v160 offset:20480
	ds_read_b128 v[214:217], v160 offset:21504
	ds_read_b128 v[218:221], v160 offset:22528
	ds_read_b128 v[222:225], v160 offset:23552
	global_load_lds_dwordx4 v[226:227], off
	s_add_i32 m0, s29, 0x2000
	s_add_u32 s30, s22, 0x10000
	v_lshl_add_u64 v[228:229], s[22:23], 0, v[134:135]
	s_addc_u32 s31, s23, 0
	s_add_i32 s29, s52, s33
	global_load_lds_dwordx4 v[228:229], off
	v_lshl_add_u64 v[230:231], s[30:31], 0, v[130:131]
	s_mov_b32 m0, s29
	v_lshl_add_u64 v[232:233], s[34:35], 0, v[132:133]
	global_load_lds_dwordx4 v[230:231], off
	v_lshl_add_u64 v[230:231], s[30:31], 0, v[134:135]
	s_add_i32 m0, s29, 0x2000
	s_nop 0
	global_load_lds_dwordx4 v[230:231], off
	v_lshl_add_u64 v[230:231], s[34:35], 0, v[128:129]
	s_mov_b32 m0, s42
	s_nop 0
	global_load_lds_dwordx4 v[230:231], off
	s_mov_b32 m0, s43
	s_nop 0
	global_load_lds_dwordx4 v[232:233], off
	s_waitcnt vmcnt(8)
	s_waitcnt lgkmcnt(0)
	s_barrier
; #define PG8_STAGE(bufoff, gbase, voff) do { _Pragma("unroll") for (int _i = 0; _i < 2; ++_i) \
;         __builtin_amdgcn_global_load_lds((const unsigned*)((const char*)(gbase) + (voff)[_i]), (PG8_LAS unsigned*)(lds + (bufoff) + ldsw + _i * 8192), 16, 0, PG8_LOAD_AUX); } while (0)
; #define PG8_LDA(dst, b, h) do { _Pragma("unroll") for (int m = 0; m < 4; ++m) _Pragma("unroll") for (int k = 0; k < 2; ++k) dst[m][k] = *(const PG8_LAS bf16x8*)(lds + PG8_SA(b, h) + aoff + m * 2048 + k * 1024); } while (0)
; #define PG8_LDB(dst, b, h) do { _Pragma("unroll") for (int n = 0; n < 2; ++n) _Pragma("unroll") for (int k = 0; k < 2; ++k) dst[n][k] = *(const PG8_LAS bf16x8*)(lds + PG8_SB(b, h) + boff + n * 2048 + k * 1024); } while (0)
; #define PG8_MMA(ai, bj, At, Bt) do { __builtin_amdgcn_s_setprio(1); _Pragma("unroll") for (int m = 0; m < 4; ++m) _Pragma("unroll") for (int n = 0; n < 2; ++n) _Pragma("unroll") for (int k = 0; k < 2; ++k) \
;         acc[ai][bj][m][n] = __builtin_amdgcn_mfma_f32_16x16x32_bf16(Bt[n][k], At[m][k], acc[ai][bj][m][n], 0, 0, 0); __builtin_amdgcn_s_setprio(0); } while (0)
; #define PG8_WAIT_V(n) asm volatile("s_waitcnt vmcnt(" #n ")" ::: "memory")
; #define PG8_WAIT_L(n) asm volatile("s_waitcnt lgkmcnt(" #n ")" ::: "memory")
; #define PG8_BAR __builtin_amdgcn_s_barrier()
; #define PG8_SCHED __builtin_amdgcn_sched_barrier(0)
; template <class Epi, class Sched, bool ALIGN_EPI = false, bool SP2 = false>
; __device__ __forceinline__ void gemm_phase(PG8_LAS unsigned char* lds, const Gemm g, const Sched& S, const Epi& E) {
;     ...
;             PG8_LDB(B0, 0, 0); PG8_LDB(B1, 0, 1); PG8_SCHED; PG8_LDA(At, 0, 0); PG8_STAGE(PG8_SA(1, 1), a1 + hstepA, voffA);
;             PG8_WAIT_V(8); PG8_WAIT_L(0); PG8_BAR; PG8_MMA(0, 0, At, B0); PG8_MMA(0, 1, At, B1); PG8_BAR; PG8_SCHED;
;             PG8_LDA(At, 0, 1); PG8_STAGE(PG8_SB(0, 0), b2, voffB); PG8_STAGE(PG8_SB(0, 1), b2 + hstepB, voffB); PG8_STAGE(PG8_SA(0, 0), a2, voffA);
;             PG8_WAIT_V(8); PG8_WAIT_L(0); PG8_BAR; PG8_MMA(1, 0, At, B0); PG8_MMA(1, 1, At, B1); PG8_BAR; PG8_SCHED;
	s_waitcnt lgkmcnt(0)
	v_mfma_f32_16x16x32_bf16 v[60:63], v[162:165], v[194:197], 0
	v_mfma_f32_16x16x32_bf16 v[56:59], v[170:173], v[194:197], 0
	v_mfma_f32_16x16x32_bf16 v[44:47], v[162:165], v[202:205], 0
	v_mfma_f32_16x16x32_bf16 v[40:43], v[170:173], v[202:205], 0
	v_mfma_f32_16x16x32_bf16 v[28:31], v[162:165], v[210:213], 0
	v_mfma_f32_16x16x32_bf16 v[24:27], v[170:173], v[210:213], 0
	v_mfma_f32_16x16x32_bf16 v[12:15], v[162:165], v[218:221], 0
	v_mfma_f32_16x16x32_bf16 v[8:11], v[170:173], v[218:221], 0
	v_mfma_f32_16x16x32_bf16 v[60:63], v[166:169], v[198:201], v[60:63]
	v_mfma_f32_16x16x32_bf16 v[56:59], v[174:177], v[198:201], v[56:59]
	v_mfma_f32_16x16x32_bf16 v[44:47], v[166:169], v[206:209], v[44:47]
	v_mfma_f32_16x16x32_bf16 v[40:43], v[174:177], v[206:209], v[40:43]
	v_mfma_f32_16x16x32_bf16 v[28:31], v[166:169], v[214:217], v[28:31]
	v_mfma_f32_16x16x32_bf16 v[24:27], v[174:177], v[214:217], v[24:27]
	v_mfma_f32_16x16x32_bf16 v[12:15], v[166:169], v[222:225], v[12:15]
	v_mfma_f32_16x16x32_bf16 v[8:11], v[174:177], v[222:225], v[8:11]
	v_mfma_f32_16x16x32_bf16 v[52:55], v[178:181], v[194:197], 0
	v_mfma_f32_16x16x32_bf16 v[48:51], v[186:189], v[194:197], 0
	v_mfma_f32_16x16x32_bf16 v[36:39], v[178:181], v[202:205], 0
	v_mfma_f32_16x16x32_bf16 v[32:35], v[186:189], v[202:205], 0
	v_mfma_f32_16x16x32_bf16 v[20:23], v[178:181], v[210:213], 0
	v_mfma_f32_16x16x32_bf16 v[16:19], v[186:189], v[210:213], 0
	v_mfma_f32_16x16x32_bf16 v[4:7], v[178:181], v[218:221], 0
	v_mfma_f32_16x16x32_bf16 v[0:3], v[186:189], v[218:221], 0
	v_mfma_f32_16x16x32_bf16 v[52:55], v[182:185], v[198:201], v[52:55]
	v_mfma_f32_16x16x32_bf16 v[48:51], v[190:193], v[198:201], v[48:51]
	v_mfma_f32_16x16x32_bf16 v[36:39], v[182:185], v[206:209], v[36:39]
	v_mfma_f32_16x16x32_bf16 v[32:35], v[190:193], v[206:209], v[32:35]
	v_mfma_f32_16x16x32_bf16 v[20:23], v[182:185], v[214:217], v[20:23]
	v_mfma_f32_16x16x32_bf16 v[16:19], v[190:193], v[214:217], v[16:19]
	v_mfma_f32_16x16x32_bf16 v[4:7], v[182:185], v[222:225], v[4:7]
	v_mfma_f32_16x16x32_bf16 v[0:3], v[190:193], v[222:225], v[0:3]
	s_barrier
	s_branch .Lkmid_P1
.LBB0_215:
	ds_read_b128 v[162:165], v158
	ds_read_b128 v[166:169], v158 offset:1024
	ds_read_b128 v[170:173], v158 offset:2048
	ds_read_b128 v[174:177], v158 offset:3072
	ds_read_b128 v[178:181], v159
	ds_read_b128 v[182:185], v159 offset:1024
	ds_read_b128 v[186:189], v159 offset:2048
	ds_read_b128 v[190:193], v159 offset:3072
	s_add_u32 s22, s20, 0xfffc0080
	s_addc_u32 s23, s21, -1
	s_cmp_eq_u32 s28, 12
	s_cselect_b32 s35, s17, s23
	s_cselect_b32 s34, s24, s22
	s_cselect_b32 s23, s15, s27
	s_cselect_b32 s22, s25, s26
	v_lshl_add_u64 v[226:227], s[20:21], 0, v[138:139]
	s_add_i32 m0, s42, 0xc000
	ds_read_b128 v[194:197], v160
	ds_read_b128 v[198:201], v160 offset:1024
	ds_read_b128 v[202:205], v160 offset:2048
	ds_read_b128 v[206:209], v160 offset:3072
	ds_read_b128 v[210:213], v160 offset:4096
	ds_read_b128 v[214:217], v160 offset:5120
	ds_read_b128 v[218:221], v160 offset:6144
	ds_read_b128 v[222:225], v160 offset:7168
	global_load_lds_dwordx4 v[226:227], off
	v_lshl_add_u64 v[226:227], s[20:21], 0, v[140:141]
	s_add_i32 m0, s42, 0xe000
	s_nop 0
	global_load_lds_dwordx4 v[226:227], off
	s_waitcnt vmcnt(8)
	s_waitcnt lgkmcnt(0)
	s_barrier
	s_waitcnt lgkmcnt(0)
	v_mfma_f32_16x16x32_bf16 v[124:127], v[162:165], v[194:197], v[124:127]
	v_mfma_f32_16x16x32_bf16 v[120:123], v[170:173], v[194:197], v[120:123]
	v_mfma_f32_16x16x32_bf16 v[108:111], v[162:165], v[202:205], v[108:111]
	v_mfma_f32_16x16x32_bf16 v[104:107], v[170:173], v[202:205], v[104:107]
	v_mfma_f32_16x16x32_bf16 v[92:95], v[162:165], v[210:213], v[92:95]
	v_mfma_f32_16x16x32_bf16 v[88:91], v[170:173], v[210:213], v[88:91]
	v_mfma_f32_16x16x32_bf16 v[76:79], v[162:165], v[218:221], v[76:79]
	v_mfma_f32_16x16x32_bf16 v[72:75], v[170:173], v[218:221], v[72:75]
	v_mfma_f32_16x16x32_bf16 v[124:127], v[166:169], v[198:201], v[124:127]
	v_mfma_f32_16x16x32_bf16 v[120:123], v[174:177], v[198:201], v[120:123]
	v_mfma_f32_16x16x32_bf16 v[108:111], v[166:169], v[206:209], v[108:111]
	v_mfma_f32_16x16x32_bf16 v[104:107], v[174:177], v[206:209], v[104:107]
	v_mfma_f32_16x16x32_bf16 v[92:95], v[166:169], v[214:217], v[92:95]
	v_mfma_f32_16x16x32_bf16 v[88:91], v[174:177], v[214:217], v[88:91]
	v_mfma_f32_16x16x32_bf16 v[76:79], v[166:169], v[222:225], v[76:79]
	v_mfma_f32_16x16x32_bf16 v[72:75], v[174:177], v[222:225], v[72:75]
	v_mfma_f32_16x16x32_bf16 v[116:119], v[178:181], v[194:197], v[116:119]
	v_mfma_f32_16x16x32_bf16 v[112:115], v[186:189], v[194:197], v[112:115]
	v_mfma_f32_16x16x32_bf16 v[100:103], v[178:181], v[202:205], v[100:103]
	v_mfma_f32_16x16x32_bf16 v[96:99], v[186:189], v[202:205], v[96:99]
	v_mfma_f32_16x16x32_bf16 v[84:87], v[178:181], v[210:213], v[84:87]
	v_mfma_f32_16x16x32_bf16 v[80:83], v[186:189], v[210:213], v[80:83]
	v_mfma_f32_16x16x32_bf16 v[68:71], v[178:181], v[218:221], v[68:71]
	v_mfma_f32_16x16x32_bf16 v[64:67], v[186:189], v[218:221], v[64:67]
	v_mfma_f32_16x16x32_bf16 v[116:119], v[182:185], v[198:201], v[116:119]
	v_mfma_f32_16x16x32_bf16 v[112:115], v[190:193], v[198:201], v[112:115]
	v_mfma_f32_16x16x32_bf16 v[100:103], v[182:185], v[206:209], v[100:103]
	v_mfma_f32_16x16x32_bf16 v[96:99], v[190:193], v[206:209], v[96:99]
	v_mfma_f32_16x16x32_bf16 v[84:87], v[182:185], v[214:217], v[84:87]
	v_mfma_f32_16x16x32_bf16 v[80:83], v[190:193], v[214:217], v[80:83]
	v_mfma_f32_16x16x32_bf16 v[68:71], v[182:185], v[222:225], v[68:71]
	v_mfma_f32_16x16x32_bf16 v[64:67], v[190:193], v[222:225], v[64:67]
	s_barrier
; #define PG8_STAGE(bufoff, gbase, voff) do { _Pragma("unroll") for (int _i = 0; _i < 2; ++_i) \
;         __builtin_amdgcn_global_load_lds((const unsigned*)((const char*)(gbase) + (voff)[_i]), (PG8_LAS unsigned*)(lds + (bufoff) + ldsw + _i * 8192), 16, 0, PG8_LOAD_AUX); } while (0)
; #define PG8_LDA(dst, b, h) do { _Pragma("unroll") for (int m = 0; m < 4; ++m) _Pragma("unroll") for (int k = 0; k < 2; ++k) dst[m][k] = *(const PG8_LAS bf16x8*)(lds + PG8_SA(b, h) + aoff + m * 2048 + k * 1024); } while (0)
; #define PG8_LDB(dst, b, h) do { _Pragma("unroll") for (int n = 0; n < 2; ++n) _Pragma("unroll") for (int k = 0; k < 2; ++k) dst[n][k] = *(const PG8_LAS bf16x8*)(lds + PG8_SB(b, h) + boff + n * 2048 + k * 1024); } while (0)
; #define PG8_MMA(ai, bj, At, Bt) do { __builtin_amdgcn_s_setprio(1); _Pragma("unroll") for (int m = 0; m < 4; ++m) _Pragma("unroll") for (int n = 0; n < 2; ++n) _Pragma("unroll") for (int k = 0; k < 2; ++k) \
;         acc[ai][bj][m][n] = __builtin_amdgcn_mfma_f32_16x16x32_bf16(Bt[n][k], At[m][k], acc[ai][bj][m][n], 0, 0, 0); __builtin_amdgcn_s_setprio(0); } while (0)
; #define PG8_WAIT_V(n) asm volatile("s_waitcnt vmcnt(" #n ")" ::: "memory")
; #define PG8_WAIT_L(n) asm volatile("s_waitcnt lgkmcnt(" #n ")" ::: "memory")
; #define PG8_BAR __builtin_amdgcn_s_barrier()
; #define PG8_SCHED __builtin_amdgcn_sched_barrier(0)
; template <class Epi, class Sched, bool ALIGN_EPI = false, bool SP2 = false>
; __device__ __forceinline__ void gemm_phase(PG8_LAS unsigned char* lds, const Gemm g, const Sched& S, const Epi& E) {
;     ...
;             PG8_LDA(At, 0, 1); PG8_STAGE(PG8_SB(0, 0), b2, voffB); PG8_STAGE(PG8_SB(0, 1), b2 + hstepB, voffB); PG8_STAGE(PG8_SA(0, 0), a2, voffA);
;             PG8_WAIT_V(8); PG8_WAIT_L(0); PG8_BAR; PG8_MMA(1, 0, At, B0); PG8_MMA(1, 1, At, B1); PG8_BAR; PG8_SCHED;
;             PG8_LDB(B0, 1, 0); PG8_LDB(B1, 1, 1); PG8_SCHED; PG8_LDA(At, 1, 0); PG8_STAGE(PG8_SA(0, 1), a2 + hstepA, voffA);
;             PG8_WAIT_V(8); PG8_WAIT_L(0); PG8_BAR; PG8_MMA(0, 0, At, B0); PG8_MMA(0, 1, At, B1); PG8_BAR; PG8_SCHED;
	s_add_i32 s29, s51, s33
	v_lshl_add_u64 v[226:227], s[22:23], 0, v[130:131]
	s_mov_b32 m0, s29
	ds_read_b128 v[194:197], v160 offset:16384
	ds_read_b128 v[198:201], v160 offset:17408
	ds_read_b128 v[202:205], v160 offset:18432
	ds_read_b128 v[206:209], v160 offset:19456
	ds_read_b128 v[210:213], v160 offset:20480
	ds_read_b128 v[214:217], v160 offset:21504
	ds_read_b128 v[218:221], v160 offset:22528
	ds_read_b128 v[222:225], v160 offset:23552
	global_load_lds_dwordx4 v[226:227], off
	s_add_i32 m0, s29, 0x2000
	s_add_u32 s30, s22, 0x10000
	v_lshl_add_u64 v[228:229], s[22:23], 0, v[134:135]
	s_addc_u32 s31, s23, 0
	s_add_i32 s29, s52, s33
	global_load_lds_dwordx4 v[228:229], off
	v_lshl_add_u64 v[230:231], s[30:31], 0, v[130:131]
	s_mov_b32 m0, s29
	v_lshl_add_u64 v[232:233], s[34:35], 0, v[132:133]
	global_load_lds_dwordx4 v[230:231], off
	v_lshl_add_u64 v[230:231], s[30:31], 0, v[134:135]
	s_add_i32 m0, s29, 0x2000
	s_nop 0
	global_load_lds_dwordx4 v[230:231], off
	v_lshl_add_u64 v[230:231], s[34:35], 0, v[128:129]
	s_mov_b32 m0, s42
	s_nop 0
	global_load_lds_dwordx4 v[230:231], off
	s_mov_b32 m0, s43
	s_nop 0
	global_load_lds_dwordx4 v[232:233], off
	s_waitcnt vmcnt(8)
	s_waitcnt lgkmcnt(0)
	s_barrier
	s_waitcnt lgkmcnt(0)
	v_mfma_f32_16x16x32_bf16 v[60:63], v[162:165], v[194:197], v[60:63]
	v_mfma_f32_16x16x32_bf16 v[56:59], v[170:173], v[194:197], v[56:59]
	v_mfma_f32_16x16x32_bf16 v[44:47], v[162:165], v[202:205], v[44:47]
	v_mfma_f32_16x16x32_bf16 v[40:43], v[170:173], v[202:205], v[40:43]
	v_mfma_f32_16x16x32_bf16 v[28:31], v[162:165], v[210:213], v[28:31]
	v_mfma_f32_16x16x32_bf16 v[24:27], v[170:173], v[210:213], v[24:27]
	v_mfma_f32_16x16x32_bf16 v[12:15], v[162:165], v[218:221], v[12:15]
	v_mfma_f32_16x16x32_bf16 v[8:11], v[170:173], v[218:221], v[8:11]
	v_mfma_f32_16x16x32_bf16 v[60:63], v[166:169], v[198:201], v[60:63]
	v_mfma_f32_16x16x32_bf16 v[56:59], v[174:177], v[198:201], v[56:59]
	v_mfma_f32_16x16x32_bf16 v[44:47], v[166:169], v[206:209], v[44:47]
	v_mfma_f32_16x16x32_bf16 v[40:43], v[174:177], v[206:209], v[40:43]
	v_mfma_f32_16x16x32_bf16 v[28:31], v[166:169], v[214:217], v[28:31]
	v_mfma_f32_16x16x32_bf16 v[24:27], v[174:177], v[214:217], v[24:27]
	v_mfma_f32_16x16x32_bf16 v[12:15], v[166:169], v[222:225], v[12:15]
	v_mfma_f32_16x16x32_bf16 v[8:11], v[174:177], v[222:225], v[8:11]
	v_mfma_f32_16x16x32_bf16 v[52:55], v[178:181], v[194:197], v[52:55]
	v_mfma_f32_16x16x32_bf16 v[48:51], v[186:189], v[194:197], v[48:51]
	v_mfma_f32_16x16x32_bf16 v[36:39], v[178:181], v[202:205], v[36:39]
	v_mfma_f32_16x16x32_bf16 v[32:35], v[186:189], v[202:205], v[32:35]
	v_mfma_f32_16x16x32_bf16 v[20:23], v[178:181], v[210:213], v[20:23]
	v_mfma_f32_16x16x32_bf16 v[16:19], v[186:189], v[210:213], v[16:19]
	v_mfma_f32_16x16x32_bf16 v[4:7], v[178:181], v[218:221], v[4:7]
	v_mfma_f32_16x16x32_bf16 v[0:3], v[186:189], v[218:221], v[0:3]
	v_mfma_f32_16x16x32_bf16 v[52:55], v[182:185], v[198:201], v[52:55]
	v_mfma_f32_16x16x32_bf16 v[48:51], v[190:193], v[198:201], v[48:51]
	v_mfma_f32_16x16x32_bf16 v[36:39], v[182:185], v[206:209], v[36:39]
	v_mfma_f32_16x16x32_bf16 v[32:35], v[190:193], v[206:209], v[32:35]
	v_mfma_f32_16x16x32_bf16 v[20:23], v[182:185], v[214:217], v[20:23]
	v_mfma_f32_16x16x32_bf16 v[16:19], v[190:193], v[214:217], v[16:19]
	v_mfma_f32_16x16x32_bf16 v[4:7], v[182:185], v[222:225], v[4:7]
	v_mfma_f32_16x16x32_bf16 v[0:3], v[190:193], v[222:225], v[0:3]
	s_barrier
.Lkmid_P1:
	s_add_i32 s29, 0, 0x18000
	v_add_u32_e32 v161, s29, v146
	s_add_i32 s38, 0, 0x1c000
	ds_read_b128 v[162:165], v161
	ds_read_b128 v[166:169], v161 offset:1024
	ds_read_b128 v[170:173], v161 offset:2048
	ds_read_b128 v[174:177], v161 offset:3072
	v_add_u32_e32 v161, s38, v146
	ds_read_b128 v[178:181], v161
	ds_read_b128 v[182:185], v161 offset:1024
	ds_read_b128 v[186:189], v161 offset:2048
	ds_read_b128 v[190:193], v161 offset:3072
	s_add_u32 s30, s34, 0x40000
	s_addc_u32 s31, s35, 0
	s_mov_b32 m0, s44
	v_lshl_add_u64 v[234:235], s[30:31], 0, v[128:129]
	ds_read_b128 v[194:197], v160 offset:32768
	ds_read_b128 v[198:201], v160 offset:33792
	ds_read_b128 v[202:205], v160 offset:34816
	ds_read_b128 v[206:209], v160 offset:35840
	ds_read_b128 v[210:213], v160 offset:36864
	ds_read_b128 v[214:217], v160 offset:37888
	ds_read_b128 v[218:221], v160 offset:38912
	ds_read_b128 v[222:225], v160 offset:39936
	global_load_lds_dwordx4 v[234:235], off
	v_lshl_add_u64 v[234:235], s[30:31], 0, v[132:133]
	s_mov_b32 m0, s45
	s_nop 0
	global_load_lds_dwordx4 v[234:235], off
	s_waitcnt vmcnt(8)
	s_waitcnt lgkmcnt(0)
	s_barrier
; #define PG8_STAGE(bufoff, gbase, voff) do { _Pragma("unroll") for (int _i = 0; _i < 2; ++_i) \
;         __builtin_amdgcn_global_load_lds((const unsigned*)((const char*)(gbase) + (voff)[_i]), (PG8_LAS unsigned*)(lds + (bufoff) + ldsw + _i * 8192), 16, 0, PG8_LOAD_AUX); } while (0)
; #define PG8_LDA(dst, b, h) do { _Pragma("unroll") for (int m = 0; m < 4; ++m) _Pragma("unroll") for (int k = 0; k < 2; ++k) dst[m][k] = *(const PG8_LAS bf16x8*)(lds + PG8_SA(b, h) + aoff + m * 2048 + k * 1024); } while (0)
; #define PG8_MMA(ai, bj, At, Bt) do { __builtin_amdgcn_s_setprio(1); _Pragma("unroll") for (int m = 0; m < 4; ++m) _Pragma("unroll") for (int n = 0; n < 2; ++n) _Pragma("unroll") for (int k = 0; k < 2; ++k) \
;         acc[ai][bj][m][n] = __builtin_amdgcn_mfma_f32_16x16x32_bf16(Bt[n][k], At[m][k], acc[ai][bj][m][n], 0, 0, 0); __builtin_amdgcn_s_setprio(0); } while (0)
; #define PG8_WAIT_V(n) asm volatile("s_waitcnt vmcnt(" #n ")" ::: "memory")
; #define PG8_WAIT_L(n) asm volatile("s_waitcnt lgkmcnt(" #n ")" ::: "memory")
; #define PG8_BAR __builtin_amdgcn_s_barrier()
; #define PG8_SCHED __builtin_amdgcn_sched_barrier(0)
; template <class Epi, class Sched, bool ALIGN_EPI = false, bool SP2 = false>
; __device__ __forceinline__ void gemm_phase(PG8_LAS unsigned char* lds, const Gemm g, const Sched& S, const Epi& E) {
;     ...
;             PG8_WAIT_V(8); PG8_WAIT_L(0); PG8_BAR; PG8_MMA(0, 0, At, B0); PG8_MMA(0, 1, At, B1); PG8_BAR; PG8_SCHED;
;             PG8_LDA(At, 1, 1); PG8_STAGE(PG8_SB(1, 0), b3, voffB); PG8_STAGE(PG8_SB(1, 1), b3 + hstepB, voffB); PG8_STAGE(PG8_SA(1, 0), a3, voffA);
;             PG8_WAIT_V(8); PG8_WAIT_L(0); PG8_BAR; PG8_MMA(1, 0, At, B0); PG8_MMA(1, 1, At, B1); PG8_BAR; PG8_SCHED;
	s_waitcnt lgkmcnt(0)
	v_mfma_f32_16x16x32_bf16 v[124:127], v[162:165], v[194:197], v[124:127]
	v_mfma_f32_16x16x32_bf16 v[120:123], v[170:173], v[194:197], v[120:123]
	v_mfma_f32_16x16x32_bf16 v[108:111], v[162:165], v[202:205], v[108:111]
	v_mfma_f32_16x16x32_bf16 v[104:107], v[170:173], v[202:205], v[104:107]
	v_mfma_f32_16x16x32_bf16 v[92:95], v[162:165], v[210:213], v[92:95]
	v_mfma_f32_16x16x32_bf16 v[88:91], v[170:173], v[210:213], v[88:91]
	v_mfma_f32_16x16x32_bf16 v[76:79], v[162:165], v[218:221], v[76:79]
	v_mfma_f32_16x16x32_bf16 v[72:75], v[170:173], v[218:221], v[72:75]
	v_mfma_f32_16x16x32_bf16 v[124:127], v[166:169], v[198:201], v[124:127]
	v_mfma_f32_16x16x32_bf16 v[120:123], v[174:177], v[198:201], v[120:123]
	v_mfma_f32_16x16x32_bf16 v[108:111], v[166:169], v[206:209], v[108:111]
	v_mfma_f32_16x16x32_bf16 v[104:107], v[174:177], v[206:209], v[104:107]
	v_mfma_f32_16x16x32_bf16 v[92:95], v[166:169], v[214:217], v[92:95]
	v_mfma_f32_16x16x32_bf16 v[88:91], v[174:177], v[214:217], v[88:91]
	v_mfma_f32_16x16x32_bf16 v[76:79], v[166:169], v[222:225], v[76:79]
	v_mfma_f32_16x16x32_bf16 v[72:75], v[174:177], v[222:225], v[72:75]
	v_mfma_f32_16x16x32_bf16 v[116:119], v[178:181], v[194:197], v[116:119]
	v_mfma_f32_16x16x32_bf16 v[112:115], v[186:189], v[194:197], v[112:115]
	v_mfma_f32_16x16x32_bf16 v[100:103], v[178:181], v[202:205], v[100:103]
	v_mfma_f32_16x16x32_bf16 v[96:99], v[186:189], v[202:205], v[96:99]
	v_mfma_f32_16x16x32_bf16 v[84:87], v[178:181], v[210:213], v[84:87]
	v_mfma_f32_16x16x32_bf16 v[80:83], v[186:189], v[210:213], v[80:83]
	v_mfma_f32_16x16x32_bf16 v[68:71], v[178:181], v[218:221], v[68:71]
	v_mfma_f32_16x16x32_bf16 v[64:67], v[186:189], v[218:221], v[64:67]
	v_mfma_f32_16x16x32_bf16 v[116:119], v[182:185], v[198:201], v[116:119]
	v_mfma_f32_16x16x32_bf16 v[112:115], v[190:193], v[198:201], v[112:115]
	v_mfma_f32_16x16x32_bf16 v[100:103], v[182:185], v[206:209], v[100:103]
	v_mfma_f32_16x16x32_bf16 v[96:99], v[190:193], v[206:209], v[96:99]
	v_mfma_f32_16x16x32_bf16 v[84:87], v[182:185], v[214:217], v[84:87]
	v_mfma_f32_16x16x32_bf16 v[80:83], v[190:193], v[214:217], v[80:83]
	v_mfma_f32_16x16x32_bf16 v[68:71], v[182:185], v[222:225], v[68:71]
	v_mfma_f32_16x16x32_bf16 v[64:67], v[190:193], v[222:225], v[64:67]
	s_barrier
	s_add_i32 s29, s29, s33
	v_lshl_add_u64 v[226:227], v[226:227], 0, s[10:11]
	s_mov_b32 m0, s29
	ds_read_b128 v[194:197], v160 offset:49152
	ds_read_b128 v[198:201], v160 offset:50176
	ds_read_b128 v[202:205], v160 offset:51200
	ds_read_b128 v[206:209], v160 offset:52224
	ds_read_b128 v[210:213], v160 offset:53248
	ds_read_b128 v[214:217], v160 offset:54272
	ds_read_b128 v[218:221], v160 offset:55296
	ds_read_b128 v[222:225], v160 offset:56320
	global_load_lds_dwordx4 v[226:227], off
	s_add_i32 m0, s29, 0x2000
	s_add_u32 s22, s22, 0x10080
	v_lshl_add_u64 v[226:227], v[228:229], 0, s[10:11]
	s_addc_u32 s23, s23, 0
	s_add_i32 s29, s38, s33
	global_load_lds_dwordx4 v[226:227], off
	v_lshl_add_u64 v[226:227], s[22:23], 0, v[130:131]
	s_mov_b32 m0, s29
	s_nop 0
	global_load_lds_dwordx4 v[226:227], off
	v_lshl_add_u64 v[226:227], s[22:23], 0, v[134:135]
	s_add_i32 m0, s29, 0x2000
	s_nop 0
	global_load_lds_dwordx4 v[226:227], off
	v_lshl_add_u64 v[226:227], v[230:231], 0, s[10:11]
	s_mov_b32 m0, s48
	s_nop 0
	global_load_lds_dwordx4 v[226:227], off
	v_lshl_add_u64 v[226:227], v[232:233], 0, s[10:11]
	s_mov_b32 m0, s49
	s_nop 0
	global_load_lds_dwordx4 v[226:227], off
	s_waitcnt vmcnt(8)
	s_waitcnt lgkmcnt(0)
	s_barrier
	s_waitcnt lgkmcnt(0)
	v_mfma_f32_16x16x32_bf16 v[60:63], v[162:165], v[194:197], v[60:63]
	v_mfma_f32_16x16x32_bf16 v[56:59], v[170:173], v[194:197], v[56:59]
	v_mfma_f32_16x16x32_bf16 v[44:47], v[162:165], v[202:205], v[44:47]
	v_mfma_f32_16x16x32_bf16 v[40:43], v[170:173], v[202:205], v[40:43]
	v_mfma_f32_16x16x32_bf16 v[28:31], v[162:165], v[210:213], v[28:31]
	v_mfma_f32_16x16x32_bf16 v[24:27], v[170:173], v[210:213], v[24:27]
	v_mfma_f32_16x16x32_bf16 v[12:15], v[162:165], v[218:221], v[12:15]
	v_mfma_f32_16x16x32_bf16 v[8:11], v[170:173], v[218:221], v[8:11]
	v_mfma_f32_16x16x32_bf16 v[60:63], v[166:169], v[198:201], v[60:63]
	v_mfma_f32_16x16x32_bf16 v[56:59], v[174:177], v[198:201], v[56:59]
	v_mfma_f32_16x16x32_bf16 v[44:47], v[166:169], v[206:209], v[44:47]
	v_mfma_f32_16x16x32_bf16 v[40:43], v[174:177], v[206:209], v[40:43]
	v_mfma_f32_16x16x32_bf16 v[28:31], v[166:169], v[214:217], v[28:31]
	v_mfma_f32_16x16x32_bf16 v[24:27], v[174:177], v[214:217], v[24:27]
	v_mfma_f32_16x16x32_bf16 v[12:15], v[166:169], v[222:225], v[12:15]
	v_mfma_f32_16x16x32_bf16 v[8:11], v[174:177], v[222:225], v[8:11]
	v_mfma_f32_16x16x32_bf16 v[52:55], v[178:181], v[194:197], v[52:55]
	v_mfma_f32_16x16x32_bf16 v[48:51], v[186:189], v[194:197], v[48:51]
	v_mfma_f32_16x16x32_bf16 v[36:39], v[178:181], v[202:205], v[36:39]
	v_mfma_f32_16x16x32_bf16 v[32:35], v[186:189], v[202:205], v[32:35]
	v_mfma_f32_16x16x32_bf16 v[20:23], v[178:181], v[210:213], v[20:23]
	v_mfma_f32_16x16x32_bf16 v[16:19], v[186:189], v[210:213], v[16:19]
	v_mfma_f32_16x16x32_bf16 v[4:7], v[178:181], v[218:221], v[4:7]
	v_mfma_f32_16x16x32_bf16 v[0:3], v[186:189], v[218:221], v[0:3]
	v_mfma_f32_16x16x32_bf16 v[52:55], v[182:185], v[198:201], v[52:55]
	v_mfma_f32_16x16x32_bf16 v[48:51], v[190:193], v[198:201], v[48:51]
	v_mfma_f32_16x16x32_bf16 v[36:39], v[182:185], v[206:209], v[36:39]
	v_mfma_f32_16x16x32_bf16 v[32:35], v[190:193], v[206:209], v[32:35]
	v_mfma_f32_16x16x32_bf16 v[20:23], v[182:185], v[214:217], v[20:23]
	v_mfma_f32_16x16x32_bf16 v[16:19], v[190:193], v[214:217], v[16:19]
	v_mfma_f32_16x16x32_bf16 v[4:7], v[182:185], v[222:225], v[4:7]
	v_mfma_f32_16x16x32_bf16 v[0:3], v[190:193], v[222:225], v[0:3]
	s_barrier
	s_add_i32 s28, s28, 2
	s_add_u32 s20, s20, 0x100
	s_addc_u32 s21, s21, 0
	s_add_u32 s26, s26, 0x100
	s_addc_u32 s27, s27, 0
	s_cmp_gt_u32 s28, 13
	s_cbranch_scc0 .LBB0_215
	s_and_b64 vcc, exec, s[12:13]
	s_cbranch_vccz .LBB0_218
	s_barrier

; #define PG8_STAGE(bufoff, gbase, voff) do { _Pragma("unroll") for (int _i = 0; _i < 2; ++_i) \
;         __builtin_amdgcn_global_load_lds((const unsigned*)((const char*)(gbase) + (voff)[_i]), (PG8_LAS unsigned*)(lds + (bufoff) + ldsw + _i * 8192), 16, 0, PG8_LOAD_AUX); } while (0)
; #define PG8_LDA(dst, b, h) do { _Pragma("unroll") for (int m = 0; m < 4; ++m) _Pragma("unroll") for (int k = 0; k < 2; ++k) dst[m][k] = *(const PG8_LAS bf16x8*)(lds + PG8_SA(b, h) + aoff + m * 2048 + k * 1024); } while (0)
; #define PG8_LDB(dst, b, h) do { _Pragma("unroll") for (int n = 0; n < 2; ++n) _Pragma("unroll") for (int k = 0; k < 2; ++k) dst[n][k] = *(const PG8_LAS bf16x8*)(lds + PG8_SB(b, h) + boff + n * 2048 + k * 1024); } while (0)
; #define PG8_WAIT_V(n) asm volatile("s_waitcnt vmcnt(" #n ")" ::: "memory")
; #define PG8_WAIT_L(n) asm volatile("s_waitcnt lgkmcnt(" #n ")" ::: "memory")
; #define PG8_BAR __builtin_amdgcn_s_barrier()
; #define PG8_SCHED __builtin_amdgcn_sched_barrier(0)
; template <class Epi, class Sched, bool ALIGN_EPI = false, bool SP2 = false>
; __device__ __forceinline__ void gemm_phase(PG8_LAS unsigned char* lds, const Gemm g, const Sched& S, const Epi& E) {
;     ...
;         const char* nA = has_next ? (const char*)g.A + (size_t)nxt.pm * tstepA + (size_t)nxt.pn * apn : cA; const char* nB = has_next ? (const char*)g.Bt + (size_t)nxt.pn * tstepB : cB;
;         for (int t = 0; t < nt; t += 2) {
;             const bool last = (t == nt - 2);
;             const char* a1 = cA + (size_t)(t + 1) * kstep;
;             const char* a2 = last ? nA : cA + (size_t)(t + 2) * kstep; const char* b2 = last ? nB : cB + (size_t)(t + 2) * kstep;
;             const char* a3 = a2 + kstep; const char* b3 = b2 + kstep;
;             if (last && has_next) S.a_ready(nxt);
;             if constexpr (SP2) {
;             PG8_LDB(B0, 0, 0); PG8_LDB(B1, 0, 1); PG8_SCHED; PG8_LDA(At, 0, 0); PG8_STAGE(PG8_SA(1, 1), a1 + hstepA, voffA);
;             PG8_WAIT_V(8); PG8_WAIT_L(0); PG8_BAR; PG8_MMA(0, 0, At, B0); PG8_MMA(0, 1, At, B1); PG8_BAR; PG8_SCHED;
;             PG8_LDA(At, 0, 1); PG8_STAGE(PG8_SB(0, 0), b2, voffB); PG8_STAGE(PG8_SB(0, 1), b2 + hstepB, voffB); PG8_STAGE(PG8_SA(0, 0), a2, voffA);
;             PG8_WAIT_V(8); PG8_WAIT_L(0); PG8_BAR; PG8_MMA(1, 0, At, B0); PG8_MMA(1, 1, At, B1); PG8_BAR; PG8_SCHED;
.LBB0_368:
	s_ashr_i32 s17, s16, 31
	s_lshl_b64 s[18:19], s[16:17], 19
	s_add_u32 s18, s33, s18
	s_addc_u32 s19, s36, s19
	s_and_b64 s[24:25], s[4:5], exec
	s_cselect_b32 s17, s19, s21
	s_cselect_b32 s24, s18, s20
	s_ashr_i32 s15, s14, 31
	s_lshl_b64 s[26:27], s[14:15], 19
	s_add_u32 s40, s64, s26
	s_addc_u32 s41, s65, s27
	s_and_b64 s[26:27], s[4:5], exec
	s_cselect_b32 s15, s41, s23
	s_cselect_b32 s25, s40, s22
	s_add_u32 s20, s20, 0x40080
	s_addc_u32 s21, s21, 0
	s_add_u32 s26, s22, 0x100
	s_addc_u32 s27, s23, 0
	s_mov_b32 s28, -2
	ds_read_b128 v[162:165], v159
	ds_read_b128 v[166:169], v159 offset:1024
	ds_read_b128 v[170:173], v159 offset:2048
	ds_read_b128 v[174:177], v159 offset:3072
	ds_read_b128 v[178:181], v160
	ds_read_b128 v[182:185], v160 offset:1024
	ds_read_b128 v[186:189], v160 offset:2048
	ds_read_b128 v[190:193], v160 offset:3072
	s_add_u32 s22, s20, 0xfffc0080
	s_addc_u32 s23, s21, -1
	s_cmp_eq_u32 s28, 12
	s_cselect_b32 s35, s17, s23
	s_cselect_b32 s34, s24, s22
	s_cselect_b32 s23, s15, s27
	s_cselect_b32 s22, s25, s26
	v_lshl_add_u64 v[226:227], s[20:21], 0, v[138:139]
	s_add_i32 m0, s44, 0xc000
	ds_read_b128 v[194:197], v161
	ds_read_b128 v[198:201], v161 offset:1024
	ds_read_b128 v[202:205], v161 offset:2048
	ds_read_b128 v[206:209], v161 offset:3072
	ds_read_b128 v[210:213], v161 offset:4096
	ds_read_b128 v[214:217], v161 offset:5120
	ds_read_b128 v[218:221], v161 offset:6144
	ds_read_b128 v[222:225], v161 offset:7168
	global_load_lds_dwordx4 v[226:227], off
	v_lshl_add_u64 v[226:227], s[20:21], 0, v[140:141]
	s_add_i32 m0, s44, 0xe000
	s_nop 0
	global_load_lds_dwordx4 v[226:227], off
	s_waitcnt vmcnt(8)
	s_waitcnt lgkmcnt(0)
	s_barrier
	s_waitcnt lgkmcnt(0)
	v_mfma_f32_16x16x32_bf16 v[124:127], v[162:165], v[194:197], 0
	v_mfma_f32_16x16x32_bf16 v[120:123], v[170:173], v[194:197], 0
	v_mfma_f32_16x16x32_bf16 v[108:111], v[162:165], v[202:205], 0
	v_mfma_f32_16x16x32_bf16 v[104:107], v[170:173], v[202:205], 0
	v_mfma_f32_16x16x32_bf16 v[92:95], v[162:165], v[210:213], 0
	v_mfma_f32_16x16x32_bf16 v[88:91], v[170:173], v[210:213], 0
	v_mfma_f32_16x16x32_bf16 v[76:79], v[162:165], v[218:221], 0
	v_mfma_f32_16x16x32_bf16 v[72:75], v[170:173], v[218:221], 0
	v_mfma_f32_16x16x32_bf16 v[124:127], v[166:169], v[198:201], v[124:127]
	v_mfma_f32_16x16x32_bf16 v[120:123], v[174:177], v[198:201], v[120:123]
	v_mfma_f32_16x16x32_bf16 v[108:111], v[166:169], v[206:209], v[108:111]
	v_mfma_f32_16x16x32_bf16 v[104:107], v[174:177], v[206:209], v[104:107]
	v_mfma_f32_16x16x32_bf16 v[92:95], v[166:169], v[214:217], v[92:95]
	v_mfma_f32_16x16x32_bf16 v[88:91], v[174:177], v[214:217], v[88:91]
	v_mfma_f32_16x16x32_bf16 v[76:79], v[166:169], v[222:225], v[76:79]
	v_mfma_f32_16x16x32_bf16 v[72:75], v[174:177], v[222:225], v[72:75]
	v_mfma_f32_16x16x32_bf16 v[116:119], v[178:181], v[194:197], 0
	v_mfma_f32_16x16x32_bf16 v[112:115], v[186:189], v[194:197], 0
	v_mfma_f32_16x16x32_bf16 v[100:103], v[178:181], v[202:205], 0
	v_mfma_f32_16x16x32_bf16 v[96:99], v[186:189], v[202:205], 0
	v_mfma_f32_16x16x32_bf16 v[84:87], v[178:181], v[210:213], 0
	v_mfma_f32_16x16x32_bf16 v[80:83], v[186:189], v[210:213], 0
	v_mfma_f32_16x16x32_bf16 v[68:71], v[178:181], v[218:221], 0
	v_mfma_f32_16x16x32_bf16 v[64:67], v[186:189], v[218:221], 0
	v_mfma_f32_16x16x32_bf16 v[116:119], v[182:185], v[198:201], v[116:119]
	v_mfma_f32_16x16x32_bf16 v[112:115], v[190:193], v[198:201], v[112:115]
	v_mfma_f32_16x16x32_bf16 v[100:103], v[182:185], v[206:209], v[100:103]
	v_mfma_f32_16x16x32_bf16 v[96:99], v[190:193], v[206:209], v[96:99]
	v_mfma_f32_16x16x32_bf16 v[84:87], v[182:185], v[214:217], v[84:87]
	v_mfma_f32_16x16x32_bf16 v[80:83], v[190:193], v[214:217], v[80:83]
	v_mfma_f32_16x16x32_bf16 v[68:71], v[182:185], v[222:225], v[68:71]
	v_mfma_f32_16x16x32_bf16 v[64:67], v[190:193], v[222:225], v[64:67]
	s_barrier
	s_add_i32 s29, s53, s37
	v_lshl_add_u64 v[226:227], s[22:23], 0, v[132:133]
	s_mov_b32 m0, s29
	ds_read_b128 v[194:197], v161 offset:16384
	ds_read_b128 v[198:201], v161 offset:17408
	ds_read_b128 v[202:205], v161 offset:18432
	ds_read_b128 v[206:209], v161 offset:19456
	ds_read_b128 v[210:213], v161 offset:20480
	ds_read_b128 v[214:217], v161 offset:21504
	ds_read_b128 v[218:221], v161 offset:22528
	ds_read_b128 v[222:225], v161 offset:23552
	global_load_lds_dwordx4 v[226:227], off
	s_add_i32 m0, s29, 0x2000
	s_add_u32 s30, s22, 0x10000
	v_lshl_add_u64 v[228:229], s[22:23], 0, v[128:129]
	s_addc_u32 s31, s23, 0
	s_add_i32 s29, s54, s37
	global_load_lds_dwordx4 v[228:229], off
	v_lshl_add_u64 v[230:231], s[30:31], 0, v[132:133]
	s_mov_b32 m0, s29
	v_lshl_add_u64 v[232:233], s[34:35], 0, v[130:131]
	global_load_lds_dwordx4 v[230:231], off
	v_lshl_add_u64 v[230:231], s[30:31], 0, v[128:129]
	s_add_i32 m0, s29, 0x2000
	s_nop 0
	global_load_lds_dwordx4 v[230:231], off
	v_lshl_add_u64 v[230:231], s[34:35], 0, v[134:135]
	s_mov_b32 m0, s44
	s_nop 0
	global_load_lds_dwordx4 v[230:231], off
	s_mov_b32 m0, s45
	s_nop 0
	global_load_lds_dwordx4 v[232:233], off
	s_waitcnt vmcnt(8)
	s_waitcnt lgkmcnt(0)
	s_barrier
; #define PG8_STAGE(bufoff, gbase, voff) do { _Pragma("unroll") for (int _i = 0; _i < 2; ++_i) \
;         __builtin_amdgcn_global_load_lds((const unsigned*)((const char*)(gbase) + (voff)[_i]), (PG8_LAS unsigned*)(lds + (bufoff) + ldsw + _i * 8192), 16, 0, PG8_LOAD_AUX); } while (0)
; #define PG8_LDA(dst, b, h) do { _Pragma("unroll") for (int m = 0; m < 4; ++m) _Pragma("unroll") for (int k = 0; k < 2; ++k) dst[m][k] = *(const PG8_LAS bf16x8*)(lds + PG8_SA(b, h) + aoff + m * 2048 + k * 1024); } while (0)
; #define PG8_LDB(dst, b, h) do { _Pragma("unroll") for (int n = 0; n < 2; ++n) _Pragma("unroll") for (int k = 0; k < 2; ++k) dst[n][k] = *(const PG8_LAS bf16x8*)(lds + PG8_SB(b, h) + boff + n * 2048 + k * 1024); } while (0)
; #define PG8_MMA(ai, bj, At, Bt) do { __builtin_amdgcn_s_setprio(1); _Pragma("unroll") for (int m = 0; m < 4; ++m) _Pragma("unroll") for (int n = 0; n < 2; ++n) _Pragma("unroll") for (int k = 0; k < 2; ++k) \
;         acc[ai][bj][m][n] = __builtin_amdgcn_mfma_f32_16x16x32_bf16(Bt[n][k], At[m][k], acc[ai][bj][m][n], 0, 0, 0); __builtin_amdgcn_s_setprio(0); } while (0)
; #define PG8_WAIT_V(n) asm volatile("s_waitcnt vmcnt(" #n ")" ::: "memory")
; #define PG8_WAIT_L(n) asm volatile("s_waitcnt lgkmcnt(" #n ")" ::: "memory")
; #define PG8_BAR __builtin_amdgcn_s_barrier()
; #define PG8_SCHED __builtin_amdgcn_sched_barrier(0)
; template <class Epi, class Sched, bool ALIGN_EPI = false, bool SP2 = false>
; __device__ __forceinline__ void gemm_phase(PG8_LAS unsigned char* lds, const Gemm g, const Sched& S, const Epi& E) {
;     ...
;             PG8_LDB(B0, 0, 0); PG8_LDB(B1, 0, 1); PG8_SCHED; PG8_LDA(At, 0, 0); PG8_STAGE(PG8_SA(1, 1), a1 + hstepA, voffA);
;             PG8_WAIT_V(8); PG8_WAIT_L(0); PG8_BAR; PG8_MMA(0, 0, At, B0); PG8_MMA(0, 1, At, B1); PG8_BAR; PG8_SCHED;
;             PG8_LDA(At, 0, 1); PG8_STAGE(PG8_SB(0, 0), b2, voffB); PG8_STAGE(PG8_SB(0, 1), b2 + hstepB, voffB); PG8_STAGE(PG8_SA(0, 0), a2, voffA);
;             PG8_WAIT_V(8); PG8_WAIT_L(0); PG8_BAR; PG8_MMA(1, 0, At, B0); PG8_MMA(1, 1, At, B1); PG8_BAR; PG8_SCHED;
	s_waitcnt lgkmcnt(0)
	v_mfma_f32_16x16x32_bf16 v[60:63], v[162:165], v[194:197], 0
	v_mfma_f32_16x16x32_bf16 v[56:59], v[170:173], v[194:197], 0
	v_mfma_f32_16x16x32_bf16 v[44:47], v[162:165], v[202:205], 0
	v_mfma_f32_16x16x32_bf16 v[40:43], v[170:173], v[202:205], 0
	v_mfma_f32_16x16x32_bf16 v[28:31], v[162:165], v[210:213], 0
	v_mfma_f32_16x16x32_bf16 v[24:27], v[170:173], v[210:213], 0
	v_mfma_f32_16x16x32_bf16 v[12:15], v[162:165], v[218:221], 0
	v_mfma_f32_16x16x32_bf16 v[8:11], v[170:173], v[218:221], 0
	v_mfma_f32_16x16x32_bf16 v[60:63], v[166:169], v[198:201], v[60:63]
	v_mfma_f32_16x16x32_bf16 v[56:59], v[174:177], v[198:201], v[56:59]
	v_mfma_f32_16x16x32_bf16 v[44:47], v[166:169], v[206:209], v[44:47]
	v_mfma_f32_16x16x32_bf16 v[40:43], v[174:177], v[206:209], v[40:43]
	v_mfma_f32_16x16x32_bf16 v[28:31], v[166:169], v[214:217], v[28:31]
	v_mfma_f32_16x16x32_bf16 v[24:27], v[174:177], v[214:217], v[24:27]
	v_mfma_f32_16x16x32_bf16 v[12:15], v[166:169], v[222:225], v[12:15]
	v_mfma_f32_16x16x32_bf16 v[8:11], v[174:177], v[222:225], v[8:11]
	v_mfma_f32_16x16x32_bf16 v[52:55], v[178:181], v[194:197], 0
	v_mfma_f32_16x16x32_bf16 v[48:51], v[186:189], v[194:197], 0
	v_mfma_f32_16x16x32_bf16 v[36:39], v[178:181], v[202:205], 0
	v_mfma_f32_16x16x32_bf16 v[32:35], v[186:189], v[202:205], 0
	v_mfma_f32_16x16x32_bf16 v[20:23], v[178:181], v[210:213], 0
	v_mfma_f32_16x16x32_bf16 v[16:19], v[186:189], v[210:213], 0
	v_mfma_f32_16x16x32_bf16 v[4:7], v[178:181], v[218:221], 0
	v_mfma_f32_16x16x32_bf16 v[0:3], v[186:189], v[218:221], 0
	v_mfma_f32_16x16x32_bf16 v[52:55], v[182:185], v[198:201], v[52:55]
	v_mfma_f32_16x16x32_bf16 v[48:51], v[190:193], v[198:201], v[48:51]
	v_mfma_f32_16x16x32_bf16 v[36:39], v[182:185], v[206:209], v[36:39]
	v_mfma_f32_16x16x32_bf16 v[32:35], v[190:193], v[206:209], v[32:35]
	v_mfma_f32_16x16x32_bf16 v[20:23], v[182:185], v[214:217], v[20:23]
	v_mfma_f32_16x16x32_bf16 v[16:19], v[190:193], v[214:217], v[16:19]
	v_mfma_f32_16x16x32_bf16 v[4:7], v[182:185], v[222:225], v[4:7]
	v_mfma_f32_16x16x32_bf16 v[0:3], v[190:193], v[222:225], v[0:3]
	s_barrier
	s_branch .Lkmid_P3
.LBB0_369:
	ds_read_b128 v[162:165], v159
	ds_read_b128 v[166:169], v159 offset:1024
	ds_read_b128 v[170:173], v159 offset:2048
	ds_read_b128 v[174:177], v159 offset:3072
	ds_read_b128 v[178:181], v160
	ds_read_b128 v[182:185], v160 offset:1024
	ds_read_b128 v[186:189], v160 offset:2048
	ds_read_b128 v[190:193], v160 offset:3072
	s_add_u32 s22, s20, 0xfffc0080
	s_addc_u32 s23, s21, -1
	s_cmp_eq_u32 s28, 12
	s_cselect_b32 s35, s17, s23
	s_cselect_b32 s34, s24, s22
	s_cselect_b32 s23, s15, s27
	s_cselect_b32 s22, s25, s26
	v_lshl_add_u64 v[226:227], s[20:21], 0, v[138:139]
	s_add_i32 m0, s44, 0xc000
	ds_read_b128 v[194:197], v161
	ds_read_b128 v[198:201], v161 offset:1024
	ds_read_b128 v[202:205], v161 offset:2048
	ds_read_b128 v[206:209], v161 offset:3072
	ds_read_b128 v[210:213], v161 offset:4096
	ds_read_b128 v[214:217], v161 offset:5120
	ds_read_b128 v[218:221], v161 offset:6144
	ds_read_b128 v[222:225], v161 offset:7168
	global_load_lds_dwordx4 v[226:227], off
	v_lshl_add_u64 v[226:227], s[20:21], 0, v[140:141]
	s_add_i32 m0, s44, 0xe000
	s_nop 0
	global_load_lds_dwordx4 v[226:227], off
	s_waitcnt vmcnt(8)
	s_waitcnt lgkmcnt(0)
	s_barrier
	s_waitcnt lgkmcnt(0)
	v_mfma_f32_16x16x32_bf16 v[124:127], v[162:165], v[194:197], v[124:127]
	v_mfma_f32_16x16x32_bf16 v[120:123], v[170:173], v[194:197], v[120:123]
	v_mfma_f32_16x16x32_bf16 v[108:111], v[162:165], v[202:205], v[108:111]
	v_mfma_f32_16x16x32_bf16 v[104:107], v[170:173], v[202:205], v[104:107]
	v_mfma_f32_16x16x32_bf16 v[92:95], v[162:165], v[210:213], v[92:95]
	v_mfma_f32_16x16x32_bf16 v[88:91], v[170:173], v[210:213], v[88:91]
	v_mfma_f32_16x16x32_bf16 v[76:79], v[162:165], v[218:221], v[76:79]
	v_mfma_f32_16x16x32_bf16 v[72:75], v[170:173], v[218:221], v[72:75]
	v_mfma_f32_16x16x32_bf16 v[124:127], v[166:169], v[198:201], v[124:127]
	v_mfma_f32_16x16x32_bf16 v[120:123], v[174:177], v[198:201], v[120:123]
	v_mfma_f32_16x16x32_bf16 v[108:111], v[166:169], v[206:209], v[108:111]
	v_mfma_f32_16x16x32_bf16 v[104:107], v[174:177], v[206:209], v[104:107]
	v_mfma_f32_16x16x32_bf16 v[92:95], v[166:169], v[214:217], v[92:95]
	v_mfma_f32_16x16x32_bf16 v[88:91], v[174:177], v[214:217], v[88:91]
	v_mfma_f32_16x16x32_bf16 v[76:79], v[166:169], v[222:225], v[76:79]
	v_mfma_f32_16x16x32_bf16 v[72:75], v[174:177], v[222:225], v[72:75]
	v_mfma_f32_16x16x32_bf16 v[116:119], v[178:181], v[194:197], v[116:119]
	v_mfma_f32_16x16x32_bf16 v[112:115], v[186:189], v[194:197], v[112:115]
	v_mfma_f32_16x16x32_bf16 v[100:103], v[178:181], v[202:205], v[100:103]
	v_mfma_f32_16x16x32_bf16 v[96:99], v[186:189], v[202:205], v[96:99]
	v_mfma_f32_16x16x32_bf16 v[84:87], v[178:181], v[210:213], v[84:87]
	v_mfma_f32_16x16x32_bf16 v[80:83], v[186:189], v[210:213], v[80:83]
	v_mfma_f32_16x16x32_bf16 v[68:71], v[178:181], v[218:221], v[68:71]
	v_mfma_f32_16x16x32_bf16 v[64:67], v[186:189], v[218:221], v[64:67]
	v_mfma_f32_16x16x32_bf16 v[116:119], v[182:185], v[198:201], v[116:119]
	v_mfma_f32_16x16x32_bf16 v[112:115], v[190:193], v[198:201], v[112:115]
	v_mfma_f32_16x16x32_bf16 v[100:103], v[182:185], v[206:209], v[100:103]
	v_mfma_f32_16x16x32_bf16 v[96:99], v[190:193], v[206:209], v[96:99]
	v_mfma_f32_16x16x32_bf16 v[84:87], v[182:185], v[214:217], v[84:87]
	v_mfma_f32_16x16x32_bf16 v[80:83], v[190:193], v[214:217], v[80:83]
	v_mfma_f32_16x16x32_bf16 v[68:71], v[182:185], v[222:225], v[68:71]
	v_mfma_f32_16x16x32_bf16 v[64:67], v[190:193], v[222:225], v[64:67]
	s_barrier
; #define PG8_STAGE(bufoff, gbase, voff) do { _Pragma("unroll") for (int _i = 0; _i < 2; ++_i) \
;         __builtin_amdgcn_global_load_lds((const unsigned*)((const char*)(gbase) + (voff)[_i]), (PG8_LAS unsigned*)(lds + (bufoff) + ldsw + _i * 8192), 16, 0, PG8_LOAD_AUX); } while (0)
; #define PG8_LDA(dst, b, h) do { _Pragma("unroll") for (int m = 0; m < 4; ++m) _Pragma("unroll") for (int k = 0; k < 2; ++k) dst[m][k] = *(const PG8_LAS bf16x8*)(lds + PG8_SA(b, h) + aoff + m * 2048 + k * 1024); } while (0)
; #define PG8_LDB(dst, b, h) do { _Pragma("unroll") for (int n = 0; n < 2; ++n) _Pragma("unroll") for (int k = 0; k < 2; ++k) dst[n][k] = *(const PG8_LAS bf16x8*)(lds + PG8_SB(b, h) + boff + n * 2048 + k * 1024); } while (0)
; #define PG8_MMA(ai, bj, At, Bt) do { __builtin_amdgcn_s_setprio(1); _Pragma("unroll") for (int m = 0; m < 4; ++m) _Pragma("unroll") for (int n = 0; n < 2; ++n) _Pragma("unroll") for (int k = 0; k < 2; ++k) \
;         acc[ai][bj][m][n] = __builtin_amdgcn_mfma_f32_16x16x32_bf16(Bt[n][k], At[m][k], acc[ai][bj][m][n], 0, 0, 0); __builtin_amdgcn_s_setprio(0); } while (0)
; #define PG8_WAIT_V(n) asm volatile("s_waitcnt vmcnt(" #n ")" ::: "memory")
; #define PG8_WAIT_L(n) asm volatile("s_waitcnt lgkmcnt(" #n ")" ::: "memory")
; #define PG8_BAR __builtin_amdgcn_s_barrier()
; #define PG8_SCHED __builtin_amdgcn_sched_barrier(0)
; template <class Epi, class Sched, bool ALIGN_EPI = false, bool SP2 = false>
; __device__ __forceinline__ void gemm_phase(PG8_LAS unsigned char* lds, const Gemm g, const Sched& S, const Epi& E) {
;     ...
;             PG8_LDA(At, 0, 1); PG8_STAGE(PG8_SB(0, 0), b2, voffB); PG8_STAGE(PG8_SB(0, 1), b2 + hstepB, voffB); PG8_STAGE(PG8_SA(0, 0), a2, voffA);
;             PG8_WAIT_V(8); PG8_WAIT_L(0); PG8_BAR; PG8_MMA(1, 0, At, B0); PG8_MMA(1, 1, At, B1); PG8_BAR; PG8_SCHED;
;             PG8_LDB(B0, 1, 0); PG8_LDB(B1, 1, 1); PG8_SCHED; PG8_LDA(At, 1, 0); PG8_STAGE(PG8_SA(0, 1), a2 + hstepA, voffA);
;             PG8_WAIT_V(8); PG8_WAIT_L(0); PG8_BAR; PG8_MMA(0, 0, At, B0); PG8_MMA(0, 1, At, B1); PG8_BAR; PG8_SCHED;
	s_add_i32 s29, s53, s37
	v_lshl_add_u64 v[226:227], s[22:23], 0, v[132:133]
	s_mov_b32 m0, s29
	ds_read_b128 v[194:197], v161 offset:16384
	ds_read_b128 v[198:201], v161 offset:17408
	ds_read_b128 v[202:205], v161 offset:18432
	ds_read_b128 v[206:209], v161 offset:19456
	ds_read_b128 v[210:213], v161 offset:20480
	ds_read_b128 v[214:217], v161 offset:21504
	ds_read_b128 v[218:221], v161 offset:22528
	ds_read_b128 v[222:225], v161 offset:23552
	global_load_lds_dwordx4 v[226:227], off
	s_add_i32 m0, s29, 0x2000
	s_add_u32 s30, s22, 0x10000
	v_lshl_add_u64 v[228:229], s[22:23], 0, v[128:129]
	s_addc_u32 s31, s23, 0
	s_add_i32 s29, s54, s37
	global_load_lds_dwordx4 v[228:229], off
	v_lshl_add_u64 v[230:231], s[30:31], 0, v[132:133]
	s_mov_b32 m0, s29
	v_lshl_add_u64 v[232:233], s[34:35], 0, v[130:131]
	global_load_lds_dwordx4 v[230:231], off
	v_lshl_add_u64 v[230:231], s[30:31], 0, v[128:129]
	s_add_i32 m0, s29, 0x2000
	s_nop 0
	global_load_lds_dwordx4 v[230:231], off
	v_lshl_add_u64 v[230:231], s[34:35], 0, v[134:135]
	s_mov_b32 m0, s44
	s_nop 0
	global_load_lds_dwordx4 v[230:231], off
	s_mov_b32 m0, s45
	s_nop 0
	global_load_lds_dwordx4 v[232:233], off
	s_waitcnt vmcnt(8)
	s_waitcnt lgkmcnt(0)
	s_barrier
	s_waitcnt lgkmcnt(0)
	v_mfma_f32_16x16x32_bf16 v[60:63], v[162:165], v[194:197], v[60:63]
	v_mfma_f32_16x16x32_bf16 v[56:59], v[170:173], v[194:197], v[56:59]
	v_mfma_f32_16x16x32_bf16 v[44:47], v[162:165], v[202:205], v[44:47]
	v_mfma_f32_16x16x32_bf16 v[40:43], v[170:173], v[202:205], v[40:43]
	v_mfma_f32_16x16x32_bf16 v[28:31], v[162:165], v[210:213], v[28:31]
	v_mfma_f32_16x16x32_bf16 v[24:27], v[170:173], v[210:213], v[24:27]
	v_mfma_f32_16x16x32_bf16 v[12:15], v[162:165], v[218:221], v[12:15]
	v_mfma_f32_16x16x32_bf16 v[8:11], v[170:173], v[218:221], v[8:11]
	v_mfma_f32_16x16x32_bf16 v[60:63], v[166:169], v[198:201], v[60:63]
	v_mfma_f32_16x16x32_bf16 v[56:59], v[174:177], v[198:201], v[56:59]
	v_mfma_f32_16x16x32_bf16 v[44:47], v[166:169], v[206:209], v[44:47]
	v_mfma_f32_16x16x32_bf16 v[40:43], v[174:177], v[206:209], v[40:43]
	v_mfma_f32_16x16x32_bf16 v[28:31], v[166:169], v[214:217], v[28:31]
	v_mfma_f32_16x16x32_bf16 v[24:27], v[174:177], v[214:217], v[24:27]
	v_mfma_f32_16x16x32_bf16 v[12:15], v[166:169], v[222:225], v[12:15]
	v_mfma_f32_16x16x32_bf16 v[8:11], v[174:177], v[222:225], v[8:11]
	v_mfma_f32_16x16x32_bf16 v[52:55], v[178:181], v[194:197], v[52:55]
	v_mfma_f32_16x16x32_bf16 v[48:51], v[186:189], v[194:197], v[48:51]
	v_mfma_f32_16x16x32_bf16 v[36:39], v[178:181], v[202:205], v[36:39]
	v_mfma_f32_16x16x32_bf16 v[32:35], v[186:189], v[202:205], v[32:35]
	v_mfma_f32_16x16x32_bf16 v[20:23], v[178:181], v[210:213], v[20:23]
	v_mfma_f32_16x16x32_bf16 v[16:19], v[186:189], v[210:213], v[16:19]
	v_mfma_f32_16x16x32_bf16 v[4:7], v[178:181], v[218:221], v[4:7]
	v_mfma_f32_16x16x32_bf16 v[0:3], v[186:189], v[218:221], v[0:3]
	v_mfma_f32_16x16x32_bf16 v[52:55], v[182:185], v[198:201], v[52:55]
	v_mfma_f32_16x16x32_bf16 v[48:51], v[190:193], v[198:201], v[48:51]
	v_mfma_f32_16x16x32_bf16 v[36:39], v[182:185], v[206:209], v[36:39]
	v_mfma_f32_16x16x32_bf16 v[32:35], v[190:193], v[206:209], v[32:35]
	v_mfma_f32_16x16x32_bf16 v[20:23], v[182:185], v[214:217], v[20:23]
	v_mfma_f32_16x16x32_bf16 v[16:19], v[190:193], v[214:217], v[16:19]
	v_mfma_f32_16x16x32_bf16 v[4:7], v[182:185], v[222:225], v[4:7]
	v_mfma_f32_16x16x32_bf16 v[0:3], v[190:193], v[222:225], v[0:3]
	s_barrier
.Lkmid_P3:
	s_add_i32 s29, 0, 0x18000
	s_add_i32 s38, 0, 0x1c000
	v_add_u32_e32 v174, s29, v146
	v_add_u32_e32 v190, s38, v146
	ds_read_b128 v[162:165], v174
	ds_read_b128 v[166:169], v174 offset:1024
	ds_read_b128 v[170:173], v174 offset:2048
	ds_read_b128 v[174:177], v174 offset:3072
	ds_read_b128 v[178:181], v190
	ds_read_b128 v[182:185], v190 offset:1024
	ds_read_b128 v[186:189], v190 offset:2048
	ds_read_b128 v[190:193], v190 offset:3072
	s_add_u32 s30, s34, 0x40000
	s_addc_u32 s31, s35, 0
	s_mov_b32 m0, s46
	v_lshl_add_u64 v[234:235], s[30:31], 0, v[134:135]
	ds_read_b128 v[194:197], v161 offset:32768
	ds_read_b128 v[198:201], v161 offset:33792
	ds_read_b128 v[202:205], v161 offset:34816
	ds_read_b128 v[206:209], v161 offset:35840
	ds_read_b128 v[210:213], v161 offset:36864
	ds_read_b128 v[214:217], v161 offset:37888
	ds_read_b128 v[218:221], v161 offset:38912
	ds_read_b128 v[222:225], v161 offset:39936
	global_load_lds_dwordx4 v[234:235], off
	v_lshl_add_u64 v[234:235], s[30:31], 0, v[130:131]
	s_mov_b32 m0, s47
	s_nop 0
	global_load_lds_dwordx4 v[234:235], off
	s_waitcnt vmcnt(8)
	s_waitcnt lgkmcnt(0)
	s_barrier
; #define PG8_STAGE(bufoff, gbase, voff) do { _Pragma("unroll") for (int _i = 0; _i < 2; ++_i) \
;         __builtin_amdgcn_global_load_lds((const unsigned*)((const char*)(gbase) + (voff)[_i]), (PG8_LAS unsigned*)(lds + (bufoff) + ldsw + _i * 8192), 16, 0, PG8_LOAD_AUX); } while (0)
; #define PG8_LDA(dst, b, h) do { _Pragma("unroll") for (int m = 0; m < 4; ++m) _Pragma("unroll") for (int k = 0; k < 2; ++k) dst[m][k] = *(const PG8_LAS bf16x8*)(lds + PG8_SA(b, h) + aoff + m * 2048 + k * 1024); } while (0)
; #define PG8_MMA(ai, bj, At, Bt) do { __builtin_amdgcn_s_setprio(1); _Pragma("unroll") for (int m = 0; m < 4; ++m) _Pragma("unroll") for (int n = 0; n < 2; ++n) _Pragma("unroll") for (int k = 0; k < 2; ++k) \
;         acc[ai][bj][m][n] = __builtin_amdgcn_mfma_f32_16x16x32_bf16(Bt[n][k], At[m][k], acc[ai][bj][m][n], 0, 0, 0); __builtin_amdgcn_s_setprio(0); } while (0)
; #define PG8_WAIT_V(n) asm volatile("s_waitcnt vmcnt(" #n ")" ::: "memory")
; #define PG8_WAIT_L(n) asm volatile("s_waitcnt lgkmcnt(" #n ")" ::: "memory")
; #define PG8_BAR __builtin_amdgcn_s_barrier()
; #define PG8_SCHED __builtin_amdgcn_sched_barrier(0)
; template <class Epi, class Sched, bool ALIGN_EPI = false, bool SP2 = false>
; __device__ __forceinline__ void gemm_phase(PG8_LAS unsigned char* lds, const Gemm g, const Sched& S, const Epi& E) {
;     ...
;             PG8_WAIT_V(8); PG8_WAIT_L(0); PG8_BAR; PG8_MMA(0, 0, At, B0); PG8_MMA(0, 1, At, B1); PG8_BAR; PG8_SCHED;
;             PG8_LDA(At, 1, 1); PG8_STAGE(PG8_SB(1, 0), b3, voffB); PG8_STAGE(PG8_SB(1, 1), b3 + hstepB, voffB); PG8_STAGE(PG8_SA(1, 0), a3, voffA);
;             PG8_WAIT_V(8); PG8_WAIT_L(0); PG8_BAR; PG8_MMA(1, 0, At, B0); PG8_MMA(1, 1, At, B1); PG8_BAR; PG8_SCHED;
	s_waitcnt lgkmcnt(0)
	v_mfma_f32_16x16x32_bf16 v[124:127], v[162:165], v[194:197], v[124:127]
	v_mfma_f32_16x16x32_bf16 v[120:123], v[170:173], v[194:197], v[120:123]
	v_mfma_f32_16x16x32_bf16 v[108:111], v[162:165], v[202:205], v[108:111]
	v_mfma_f32_16x16x32_bf16 v[104:107], v[170:173], v[202:205], v[104:107]
	v_mfma_f32_16x16x32_bf16 v[92:95], v[162:165], v[210:213], v[92:95]
	v_mfma_f32_16x16x32_bf16 v[88:91], v[170:173], v[210:213], v[88:91]
	v_mfma_f32_16x16x32_bf16 v[76:79], v[162:165], v[218:221], v[76:79]
	v_mfma_f32_16x16x32_bf16 v[72:75], v[170:173], v[218:221], v[72:75]
	v_mfma_f32_16x16x32_bf16 v[124:127], v[166:169], v[198:201], v[124:127]
	v_mfma_f32_16x16x32_bf16 v[120:123], v[174:177], v[198:201], v[120:123]
	v_mfma_f32_16x16x32_bf16 v[108:111], v[166:169], v[206:209], v[108:111]
	v_mfma_f32_16x16x32_bf16 v[104:107], v[174:177], v[206:209], v[104:107]
	v_mfma_f32_16x16x32_bf16 v[92:95], v[166:169], v[214:217], v[92:95]
	v_mfma_f32_16x16x32_bf16 v[88:91], v[174:177], v[214:217], v[88:91]
	v_mfma_f32_16x16x32_bf16 v[76:79], v[166:169], v[222:225], v[76:79]
	v_mfma_f32_16x16x32_bf16 v[72:75], v[174:177], v[222:225], v[72:75]
	v_mfma_f32_16x16x32_bf16 v[116:119], v[178:181], v[194:197], v[116:119]
	v_mfma_f32_16x16x32_bf16 v[112:115], v[186:189], v[194:197], v[112:115]
	v_mfma_f32_16x16x32_bf16 v[100:103], v[178:181], v[202:205], v[100:103]
	v_mfma_f32_16x16x32_bf16 v[96:99], v[186:189], v[202:205], v[96:99]
	v_mfma_f32_16x16x32_bf16 v[84:87], v[178:181], v[210:213], v[84:87]
	v_mfma_f32_16x16x32_bf16 v[80:83], v[186:189], v[210:213], v[80:83]
	v_mfma_f32_16x16x32_bf16 v[68:71], v[178:181], v[218:221], v[68:71]
	v_mfma_f32_16x16x32_bf16 v[64:67], v[186:189], v[218:221], v[64:67]
	v_mfma_f32_16x16x32_bf16 v[116:119], v[182:185], v[198:201], v[116:119]
	v_mfma_f32_16x16x32_bf16 v[112:115], v[190:193], v[198:201], v[112:115]
	v_mfma_f32_16x16x32_bf16 v[100:103], v[182:185], v[206:209], v[100:103]
	v_mfma_f32_16x16x32_bf16 v[96:99], v[190:193], v[206:209], v[96:99]
	v_mfma_f32_16x16x32_bf16 v[84:87], v[182:185], v[214:217], v[84:87]
	v_mfma_f32_16x16x32_bf16 v[80:83], v[190:193], v[214:217], v[80:83]
	v_mfma_f32_16x16x32_bf16 v[68:71], v[182:185], v[222:225], v[68:71]
	v_mfma_f32_16x16x32_bf16 v[64:67], v[190:193], v[222:225], v[64:67]
	s_barrier
	s_add_i32 s29, s29, s37
	v_lshl_add_u64 v[226:227], v[226:227], 0, s[10:11]
	s_mov_b32 m0, s29
	ds_read_b128 v[194:197], v161 offset:49152
	ds_read_b128 v[198:201], v161 offset:50176
	ds_read_b128 v[202:205], v161 offset:51200
	ds_read_b128 v[206:209], v161 offset:52224
	ds_read_b128 v[210:213], v161 offset:53248
	ds_read_b128 v[214:217], v161 offset:54272
	ds_read_b128 v[218:221], v161 offset:55296
	ds_read_b128 v[222:225], v161 offset:56320
	global_load_lds_dwordx4 v[226:227], off
	s_add_i32 m0, s29, 0x2000
	s_add_u32 s22, s22, 0x10080
	v_lshl_add_u64 v[226:227], v[228:229], 0, s[10:11]
	s_addc_u32 s23, s23, 0
	s_add_i32 s29, s38, s37
	global_load_lds_dwordx4 v[226:227], off
	v_lshl_add_u64 v[226:227], s[22:23], 0, v[132:133]
	s_mov_b32 m0, s29
	s_nop 0
	global_load_lds_dwordx4 v[226:227], off
	v_lshl_add_u64 v[226:227], s[22:23], 0, v[128:129]
	s_add_i32 m0, s29, 0x2000
	s_nop 0
	global_load_lds_dwordx4 v[226:227], off
	v_lshl_add_u64 v[226:227], v[230:231], 0, s[10:11]
	s_mov_b32 m0, s49
	s_nop 0
	global_load_lds_dwordx4 v[226:227], off
	v_lshl_add_u64 v[226:227], v[232:233], 0, s[10:11]
	s_mov_b32 m0, s50
	s_nop 0
	global_load_lds_dwordx4 v[226:227], off
	s_waitcnt vmcnt(8)
	s_waitcnt lgkmcnt(0)
	s_barrier
	s_waitcnt lgkmcnt(0)
	v_mfma_f32_16x16x32_bf16 v[60:63], v[162:165], v[194:197], v[60:63]
	v_mfma_f32_16x16x32_bf16 v[56:59], v[170:173], v[194:197], v[56:59]
	v_mfma_f32_16x16x32_bf16 v[44:47], v[162:165], v[202:205], v[44:47]
	v_mfma_f32_16x16x32_bf16 v[40:43], v[170:173], v[202:205], v[40:43]
	v_mfma_f32_16x16x32_bf16 v[28:31], v[162:165], v[210:213], v[28:31]
	v_mfma_f32_16x16x32_bf16 v[24:27], v[170:173], v[210:213], v[24:27]
	v_mfma_f32_16x16x32_bf16 v[12:15], v[162:165], v[218:221], v[12:15]
	v_mfma_f32_16x16x32_bf16 v[8:11], v[170:173], v[218:221], v[8:11]
	v_mfma_f32_16x16x32_bf16 v[60:63], v[166:169], v[198:201], v[60:63]
	v_mfma_f32_16x16x32_bf16 v[56:59], v[174:177], v[198:201], v[56:59]
	v_mfma_f32_16x16x32_bf16 v[44:47], v[166:169], v[206:209], v[44:47]
	v_mfma_f32_16x16x32_bf16 v[40:43], v[174:177], v[206:209], v[40:43]
	v_mfma_f32_16x16x32_bf16 v[28:31], v[166:169], v[214:217], v[28:31]
	v_mfma_f32_16x16x32_bf16 v[24:27], v[174:177], v[214:217], v[24:27]
	v_mfma_f32_16x16x32_bf16 v[12:15], v[166:169], v[222:225], v[12:15]
	v_mfma_f32_16x16x32_bf16 v[8:11], v[174:177], v[222:225], v[8:11]
	v_mfma_f32_16x16x32_bf16 v[52:55], v[178:181], v[194:197], v[52:55]
	v_mfma_f32_16x16x32_bf16 v[48:51], v[186:189], v[194:197], v[48:51]
	v_mfma_f32_16x16x32_bf16 v[36:39], v[178:181], v[202:205], v[36:39]
	v_mfma_f32_16x16x32_bf16 v[32:35], v[186:189], v[202:205], v[32:35]
	v_mfma_f32_16x16x32_bf16 v[20:23], v[178:181], v[210:213], v[20:23]
	v_mfma_f32_16x16x32_bf16 v[16:19], v[186:189], v[210:213], v[16:19]
	v_mfma_f32_16x16x32_bf16 v[4:7], v[178:181], v[218:221], v[4:7]
	v_mfma_f32_16x16x32_bf16 v[0:3], v[186:189], v[218:221], v[0:3]
	v_mfma_f32_16x16x32_bf16 v[52:55], v[182:185], v[198:201], v[52:55]
	v_mfma_f32_16x16x32_bf16 v[48:51], v[190:193], v[198:201], v[48:51]
	v_mfma_f32_16x16x32_bf16 v[36:39], v[182:185], v[206:209], v[36:39]
	v_mfma_f32_16x16x32_bf16 v[32:35], v[190:193], v[206:209], v[32:35]
	v_mfma_f32_16x16x32_bf16 v[20:23], v[182:185], v[214:217], v[20:23]
	v_mfma_f32_16x16x32_bf16 v[16:19], v[190:193], v[214:217], v[16:19]
	v_mfma_f32_16x16x32_bf16 v[4:7], v[182:185], v[222:225], v[4:7]
	v_mfma_f32_16x16x32_bf16 v[0:3], v[190:193], v[222:225], v[0:3]
	s_barrier
	s_add_i32 s28, s28, 2
	s_add_u32 s20, s20, 0x100
	s_addc_u32 s21, s21, 0
	s_add_u32 s26, s26, 0x100
	s_addc_u32 s27, s27, 0
	s_cmp_gt_u32 s28, 13
	s_cbranch_scc0 .LBB0_369
	s_and_b64 vcc, exec, s[12:13]
	s_cbranch_vccz .LBB0_372
	s_barrier

; #define PG8_STAGE(bufoff, gbase, voff) do { _Pragma("unroll") for (int _i = 0; _i < 2; ++_i) \
;         __builtin_amdgcn_global_load_lds((const unsigned*)((const char*)(gbase) + (voff)[_i]), (PG8_LAS unsigned*)(lds + (bufoff) + ldsw + _i * 8192), 16, 0, PG8_LOAD_AUX); } while (0)
; #define PG8_LDA(dst, b, h) do { _Pragma("unroll") for (int m = 0; m < 4; ++m) _Pragma("unroll") for (int k = 0; k < 2; ++k) dst[m][k] = *(const PG8_LAS bf16x8*)(lds + PG8_SA(b, h) + aoff + m * 2048 + k * 1024); } while (0)
; #define PG8_LDB(dst, b, h) do { _Pragma("unroll") for (int n = 0; n < 2; ++n) _Pragma("unroll") for (int k = 0; k < 2; ++k) dst[n][k] = *(const PG8_LAS bf16x8*)(lds + PG8_SB(b, h) + boff + n * 2048 + k * 1024); } while (0)
; #define PG8_WAIT_V(n) asm volatile("s_waitcnt vmcnt(" #n ")" ::: "memory")
; #define PG8_WAIT_L(n) asm volatile("s_waitcnt lgkmcnt(" #n ")" ::: "memory")
; #define PG8_BAR __builtin_amdgcn_s_barrier()
; #define PG8_SCHED __builtin_amdgcn_sched_barrier(0)
; template <class Epi, class Sched, bool ALIGN_EPI = false, bool SP2 = false>
; __device__ __forceinline__ void gemm_phase(PG8_LAS unsigned char* lds, const Gemm g, const Sched& S, const Epi& E) {
;     ...
;         const char* nA = has_next ? (const char*)g.A + (size_t)nxt.pm * tstepA + (size_t)nxt.pn * apn : cA; const char* nB = has_next ? (const char*)g.Bt + (size_t)nxt.pn * tstepB : cB;
;         for (int t = 0; t < nt; t += 2) {
;             const bool last = (t == nt - 2);
;             const char* a1 = cA + (size_t)(t + 1) * kstep;
;             const char* a2 = last ? nA : cA + (size_t)(t + 2) * kstep; const char* b2 = last ? nB : cB + (size_t)(t + 2) * kstep;
;             const char* a3 = a2 + kstep; const char* b3 = b2 + kstep;
;             if (last && has_next) S.a_ready(nxt);
;             if constexpr (SP2) {
;             PG8_LDB(B0, 0, 0); PG8_LDB(B1, 0, 1); PG8_SCHED; PG8_LDA(At, 0, 0); PG8_STAGE(PG8_SA(1, 1), a1 + hstepA, voffA);
;             PG8_WAIT_V(8); PG8_WAIT_L(0); PG8_BAR; PG8_MMA(0, 0, At, B0); PG8_MMA(0, 1, At, B1); PG8_BAR; PG8_SCHED;
;             PG8_LDA(At, 0, 1); PG8_STAGE(PG8_SB(0, 0), b2, voffB); PG8_STAGE(PG8_SB(0, 1), b2 + hstepB, voffB); PG8_STAGE(PG8_SA(0, 0), a2, voffA);
;             PG8_WAIT_V(8); PG8_WAIT_L(0); PG8_BAR; PG8_MMA(1, 0, At, B0); PG8_MMA(1, 1, At, B1); PG8_BAR; PG8_SCHED;
.LBB0_584:
	s_ashr_i32 s41, s40, 31
	s_lshl_b64 s[22:23], s[40:41], 19
	v_readlane_b32 s24, v239, 47
	v_readlane_b32 s25, v239, 48
	s_add_u32 s42, s24, s22
	s_addc_u32 s43, s25, s23
	s_and_b64 s[22:23], s[6:7], exec
	s_cselect_b32 s24, s43, s1
	s_cselect_b32 s25, s42, s0
	s_ashr_i32 s19, s18, 31
	s_lshl_b64 s[22:23], s[18:19], 19
	v_readlane_b32 s26, v239, 34
	v_readlane_b32 s27, v239, 35
	s_add_u32 s46, s26, s22
	s_addc_u32 s47, s27, s23
	s_and_b64 s[22:23], s[6:7], exec
	s_cselect_b32 s19, s47, s21
	s_cselect_b32 s26, s46, s20
	s_add_u32 s0, s0, 0x40080
	s_addc_u32 s1, s1, 0
	s_add_u32 s27, s20, 0x100
	s_addc_u32 s28, s21, 0
	s_mov_b32 s29, -2
	s_waitcnt lgkmcnt(0)
	ds_read_b128 v[146:149], v157
	ds_read_b128 v[162:165], v157 offset:1024
	ds_read_b128 v[166:169], v157 offset:2048
	ds_read_b128 v[170:173], v157 offset:3072
	ds_read_b128 v[174:177], v158
	ds_read_b128 v[178:181], v158 offset:1024
	ds_read_b128 v[182:185], v158 offset:2048
	ds_read_b128 v[186:189], v158 offset:3072
	s_add_u32 s20, s0, 0xfffc0080
	s_addc_u32 s21, s1, -1
	s_cmp_eq_u32 s29, 12
	s_cselect_b32 s23, s24, s21
	s_cselect_b32 s22, s25, s20
	s_cselect_b32 s21, s19, s28
	s_cselect_b32 s20, s26, s27
	v_lshl_add_u64 v[222:223], s[0:1], 0, v[138:139]
	s_add_i32 m0, s35, 0xc000
	ds_read_b128 v[190:193], v159
	ds_read_b128 v[194:197], v159 offset:1024
	ds_read_b128 v[198:201], v159 offset:2048
	ds_read_b128 v[202:205], v159 offset:3072
	ds_read_b128 v[206:209], v159 offset:4096
	ds_read_b128 v[210:213], v159 offset:5120
	ds_read_b128 v[214:217], v159 offset:6144
	ds_read_b128 v[218:221], v159 offset:7168
	global_load_lds_dwordx4 v[222:223], off
	v_lshl_add_u64 v[222:223], s[0:1], 0, v[140:141]
	s_add_i32 m0, s35, 0xe000
	s_nop 0
	global_load_lds_dwordx4 v[222:223], off
	s_waitcnt vmcnt(8)
	s_waitcnt lgkmcnt(0)
	s_barrier
	s_waitcnt lgkmcnt(0)
	v_mfma_f32_16x16x32_bf16 v[124:127], v[146:149], v[190:193], 0
	v_mfma_f32_16x16x32_bf16 v[120:123], v[166:169], v[190:193], 0
	v_mfma_f32_16x16x32_bf16 v[108:111], v[146:149], v[198:201], 0
	v_mfma_f32_16x16x32_bf16 v[104:107], v[166:169], v[198:201], 0
	v_mfma_f32_16x16x32_bf16 v[92:95], v[146:149], v[206:209], 0
	v_mfma_f32_16x16x32_bf16 v[88:91], v[166:169], v[206:209], 0
	v_mfma_f32_16x16x32_bf16 v[76:79], v[146:149], v[214:217], 0
	v_mfma_f32_16x16x32_bf16 v[72:75], v[166:169], v[214:217], 0
	v_mfma_f32_16x16x32_bf16 v[124:127], v[162:165], v[194:197], v[124:127]
	v_mfma_f32_16x16x32_bf16 v[120:123], v[170:173], v[194:197], v[120:123]
	v_mfma_f32_16x16x32_bf16 v[108:111], v[162:165], v[202:205], v[108:111]
	v_mfma_f32_16x16x32_bf16 v[104:107], v[170:173], v[202:205], v[104:107]
	v_mfma_f32_16x16x32_bf16 v[92:95], v[162:165], v[210:213], v[92:95]
	v_mfma_f32_16x16x32_bf16 v[88:91], v[170:173], v[210:213], v[88:91]
	v_mfma_f32_16x16x32_bf16 v[76:79], v[162:165], v[218:221], v[76:79]
	v_mfma_f32_16x16x32_bf16 v[72:75], v[170:173], v[218:221], v[72:75]
	v_mfma_f32_16x16x32_bf16 v[116:119], v[174:177], v[190:193], 0
	v_mfma_f32_16x16x32_bf16 v[112:115], v[182:185], v[190:193], 0
	v_mfma_f32_16x16x32_bf16 v[100:103], v[174:177], v[198:201], 0
	v_mfma_f32_16x16x32_bf16 v[96:99], v[182:185], v[198:201], 0
	v_mfma_f32_16x16x32_bf16 v[84:87], v[174:177], v[206:209], 0
	v_mfma_f32_16x16x32_bf16 v[80:83], v[182:185], v[206:209], 0
	v_mfma_f32_16x16x32_bf16 v[68:71], v[174:177], v[214:217], 0
	v_mfma_f32_16x16x32_bf16 v[64:67], v[182:185], v[214:217], 0
	v_mfma_f32_16x16x32_bf16 v[116:119], v[178:181], v[194:197], v[116:119]
	v_mfma_f32_16x16x32_bf16 v[112:115], v[186:189], v[194:197], v[112:115]
	v_mfma_f32_16x16x32_bf16 v[100:103], v[178:181], v[202:205], v[100:103]
	v_mfma_f32_16x16x32_bf16 v[96:99], v[186:189], v[202:205], v[96:99]
	v_mfma_f32_16x16x32_bf16 v[84:87], v[178:181], v[210:213], v[84:87]
	v_mfma_f32_16x16x32_bf16 v[80:83], v[186:189], v[210:213], v[80:83]
	v_mfma_f32_16x16x32_bf16 v[68:71], v[178:181], v[218:221], v[68:71]
	v_mfma_f32_16x16x32_bf16 v[64:67], v[186:189], v[218:221], v[64:67]
	s_barrier
	s_add_i32 s30, s60, s34
	v_lshl_add_u64 v[222:223], s[20:21], 0, v[130:131]
	s_mov_b32 m0, s30
	ds_read_b128 v[190:193], v159 offset:16384
	ds_read_b128 v[194:197], v159 offset:17408
	ds_read_b128 v[198:201], v159 offset:18432
	ds_read_b128 v[202:205], v159 offset:19456
	ds_read_b128 v[206:209], v159 offset:20480
	ds_read_b128 v[210:213], v159 offset:21504
	ds_read_b128 v[214:217], v159 offset:22528
	ds_read_b128 v[218:221], v159 offset:23552
	global_load_lds_dwordx4 v[222:223], off
	s_add_i32 m0, s30, 0x2000
	s_add_u32 s30, s20, 0x10000
	v_lshl_add_u64 v[224:225], s[20:21], 0, v[134:135]
	s_addc_u32 s31, s21, 0
	s_add_i32 s33, s61, s34
	global_load_lds_dwordx4 v[224:225], off
	v_lshl_add_u64 v[226:227], s[30:31], 0, v[130:131]
	s_mov_b32 m0, s33
	v_lshl_add_u64 v[228:229], s[22:23], 0, v[132:133]
	global_load_lds_dwordx4 v[226:227], off
	v_lshl_add_u64 v[226:227], s[30:31], 0, v[134:135]
	s_add_i32 m0, s33, 0x2000
	s_nop 0
	global_load_lds_dwordx4 v[226:227], off
	v_lshl_add_u64 v[226:227], s[22:23], 0, v[128:129]
	s_mov_b32 m0, s35
	s_nop 0
	global_load_lds_dwordx4 v[226:227], off
	s_mov_b32 m0, s49
	s_nop 0
	global_load_lds_dwordx4 v[228:229], off
	s_waitcnt vmcnt(8)
	s_waitcnt lgkmcnt(0)
	s_barrier
; #define PG8_STAGE(bufoff, gbase, voff) do { _Pragma("unroll") for (int _i = 0; _i < 2; ++_i) \
;         __builtin_amdgcn_global_load_lds((const unsigned*)((const char*)(gbase) + (voff)[_i]), (PG8_LAS unsigned*)(lds + (bufoff) + ldsw + _i * 8192), 16, 0, PG8_LOAD_AUX); } while (0)
; #define PG8_LDA(dst, b, h) do { _Pragma("unroll") for (int m = 0; m < 4; ++m) _Pragma("unroll") for (int k = 0; k < 2; ++k) dst[m][k] = *(const PG8_LAS bf16x8*)(lds + PG8_SA(b, h) + aoff + m * 2048 + k * 1024); } while (0)
; #define PG8_LDB(dst, b, h) do { _Pragma("unroll") for (int n = 0; n < 2; ++n) _Pragma("unroll") for (int k = 0; k < 2; ++k) dst[n][k] = *(const PG8_LAS bf16x8*)(lds + PG8_SB(b, h) + boff + n * 2048 + k * 1024); } while (0)
; #define PG8_MMA(ai, bj, At, Bt) do { __builtin_amdgcn_s_setprio(1); _Pragma("unroll") for (int m = 0; m < 4; ++m) _Pragma("unroll") for (int n = 0; n < 2; ++n) _Pragma("unroll") for (int k = 0; k < 2; ++k) \
;         acc[ai][bj][m][n] = __builtin_amdgcn_mfma_f32_16x16x32_bf16(Bt[n][k], At[m][k], acc[ai][bj][m][n], 0, 0, 0); __builtin_amdgcn_s_setprio(0); } while (0)
; #define PG8_WAIT_V(n) asm volatile("s_waitcnt vmcnt(" #n ")" ::: "memory")
; #define PG8_WAIT_L(n) asm volatile("s_waitcnt lgkmcnt(" #n ")" ::: "memory")
; #define PG8_BAR __builtin_amdgcn_s_barrier()
; #define PG8_SCHED __builtin_amdgcn_sched_barrier(0)
; template <class Epi, class Sched, bool ALIGN_EPI = false, bool SP2 = false>
; __device__ __forceinline__ void gemm_phase(PG8_LAS unsigned char* lds, const Gemm g, const Sched& S, const Epi& E) {
;     ...
;             PG8_LDB(B0, 0, 0); PG8_LDB(B1, 0, 1); PG8_SCHED; PG8_LDA(At, 0, 0); PG8_STAGE(PG8_SA(1, 1), a1 + hstepA, voffA);
;             PG8_WAIT_V(8); PG8_WAIT_L(0); PG8_BAR; PG8_MMA(0, 0, At, B0); PG8_MMA(0, 1, At, B1); PG8_BAR; PG8_SCHED;
;             PG8_LDA(At, 0, 1); PG8_STAGE(PG8_SB(0, 0), b2, voffB); PG8_STAGE(PG8_SB(0, 1), b2 + hstepB, voffB); PG8_STAGE(PG8_SA(0, 0), a2, voffA);
;             PG8_WAIT_V(8); PG8_WAIT_L(0); PG8_BAR; PG8_MMA(1, 0, At, B0); PG8_MMA(1, 1, At, B1); PG8_BAR; PG8_SCHED;
	s_waitcnt lgkmcnt(0)
	v_mfma_f32_16x16x32_bf16 v[60:63], v[146:149], v[190:193], 0
	v_mfma_f32_16x16x32_bf16 v[56:59], v[166:169], v[190:193], 0
	v_mfma_f32_16x16x32_bf16 v[44:47], v[146:149], v[198:201], 0
	v_mfma_f32_16x16x32_bf16 v[40:43], v[166:169], v[198:201], 0
	v_mfma_f32_16x16x32_bf16 v[28:31], v[146:149], v[206:209], 0
	v_mfma_f32_16x16x32_bf16 v[24:27], v[166:169], v[206:209], 0
	v_mfma_f32_16x16x32_bf16 v[12:15], v[146:149], v[214:217], 0
	v_mfma_f32_16x16x32_bf16 v[8:11], v[166:169], v[214:217], 0
	v_mfma_f32_16x16x32_bf16 v[60:63], v[162:165], v[194:197], v[60:63]
	v_mfma_f32_16x16x32_bf16 v[56:59], v[170:173], v[194:197], v[56:59]
	v_mfma_f32_16x16x32_bf16 v[44:47], v[162:165], v[202:205], v[44:47]
	v_mfma_f32_16x16x32_bf16 v[40:43], v[170:173], v[202:205], v[40:43]
	v_mfma_f32_16x16x32_bf16 v[28:31], v[162:165], v[210:213], v[28:31]
	v_mfma_f32_16x16x32_bf16 v[24:27], v[170:173], v[210:213], v[24:27]
	v_mfma_f32_16x16x32_bf16 v[12:15], v[162:165], v[218:221], v[12:15]
	v_mfma_f32_16x16x32_bf16 v[8:11], v[170:173], v[218:221], v[8:11]
	v_mfma_f32_16x16x32_bf16 v[52:55], v[174:177], v[190:193], 0
	v_mfma_f32_16x16x32_bf16 v[48:51], v[182:185], v[190:193], 0
	v_mfma_f32_16x16x32_bf16 v[36:39], v[174:177], v[198:201], 0
	v_mfma_f32_16x16x32_bf16 v[32:35], v[182:185], v[198:201], 0
	v_mfma_f32_16x16x32_bf16 v[20:23], v[174:177], v[206:209], 0
	v_mfma_f32_16x16x32_bf16 v[16:19], v[182:185], v[206:209], 0
	v_mfma_f32_16x16x32_bf16 v[4:7], v[174:177], v[214:217], 0
	v_mfma_f32_16x16x32_bf16 v[0:3], v[182:185], v[214:217], 0
	v_mfma_f32_16x16x32_bf16 v[52:55], v[178:181], v[194:197], v[52:55]
	v_mfma_f32_16x16x32_bf16 v[48:51], v[186:189], v[194:197], v[48:51]
	v_mfma_f32_16x16x32_bf16 v[36:39], v[178:181], v[202:205], v[36:39]
	v_mfma_f32_16x16x32_bf16 v[32:35], v[186:189], v[202:205], v[32:35]
	v_mfma_f32_16x16x32_bf16 v[20:23], v[178:181], v[210:213], v[20:23]
	v_mfma_f32_16x16x32_bf16 v[16:19], v[186:189], v[210:213], v[16:19]
	v_mfma_f32_16x16x32_bf16 v[4:7], v[178:181], v[218:221], v[4:7]
	v_mfma_f32_16x16x32_bf16 v[0:3], v[186:189], v[218:221], v[0:3]
	s_barrier
	s_branch .Lkmid_P6
.LBB0_585:
	ds_read_b128 v[146:149], v157
	ds_read_b128 v[162:165], v157 offset:1024
	ds_read_b128 v[166:169], v157 offset:2048
	ds_read_b128 v[170:173], v157 offset:3072
	ds_read_b128 v[174:177], v158
	ds_read_b128 v[178:181], v158 offset:1024
	ds_read_b128 v[182:185], v158 offset:2048
	ds_read_b128 v[186:189], v158 offset:3072
	s_add_u32 s20, s0, 0xfffc0080
	s_addc_u32 s21, s1, -1
	s_cmp_eq_u32 s29, 12
	s_cselect_b32 s23, s24, s21
	s_cselect_b32 s22, s25, s20
	s_cselect_b32 s21, s19, s28
	s_cselect_b32 s20, s26, s27
	v_lshl_add_u64 v[222:223], s[0:1], 0, v[138:139]
	s_add_i32 m0, s35, 0xc000
	ds_read_b128 v[190:193], v159
	ds_read_b128 v[194:197], v159 offset:1024
	ds_read_b128 v[198:201], v159 offset:2048
	ds_read_b128 v[202:205], v159 offset:3072
	ds_read_b128 v[206:209], v159 offset:4096
	ds_read_b128 v[210:213], v159 offset:5120
	ds_read_b128 v[214:217], v159 offset:6144
	ds_read_b128 v[218:221], v159 offset:7168
	global_load_lds_dwordx4 v[222:223], off
	v_lshl_add_u64 v[222:223], s[0:1], 0, v[140:141]
	s_add_i32 m0, s35, 0xe000
	s_nop 0
	global_load_lds_dwordx4 v[222:223], off
	s_waitcnt vmcnt(8)
	s_waitcnt lgkmcnt(0)
	s_barrier
	s_waitcnt lgkmcnt(0)
	v_mfma_f32_16x16x32_bf16 v[124:127], v[146:149], v[190:193], v[124:127]
	v_mfma_f32_16x16x32_bf16 v[120:123], v[166:169], v[190:193], v[120:123]
	v_mfma_f32_16x16x32_bf16 v[108:111], v[146:149], v[198:201], v[108:111]
	v_mfma_f32_16x16x32_bf16 v[104:107], v[166:169], v[198:201], v[104:107]
	v_mfma_f32_16x16x32_bf16 v[92:95], v[146:149], v[206:209], v[92:95]
	v_mfma_f32_16x16x32_bf16 v[88:91], v[166:169], v[206:209], v[88:91]
	v_mfma_f32_16x16x32_bf16 v[76:79], v[146:149], v[214:217], v[76:79]
	v_mfma_f32_16x16x32_bf16 v[72:75], v[166:169], v[214:217], v[72:75]
	v_mfma_f32_16x16x32_bf16 v[124:127], v[162:165], v[194:197], v[124:127]
	v_mfma_f32_16x16x32_bf16 v[120:123], v[170:173], v[194:197], v[120:123]
	v_mfma_f32_16x16x32_bf16 v[108:111], v[162:165], v[202:205], v[108:111]
	v_mfma_f32_16x16x32_bf16 v[104:107], v[170:173], v[202:205], v[104:107]
	v_mfma_f32_16x16x32_bf16 v[92:95], v[162:165], v[210:213], v[92:95]
	v_mfma_f32_16x16x32_bf16 v[88:91], v[170:173], v[210:213], v[88:91]
	v_mfma_f32_16x16x32_bf16 v[76:79], v[162:165], v[218:221], v[76:79]
	v_mfma_f32_16x16x32_bf16 v[72:75], v[170:173], v[218:221], v[72:75]
	v_mfma_f32_16x16x32_bf16 v[116:119], v[174:177], v[190:193], v[116:119]
	v_mfma_f32_16x16x32_bf16 v[112:115], v[182:185], v[190:193], v[112:115]
	v_mfma_f32_16x16x32_bf16 v[100:103], v[174:177], v[198:201], v[100:103]
	v_mfma_f32_16x16x32_bf16 v[96:99], v[182:185], v[198:201], v[96:99]
	v_mfma_f32_16x16x32_bf16 v[84:87], v[174:177], v[206:209], v[84:87]
	v_mfma_f32_16x16x32_bf16 v[80:83], v[182:185], v[206:209], v[80:83]
	v_mfma_f32_16x16x32_bf16 v[68:71], v[174:177], v[214:217], v[68:71]
	v_mfma_f32_16x16x32_bf16 v[64:67], v[182:185], v[214:217], v[64:67]
	v_mfma_f32_16x16x32_bf16 v[116:119], v[178:181], v[194:197], v[116:119]
	v_mfma_f32_16x16x32_bf16 v[112:115], v[186:189], v[194:197], v[112:115]
	v_mfma_f32_16x16x32_bf16 v[100:103], v[178:181], v[202:205], v[100:103]
	v_mfma_f32_16x16x32_bf16 v[96:99], v[186:189], v[202:205], v[96:99]
	v_mfma_f32_16x16x32_bf16 v[84:87], v[178:181], v[210:213], v[84:87]
	v_mfma_f32_16x16x32_bf16 v[80:83], v[186:189], v[210:213], v[80:83]
	v_mfma_f32_16x16x32_bf16 v[68:71], v[178:181], v[218:221], v[68:71]
	v_mfma_f32_16x16x32_bf16 v[64:67], v[186:189], v[218:221], v[64:67]
	s_barrier
; #define PG8_STAGE(bufoff, gbase, voff) do { _Pragma("unroll") for (int _i = 0; _i < 2; ++_i) \
;         __builtin_amdgcn_global_load_lds((const unsigned*)((const char*)(gbase) + (voff)[_i]), (PG8_LAS unsigned*)(lds + (bufoff) + ldsw + _i * 8192), 16, 0, PG8_LOAD_AUX); } while (0)
; #define PG8_LDA(dst, b, h) do { _Pragma("unroll") for (int m = 0; m < 4; ++m) _Pragma("unroll") for (int k = 0; k < 2; ++k) dst[m][k] = *(const PG8_LAS bf16x8*)(lds + PG8_SA(b, h) + aoff + m * 2048 + k * 1024); } while (0)
; #define PG8_LDB(dst, b, h) do { _Pragma("unroll") for (int n = 0; n < 2; ++n) _Pragma("unroll") for (int k = 0; k < 2; ++k) dst[n][k] = *(const PG8_LAS bf16x8*)(lds + PG8_SB(b, h) + boff + n * 2048 + k * 1024); } while (0)
; #define PG8_MMA(ai, bj, At, Bt) do { __builtin_amdgcn_s_setprio(1); _Pragma("unroll") for (int m = 0; m < 4; ++m) _Pragma("unroll") for (int n = 0; n < 2; ++n) _Pragma("unroll") for (int k = 0; k < 2; ++k) \
;         acc[ai][bj][m][n] = __builtin_amdgcn_mfma_f32_16x16x32_bf16(Bt[n][k], At[m][k], acc[ai][bj][m][n], 0, 0, 0); __builtin_amdgcn_s_setprio(0); } while (0)
; #define PG8_WAIT_V(n) asm volatile("s_waitcnt vmcnt(" #n ")" ::: "memory")
; #define PG8_WAIT_L(n) asm volatile("s_waitcnt lgkmcnt(" #n ")" ::: "memory")
; #define PG8_BAR __builtin_amdgcn_s_barrier()
; #define PG8_SCHED __builtin_amdgcn_sched_barrier(0)
; template <class Epi, class Sched, bool ALIGN_EPI = false, bool SP2 = false>
; __device__ __forceinline__ void gemm_phase(PG8_LAS unsigned char* lds, const Gemm g, const Sched& S, const Epi& E) {
;     ...
;             PG8_LDA(At, 0, 1); PG8_STAGE(PG8_SB(0, 0), b2, voffB); PG8_STAGE(PG8_SB(0, 1), b2 + hstepB, voffB); PG8_STAGE(PG8_SA(0, 0), a2, voffA);
;             PG8_WAIT_V(8); PG8_WAIT_L(0); PG8_BAR; PG8_MMA(1, 0, At, B0); PG8_MMA(1, 1, At, B1); PG8_BAR; PG8_SCHED;
;             PG8_LDB(B0, 1, 0); PG8_LDB(B1, 1, 1); PG8_SCHED; PG8_LDA(At, 1, 0); PG8_STAGE(PG8_SA(0, 1), a2 + hstepA, voffA);
;             PG8_WAIT_V(8); PG8_WAIT_L(0); PG8_BAR; PG8_MMA(0, 0, At, B0); PG8_MMA(0, 1, At, B1); PG8_BAR; PG8_SCHED;
	s_add_i32 s30, s60, s34
	v_lshl_add_u64 v[222:223], s[20:21], 0, v[130:131]
	s_mov_b32 m0, s30
	ds_read_b128 v[190:193], v159 offset:16384
	ds_read_b128 v[194:197], v159 offset:17408
	ds_read_b128 v[198:201], v159 offset:18432
	ds_read_b128 v[202:205], v159 offset:19456
	ds_read_b128 v[206:209], v159 offset:20480
	ds_read_b128 v[210:213], v159 offset:21504
	ds_read_b128 v[214:217], v159 offset:22528
	ds_read_b128 v[218:221], v159 offset:23552
	global_load_lds_dwordx4 v[222:223], off
	s_add_i32 m0, s30, 0x2000
	s_add_u32 s30, s20, 0x10000
	v_lshl_add_u64 v[224:225], s[20:21], 0, v[134:135]
	s_addc_u32 s31, s21, 0
	s_add_i32 s33, s61, s34
	global_load_lds_dwordx4 v[224:225], off
	v_lshl_add_u64 v[226:227], s[30:31], 0, v[130:131]
	s_mov_b32 m0, s33
	v_lshl_add_u64 v[228:229], s[22:23], 0, v[132:133]
	global_load_lds_dwordx4 v[226:227], off
	v_lshl_add_u64 v[226:227], s[30:31], 0, v[134:135]
	s_add_i32 m0, s33, 0x2000
	s_nop 0
	global_load_lds_dwordx4 v[226:227], off
	v_lshl_add_u64 v[226:227], s[22:23], 0, v[128:129]
	s_mov_b32 m0, s35
	s_nop 0
	global_load_lds_dwordx4 v[226:227], off
	s_mov_b32 m0, s49
	s_nop 0
	global_load_lds_dwordx4 v[228:229], off
	s_waitcnt vmcnt(8)
	s_waitcnt lgkmcnt(0)
	s_barrier
	s_waitcnt lgkmcnt(0)
	v_mfma_f32_16x16x32_bf16 v[60:63], v[146:149], v[190:193], v[60:63]
	v_mfma_f32_16x16x32_bf16 v[56:59], v[166:169], v[190:193], v[56:59]
	v_mfma_f32_16x16x32_bf16 v[44:47], v[146:149], v[198:201], v[44:47]
	v_mfma_f32_16x16x32_bf16 v[40:43], v[166:169], v[198:201], v[40:43]
	v_mfma_f32_16x16x32_bf16 v[28:31], v[146:149], v[206:209], v[28:31]
	v_mfma_f32_16x16x32_bf16 v[24:27], v[166:169], v[206:209], v[24:27]
	v_mfma_f32_16x16x32_bf16 v[12:15], v[146:149], v[214:217], v[12:15]
	v_mfma_f32_16x16x32_bf16 v[8:11], v[166:169], v[214:217], v[8:11]
	v_mfma_f32_16x16x32_bf16 v[60:63], v[162:165], v[194:197], v[60:63]
	v_mfma_f32_16x16x32_bf16 v[56:59], v[170:173], v[194:197], v[56:59]
	v_mfma_f32_16x16x32_bf16 v[44:47], v[162:165], v[202:205], v[44:47]
	v_mfma_f32_16x16x32_bf16 v[40:43], v[170:173], v[202:205], v[40:43]
	v_mfma_f32_16x16x32_bf16 v[28:31], v[162:165], v[210:213], v[28:31]
	v_mfma_f32_16x16x32_bf16 v[24:27], v[170:173], v[210:213], v[24:27]
	v_mfma_f32_16x16x32_bf16 v[12:15], v[162:165], v[218:221], v[12:15]
	v_mfma_f32_16x16x32_bf16 v[8:11], v[170:173], v[218:221], v[8:11]
	v_mfma_f32_16x16x32_bf16 v[52:55], v[174:177], v[190:193], v[52:55]
	v_mfma_f32_16x16x32_bf16 v[48:51], v[182:185], v[190:193], v[48:51]
	v_mfma_f32_16x16x32_bf16 v[36:39], v[174:177], v[198:201], v[36:39]
	v_mfma_f32_16x16x32_bf16 v[32:35], v[182:185], v[198:201], v[32:35]
	v_mfma_f32_16x16x32_bf16 v[20:23], v[174:177], v[206:209], v[20:23]
	v_mfma_f32_16x16x32_bf16 v[16:19], v[182:185], v[206:209], v[16:19]
	v_mfma_f32_16x16x32_bf16 v[4:7], v[174:177], v[214:217], v[4:7]
	v_mfma_f32_16x16x32_bf16 v[0:3], v[182:185], v[214:217], v[0:3]
	v_mfma_f32_16x16x32_bf16 v[52:55], v[178:181], v[194:197], v[52:55]
	v_mfma_f32_16x16x32_bf16 v[48:51], v[186:189], v[194:197], v[48:51]
	v_mfma_f32_16x16x32_bf16 v[36:39], v[178:181], v[202:205], v[36:39]
	v_mfma_f32_16x16x32_bf16 v[32:35], v[186:189], v[202:205], v[32:35]
	v_mfma_f32_16x16x32_bf16 v[20:23], v[178:181], v[210:213], v[20:23]
	v_mfma_f32_16x16x32_bf16 v[16:19], v[186:189], v[210:213], v[16:19]
	v_mfma_f32_16x16x32_bf16 v[4:7], v[178:181], v[218:221], v[4:7]
	v_mfma_f32_16x16x32_bf16 v[0:3], v[186:189], v[218:221], v[0:3]
	s_barrier
.Lkmid_P6:
	s_add_i32 s30, 0, 0x18000
	v_add_u32_e32 v161, s30, v152
	s_add_i32 s31, 0, 0x1c000
	ds_read_b128 v[146:149], v161
	ds_read_b128 v[162:165], v161 offset:1024
	ds_read_b128 v[166:169], v161 offset:2048
	ds_read_b128 v[170:173], v161 offset:3072
	v_add_u32_e32 v161, s31, v152
	ds_read_b128 v[174:177], v161
	ds_read_b128 v[178:181], v161 offset:1024
	ds_read_b128 v[182:185], v161 offset:2048
	ds_read_b128 v[186:189], v161 offset:3072
	s_add_u32 s22, s22, 0x40000
	s_addc_u32 s23, s23, 0
	s_mov_b32 m0, s50
	v_lshl_add_u64 v[230:231], s[22:23], 0, v[128:129]
	ds_read_b128 v[190:193], v159 offset:32768
	ds_read_b128 v[194:197], v159 offset:33792
	ds_read_b128 v[198:201], v159 offset:34816
	ds_read_b128 v[202:205], v159 offset:35840
	ds_read_b128 v[206:209], v159 offset:36864
	ds_read_b128 v[210:213], v159 offset:37888
	ds_read_b128 v[214:217], v159 offset:38912
	ds_read_b128 v[218:221], v159 offset:39936
	global_load_lds_dwordx4 v[230:231], off
	v_lshl_add_u64 v[230:231], s[22:23], 0, v[132:133]
	s_mov_b32 m0, s51
	s_nop 0
	global_load_lds_dwordx4 v[230:231], off
	s_waitcnt vmcnt(8)
	s_waitcnt lgkmcnt(0)
	s_barrier
; #define PG8_STAGE(bufoff, gbase, voff) do { _Pragma("unroll") for (int _i = 0; _i < 2; ++_i) \
;         __builtin_amdgcn_global_load_lds((const unsigned*)((const char*)(gbase) + (voff)[_i]), (PG8_LAS unsigned*)(lds + (bufoff) + ldsw + _i * 8192), 16, 0, PG8_LOAD_AUX); } while (0)
; #define PG8_LDA(dst, b, h) do { _Pragma("unroll") for (int m = 0; m < 4; ++m) _Pragma("unroll") for (int k = 0; k < 2; ++k) dst[m][k] = *(const PG8_LAS bf16x8*)(lds + PG8_SA(b, h) + aoff + m * 2048 + k * 1024); } while (0)
; #define PG8_MMA(ai, bj, At, Bt) do { __builtin_amdgcn_s_setprio(1); _Pragma("unroll") for (int m = 0; m < 4; ++m) _Pragma("unroll") for (int n = 0; n < 2; ++n) _Pragma("unroll") for (int k = 0; k < 2; ++k) \
;         acc[ai][bj][m][n] = __builtin_amdgcn_mfma_f32_16x16x32_bf16(Bt[n][k], At[m][k], acc[ai][bj][m][n], 0, 0, 0); __builtin_amdgcn_s_setprio(0); } while (0)
; #define PG8_WAIT_V(n) asm volatile("s_waitcnt vmcnt(" #n ")" ::: "memory")
; #define PG8_WAIT_L(n) asm volatile("s_waitcnt lgkmcnt(" #n ")" ::: "memory")
; #define PG8_BAR __builtin_amdgcn_s_barrier()
; #define PG8_SCHED __builtin_amdgcn_sched_barrier(0)
; template <class Epi, class Sched, bool ALIGN_EPI = false, bool SP2 = false>
; __device__ __forceinline__ void gemm_phase(PG8_LAS unsigned char* lds, const Gemm g, const Sched& S, const Epi& E) {
;     ...
;             PG8_WAIT_V(8); PG8_WAIT_L(0); PG8_BAR; PG8_MMA(0, 0, At, B0); PG8_MMA(0, 1, At, B1); PG8_BAR; PG8_SCHED;
;             PG8_LDA(At, 1, 1); PG8_STAGE(PG8_SB(1, 0), b3, voffB); PG8_STAGE(PG8_SB(1, 1), b3 + hstepB, voffB); PG8_STAGE(PG8_SA(1, 0), a3, voffA);
;             PG8_WAIT_V(8); PG8_WAIT_L(0); PG8_BAR; PG8_MMA(1, 0, At, B0); PG8_MMA(1, 1, At, B1); PG8_BAR; PG8_SCHED;
	s_waitcnt lgkmcnt(0)
	v_mfma_f32_16x16x32_bf16 v[124:127], v[146:149], v[190:193], v[124:127]
	v_mfma_f32_16x16x32_bf16 v[120:123], v[166:169], v[190:193], v[120:123]
	v_mfma_f32_16x16x32_bf16 v[108:111], v[146:149], v[198:201], v[108:111]
	v_mfma_f32_16x16x32_bf16 v[104:107], v[166:169], v[198:201], v[104:107]
	v_mfma_f32_16x16x32_bf16 v[92:95], v[146:149], v[206:209], v[92:95]
	v_mfma_f32_16x16x32_bf16 v[88:91], v[166:169], v[206:209], v[88:91]
	v_mfma_f32_16x16x32_bf16 v[76:79], v[146:149], v[214:217], v[76:79]
	v_mfma_f32_16x16x32_bf16 v[72:75], v[166:169], v[214:217], v[72:75]
	v_mfma_f32_16x16x32_bf16 v[124:127], v[162:165], v[194:197], v[124:127]
	v_mfma_f32_16x16x32_bf16 v[120:123], v[170:173], v[194:197], v[120:123]
	v_mfma_f32_16x16x32_bf16 v[108:111], v[162:165], v[202:205], v[108:111]
	v_mfma_f32_16x16x32_bf16 v[104:107], v[170:173], v[202:205], v[104:107]
	v_mfma_f32_16x16x32_bf16 v[92:95], v[162:165], v[210:213], v[92:95]
	v_mfma_f32_16x16x32_bf16 v[88:91], v[170:173], v[210:213], v[88:91]
	v_mfma_f32_16x16x32_bf16 v[76:79], v[162:165], v[218:221], v[76:79]
	v_mfma_f32_16x16x32_bf16 v[72:75], v[170:173], v[218:221], v[72:75]
	v_mfma_f32_16x16x32_bf16 v[116:119], v[174:177], v[190:193], v[116:119]
	v_mfma_f32_16x16x32_bf16 v[112:115], v[182:185], v[190:193], v[112:115]
	v_mfma_f32_16x16x32_bf16 v[100:103], v[174:177], v[198:201], v[100:103]
	v_mfma_f32_16x16x32_bf16 v[96:99], v[182:185], v[198:201], v[96:99]
	v_mfma_f32_16x16x32_bf16 v[84:87], v[174:177], v[206:209], v[84:87]
	v_mfma_f32_16x16x32_bf16 v[80:83], v[182:185], v[206:209], v[80:83]
	v_mfma_f32_16x16x32_bf16 v[68:71], v[174:177], v[214:217], v[68:71]
	v_mfma_f32_16x16x32_bf16 v[64:67], v[182:185], v[214:217], v[64:67]
	v_mfma_f32_16x16x32_bf16 v[116:119], v[178:181], v[194:197], v[116:119]
	v_mfma_f32_16x16x32_bf16 v[112:115], v[186:189], v[194:197], v[112:115]
	v_mfma_f32_16x16x32_bf16 v[100:103], v[178:181], v[202:205], v[100:103]
	v_mfma_f32_16x16x32_bf16 v[96:99], v[186:189], v[202:205], v[96:99]
	v_mfma_f32_16x16x32_bf16 v[84:87], v[178:181], v[210:213], v[84:87]
	v_mfma_f32_16x16x32_bf16 v[80:83], v[186:189], v[210:213], v[80:83]
	v_mfma_f32_16x16x32_bf16 v[68:71], v[178:181], v[218:221], v[68:71]
	v_mfma_f32_16x16x32_bf16 v[64:67], v[186:189], v[218:221], v[64:67]
	s_barrier
	s_add_i32 s22, s30, s34
	v_lshl_add_u64 v[222:223], v[222:223], 0, s[14:15]
	s_mov_b32 m0, s22
	ds_read_b128 v[190:193], v159 offset:49152
	ds_read_b128 v[194:197], v159 offset:50176
	ds_read_b128 v[198:201], v159 offset:51200
	ds_read_b128 v[202:205], v159 offset:52224
	ds_read_b128 v[206:209], v159 offset:53248
	ds_read_b128 v[210:213], v159 offset:54272
	ds_read_b128 v[214:217], v159 offset:55296
	ds_read_b128 v[218:221], v159 offset:56320
	global_load_lds_dwordx4 v[222:223], off
	s_add_i32 m0, s22, 0x2000
	s_add_u32 s20, s20, 0x10080
	v_lshl_add_u64 v[222:223], v[224:225], 0, s[14:15]
	s_addc_u32 s21, s21, 0
	s_add_i32 s22, s31, s34
	global_load_lds_dwordx4 v[222:223], off
	v_lshl_add_u64 v[222:223], s[20:21], 0, v[130:131]
	s_mov_b32 m0, s22
	s_nop 0
	global_load_lds_dwordx4 v[222:223], off
	v_lshl_add_u64 v[222:223], s[20:21], 0, v[134:135]
	s_add_i32 m0, s22, 0x2000
	s_nop 0
	global_load_lds_dwordx4 v[222:223], off
	v_lshl_add_u64 v[222:223], v[226:227], 0, s[14:15]
	s_mov_b32 m0, s57
	s_nop 0
	global_load_lds_dwordx4 v[222:223], off
	v_lshl_add_u64 v[222:223], v[228:229], 0, s[14:15]
	s_mov_b32 m0, s58
	s_nop 0
	global_load_lds_dwordx4 v[222:223], off
	s_waitcnt vmcnt(8)
	s_waitcnt lgkmcnt(0)
	s_barrier
	s_waitcnt lgkmcnt(0)
	v_mfma_f32_16x16x32_bf16 v[60:63], v[146:149], v[190:193], v[60:63]
	v_mfma_f32_16x16x32_bf16 v[56:59], v[166:169], v[190:193], v[56:59]
	v_mfma_f32_16x16x32_bf16 v[44:47], v[146:149], v[198:201], v[44:47]
	v_mfma_f32_16x16x32_bf16 v[40:43], v[166:169], v[198:201], v[40:43]
	v_mfma_f32_16x16x32_bf16 v[28:31], v[146:149], v[206:209], v[28:31]
	v_mfma_f32_16x16x32_bf16 v[24:27], v[166:169], v[206:209], v[24:27]
	v_mfma_f32_16x16x32_bf16 v[12:15], v[146:149], v[214:217], v[12:15]
	v_mfma_f32_16x16x32_bf16 v[8:11], v[166:169], v[214:217], v[8:11]
	v_mfma_f32_16x16x32_bf16 v[60:63], v[162:165], v[194:197], v[60:63]
	v_mfma_f32_16x16x32_bf16 v[56:59], v[170:173], v[194:197], v[56:59]
	v_mfma_f32_16x16x32_bf16 v[44:47], v[162:165], v[202:205], v[44:47]
	v_mfma_f32_16x16x32_bf16 v[40:43], v[170:173], v[202:205], v[40:43]
	v_mfma_f32_16x16x32_bf16 v[28:31], v[162:165], v[210:213], v[28:31]
	v_mfma_f32_16x16x32_bf16 v[24:27], v[170:173], v[210:213], v[24:27]
	v_mfma_f32_16x16x32_bf16 v[12:15], v[162:165], v[218:221], v[12:15]
	v_mfma_f32_16x16x32_bf16 v[8:11], v[170:173], v[218:221], v[8:11]
	v_mfma_f32_16x16x32_bf16 v[52:55], v[174:177], v[190:193], v[52:55]
	v_mfma_f32_16x16x32_bf16 v[48:51], v[182:185], v[190:193], v[48:51]
	v_mfma_f32_16x16x32_bf16 v[36:39], v[174:177], v[198:201], v[36:39]
	v_mfma_f32_16x16x32_bf16 v[32:35], v[182:185], v[198:201], v[32:35]
	v_mfma_f32_16x16x32_bf16 v[20:23], v[174:177], v[206:209], v[20:23]
	v_mfma_f32_16x16x32_bf16 v[16:19], v[182:185], v[206:209], v[16:19]
	v_mfma_f32_16x16x32_bf16 v[4:7], v[174:177], v[214:217], v[4:7]
	v_mfma_f32_16x16x32_bf16 v[0:3], v[182:185], v[214:217], v[0:3]
	v_mfma_f32_16x16x32_bf16 v[52:55], v[178:181], v[194:197], v[52:55]
	v_mfma_f32_16x16x32_bf16 v[48:51], v[186:189], v[194:197], v[48:51]
	v_mfma_f32_16x16x32_bf16 v[36:39], v[178:181], v[202:205], v[36:39]
	v_mfma_f32_16x16x32_bf16 v[32:35], v[186:189], v[202:205], v[32:35]
	v_mfma_f32_16x16x32_bf16 v[20:23], v[178:181], v[210:213], v[20:23]
	v_mfma_f32_16x16x32_bf16 v[16:19], v[186:189], v[210:213], v[16:19]
	v_mfma_f32_16x16x32_bf16 v[4:7], v[178:181], v[218:221], v[4:7]
	v_mfma_f32_16x16x32_bf16 v[0:3], v[186:189], v[218:221], v[0:3]
	s_barrier
	s_add_i32 s29, s29, 2
	s_add_u32 s0, s0, 0x100
	s_addc_u32 s1, s1, 0
	s_add_u32 s27, s27, 0x100
	s_addc_u32 s28, s28, 0
	s_cmp_gt_u32 s29, 13
	s_cbranch_scc0 .LBB0_585
	s_and_b64 vcc, exec, s[16:17]
	s_cbranch_vccz .LBB0_588
	s_barrier

; #define PG8_STAGE(bufoff, gbase, voff) do { _Pragma("unroll") for (int _i = 0; _i < 2; ++_i) \
;         __builtin_amdgcn_global_load_lds((const unsigned*)((const char*)(gbase) + (voff)[_i]), (PG8_LAS unsigned*)(lds + (bufoff) + ldsw + _i * 8192), 16, 0, PG8_LOAD_AUX); } while (0)
; #define PG8_LDA(dst, b, h) do { _Pragma("unroll") for (int m = 0; m < 4; ++m) _Pragma("unroll") for (int k = 0; k < 2; ++k) dst[m][k] = *(const PG8_LAS bf16x8*)(lds + PG8_SA(b, h) + aoff + m * 2048 + k * 1024); } while (0)
; #define PG8_LDB(dst, b, h) do { _Pragma("unroll") for (int n = 0; n < 2; ++n) _Pragma("unroll") for (int k = 0; k < 2; ++k) dst[n][k] = *(const PG8_LAS bf16x8*)(lds + PG8_SB(b, h) + boff + n * 2048 + k * 1024); } while (0)
; #define PG8_WAIT_V(n) asm volatile("s_waitcnt vmcnt(" #n ")" ::: "memory")
; #define PG8_WAIT_L(n) asm volatile("s_waitcnt lgkmcnt(" #n ")" ::: "memory")
; #define PG8_BAR __builtin_amdgcn_s_barrier()
; #define PG8_SCHED __builtin_amdgcn_sched_barrier(0)
; template <class Epi, class Sched, bool ALIGN_EPI = false, bool SP2 = false>
; __device__ __forceinline__ void gemm_phase(PG8_LAS unsigned char* lds, const Gemm g, const Sched& S, const Epi& E) {
;     ...
;         const char* nA = has_next ? (const char*)g.A + (size_t)nxt.pm * tstepA + (size_t)nxt.pn * apn : cA; const char* nB = has_next ? (const char*)g.Bt + (size_t)nxt.pn * tstepB : cB;
;         for (int t = 0; t < nt; t += 2) {
;             const bool last = (t == nt - 2);
;             const char* a1 = cA + (size_t)(t + 1) * kstep;
;             const char* a2 = last ? nA : cA + (size_t)(t + 2) * kstep; const char* b2 = last ? nB : cB + (size_t)(t + 2) * kstep;
;             const char* a3 = a2 + kstep; const char* b3 = b2 + kstep;
;             if (last && has_next) S.a_ready(nxt);
;             if constexpr (SP2) {
;             PG8_LDB(B0, 0, 0); PG8_LDB(B1, 0, 1); PG8_SCHED; PG8_LDA(At, 0, 0); PG8_STAGE(PG8_SA(1, 1), a1 + hstepA, voffA);
;             PG8_WAIT_V(8); PG8_WAIT_L(0); PG8_BAR; PG8_MMA(0, 0, At, B0); PG8_MMA(0, 1, At, B1); PG8_BAR; PG8_SCHED;
;             PG8_LDA(At, 0, 1); PG8_STAGE(PG8_SB(0, 0), b2, voffB); PG8_STAGE(PG8_SB(0, 1), b2 + hstepB, voffB); PG8_STAGE(PG8_SA(0, 0), a2, voffA);
;             PG8_WAIT_V(8); PG8_WAIT_L(0); PG8_BAR; PG8_MMA(1, 0, At, B0); PG8_MMA(1, 1, At, B1); PG8_BAR; PG8_SCHED;
.LBB0_671:
	s_ashr_i32 s17, s16, 31
	s_lshl_b64 s[18:19], s[16:17], 19
	s_add_u32 s18, s30, s18
	s_addc_u32 s19, s31, s19
	s_and_b64 s[24:25], s[2:3], exec
	s_cselect_b32 s17, s19, s21
	s_cselect_b32 s24, s18, s20
	s_ashr_i32 s15, s14, 31
	s_lshl_b64 s[26:27], s[14:15], 19
	v_readlane_b32 s15, v239, 40
	s_add_u32 s36, s15, s26
	v_readlane_b32 s15, v239, 41
	s_addc_u32 s37, s15, s27
	s_and_b64 s[26:27], s[2:3], exec
	s_cselect_b32 s15, s37, s23
	s_cselect_b32 s25, s36, s22
	s_add_u32 s20, s20, 0x40080
	s_addc_u32 s21, s21, 0
	s_add_u32 s26, s22, 0x100
	s_addc_u32 s27, s23, 0
	s_mov_b32 s28, -2
	ds_read_b128 v[146:149], v158
	ds_read_b128 v[164:167], v158 offset:1024
	ds_read_b128 v[168:171], v158 offset:2048
	ds_read_b128 v[172:175], v158 offset:3072
	ds_read_b128 v[176:179], v159
	ds_read_b128 v[180:183], v159 offset:1024
	ds_read_b128 v[184:187], v159 offset:2048
	ds_read_b128 v[188:191], v159 offset:3072
	s_add_u32 s22, s20, 0xfffc0080
	s_addc_u32 s23, s21, -1
	s_cmp_eq_u32 s28, 12
	s_cselect_b32 s35, s17, s23
	s_cselect_b32 s34, s24, s22
	s_cselect_b32 s23, s15, s27
	s_cselect_b32 s22, s25, s26
	v_lshl_add_u64 v[150:151], s[20:21], 0, v[138:139]
	s_add_i32 m0, s43, 0xc000
	ds_read_b128 v[192:195], v160
	ds_read_b128 v[196:199], v160 offset:1024
	ds_read_b128 v[200:203], v160 offset:2048
	ds_read_b128 v[204:207], v160 offset:3072
	ds_read_b128 v[208:211], v160 offset:4096
	ds_read_b128 v[212:215], v160 offset:5120
	ds_read_b128 v[216:219], v160 offset:6144
	ds_read_b128 v[220:223], v160 offset:7168
	global_load_lds_dwordx4 v[150:151], off
	v_lshl_add_u64 v[150:151], s[20:21], 0, v[140:141]
	s_add_i32 m0, s43, 0xe000
	s_nop 0
	global_load_lds_dwordx4 v[150:151], off
	s_waitcnt vmcnt(8)
	s_waitcnt lgkmcnt(0)
	s_barrier
	s_waitcnt lgkmcnt(0)
	v_mfma_f32_16x16x32_bf16 v[124:127], v[146:149], v[192:195], 0
	v_mfma_f32_16x16x32_bf16 v[120:123], v[168:171], v[192:195], 0
	v_mfma_f32_16x16x32_bf16 v[108:111], v[146:149], v[200:203], 0
	v_mfma_f32_16x16x32_bf16 v[104:107], v[168:171], v[200:203], 0
	v_mfma_f32_16x16x32_bf16 v[92:95], v[146:149], v[208:211], 0
	v_mfma_f32_16x16x32_bf16 v[88:91], v[168:171], v[208:211], 0
	v_mfma_f32_16x16x32_bf16 v[76:79], v[146:149], v[216:219], 0
	v_mfma_f32_16x16x32_bf16 v[72:75], v[168:171], v[216:219], 0
	v_mfma_f32_16x16x32_bf16 v[124:127], v[164:167], v[196:199], v[124:127]
	v_mfma_f32_16x16x32_bf16 v[120:123], v[172:175], v[196:199], v[120:123]
	v_mfma_f32_16x16x32_bf16 v[108:111], v[164:167], v[204:207], v[108:111]
	v_mfma_f32_16x16x32_bf16 v[104:107], v[172:175], v[204:207], v[104:107]
	v_mfma_f32_16x16x32_bf16 v[92:95], v[164:167], v[212:215], v[92:95]
	v_mfma_f32_16x16x32_bf16 v[88:91], v[172:175], v[212:215], v[88:91]
	v_mfma_f32_16x16x32_bf16 v[76:79], v[164:167], v[220:223], v[76:79]
	v_mfma_f32_16x16x32_bf16 v[72:75], v[172:175], v[220:223], v[72:75]
	v_mfma_f32_16x16x32_bf16 v[116:119], v[176:179], v[192:195], 0
	v_mfma_f32_16x16x32_bf16 v[112:115], v[184:187], v[192:195], 0
	v_mfma_f32_16x16x32_bf16 v[100:103], v[176:179], v[200:203], 0
	v_mfma_f32_16x16x32_bf16 v[96:99], v[184:187], v[200:203], 0
	v_mfma_f32_16x16x32_bf16 v[84:87], v[176:179], v[208:211], 0
	v_mfma_f32_16x16x32_bf16 v[80:83], v[184:187], v[208:211], 0
	v_mfma_f32_16x16x32_bf16 v[68:71], v[176:179], v[216:219], 0
	v_mfma_f32_16x16x32_bf16 v[64:67], v[184:187], v[216:219], 0
	v_mfma_f32_16x16x32_bf16 v[116:119], v[180:183], v[196:199], v[116:119]
	v_mfma_f32_16x16x32_bf16 v[112:115], v[188:191], v[196:199], v[112:115]
	v_mfma_f32_16x16x32_bf16 v[100:103], v[180:183], v[204:207], v[100:103]
	v_mfma_f32_16x16x32_bf16 v[96:99], v[188:191], v[204:207], v[96:99]
	v_mfma_f32_16x16x32_bf16 v[84:87], v[180:183], v[212:215], v[84:87]
	v_mfma_f32_16x16x32_bf16 v[80:83], v[188:191], v[212:215], v[80:83]
	v_mfma_f32_16x16x32_bf16 v[68:71], v[180:183], v[220:223], v[68:71]
	v_mfma_f32_16x16x32_bf16 v[64:67], v[188:191], v[220:223], v[64:67]
	s_barrier
	s_add_i32 s29, s54, s40
	v_lshl_add_u64 v[150:151], s[22:23], 0, v[130:131]
	s_mov_b32 m0, s29
	ds_read_b128 v[192:195], v160 offset:16384
	ds_read_b128 v[196:199], v160 offset:17408
	ds_read_b128 v[200:203], v160 offset:18432
	ds_read_b128 v[204:207], v160 offset:19456
	ds_read_b128 v[208:211], v160 offset:20480
	ds_read_b128 v[212:215], v160 offset:21504
	ds_read_b128 v[216:219], v160 offset:22528
	ds_read_b128 v[220:223], v160 offset:23552
	global_load_lds_dwordx4 v[150:151], off
	s_add_i32 m0, s29, 0x2000
	s_add_u32 s30, s22, 0x40000
	v_lshl_add_u64 v[224:225], s[22:23], 0, v[134:135]
	s_addc_u32 s31, s23, 0
	s_add_i32 s29, s55, s40
	global_load_lds_dwordx4 v[224:225], off
	v_lshl_add_u64 v[226:227], s[30:31], 0, v[130:131]
	s_mov_b32 m0, s29
	v_lshl_add_u64 v[228:229], s[34:35], 0, v[132:133]
	global_load_lds_dwordx4 v[226:227], off
	v_lshl_add_u64 v[226:227], s[30:31], 0, v[134:135]
	s_add_i32 m0, s29, 0x2000
	s_nop 0
	global_load_lds_dwordx4 v[226:227], off
	v_lshl_add_u64 v[226:227], s[34:35], 0, v[128:129]
	s_mov_b32 m0, s43
	s_nop 0
	global_load_lds_dwordx4 v[226:227], off
	s_mov_b32 m0, s46
	s_nop 0
	global_load_lds_dwordx4 v[228:229], off
	s_waitcnt vmcnt(8)
	s_waitcnt lgkmcnt(0)
	s_barrier
; #define PG8_STAGE(bufoff, gbase, voff) do { _Pragma("unroll") for (int _i = 0; _i < 2; ++_i) \
;         __builtin_amdgcn_global_load_lds((const unsigned*)((const char*)(gbase) + (voff)[_i]), (PG8_LAS unsigned*)(lds + (bufoff) + ldsw + _i * 8192), 16, 0, PG8_LOAD_AUX); } while (0)
; #define PG8_LDA(dst, b, h) do { _Pragma("unroll") for (int m = 0; m < 4; ++m) _Pragma("unroll") for (int k = 0; k < 2; ++k) dst[m][k] = *(const PG8_LAS bf16x8*)(lds + PG8_SA(b, h) + aoff + m * 2048 + k * 1024); } while (0)
; #define PG8_LDB(dst, b, h) do { _Pragma("unroll") for (int n = 0; n < 2; ++n) _Pragma("unroll") for (int k = 0; k < 2; ++k) dst[n][k] = *(const PG8_LAS bf16x8*)(lds + PG8_SB(b, h) + boff + n * 2048 + k * 1024); } while (0)
; #define PG8_MMA(ai, bj, At, Bt) do { __builtin_amdgcn_s_setprio(1); _Pragma("unroll") for (int m = 0; m < 4; ++m) _Pragma("unroll") for (int n = 0; n < 2; ++n) _Pragma("unroll") for (int k = 0; k < 2; ++k) \
;         acc[ai][bj][m][n] = __builtin_amdgcn_mfma_f32_16x16x32_bf16(Bt[n][k], At[m][k], acc[ai][bj][m][n], 0, 0, 0); __builtin_amdgcn_s_setprio(0); } while (0)
; #define PG8_WAIT_V(n) asm volatile("s_waitcnt vmcnt(" #n ")" ::: "memory")
; #define PG8_WAIT_L(n) asm volatile("s_waitcnt lgkmcnt(" #n ")" ::: "memory")
; #define PG8_BAR __builtin_amdgcn_s_barrier()
; #define PG8_SCHED __builtin_amdgcn_sched_barrier(0)
; template <class Epi, class Sched, bool ALIGN_EPI = false, bool SP2 = false>
; __device__ __forceinline__ void gemm_phase(PG8_LAS unsigned char* lds, const Gemm g, const Sched& S, const Epi& E) {
;     ...
;             PG8_LDB(B0, 0, 0); PG8_LDB(B1, 0, 1); PG8_SCHED; PG8_LDA(At, 0, 0); PG8_STAGE(PG8_SA(1, 1), a1 + hstepA, voffA);
;             PG8_WAIT_V(8); PG8_WAIT_L(0); PG8_BAR; PG8_MMA(0, 0, At, B0); PG8_MMA(0, 1, At, B1); PG8_BAR; PG8_SCHED;
;             PG8_LDA(At, 0, 1); PG8_STAGE(PG8_SB(0, 0), b2, voffB); PG8_STAGE(PG8_SB(0, 1), b2 + hstepB, voffB); PG8_STAGE(PG8_SA(0, 0), a2, voffA);
;             PG8_WAIT_V(8); PG8_WAIT_L(0); PG8_BAR; PG8_MMA(1, 0, At, B0); PG8_MMA(1, 1, At, B1); PG8_BAR; PG8_SCHED;
	s_waitcnt lgkmcnt(0)
	v_mfma_f32_16x16x32_bf16 v[60:63], v[146:149], v[192:195], 0
	v_mfma_f32_16x16x32_bf16 v[56:59], v[168:171], v[192:195], 0
	v_mfma_f32_16x16x32_bf16 v[44:47], v[146:149], v[200:203], 0
	v_mfma_f32_16x16x32_bf16 v[40:43], v[168:171], v[200:203], 0
	v_mfma_f32_16x16x32_bf16 v[28:31], v[146:149], v[208:211], 0
	v_mfma_f32_16x16x32_bf16 v[24:27], v[168:171], v[208:211], 0
	v_mfma_f32_16x16x32_bf16 v[12:15], v[146:149], v[216:219], 0
	v_mfma_f32_16x16x32_bf16 v[8:11], v[168:171], v[216:219], 0
	v_mfma_f32_16x16x32_bf16 v[60:63], v[164:167], v[196:199], v[60:63]
	v_mfma_f32_16x16x32_bf16 v[56:59], v[172:175], v[196:199], v[56:59]
	v_mfma_f32_16x16x32_bf16 v[44:47], v[164:167], v[204:207], v[44:47]
	v_mfma_f32_16x16x32_bf16 v[40:43], v[172:175], v[204:207], v[40:43]
	v_mfma_f32_16x16x32_bf16 v[28:31], v[164:167], v[212:215], v[28:31]
	v_mfma_f32_16x16x32_bf16 v[24:27], v[172:175], v[212:215], v[24:27]
	v_mfma_f32_16x16x32_bf16 v[12:15], v[164:167], v[220:223], v[12:15]
	v_mfma_f32_16x16x32_bf16 v[8:11], v[172:175], v[220:223], v[8:11]
	v_mfma_f32_16x16x32_bf16 v[52:55], v[176:179], v[192:195], 0
	v_mfma_f32_16x16x32_bf16 v[48:51], v[184:187], v[192:195], 0
	v_mfma_f32_16x16x32_bf16 v[36:39], v[176:179], v[200:203], 0
	v_mfma_f32_16x16x32_bf16 v[32:35], v[184:187], v[200:203], 0
	v_mfma_f32_16x16x32_bf16 v[20:23], v[176:179], v[208:211], 0
	v_mfma_f32_16x16x32_bf16 v[16:19], v[184:187], v[208:211], 0
	v_mfma_f32_16x16x32_bf16 v[4:7], v[176:179], v[216:219], 0
	v_mfma_f32_16x16x32_bf16 v[0:3], v[184:187], v[216:219], 0
	v_mfma_f32_16x16x32_bf16 v[52:55], v[180:183], v[196:199], v[52:55]
	v_mfma_f32_16x16x32_bf16 v[48:51], v[188:191], v[196:199], v[48:51]
	v_mfma_f32_16x16x32_bf16 v[36:39], v[180:183], v[204:207], v[36:39]
	v_mfma_f32_16x16x32_bf16 v[32:35], v[188:191], v[204:207], v[32:35]
	v_mfma_f32_16x16x32_bf16 v[20:23], v[180:183], v[212:215], v[20:23]
	v_mfma_f32_16x16x32_bf16 v[16:19], v[188:191], v[212:215], v[16:19]
	v_mfma_f32_16x16x32_bf16 v[4:7], v[180:183], v[220:223], v[4:7]
	v_mfma_f32_16x16x32_bf16 v[0:3], v[188:191], v[220:223], v[0:3]
	s_barrier
	s_branch .Lkmid_P7
.LBB0_672:
	ds_read_b128 v[146:149], v158
	ds_read_b128 v[164:167], v158 offset:1024
	ds_read_b128 v[168:171], v158 offset:2048
	ds_read_b128 v[172:175], v158 offset:3072
	ds_read_b128 v[176:179], v159
	ds_read_b128 v[180:183], v159 offset:1024
	ds_read_b128 v[184:187], v159 offset:2048
	ds_read_b128 v[188:191], v159 offset:3072
	s_add_u32 s22, s20, 0xfffc0080
	s_addc_u32 s23, s21, -1
	s_cmp_eq_u32 s28, 12
	s_cselect_b32 s35, s17, s23
	s_cselect_b32 s34, s24, s22
	s_cselect_b32 s23, s15, s27
	s_cselect_b32 s22, s25, s26
	v_lshl_add_u64 v[150:151], s[20:21], 0, v[138:139]
	s_add_i32 m0, s43, 0xc000
	ds_read_b128 v[192:195], v160
	ds_read_b128 v[196:199], v160 offset:1024
	ds_read_b128 v[200:203], v160 offset:2048
	ds_read_b128 v[204:207], v160 offset:3072
	ds_read_b128 v[208:211], v160 offset:4096
	ds_read_b128 v[212:215], v160 offset:5120
	ds_read_b128 v[216:219], v160 offset:6144
	ds_read_b128 v[220:223], v160 offset:7168
	global_load_lds_dwordx4 v[150:151], off
	v_lshl_add_u64 v[150:151], s[20:21], 0, v[140:141]
	s_add_i32 m0, s43, 0xe000
	s_nop 0
	global_load_lds_dwordx4 v[150:151], off
	s_waitcnt vmcnt(8)
	s_waitcnt lgkmcnt(0)
	s_barrier
	s_waitcnt lgkmcnt(0)
	v_mfma_f32_16x16x32_bf16 v[124:127], v[146:149], v[192:195], v[124:127]
	v_mfma_f32_16x16x32_bf16 v[120:123], v[168:171], v[192:195], v[120:123]
	v_mfma_f32_16x16x32_bf16 v[108:111], v[146:149], v[200:203], v[108:111]
	v_mfma_f32_16x16x32_bf16 v[104:107], v[168:171], v[200:203], v[104:107]
	v_mfma_f32_16x16x32_bf16 v[92:95], v[146:149], v[208:211], v[92:95]
	v_mfma_f32_16x16x32_bf16 v[88:91], v[168:171], v[208:211], v[88:91]
	v_mfma_f32_16x16x32_bf16 v[76:79], v[146:149], v[216:219], v[76:79]
	v_mfma_f32_16x16x32_bf16 v[72:75], v[168:171], v[216:219], v[72:75]
	v_mfma_f32_16x16x32_bf16 v[124:127], v[164:167], v[196:199], v[124:127]
	v_mfma_f32_16x16x32_bf16 v[120:123], v[172:175], v[196:199], v[120:123]
	v_mfma_f32_16x16x32_bf16 v[108:111], v[164:167], v[204:207], v[108:111]
	v_mfma_f32_16x16x32_bf16 v[104:107], v[172:175], v[204:207], v[104:107]
	v_mfma_f32_16x16x32_bf16 v[92:95], v[164:167], v[212:215], v[92:95]
	v_mfma_f32_16x16x32_bf16 v[88:91], v[172:175], v[212:215], v[88:91]
	v_mfma_f32_16x16x32_bf16 v[76:79], v[164:167], v[220:223], v[76:79]
	v_mfma_f32_16x16x32_bf16 v[72:75], v[172:175], v[220:223], v[72:75]
	v_mfma_f32_16x16x32_bf16 v[116:119], v[176:179], v[192:195], v[116:119]
	v_mfma_f32_16x16x32_bf16 v[112:115], v[184:187], v[192:195], v[112:115]
	v_mfma_f32_16x16x32_bf16 v[100:103], v[176:179], v[200:203], v[100:103]
	v_mfma_f32_16x16x32_bf16 v[96:99], v[184:187], v[200:203], v[96:99]
	v_mfma_f32_16x16x32_bf16 v[84:87], v[176:179], v[208:211], v[84:87]
	v_mfma_f32_16x16x32_bf16 v[80:83], v[184:187], v[208:211], v[80:83]
	v_mfma_f32_16x16x32_bf16 v[68:71], v[176:179], v[216:219], v[68:71]
	v_mfma_f32_16x16x32_bf16 v[64:67], v[184:187], v[216:219], v[64:67]
	v_mfma_f32_16x16x32_bf16 v[116:119], v[180:183], v[196:199], v[116:119]
	v_mfma_f32_16x16x32_bf16 v[112:115], v[188:191], v[196:199], v[112:115]
	v_mfma_f32_16x16x32_bf16 v[100:103], v[180:183], v[204:207], v[100:103]
	v_mfma_f32_16x16x32_bf16 v[96:99], v[188:191], v[204:207], v[96:99]
	v_mfma_f32_16x16x32_bf16 v[84:87], v[180:183], v[212:215], v[84:87]
	v_mfma_f32_16x16x32_bf16 v[80:83], v[188:191], v[212:215], v[80:83]
	v_mfma_f32_16x16x32_bf16 v[68:71], v[180:183], v[220:223], v[68:71]
	v_mfma_f32_16x16x32_bf16 v[64:67], v[188:191], v[220:223], v[64:67]
	s_barrier
; #define PG8_STAGE(bufoff, gbase, voff) do { _Pragma("unroll") for (int _i = 0; _i < 2; ++_i) \
;         __builtin_amdgcn_global_load_lds((const unsigned*)((const char*)(gbase) + (voff)[_i]), (PG8_LAS unsigned*)(lds + (bufoff) + ldsw + _i * 8192), 16, 0, PG8_LOAD_AUX); } while (0)
; #define PG8_LDA(dst, b, h) do { _Pragma("unroll") for (int m = 0; m < 4; ++m) _Pragma("unroll") for (int k = 0; k < 2; ++k) dst[m][k] = *(const PG8_LAS bf16x8*)(lds + PG8_SA(b, h) + aoff + m * 2048 + k * 1024); } while (0)
; #define PG8_LDB(dst, b, h) do { _Pragma("unroll") for (int n = 0; n < 2; ++n) _Pragma("unroll") for (int k = 0; k < 2; ++k) dst[n][k] = *(const PG8_LAS bf16x8*)(lds + PG8_SB(b, h) + boff + n * 2048 + k * 1024); } while (0)
; #define PG8_MMA(ai, bj, At, Bt) do { __builtin_amdgcn_s_setprio(1); _Pragma("unroll") for (int m = 0; m < 4; ++m) _Pragma("unroll") for (int n = 0; n < 2; ++n) _Pragma("unroll") for (int k = 0; k < 2; ++k) \
;         acc[ai][bj][m][n] = __builtin_amdgcn_mfma_f32_16x16x32_bf16(Bt[n][k], At[m][k], acc[ai][bj][m][n], 0, 0, 0); __builtin_amdgcn_s_setprio(0); } while (0)
; #define PG8_WAIT_V(n) asm volatile("s_waitcnt vmcnt(" #n ")" ::: "memory")
; #define PG8_WAIT_L(n) asm volatile("s_waitcnt lgkmcnt(" #n ")" ::: "memory")
; #define PG8_BAR __builtin_amdgcn_s_barrier()
; #define PG8_SCHED __builtin_amdgcn_sched_barrier(0)
; template <class Epi, class Sched, bool ALIGN_EPI = false, bool SP2 = false>
; __device__ __forceinline__ void gemm_phase(PG8_LAS unsigned char* lds, const Gemm g, const Sched& S, const Epi& E) {
;     ...
;             PG8_LDA(At, 0, 1); PG8_STAGE(PG8_SB(0, 0), b2, voffB); PG8_STAGE(PG8_SB(0, 1), b2 + hstepB, voffB); PG8_STAGE(PG8_SA(0, 0), a2, voffA);
;             PG8_WAIT_V(8); PG8_WAIT_L(0); PG8_BAR; PG8_MMA(1, 0, At, B0); PG8_MMA(1, 1, At, B1); PG8_BAR; PG8_SCHED;
;             PG8_LDB(B0, 1, 0); PG8_LDB(B1, 1, 1); PG8_SCHED; PG8_LDA(At, 1, 0); PG8_STAGE(PG8_SA(0, 1), a2 + hstepA, voffA);
;             PG8_WAIT_V(8); PG8_WAIT_L(0); PG8_BAR; PG8_MMA(0, 0, At, B0); PG8_MMA(0, 1, At, B1); PG8_BAR; PG8_SCHED;
	s_add_i32 s29, s54, s40
	v_lshl_add_u64 v[150:151], s[22:23], 0, v[130:131]
	s_mov_b32 m0, s29
	ds_read_b128 v[192:195], v160 offset:16384
	ds_read_b128 v[196:199], v160 offset:17408
	ds_read_b128 v[200:203], v160 offset:18432
	ds_read_b128 v[204:207], v160 offset:19456
	ds_read_b128 v[208:211], v160 offset:20480
	ds_read_b128 v[212:215], v160 offset:21504
	ds_read_b128 v[216:219], v160 offset:22528
	ds_read_b128 v[220:223], v160 offset:23552
	global_load_lds_dwordx4 v[150:151], off
	s_add_i32 m0, s29, 0x2000
	s_add_u32 s30, s22, 0x40000
	v_lshl_add_u64 v[224:225], s[22:23], 0, v[134:135]
	s_addc_u32 s31, s23, 0
	s_add_i32 s29, s55, s40
	global_load_lds_dwordx4 v[224:225], off
	v_lshl_add_u64 v[226:227], s[30:31], 0, v[130:131]
	s_mov_b32 m0, s29
	v_lshl_add_u64 v[228:229], s[34:35], 0, v[132:133]
	global_load_lds_dwordx4 v[226:227], off
	v_lshl_add_u64 v[226:227], s[30:31], 0, v[134:135]
	s_add_i32 m0, s29, 0x2000
	s_nop 0
	global_load_lds_dwordx4 v[226:227], off
	v_lshl_add_u64 v[226:227], s[34:35], 0, v[128:129]
	s_mov_b32 m0, s43
	s_nop 0
	global_load_lds_dwordx4 v[226:227], off
	s_mov_b32 m0, s46
	s_nop 0
	global_load_lds_dwordx4 v[228:229], off
	s_waitcnt vmcnt(8)
	s_waitcnt lgkmcnt(0)
	s_barrier
	s_waitcnt lgkmcnt(0)
	v_mfma_f32_16x16x32_bf16 v[60:63], v[146:149], v[192:195], v[60:63]
	v_mfma_f32_16x16x32_bf16 v[56:59], v[168:171], v[192:195], v[56:59]
	v_mfma_f32_16x16x32_bf16 v[44:47], v[146:149], v[200:203], v[44:47]
	v_mfma_f32_16x16x32_bf16 v[40:43], v[168:171], v[200:203], v[40:43]
	v_mfma_f32_16x16x32_bf16 v[28:31], v[146:149], v[208:211], v[28:31]
	v_mfma_f32_16x16x32_bf16 v[24:27], v[168:171], v[208:211], v[24:27]
	v_mfma_f32_16x16x32_bf16 v[12:15], v[146:149], v[216:219], v[12:15]
	v_mfma_f32_16x16x32_bf16 v[8:11], v[168:171], v[216:219], v[8:11]
	v_mfma_f32_16x16x32_bf16 v[60:63], v[164:167], v[196:199], v[60:63]
	v_mfma_f32_16x16x32_bf16 v[56:59], v[172:175], v[196:199], v[56:59]
	v_mfma_f32_16x16x32_bf16 v[44:47], v[164:167], v[204:207], v[44:47]
	v_mfma_f32_16x16x32_bf16 v[40:43], v[172:175], v[204:207], v[40:43]
	v_mfma_f32_16x16x32_bf16 v[28:31], v[164:167], v[212:215], v[28:31]
	v_mfma_f32_16x16x32_bf16 v[24:27], v[172:175], v[212:215], v[24:27]
	v_mfma_f32_16x16x32_bf16 v[12:15], v[164:167], v[220:223], v[12:15]
	v_mfma_f32_16x16x32_bf16 v[8:11], v[172:175], v[220:223], v[8:11]
	v_mfma_f32_16x16x32_bf16 v[52:55], v[176:179], v[192:195], v[52:55]
	v_mfma_f32_16x16x32_bf16 v[48:51], v[184:187], v[192:195], v[48:51]
	v_mfma_f32_16x16x32_bf16 v[36:39], v[176:179], v[200:203], v[36:39]
	v_mfma_f32_16x16x32_bf16 v[32:35], v[184:187], v[200:203], v[32:35]
	v_mfma_f32_16x16x32_bf16 v[20:23], v[176:179], v[208:211], v[20:23]
	v_mfma_f32_16x16x32_bf16 v[16:19], v[184:187], v[208:211], v[16:19]
	v_mfma_f32_16x16x32_bf16 v[4:7], v[176:179], v[216:219], v[4:7]
	v_mfma_f32_16x16x32_bf16 v[0:3], v[184:187], v[216:219], v[0:3]
	v_mfma_f32_16x16x32_bf16 v[52:55], v[180:183], v[196:199], v[52:55]
	v_mfma_f32_16x16x32_bf16 v[48:51], v[188:191], v[196:199], v[48:51]
	v_mfma_f32_16x16x32_bf16 v[36:39], v[180:183], v[204:207], v[36:39]
	v_mfma_f32_16x16x32_bf16 v[32:35], v[188:191], v[204:207], v[32:35]
	v_mfma_f32_16x16x32_bf16 v[20:23], v[180:183], v[212:215], v[20:23]
	v_mfma_f32_16x16x32_bf16 v[16:19], v[188:191], v[212:215], v[16:19]
	v_mfma_f32_16x16x32_bf16 v[4:7], v[180:183], v[220:223], v[4:7]
	v_mfma_f32_16x16x32_bf16 v[0:3], v[188:191], v[220:223], v[0:3]
	s_barrier
.Lkmid_P7:
	s_add_i32 s29, 0, 0x18000
	v_add_u32_e32 v163, s29, v156
	s_add_i32 s33, 0, 0x1c000
	ds_read_b128 v[146:149], v163
	ds_read_b128 v[164:167], v163 offset:1024
	ds_read_b128 v[168:171], v163 offset:2048
	ds_read_b128 v[172:175], v163 offset:3072
	v_add_u32_e32 v163, s33, v156
	ds_read_b128 v[176:179], v163
	ds_read_b128 v[180:183], v163 offset:1024
	ds_read_b128 v[184:187], v163 offset:2048
	ds_read_b128 v[188:191], v163 offset:3072
	s_add_u32 s30, s34, 0x40000
	s_addc_u32 s31, s35, 0
	s_mov_b32 m0, s47
	v_lshl_add_u64 v[230:231], s[30:31], 0, v[128:129]
	ds_read_b128 v[192:195], v160 offset:32768
	ds_read_b128 v[196:199], v160 offset:33792
	ds_read_b128 v[200:203], v160 offset:34816
	ds_read_b128 v[204:207], v160 offset:35840
	ds_read_b128 v[208:211], v160 offset:36864
	ds_read_b128 v[212:215], v160 offset:37888
	ds_read_b128 v[216:219], v160 offset:38912
	ds_read_b128 v[220:223], v160 offset:39936
	global_load_lds_dwordx4 v[230:231], off
	v_lshl_add_u64 v[230:231], s[30:31], 0, v[132:133]
	s_mov_b32 m0, s48
	s_nop 0
	global_load_lds_dwordx4 v[230:231], off
	s_waitcnt vmcnt(8)
	s_waitcnt lgkmcnt(0)
	s_barrier
; #define PG8_STAGE(bufoff, gbase, voff) do { _Pragma("unroll") for (int _i = 0; _i < 2; ++_i) \
;         __builtin_amdgcn_global_load_lds((const unsigned*)((const char*)(gbase) + (voff)[_i]), (PG8_LAS unsigned*)(lds + (bufoff) + ldsw + _i * 8192), 16, 0, PG8_LOAD_AUX); } while (0)
; #define PG8_LDA(dst, b, h) do { _Pragma("unroll") for (int m = 0; m < 4; ++m) _Pragma("unroll") for (int k = 0; k < 2; ++k) dst[m][k] = *(const PG8_LAS bf16x8*)(lds + PG8_SA(b, h) + aoff + m * 2048 + k * 1024); } while (0)
; #define PG8_MMA(ai, bj, At, Bt) do { __builtin_amdgcn_s_setprio(1); _Pragma("unroll") for (int m = 0; m < 4; ++m) _Pragma("unroll") for (int n = 0; n < 2; ++n) _Pragma("unroll") for (int k = 0; k < 2; ++k) \
;         acc[ai][bj][m][n] = __builtin_amdgcn_mfma_f32_16x16x32_bf16(Bt[n][k], At[m][k], acc[ai][bj][m][n], 0, 0, 0); __builtin_amdgcn_s_setprio(0); } while (0)
; #define PG8_WAIT_V(n) asm volatile("s_waitcnt vmcnt(" #n ")" ::: "memory")
; #define PG8_WAIT_L(n) asm volatile("s_waitcnt lgkmcnt(" #n ")" ::: "memory")
; #define PG8_BAR __builtin_amdgcn_s_barrier()
; #define PG8_SCHED __builtin_amdgcn_sched_barrier(0)
;     __device__ __forceinline__ void operator()(const f32x4 (&acc)[2][2][4][2], const Unit& u, int wr, int wc, int fr, int fq) const {
;     ...
;             for (int m = 0; m < 4; ++m) { const int row = row0 + ai * HALF + m * 16;
;                 const float sc = rstd_from_slots(slots, row, fq);
; template <class Epi, class Sched, bool ALIGN_EPI = false, bool SP2 = false>
; __device__ __forceinline__ void gemm_phase(PG8_LAS unsigned char* lds, const Gemm g, const Sched& S, const Epi& E) {
;     ...
;             PG8_WAIT_V(8); PG8_WAIT_L(0); PG8_BAR; PG8_MMA(0, 0, At, B0); PG8_MMA(0, 1, At, B1); PG8_BAR; PG8_SCHED;
;             PG8_LDA(At, 1, 1); PG8_STAGE(PG8_SB(1, 0), b3, voffB); PG8_STAGE(PG8_SB(1, 1), b3 + hstepB, voffB); PG8_STAGE(PG8_SA(1, 0), a3, voffA);
;             PG8_WAIT_V(8); PG8_WAIT_L(0); PG8_BAR; PG8_MMA(1, 0, At, B0); PG8_MMA(1, 1, At, B1); PG8_BAR; PG8_SCHED;
	s_waitcnt lgkmcnt(0)
	v_mfma_f32_16x16x32_bf16 v[124:127], v[146:149], v[192:195], v[124:127]
	v_mfma_f32_16x16x32_bf16 v[120:123], v[168:171], v[192:195], v[120:123]
	v_mfma_f32_16x16x32_bf16 v[108:111], v[146:149], v[200:203], v[108:111]
	v_mfma_f32_16x16x32_bf16 v[104:107], v[168:171], v[200:203], v[104:107]
	v_mfma_f32_16x16x32_bf16 v[92:95], v[146:149], v[208:211], v[92:95]
	v_mfma_f32_16x16x32_bf16 v[88:91], v[168:171], v[208:211], v[88:91]
	v_mfma_f32_16x16x32_bf16 v[76:79], v[146:149], v[216:219], v[76:79]
	v_mfma_f32_16x16x32_bf16 v[72:75], v[168:171], v[216:219], v[72:75]
	v_mfma_f32_16x16x32_bf16 v[124:127], v[164:167], v[196:199], v[124:127]
	v_mfma_f32_16x16x32_bf16 v[120:123], v[172:175], v[196:199], v[120:123]
	v_mfma_f32_16x16x32_bf16 v[108:111], v[164:167], v[204:207], v[108:111]
	v_mfma_f32_16x16x32_bf16 v[104:107], v[172:175], v[204:207], v[104:107]
	v_mfma_f32_16x16x32_bf16 v[92:95], v[164:167], v[212:215], v[92:95]
	v_mfma_f32_16x16x32_bf16 v[88:91], v[172:175], v[212:215], v[88:91]
	v_mfma_f32_16x16x32_bf16 v[76:79], v[164:167], v[220:223], v[76:79]
	v_mfma_f32_16x16x32_bf16 v[72:75], v[172:175], v[220:223], v[72:75]
	v_mfma_f32_16x16x32_bf16 v[116:119], v[176:179], v[192:195], v[116:119]
	v_mfma_f32_16x16x32_bf16 v[112:115], v[184:187], v[192:195], v[112:115]
	v_mfma_f32_16x16x32_bf16 v[100:103], v[176:179], v[200:203], v[100:103]
	v_mfma_f32_16x16x32_bf16 v[96:99], v[184:187], v[200:203], v[96:99]
	v_mfma_f32_16x16x32_bf16 v[84:87], v[176:179], v[208:211], v[84:87]
	v_mfma_f32_16x16x32_bf16 v[80:83], v[184:187], v[208:211], v[80:83]
	v_mfma_f32_16x16x32_bf16 v[68:71], v[176:179], v[216:219], v[68:71]
	v_mfma_f32_16x16x32_bf16 v[64:67], v[184:187], v[216:219], v[64:67]
	v_mfma_f32_16x16x32_bf16 v[116:119], v[180:183], v[196:199], v[116:119]
	v_mfma_f32_16x16x32_bf16 v[112:115], v[188:191], v[196:199], v[112:115]
	v_mfma_f32_16x16x32_bf16 v[100:103], v[180:183], v[204:207], v[100:103]
	v_mfma_f32_16x16x32_bf16 v[96:99], v[188:191], v[204:207], v[96:99]
	v_mfma_f32_16x16x32_bf16 v[84:87], v[180:183], v[212:215], v[84:87]
	v_mfma_f32_16x16x32_bf16 v[80:83], v[188:191], v[212:215], v[80:83]
	v_mfma_f32_16x16x32_bf16 v[68:71], v[180:183], v[220:223], v[68:71]
	v_mfma_f32_16x16x32_bf16 v[64:67], v[188:191], v[220:223], v[64:67]
	s_barrier
	s_add_i32 s29, s29, s40
	v_lshl_add_u64 v[150:151], v[150:151], 0, s[8:9]
	s_mov_b32 m0, s29
	ds_read_b128 v[192:195], v160 offset:49152
	ds_read_b128 v[196:199], v160 offset:50176
	ds_read_b128 v[200:203], v160 offset:51200
	ds_read_b128 v[204:207], v160 offset:52224
	ds_read_b128 v[208:211], v160 offset:53248
	ds_read_b128 v[212:215], v160 offset:54272
	ds_read_b128 v[216:219], v160 offset:55296
	ds_read_b128 v[220:223], v160 offset:56320
	global_load_lds_dwordx4 v[150:151], off
	s_add_i32 m0, s29, 0x2000
	s_add_u32 s22, s22, 0x40080
	v_lshl_add_u64 v[150:151], v[224:225], 0, s[8:9]
	s_addc_u32 s23, s23, 0
	s_add_i32 s29, s33, s40
	global_load_lds_dwordx4 v[150:151], off
	v_lshl_add_u64 v[150:151], s[22:23], 0, v[130:131]
	s_mov_b32 m0, s29
	s_nop 0
	global_load_lds_dwordx4 v[150:151], off
	v_lshl_add_u64 v[150:151], s[22:23], 0, v[134:135]
	s_add_i32 m0, s29, 0x2000
	s_nop 0
	global_load_lds_dwordx4 v[150:151], off
	v_lshl_add_u64 v[150:151], v[226:227], 0, s[8:9]
	s_mov_b32 m0, s51
	s_nop 0
	global_load_lds_dwordx4 v[150:151], off
	v_lshl_add_u64 v[150:151], v[228:229], 0, s[8:9]
	s_mov_b32 m0, s52
	s_nop 0
	global_load_lds_dwordx4 v[150:151], off
	s_waitcnt vmcnt(8)
	s_waitcnt lgkmcnt(0)
	s_barrier
	s_waitcnt lgkmcnt(0)
	v_mfma_f32_16x16x32_bf16 v[60:63], v[146:149], v[192:195], v[60:63]
	v_mfma_f32_16x16x32_bf16 v[56:59], v[168:171], v[192:195], v[56:59]
	v_mfma_f32_16x16x32_bf16 v[44:47], v[146:149], v[200:203], v[44:47]
	v_mfma_f32_16x16x32_bf16 v[40:43], v[168:171], v[200:203], v[40:43]
	v_mfma_f32_16x16x32_bf16 v[28:31], v[146:149], v[208:211], v[28:31]
	v_mfma_f32_16x16x32_bf16 v[24:27], v[168:171], v[208:211], v[24:27]
	v_mfma_f32_16x16x32_bf16 v[12:15], v[146:149], v[216:219], v[12:15]
	v_mfma_f32_16x16x32_bf16 v[8:11], v[168:171], v[216:219], v[8:11]
	v_mfma_f32_16x16x32_bf16 v[60:63], v[164:167], v[196:199], v[60:63]
	v_mfma_f32_16x16x32_bf16 v[56:59], v[172:175], v[196:199], v[56:59]
	v_mfma_f32_16x16x32_bf16 v[44:47], v[164:167], v[204:207], v[44:47]
	v_mfma_f32_16x16x32_bf16 v[40:43], v[172:175], v[204:207], v[40:43]
	v_mfma_f32_16x16x32_bf16 v[28:31], v[164:167], v[212:215], v[28:31]
	v_mfma_f32_16x16x32_bf16 v[24:27], v[172:175], v[212:215], v[24:27]
	v_mfma_f32_16x16x32_bf16 v[12:15], v[164:167], v[220:223], v[12:15]
	v_mfma_f32_16x16x32_bf16 v[8:11], v[172:175], v[220:223], v[8:11]
	v_mfma_f32_16x16x32_bf16 v[52:55], v[176:179], v[192:195], v[52:55]
	v_mfma_f32_16x16x32_bf16 v[48:51], v[184:187], v[192:195], v[48:51]
	v_mfma_f32_16x16x32_bf16 v[36:39], v[176:179], v[200:203], v[36:39]
	v_mfma_f32_16x16x32_bf16 v[32:35], v[184:187], v[200:203], v[32:35]
	v_mfma_f32_16x16x32_bf16 v[20:23], v[176:179], v[208:211], v[20:23]
	v_mfma_f32_16x16x32_bf16 v[16:19], v[184:187], v[208:211], v[16:19]
	v_mfma_f32_16x16x32_bf16 v[4:7], v[176:179], v[216:219], v[4:7]
	v_mfma_f32_16x16x32_bf16 v[0:3], v[184:187], v[216:219], v[0:3]
	v_mfma_f32_16x16x32_bf16 v[52:55], v[180:183], v[196:199], v[52:55]
	v_mfma_f32_16x16x32_bf16 v[48:51], v[188:191], v[196:199], v[48:51]
	v_mfma_f32_16x16x32_bf16 v[36:39], v[180:183], v[204:207], v[36:39]
	v_mfma_f32_16x16x32_bf16 v[32:35], v[188:191], v[204:207], v[32:35]
	v_mfma_f32_16x16x32_bf16 v[20:23], v[180:183], v[212:215], v[20:23]
	v_mfma_f32_16x16x32_bf16 v[16:19], v[188:191], v[212:215], v[16:19]
	v_mfma_f32_16x16x32_bf16 v[4:7], v[180:183], v[220:223], v[4:7]
	v_mfma_f32_16x16x32_bf16 v[0:3], v[188:191], v[220:223], v[0:3]
	s_barrier
	s_add_i32 s28, s28, 2
	s_add_u32 s20, s20, 0x100
	s_addc_u32 s21, s21, 0
	s_add_u32 s26, s26, 0x100
	s_addc_u32 s27, s27, 0
	s_cmp_gt_u32 s28, 13
	s_cbranch_scc0 .LBB0_672
	v_lshl_add_u32 v204, s0, 8, v152
	v_ashrrev_i32_e32 v205, 31, v204
	v_lshlrev_b64 v[204:205], 6, v[204:205]
	v_lshl_add_u64 v[204:205], v[136:137], 0, v[204:205]
	v_add_co_u32_e32 v206, vcc, 0x2000, v204
	s_nop 1
	v_addc_co_u32_e32 v207, vcc, 0, v205, vcc
	global_load_dwordx4 v[172:175], v[204:205], off
	global_load_dwordx4 v[176:179], v[204:205], off offset:1024
	global_load_dwordx4 v[180:183], v[204:205], off offset:2048
	global_load_dwordx4 v[184:187], v[204:205], off offset:3072
	global_load_dwordx4 v[188:191], v[206:207], off
	global_load_dwordx4 v[192:195], v[206:207], off offset:1024
	global_load_dwordx4 v[196:199], v[206:207], off offset:2048
	global_load_dwordx4 v[200:203], v[206:207], off offset:3072
	s_and_b64 vcc, exec, s[12:13]
	s_cbranch_vccz .LBB0_675
	s_barrier

; #define PG8_STAGE(bufoff, gbase, voff) do { _Pragma("unroll") for (int _i = 0; _i < 2; ++_i) \
;         __builtin_amdgcn_global_load_lds((const unsigned*)((const char*)(gbase) + (voff)[_i]), (PG8_LAS unsigned*)(lds + (bufoff) + ldsw + _i * 8192), 16, 0, PG8_LOAD_AUX); } while (0)
; #define PG8_LDA(dst, b, h) do { _Pragma("unroll") for (int m = 0; m < 4; ++m) _Pragma("unroll") for (int k = 0; k < 2; ++k) dst[m][k] = *(const PG8_LAS bf16x8*)(lds + PG8_SA(b, h) + aoff + m * 2048 + k * 1024); } while (0)
; #define PG8_LDB(dst, b, h) do { _Pragma("unroll") for (int n = 0; n < 2; ++n) _Pragma("unroll") for (int k = 0; k < 2; ++k) dst[n][k] = *(const PG8_LAS bf16x8*)(lds + PG8_SB(b, h) + boff + n * 2048 + k * 1024); } while (0)
; #define PG8_WAIT_V(n) asm volatile("s_waitcnt vmcnt(" #n ")" ::: "memory")
; #define PG8_WAIT_L(n) asm volatile("s_waitcnt lgkmcnt(" #n ")" ::: "memory")
; #define PG8_BAR __builtin_amdgcn_s_barrier()
; #define PG8_SCHED __builtin_amdgcn_sched_barrier(0)
; template <class Epi, class Sched, bool ALIGN_EPI = false, bool SP2 = false>
; __device__ __forceinline__ void gemm_phase(PG8_LAS unsigned char* lds, const Gemm g, const Sched& S, const Epi& E) {
;     ...
;         const char* nA = has_next ? (const char*)g.A + (size_t)nxt.pm * tstepA + (size_t)nxt.pn * apn : cA; const char* nB = has_next ? (const char*)g.Bt + (size_t)nxt.pn * tstepB : cB;
;         for (int t = 0; t < nt; t += 2) {
;             const bool last = (t == nt - 2);
;             const char* a1 = cA + (size_t)(t + 1) * kstep;
;             const char* a2 = last ? nA : cA + (size_t)(t + 2) * kstep; const char* b2 = last ? nB : cB + (size_t)(t + 2) * kstep;
;             const char* a3 = a2 + kstep; const char* b3 = b2 + kstep;
;             if (last && has_next) S.a_ready(nxt);
;             if constexpr (SP2) {
;             PG8_LDB(B0, 0, 0); PG8_LDB(B1, 0, 1); PG8_SCHED; PG8_LDA(At, 0, 0); PG8_STAGE(PG8_SA(1, 1), a1 + hstepA, voffA);
;             PG8_WAIT_V(8); PG8_WAIT_L(0); PG8_BAR; PG8_MMA(0, 0, At, B0); PG8_MMA(0, 1, At, B1); PG8_BAR; PG8_SCHED;
;             PG8_LDA(At, 0, 1); PG8_STAGE(PG8_SB(0, 0), b2, voffB); PG8_STAGE(PG8_SB(0, 1), b2 + hstepB, voffB); PG8_STAGE(PG8_SA(0, 0), a2, voffA);
;             PG8_WAIT_V(8); PG8_WAIT_L(0); PG8_BAR; PG8_MMA(1, 0, At, B0); PG8_MMA(1, 1, At, B1); PG8_BAR; PG8_SCHED;
.LBB0_756:
	s_add_u32 s0, s0, 0xb0080
	s_addc_u32 s1, s1, 0
	s_add_u32 s25, s20, 0x100
	s_addc_u32 s26, s21, 0
	s_mov_b32 s27, -2
	s_waitcnt lgkmcnt(0)
	ds_read_b128 v[146:149], v157
	ds_read_b128 v[162:165], v157 offset:1024
	ds_read_b128 v[166:169], v157 offset:2048
	ds_read_b128 v[170:173], v157 offset:3072
	ds_read_b128 v[174:177], v158
	ds_read_b128 v[178:181], v158 offset:1024
	ds_read_b128 v[182:185], v158 offset:2048
	ds_read_b128 v[186:189], v158 offset:3072
	s_add_u32 s20, s0, 0xfff50080
	s_addc_u32 s21, s1, -1
	s_cmp_eq_u32 s27, 40
	s_cselect_b32 s23, s9, s21
	s_cselect_b32 s22, s8, s20
	s_cselect_b32 s21, s41, s26
	s_cselect_b32 s20, s40, s25
	v_lshl_add_u64 v[222:223], s[0:1], 0, v[138:139]
	s_add_i32 m0, s35, 0xc000
	ds_read_b128 v[190:193], v159
	ds_read_b128 v[194:197], v159 offset:1024
	ds_read_b128 v[198:201], v159 offset:2048
	ds_read_b128 v[202:205], v159 offset:3072
	ds_read_b128 v[206:209], v159 offset:4096
	ds_read_b128 v[210:213], v159 offset:5120
	ds_read_b128 v[214:217], v159 offset:6144
	ds_read_b128 v[218:221], v159 offset:7168
	global_load_lds_dwordx4 v[222:223], off
	v_lshl_add_u64 v[222:223], s[0:1], 0, v[140:141]
	s_add_i32 m0, s35, 0xe000
	s_nop 0
	global_load_lds_dwordx4 v[222:223], off
	s_waitcnt vmcnt(8)
	s_waitcnt lgkmcnt(0)
	s_barrier
	s_waitcnt lgkmcnt(0)
	v_mfma_f32_16x16x32_bf16 v[124:127], v[146:149], v[190:193], 0
	v_mfma_f32_16x16x32_bf16 v[120:123], v[166:169], v[190:193], 0
	v_mfma_f32_16x16x32_bf16 v[108:111], v[146:149], v[198:201], 0
	v_mfma_f32_16x16x32_bf16 v[104:107], v[166:169], v[198:201], 0
	v_mfma_f32_16x16x32_bf16 v[92:95], v[146:149], v[206:209], 0
	v_mfma_f32_16x16x32_bf16 v[88:91], v[166:169], v[206:209], 0
	v_mfma_f32_16x16x32_bf16 v[76:79], v[146:149], v[214:217], 0
	v_mfma_f32_16x16x32_bf16 v[72:75], v[166:169], v[214:217], 0
	v_mfma_f32_16x16x32_bf16 v[124:127], v[162:165], v[194:197], v[124:127]
	v_mfma_f32_16x16x32_bf16 v[120:123], v[170:173], v[194:197], v[120:123]
	v_mfma_f32_16x16x32_bf16 v[108:111], v[162:165], v[202:205], v[108:111]
	v_mfma_f32_16x16x32_bf16 v[104:107], v[170:173], v[202:205], v[104:107]
	v_mfma_f32_16x16x32_bf16 v[92:95], v[162:165], v[210:213], v[92:95]
	v_mfma_f32_16x16x32_bf16 v[88:91], v[170:173], v[210:213], v[88:91]
	v_mfma_f32_16x16x32_bf16 v[76:79], v[162:165], v[218:221], v[76:79]
	v_mfma_f32_16x16x32_bf16 v[72:75], v[170:173], v[218:221], v[72:75]
	v_mfma_f32_16x16x32_bf16 v[116:119], v[174:177], v[190:193], 0
	v_mfma_f32_16x16x32_bf16 v[112:115], v[182:185], v[190:193], 0
	v_mfma_f32_16x16x32_bf16 v[100:103], v[174:177], v[198:201], 0
	v_mfma_f32_16x16x32_bf16 v[96:99], v[182:185], v[198:201], 0
	v_mfma_f32_16x16x32_bf16 v[84:87], v[174:177], v[206:209], 0
	v_mfma_f32_16x16x32_bf16 v[80:83], v[182:185], v[206:209], 0
	v_mfma_f32_16x16x32_bf16 v[68:71], v[174:177], v[214:217], 0
	v_mfma_f32_16x16x32_bf16 v[64:67], v[182:185], v[214:217], 0
	v_mfma_f32_16x16x32_bf16 v[116:119], v[178:181], v[194:197], v[116:119]
	v_mfma_f32_16x16x32_bf16 v[112:115], v[186:189], v[194:197], v[112:115]
	v_mfma_f32_16x16x32_bf16 v[100:103], v[178:181], v[202:205], v[100:103]
	v_mfma_f32_16x16x32_bf16 v[96:99], v[186:189], v[202:205], v[96:99]
	v_mfma_f32_16x16x32_bf16 v[84:87], v[178:181], v[210:213], v[84:87]
	v_mfma_f32_16x16x32_bf16 v[80:83], v[186:189], v[210:213], v[80:83]
	v_mfma_f32_16x16x32_bf16 v[68:71], v[178:181], v[218:221], v[68:71]
	v_mfma_f32_16x16x32_bf16 v[64:67], v[186:189], v[218:221], v[64:67]
	s_barrier
	s_add_i32 s28, s55, s34
	v_lshl_add_u64 v[222:223], s[20:21], 0, v[130:131]
	s_mov_b32 m0, s28
	ds_read_b128 v[190:193], v159 offset:16384
	ds_read_b128 v[194:197], v159 offset:17408
	ds_read_b128 v[198:201], v159 offset:18432
	ds_read_b128 v[202:205], v159 offset:19456
	ds_read_b128 v[206:209], v159 offset:20480
	ds_read_b128 v[210:213], v159 offset:21504
	ds_read_b128 v[214:217], v159 offset:22528
	ds_read_b128 v[218:221], v159 offset:23552
	global_load_lds_dwordx4 v[222:223], off
	s_add_i32 m0, s28, 0x2000
	s_add_u32 s28, s20, 0x2c000
	v_lshl_add_u64 v[224:225], s[20:21], 0, v[134:135]
	s_addc_u32 s29, s21, 0
	s_add_i32 s30, s56, s34
	global_load_lds_dwordx4 v[224:225], off
	v_lshl_add_u64 v[226:227], s[28:29], 0, v[130:131]
	s_mov_b32 m0, s30
	v_lshl_add_u64 v[228:229], s[22:23], 0, v[132:133]
	global_load_lds_dwordx4 v[226:227], off
	v_lshl_add_u64 v[226:227], s[28:29], 0, v[134:135]
	s_add_i32 m0, s30, 0x2000
	s_nop 0
	global_load_lds_dwordx4 v[226:227], off
	v_lshl_add_u64 v[226:227], s[22:23], 0, v[128:129]
	s_mov_b32 m0, s35
	s_nop 0
	global_load_lds_dwordx4 v[226:227], off
	s_mov_b32 m0, s42
	s_nop 0
	global_load_lds_dwordx4 v[228:229], off
	s_waitcnt vmcnt(8)
	s_waitcnt lgkmcnt(0)
	s_barrier
	s_waitcnt lgkmcnt(0)
	v_mfma_f32_16x16x32_bf16 v[60:63], v[146:149], v[190:193], 0
	v_mfma_f32_16x16x32_bf16 v[56:59], v[166:169], v[190:193], 0
	v_mfma_f32_16x16x32_bf16 v[44:47], v[146:149], v[198:201], 0
	v_mfma_f32_16x16x32_bf16 v[40:43], v[166:169], v[198:201], 0
	v_mfma_f32_16x16x32_bf16 v[28:31], v[146:149], v[206:209], 0
	v_mfma_f32_16x16x32_bf16 v[24:27], v[166:169], v[206:209], 0
	v_mfma_f32_16x16x32_bf16 v[12:15], v[146:149], v[214:217], 0
	v_mfma_f32_16x16x32_bf16 v[8:11], v[166:169], v[214:217], 0
	v_mfma_f32_16x16x32_bf16 v[60:63], v[162:165], v[194:197], v[60:63]
	v_mfma_f32_16x16x32_bf16 v[56:59], v[170:173], v[194:197], v[56:59]
	v_mfma_f32_16x16x32_bf16 v[44:47], v[162:165], v[202:205], v[44:47]
	v_mfma_f32_16x16x32_bf16 v[40:43], v[170:173], v[202:205], v[40:43]
	v_mfma_f32_16x16x32_bf16 v[28:31], v[162:165], v[210:213], v[28:31]
	v_mfma_f32_16x16x32_bf16 v[24:27], v[170:173], v[210:213], v[24:27]
	v_mfma_f32_16x16x32_bf16 v[12:15], v[162:165], v[218:221], v[12:15]
	v_mfma_f32_16x16x32_bf16 v[8:11], v[170:173], v[218:221], v[8:11]
	v_mfma_f32_16x16x32_bf16 v[52:55], v[174:177], v[190:193], 0
	v_mfma_f32_16x16x32_bf16 v[48:51], v[182:185], v[190:193], 0
	v_mfma_f32_16x16x32_bf16 v[36:39], v[174:177], v[198:201], 0
	v_mfma_f32_16x16x32_bf16 v[32:35], v[182:185], v[198:201], 0
	v_mfma_f32_16x16x32_bf16 v[20:23], v[174:177], v[206:209], 0
	v_mfma_f32_16x16x32_bf16 v[16:19], v[182:185], v[206:209], 0
	v_mfma_f32_16x16x32_bf16 v[4:7], v[174:177], v[214:217], 0
	v_mfma_f32_16x16x32_bf16 v[0:3], v[182:185], v[214:217], 0
	v_mfma_f32_16x16x32_bf16 v[52:55], v[178:181], v[194:197], v[52:55]
	v_mfma_f32_16x16x32_bf16 v[48:51], v[186:189], v[194:197], v[48:51]
	v_mfma_f32_16x16x32_bf16 v[36:39], v[178:181], v[202:205], v[36:39]
	v_mfma_f32_16x16x32_bf16 v[32:35], v[186:189], v[202:205], v[32:35]
	v_mfma_f32_16x16x32_bf16 v[20:23], v[178:181], v[210:213], v[20:23]
	v_mfma_f32_16x16x32_bf16 v[16:19], v[186:189], v[210:213], v[16:19]
	v_mfma_f32_16x16x32_bf16 v[4:7], v[178:181], v[218:221], v[4:7]
	v_mfma_f32_16x16x32_bf16 v[0:3], v[186:189], v[218:221], v[0:3]
	s_barrier
	s_branch .Lkmid_P8
; #define PG8_STAGE(bufoff, gbase, voff) do { _Pragma("unroll") for (int _i = 0; _i < 2; ++_i) \
;         __builtin_amdgcn_global_load_lds((const unsigned*)((const char*)(gbase) + (voff)[_i]), (PG8_LAS unsigned*)(lds + (bufoff) + ldsw + _i * 8192), 16, 0, PG8_LOAD_AUX); } while (0)
; #define PG8_LDA(dst, b, h) do { _Pragma("unroll") for (int m = 0; m < 4; ++m) _Pragma("unroll") for (int k = 0; k < 2; ++k) dst[m][k] = *(const PG8_LAS bf16x8*)(lds + PG8_SA(b, h) + aoff + m * 2048 + k * 1024); } while (0)
; #define PG8_LDB(dst, b, h) do { _Pragma("unroll") for (int n = 0; n < 2; ++n) _Pragma("unroll") for (int k = 0; k < 2; ++k) dst[n][k] = *(const PG8_LAS bf16x8*)(lds + PG8_SB(b, h) + boff + n * 2048 + k * 1024); } while (0)
; #define PG8_MMA(ai, bj, At, Bt) do { __builtin_amdgcn_s_setprio(1); _Pragma("unroll") for (int m = 0; m < 4; ++m) _Pragma("unroll") for (int n = 0; n < 2; ++n) _Pragma("unroll") for (int k = 0; k < 2; ++k) \
;         acc[ai][bj][m][n] = __builtin_amdgcn_mfma_f32_16x16x32_bf16(Bt[n][k], At[m][k], acc[ai][bj][m][n], 0, 0, 0); __builtin_amdgcn_s_setprio(0); } while (0)
; #define PG8_WAIT_V(n) asm volatile("s_waitcnt vmcnt(" #n ")" ::: "memory")
; #define PG8_WAIT_L(n) asm volatile("s_waitcnt lgkmcnt(" #n ")" ::: "memory")
; #define PG8_BAR __builtin_amdgcn_s_barrier()
; #define PG8_SCHED __builtin_amdgcn_sched_barrier(0)
; template <class Epi, class Sched, bool ALIGN_EPI = false, bool SP2 = false>
; __device__ __forceinline__ void gemm_phase(PG8_LAS unsigned char* lds, const Gemm g, const Sched& S, const Epi& E) {
;     ...
;             PG8_LDB(B0, 0, 0); PG8_LDB(B1, 0, 1); PG8_SCHED; PG8_LDA(At, 0, 0); PG8_STAGE(PG8_SA(1, 1), a1 + hstepA, voffA);
;             PG8_WAIT_V(8); PG8_WAIT_L(0); PG8_BAR; PG8_MMA(0, 0, At, B0); PG8_MMA(0, 1, At, B1); PG8_BAR; PG8_SCHED;
;             PG8_LDA(At, 0, 1); PG8_STAGE(PG8_SB(0, 0), b2, voffB); PG8_STAGE(PG8_SB(0, 1), b2 + hstepB, voffB); PG8_STAGE(PG8_SA(0, 0), a2, voffA);
;             PG8_WAIT_V(8); PG8_WAIT_L(0); PG8_BAR; PG8_MMA(1, 0, At, B0); PG8_MMA(1, 1, At, B1); PG8_BAR; PG8_SCHED;
.LBB0_757:
	ds_read_b128 v[146:149], v157
	ds_read_b128 v[162:165], v157 offset:1024
	ds_read_b128 v[166:169], v157 offset:2048
	ds_read_b128 v[170:173], v157 offset:3072
	ds_read_b128 v[174:177], v158
	ds_read_b128 v[178:181], v158 offset:1024
	ds_read_b128 v[182:185], v158 offset:2048
	ds_read_b128 v[186:189], v158 offset:3072
	s_add_u32 s20, s0, 0xfff50080
	s_addc_u32 s21, s1, -1
	s_cmp_eq_u32 s27, 40
	s_cselect_b32 s23, s9, s21
	s_cselect_b32 s22, s8, s20
	s_cselect_b32 s21, s41, s26
	s_cselect_b32 s20, s40, s25
	v_lshl_add_u64 v[222:223], s[0:1], 0, v[138:139]
	s_add_i32 m0, s35, 0xc000
	ds_read_b128 v[190:193], v159
	ds_read_b128 v[194:197], v159 offset:1024
	ds_read_b128 v[198:201], v159 offset:2048
	ds_read_b128 v[202:205], v159 offset:3072
	ds_read_b128 v[206:209], v159 offset:4096
	ds_read_b128 v[210:213], v159 offset:5120
	ds_read_b128 v[214:217], v159 offset:6144
	ds_read_b128 v[218:221], v159 offset:7168
	global_load_lds_dwordx4 v[222:223], off
	v_lshl_add_u64 v[222:223], s[0:1], 0, v[140:141]
	s_add_i32 m0, s35, 0xe000
	s_nop 0
	global_load_lds_dwordx4 v[222:223], off
	s_waitcnt vmcnt(8)
	s_waitcnt lgkmcnt(0)
	s_barrier
	s_waitcnt lgkmcnt(0)
	v_mfma_f32_16x16x32_bf16 v[124:127], v[146:149], v[190:193], v[124:127]
	v_mfma_f32_16x16x32_bf16 v[120:123], v[166:169], v[190:193], v[120:123]
	v_mfma_f32_16x16x32_bf16 v[108:111], v[146:149], v[198:201], v[108:111]
	v_mfma_f32_16x16x32_bf16 v[104:107], v[166:169], v[198:201], v[104:107]
	v_mfma_f32_16x16x32_bf16 v[92:95], v[146:149], v[206:209], v[92:95]
	v_mfma_f32_16x16x32_bf16 v[88:91], v[166:169], v[206:209], v[88:91]
	v_mfma_f32_16x16x32_bf16 v[76:79], v[146:149], v[214:217], v[76:79]
	v_mfma_f32_16x16x32_bf16 v[72:75], v[166:169], v[214:217], v[72:75]
	v_mfma_f32_16x16x32_bf16 v[124:127], v[162:165], v[194:197], v[124:127]
	v_mfma_f32_16x16x32_bf16 v[120:123], v[170:173], v[194:197], v[120:123]
	v_mfma_f32_16x16x32_bf16 v[108:111], v[162:165], v[202:205], v[108:111]
	v_mfma_f32_16x16x32_bf16 v[104:107], v[170:173], v[202:205], v[104:107]
	v_mfma_f32_16x16x32_bf16 v[92:95], v[162:165], v[210:213], v[92:95]
	v_mfma_f32_16x16x32_bf16 v[88:91], v[170:173], v[210:213], v[88:91]
	v_mfma_f32_16x16x32_bf16 v[76:79], v[162:165], v[218:221], v[76:79]
	v_mfma_f32_16x16x32_bf16 v[72:75], v[170:173], v[218:221], v[72:75]
	v_mfma_f32_16x16x32_bf16 v[116:119], v[174:177], v[190:193], v[116:119]
	v_mfma_f32_16x16x32_bf16 v[112:115], v[182:185], v[190:193], v[112:115]
	v_mfma_f32_16x16x32_bf16 v[100:103], v[174:177], v[198:201], v[100:103]
	v_mfma_f32_16x16x32_bf16 v[96:99], v[182:185], v[198:201], v[96:99]
	v_mfma_f32_16x16x32_bf16 v[84:87], v[174:177], v[206:209], v[84:87]
	v_mfma_f32_16x16x32_bf16 v[80:83], v[182:185], v[206:209], v[80:83]
	v_mfma_f32_16x16x32_bf16 v[68:71], v[174:177], v[214:217], v[68:71]
	v_mfma_f32_16x16x32_bf16 v[64:67], v[182:185], v[214:217], v[64:67]
	v_mfma_f32_16x16x32_bf16 v[116:119], v[178:181], v[194:197], v[116:119]
	v_mfma_f32_16x16x32_bf16 v[112:115], v[186:189], v[194:197], v[112:115]
	v_mfma_f32_16x16x32_bf16 v[100:103], v[178:181], v[202:205], v[100:103]
	v_mfma_f32_16x16x32_bf16 v[96:99], v[186:189], v[202:205], v[96:99]
	v_mfma_f32_16x16x32_bf16 v[84:87], v[178:181], v[210:213], v[84:87]
	v_mfma_f32_16x16x32_bf16 v[80:83], v[186:189], v[210:213], v[80:83]
	v_mfma_f32_16x16x32_bf16 v[68:71], v[178:181], v[218:221], v[68:71]
	v_mfma_f32_16x16x32_bf16 v[64:67], v[186:189], v[218:221], v[64:67]
	s_barrier
	s_add_i32 s28, s55, s34
	v_lshl_add_u64 v[222:223], s[20:21], 0, v[130:131]
	s_mov_b32 m0, s28
	ds_read_b128 v[190:193], v159 offset:16384
	ds_read_b128 v[194:197], v159 offset:17408
	ds_read_b128 v[198:201], v159 offset:18432
	ds_read_b128 v[202:205], v159 offset:19456
	ds_read_b128 v[206:209], v159 offset:20480
	ds_read_b128 v[210:213], v159 offset:21504
	ds_read_b128 v[214:217], v159 offset:22528
	ds_read_b128 v[218:221], v159 offset:23552
	global_load_lds_dwordx4 v[222:223], off
	s_add_i32 m0, s28, 0x2000
	s_add_u32 s28, s20, 0x2c000
	v_lshl_add_u64 v[224:225], s[20:21], 0, v[134:135]
	s_addc_u32 s29, s21, 0
	s_add_i32 s30, s56, s34
	global_load_lds_dwordx4 v[224:225], off
	v_lshl_add_u64 v[226:227], s[28:29], 0, v[130:131]
	s_mov_b32 m0, s30
	v_lshl_add_u64 v[228:229], s[22:23], 0, v[132:133]
	global_load_lds_dwordx4 v[226:227], off
	v_lshl_add_u64 v[226:227], s[28:29], 0, v[134:135]
	s_add_i32 m0, s30, 0x2000
	s_nop 0
	global_load_lds_dwordx4 v[226:227], off
	v_lshl_add_u64 v[226:227], s[22:23], 0, v[128:129]
	s_mov_b32 m0, s35
	s_nop 0
	global_load_lds_dwordx4 v[226:227], off
	s_mov_b32 m0, s42
	s_nop 0
	global_load_lds_dwordx4 v[228:229], off
	s_waitcnt vmcnt(8)
	s_waitcnt lgkmcnt(0)
	s_barrier
	s_waitcnt lgkmcnt(0)
	v_mfma_f32_16x16x32_bf16 v[60:63], v[146:149], v[190:193], v[60:63]
	v_mfma_f32_16x16x32_bf16 v[56:59], v[166:169], v[190:193], v[56:59]
	v_mfma_f32_16x16x32_bf16 v[44:47], v[146:149], v[198:201], v[44:47]
	v_mfma_f32_16x16x32_bf16 v[40:43], v[166:169], v[198:201], v[40:43]
	v_mfma_f32_16x16x32_bf16 v[28:31], v[146:149], v[206:209], v[28:31]
	v_mfma_f32_16x16x32_bf16 v[24:27], v[166:169], v[206:209], v[24:27]
	v_mfma_f32_16x16x32_bf16 v[12:15], v[146:149], v[214:217], v[12:15]
	v_mfma_f32_16x16x32_bf16 v[8:11], v[166:169], v[214:217], v[8:11]
	v_mfma_f32_16x16x32_bf16 v[60:63], v[162:165], v[194:197], v[60:63]
	v_mfma_f32_16x16x32_bf16 v[56:59], v[170:173], v[194:197], v[56:59]
	v_mfma_f32_16x16x32_bf16 v[44:47], v[162:165], v[202:205], v[44:47]
	v_mfma_f32_16x16x32_bf16 v[40:43], v[170:173], v[202:205], v[40:43]
	v_mfma_f32_16x16x32_bf16 v[28:31], v[162:165], v[210:213], v[28:31]
	v_mfma_f32_16x16x32_bf16 v[24:27], v[170:173], v[210:213], v[24:27]
	v_mfma_f32_16x16x32_bf16 v[12:15], v[162:165], v[218:221], v[12:15]
	v_mfma_f32_16x16x32_bf16 v[8:11], v[170:173], v[218:221], v[8:11]
	v_mfma_f32_16x16x32_bf16 v[52:55], v[174:177], v[190:193], v[52:55]
	v_mfma_f32_16x16x32_bf16 v[48:51], v[182:185], v[190:193], v[48:51]
	v_mfma_f32_16x16x32_bf16 v[36:39], v[174:177], v[198:201], v[36:39]
	v_mfma_f32_16x16x32_bf16 v[32:35], v[182:185], v[198:201], v[32:35]
	v_mfma_f32_16x16x32_bf16 v[20:23], v[174:177], v[206:209], v[20:23]
	v_mfma_f32_16x16x32_bf16 v[16:19], v[182:185], v[206:209], v[16:19]
	v_mfma_f32_16x16x32_bf16 v[4:7], v[174:177], v[214:217], v[4:7]
	v_mfma_f32_16x16x32_bf16 v[0:3], v[182:185], v[214:217], v[0:3]
	v_mfma_f32_16x16x32_bf16 v[52:55], v[178:181], v[194:197], v[52:55]
	v_mfma_f32_16x16x32_bf16 v[48:51], v[186:189], v[194:197], v[48:51]
	v_mfma_f32_16x16x32_bf16 v[36:39], v[178:181], v[202:205], v[36:39]
	v_mfma_f32_16x16x32_bf16 v[32:35], v[186:189], v[202:205], v[32:35]
	v_mfma_f32_16x16x32_bf16 v[20:23], v[178:181], v[210:213], v[20:23]
	v_mfma_f32_16x16x32_bf16 v[16:19], v[186:189], v[210:213], v[16:19]
	v_mfma_f32_16x16x32_bf16 v[4:7], v[178:181], v[218:221], v[4:7]
	v_mfma_f32_16x16x32_bf16 v[0:3], v[186:189], v[218:221], v[0:3]
	s_barrier
; #define PG8_STAGE(bufoff, gbase, voff) do { _Pragma("unroll") for (int _i = 0; _i < 2; ++_i) \
;         __builtin_amdgcn_global_load_lds((const unsigned*)((const char*)(gbase) + (voff)[_i]), (PG8_LAS unsigned*)(lds + (bufoff) + ldsw + _i * 8192), 16, 0, PG8_LOAD_AUX); } while (0)
; #define PG8_LDA(dst, b, h) do { _Pragma("unroll") for (int m = 0; m < 4; ++m) _Pragma("unroll") for (int k = 0; k < 2; ++k) dst[m][k] = *(const PG8_LAS bf16x8*)(lds + PG8_SA(b, h) + aoff + m * 2048 + k * 1024); } while (0)
; #define PG8_LDB(dst, b, h) do { _Pragma("unroll") for (int n = 0; n < 2; ++n) _Pragma("unroll") for (int k = 0; k < 2; ++k) dst[n][k] = *(const PG8_LAS bf16x8*)(lds + PG8_SB(b, h) + boff + n * 2048 + k * 1024); } while (0)
; #define PG8_MMA(ai, bj, At, Bt) do { __builtin_amdgcn_s_setprio(1); _Pragma("unroll") for (int m = 0; m < 4; ++m) _Pragma("unroll") for (int n = 0; n < 2; ++n) _Pragma("unroll") for (int k = 0; k < 2; ++k) \
;         acc[ai][bj][m][n] = __builtin_amdgcn_mfma_f32_16x16x32_bf16(Bt[n][k], At[m][k], acc[ai][bj][m][n], 0, 0, 0); __builtin_amdgcn_s_setprio(0); } while (0)
; #define PG8_WAIT_V(n) asm volatile("s_waitcnt vmcnt(" #n ")" ::: "memory")
; #define PG8_WAIT_L(n) asm volatile("s_waitcnt lgkmcnt(" #n ")" ::: "memory")
; #define PG8_BAR __builtin_amdgcn_s_barrier()
; #define PG8_SCHED __builtin_amdgcn_sched_barrier(0)
; template <class Epi, class Sched, bool ALIGN_EPI = false, bool SP2 = false>
; __device__ __forceinline__ void gemm_phase(PG8_LAS unsigned char* lds, const Gemm g, const Sched& S, const Epi& E) {
;     ...
;             PG8_LDB(B0, 1, 0); PG8_LDB(B1, 1, 1); PG8_SCHED; PG8_LDA(At, 1, 0); PG8_STAGE(PG8_SA(0, 1), a2 + hstepA, voffA);
;             PG8_WAIT_V(8); PG8_WAIT_L(0); PG8_BAR; PG8_MMA(0, 0, At, B0); PG8_MMA(0, 1, At, B1); PG8_BAR; PG8_SCHED;
.Lkmid_P8:
	s_add_i32 s28, 0, 0x18000
	v_add_u32_e32 v161, s28, v151
	s_add_i32 s29, 0, 0x1c000
	ds_read_b128 v[146:149], v161
	ds_read_b128 v[162:165], v161 offset:1024
	ds_read_b128 v[166:169], v161 offset:2048
	ds_read_b128 v[170:173], v161 offset:3072
	v_add_u32_e32 v161, s29, v151
	ds_read_b128 v[174:177], v161
	ds_read_b128 v[178:181], v161 offset:1024
	ds_read_b128 v[182:185], v161 offset:2048
	ds_read_b128 v[186:189], v161 offset:3072
	s_add_u32 s22, s22, 0xb0000
	s_addc_u32 s23, s23, 0
	s_mov_b32 m0, s43
	v_lshl_add_u64 v[230:231], s[22:23], 0, v[128:129]
	ds_read_b128 v[190:193], v159 offset:32768
	ds_read_b128 v[194:197], v159 offset:33792
	ds_read_b128 v[198:201], v159 offset:34816
	ds_read_b128 v[202:205], v159 offset:35840
	ds_read_b128 v[206:209], v159 offset:36864
	ds_read_b128 v[210:213], v159 offset:37888
	ds_read_b128 v[214:217], v159 offset:38912
	ds_read_b128 v[218:221], v159 offset:39936
	global_load_lds_dwordx4 v[230:231], off
	v_lshl_add_u64 v[230:231], s[22:23], 0, v[132:133]
	s_mov_b32 m0, s46
	s_nop 0
	global_load_lds_dwordx4 v[230:231], off
	s_waitcnt vmcnt(8)
	s_waitcnt lgkmcnt(0)
	s_barrier
	s_waitcnt lgkmcnt(0)
	v_mfma_f32_16x16x32_bf16 v[124:127], v[146:149], v[190:193], v[124:127]
	v_mfma_f32_16x16x32_bf16 v[120:123], v[166:169], v[190:193], v[120:123]
	v_mfma_f32_16x16x32_bf16 v[108:111], v[146:149], v[198:201], v[108:111]
	v_mfma_f32_16x16x32_bf16 v[104:107], v[166:169], v[198:201], v[104:107]
	v_mfma_f32_16x16x32_bf16 v[92:95], v[146:149], v[206:209], v[92:95]
	v_mfma_f32_16x16x32_bf16 v[88:91], v[166:169], v[206:209], v[88:91]
	v_mfma_f32_16x16x32_bf16 v[76:79], v[146:149], v[214:217], v[76:79]
	v_mfma_f32_16x16x32_bf16 v[72:75], v[166:169], v[214:217], v[72:75]
	v_mfma_f32_16x16x32_bf16 v[124:127], v[162:165], v[194:197], v[124:127]
	v_mfma_f32_16x16x32_bf16 v[120:123], v[170:173], v[194:197], v[120:123]
	v_mfma_f32_16x16x32_bf16 v[108:111], v[162:165], v[202:205], v[108:111]
	v_mfma_f32_16x16x32_bf16 v[104:107], v[170:173], v[202:205], v[104:107]
	v_mfma_f32_16x16x32_bf16 v[92:95], v[162:165], v[210:213], v[92:95]
	v_mfma_f32_16x16x32_bf16 v[88:91], v[170:173], v[210:213], v[88:91]
	v_mfma_f32_16x16x32_bf16 v[76:79], v[162:165], v[218:221], v[76:79]
	v_mfma_f32_16x16x32_bf16 v[72:75], v[170:173], v[218:221], v[72:75]
	v_mfma_f32_16x16x32_bf16 v[116:119], v[174:177], v[190:193], v[116:119]
	v_mfma_f32_16x16x32_bf16 v[112:115], v[182:185], v[190:193], v[112:115]
	v_mfma_f32_16x16x32_bf16 v[100:103], v[174:177], v[198:201], v[100:103]
	v_mfma_f32_16x16x32_bf16 v[96:99], v[182:185], v[198:201], v[96:99]
	v_mfma_f32_16x16x32_bf16 v[84:87], v[174:177], v[206:209], v[84:87]
	v_mfma_f32_16x16x32_bf16 v[80:83], v[182:185], v[206:209], v[80:83]
	v_mfma_f32_16x16x32_bf16 v[68:71], v[174:177], v[214:217], v[68:71]
	v_mfma_f32_16x16x32_bf16 v[64:67], v[182:185], v[214:217], v[64:67]
	v_mfma_f32_16x16x32_bf16 v[116:119], v[178:181], v[194:197], v[116:119]
	v_mfma_f32_16x16x32_bf16 v[112:115], v[186:189], v[194:197], v[112:115]
	v_mfma_f32_16x16x32_bf16 v[100:103], v[178:181], v[202:205], v[100:103]
	v_mfma_f32_16x16x32_bf16 v[96:99], v[186:189], v[202:205], v[96:99]
	v_mfma_f32_16x16x32_bf16 v[84:87], v[178:181], v[210:213], v[84:87]
	v_mfma_f32_16x16x32_bf16 v[80:83], v[186:189], v[210:213], v[80:83]
	v_mfma_f32_16x16x32_bf16 v[68:71], v[178:181], v[218:221], v[68:71]
	v_mfma_f32_16x16x32_bf16 v[64:67], v[186:189], v[218:221], v[64:67]
	s_barrier
; #define PG8_STAGE(bufoff, gbase, voff) do { _Pragma("unroll") for (int _i = 0; _i < 2; ++_i) \
;         __builtin_amdgcn_global_load_lds((const unsigned*)((const char*)(gbase) + (voff)[_i]), (PG8_LAS unsigned*)(lds + (bufoff) + ldsw + _i * 8192), 16, 0, PG8_LOAD_AUX); } while (0)
; #define PG8_LDA(dst, b, h) do { _Pragma("unroll") for (int m = 0; m < 4; ++m) _Pragma("unroll") for (int k = 0; k < 2; ++k) dst[m][k] = *(const PG8_LAS bf16x8*)(lds + PG8_SA(b, h) + aoff + m * 2048 + k * 1024); } while (0)
; #define PG8_MMA(ai, bj, At, Bt) do { __builtin_amdgcn_s_setprio(1); _Pragma("unroll") for (int m = 0; m < 4; ++m) _Pragma("unroll") for (int n = 0; n < 2; ++n) _Pragma("unroll") for (int k = 0; k < 2; ++k) \
;         acc[ai][bj][m][n] = __builtin_amdgcn_mfma_f32_16x16x32_bf16(Bt[n][k], At[m][k], acc[ai][bj][m][n], 0, 0, 0); __builtin_amdgcn_s_setprio(0); } while (0)
; #define PG8_WAIT_V(n) asm volatile("s_waitcnt vmcnt(" #n ")" ::: "memory")
; #define PG8_WAIT_L(n) asm volatile("s_waitcnt lgkmcnt(" #n ")" ::: "memory")
; #define PG8_BAR __builtin_amdgcn_s_barrier()
; #define PG8_SCHED __builtin_amdgcn_sched_barrier(0)
; template <class Epi, class Sched, bool ALIGN_EPI = false, bool SP2 = false>
; __device__ __forceinline__ void gemm_phase(PG8_LAS unsigned char* lds, const Gemm g, const Sched& S, const Epi& E) {
;     ...
;             PG8_LDA(At, 1, 1); PG8_STAGE(PG8_SB(1, 0), b3, voffB); PG8_STAGE(PG8_SB(1, 1), b3 + hstepB, voffB); PG8_STAGE(PG8_SA(1, 0), a3, voffA);
;             PG8_WAIT_V(8); PG8_WAIT_L(0); PG8_BAR; PG8_MMA(1, 0, At, B0); PG8_MMA(1, 1, At, B1); PG8_BAR; PG8_SCHED;
	s_add_i32 s22, s28, s34
	v_lshl_add_u64 v[222:223], v[222:223], 0, s[18:19]
	s_mov_b32 m0, s22
	ds_read_b128 v[190:193], v159 offset:49152
	ds_read_b128 v[194:197], v159 offset:50176
	ds_read_b128 v[198:201], v159 offset:51200
	ds_read_b128 v[202:205], v159 offset:52224
	ds_read_b128 v[206:209], v159 offset:53248
	ds_read_b128 v[210:213], v159 offset:54272
	ds_read_b128 v[214:217], v159 offset:55296
	ds_read_b128 v[218:221], v159 offset:56320
	global_load_lds_dwordx4 v[222:223], off
	s_add_i32 m0, s22, 0x2000
	s_add_u32 s20, s20, 0x2c080
	v_lshl_add_u64 v[222:223], v[224:225], 0, s[18:19]
	s_addc_u32 s21, s21, 0
	s_add_i32 s22, s29, s34
	global_load_lds_dwordx4 v[222:223], off
	v_lshl_add_u64 v[222:223], s[20:21], 0, v[130:131]
	s_mov_b32 m0, s22
	s_nop 0
	global_load_lds_dwordx4 v[222:223], off
	v_lshl_add_u64 v[222:223], s[20:21], 0, v[134:135]
	s_add_i32 m0, s22, 0x2000
	s_nop 0
	global_load_lds_dwordx4 v[222:223], off
	v_lshl_add_u64 v[222:223], v[226:227], 0, s[18:19]
	s_mov_b32 m0, s50
	s_nop 0
	global_load_lds_dwordx4 v[222:223], off
	v_lshl_add_u64 v[222:223], v[228:229], 0, s[18:19]
	s_mov_b32 m0, s51
	s_nop 0
	global_load_lds_dwordx4 v[222:223], off
	s_waitcnt vmcnt(8)
	s_waitcnt lgkmcnt(0)
	s_barrier
	s_waitcnt lgkmcnt(0)
	v_mfma_f32_16x16x32_bf16 v[60:63], v[146:149], v[190:193], v[60:63]
	v_mfma_f32_16x16x32_bf16 v[56:59], v[166:169], v[190:193], v[56:59]
	v_mfma_f32_16x16x32_bf16 v[44:47], v[146:149], v[198:201], v[44:47]
	v_mfma_f32_16x16x32_bf16 v[40:43], v[166:169], v[198:201], v[40:43]
	v_mfma_f32_16x16x32_bf16 v[28:31], v[146:149], v[206:209], v[28:31]
	v_mfma_f32_16x16x32_bf16 v[24:27], v[166:169], v[206:209], v[24:27]
	v_mfma_f32_16x16x32_bf16 v[12:15], v[146:149], v[214:217], v[12:15]
	v_mfma_f32_16x16x32_bf16 v[8:11], v[166:169], v[214:217], v[8:11]
	v_mfma_f32_16x16x32_bf16 v[60:63], v[162:165], v[194:197], v[60:63]
	v_mfma_f32_16x16x32_bf16 v[56:59], v[170:173], v[194:197], v[56:59]
	v_mfma_f32_16x16x32_bf16 v[44:47], v[162:165], v[202:205], v[44:47]
	v_mfma_f32_16x16x32_bf16 v[40:43], v[170:173], v[202:205], v[40:43]
	v_mfma_f32_16x16x32_bf16 v[28:31], v[162:165], v[210:213], v[28:31]
	v_mfma_f32_16x16x32_bf16 v[24:27], v[170:173], v[210:213], v[24:27]
	v_mfma_f32_16x16x32_bf16 v[12:15], v[162:165], v[218:221], v[12:15]
	v_mfma_f32_16x16x32_bf16 v[8:11], v[170:173], v[218:221], v[8:11]
	v_mfma_f32_16x16x32_bf16 v[52:55], v[174:177], v[190:193], v[52:55]
	v_mfma_f32_16x16x32_bf16 v[48:51], v[182:185], v[190:193], v[48:51]
	v_mfma_f32_16x16x32_bf16 v[36:39], v[174:177], v[198:201], v[36:39]
	v_mfma_f32_16x16x32_bf16 v[32:35], v[182:185], v[198:201], v[32:35]
	v_mfma_f32_16x16x32_bf16 v[20:23], v[174:177], v[206:209], v[20:23]
	v_mfma_f32_16x16x32_bf16 v[16:19], v[182:185], v[206:209], v[16:19]
	v_mfma_f32_16x16x32_bf16 v[4:7], v[174:177], v[214:217], v[4:7]
	v_mfma_f32_16x16x32_bf16 v[0:3], v[182:185], v[214:217], v[0:3]
	v_mfma_f32_16x16x32_bf16 v[52:55], v[178:181], v[194:197], v[52:55]
	v_mfma_f32_16x16x32_bf16 v[48:51], v[186:189], v[194:197], v[48:51]
	v_mfma_f32_16x16x32_bf16 v[36:39], v[178:181], v[202:205], v[36:39]
	v_mfma_f32_16x16x32_bf16 v[32:35], v[186:189], v[202:205], v[32:35]
	v_mfma_f32_16x16x32_bf16 v[20:23], v[178:181], v[210:213], v[20:23]
	v_mfma_f32_16x16x32_bf16 v[16:19], v[186:189], v[210:213], v[16:19]
	v_mfma_f32_16x16x32_bf16 v[4:7], v[178:181], v[218:221], v[4:7]
	v_mfma_f32_16x16x32_bf16 v[0:3], v[186:189], v[218:221], v[0:3]
	s_barrier
	s_add_i32 s27, s27, 2
	s_add_u32 s0, s0, 0x100
	s_addc_u32 s1, s1, 0
	s_add_u32 s25, s25, 0x100
	s_addc_u32 s26, s26, 0
	s_cmp_gt_u32 s27, 41
	s_cbranch_scc0 .LBB0_757
	s_and_b64 vcc, exec, s[36:37]
	s_cbranch_vccz .LBB0_760
	s_barrier

; #define PG8_STAGE(bufoff, gbase, voff) do { _Pragma("unroll") for (int _i = 0; _i < 2; ++_i) \
;         __builtin_amdgcn_global_load_lds((const unsigned*)((const char*)(gbase) + (voff)[_i]), (PG8_LAS unsigned*)(lds + (bufoff) + ldsw + _i * 8192), 16, 0, PG8_LOAD_AUX); } while (0)
; #define PG8_LDA(dst, b, h) do { _Pragma("unroll") for (int m = 0; m < 4; ++m) _Pragma("unroll") for (int k = 0; k < 2; ++k) dst[m][k] = *(const PG8_LAS bf16x8*)(lds + PG8_SA(b, h) + aoff + m * 2048 + k * 1024); } while (0)
; #define PG8_LDB(dst, b, h) do { _Pragma("unroll") for (int n = 0; n < 2; ++n) _Pragma("unroll") for (int k = 0; k < 2; ++k) dst[n][k] = *(const PG8_LAS bf16x8*)(lds + PG8_SB(b, h) + boff + n * 2048 + k * 1024); } while (0)
; #define PG8_WAIT_V(n) asm volatile("s_waitcnt vmcnt(" #n ")" ::: "memory")
; #define PG8_WAIT_L(n) asm volatile("s_waitcnt lgkmcnt(" #n ")" ::: "memory")
; #define PG8_BAR __builtin_amdgcn_s_barrier()
; #define PG8_SCHED __builtin_amdgcn_sched_barrier(0)
; template <class Epi, class Sched, bool ALIGN_EPI = false, bool SP2 = false>
; __device__ __forceinline__ void gemm_phase(PG8_LAS unsigned char* lds, const Gemm g, const Sched& S, const Epi& E) {
;     ...
;         const char* nA = has_next ? (const char*)g.A + (size_t)nxt.pm * tstepA + (size_t)nxt.pn * apn : cA; const char* nB = has_next ? (const char*)g.Bt + (size_t)nxt.pn * tstepB : cB;
;         for (int t = 0; t < nt; t += 2) {
;             const bool last = (t == nt - 2);
;             const char* a1 = cA + (size_t)(t + 1) * kstep;
;             const char* a2 = last ? nA : cA + (size_t)(t + 2) * kstep; const char* b2 = last ? nB : cB + (size_t)(t + 2) * kstep;
;             const char* a3 = a2 + kstep; const char* b3 = b2 + kstep;
;             if (last && has_next) S.a_ready(nxt);
;             if constexpr (SP2) {
;             PG8_LDB(B0, 0, 0); PG8_LDB(B1, 0, 1); PG8_SCHED; PG8_LDA(At, 0, 0); PG8_STAGE(PG8_SA(1, 1), a1 + hstepA, voffA);
;             PG8_WAIT_V(8); PG8_WAIT_L(0); PG8_BAR; PG8_MMA(0, 0, At, B0); PG8_MMA(0, 1, At, B1); PG8_BAR; PG8_SCHED;
;             PG8_LDA(At, 0, 1); PG8_STAGE(PG8_SB(0, 0), b2, voffB); PG8_STAGE(PG8_SB(0, 1), b2 + hstepB, voffB); PG8_STAGE(PG8_SA(0, 0), a2, voffA);
;             PG8_WAIT_V(8); PG8_WAIT_L(0); PG8_BAR; PG8_MMA(1, 0, At, B0); PG8_MMA(1, 1, At, B1); PG8_BAR; PG8_SCHED;
.LBB0_849:
	s_ashr_i32 s41, s40, 31
	s_lshl_b64 s[22:23], s[40:41], 19
	s_add_u32 s42, s30, s22
	s_addc_u32 s43, s31, s23
	s_and_b64 s[22:23], s[4:5], exec
	s_cselect_b32 s7, s43, s1
	s_cselect_b32 s24, s42, s0
	s_ashr_i32 s37, s36, 31
	s_lshl_b64 s[22:23], s[36:37], 19
	v_readlane_b32 s26, v239, 36
	v_readlane_b32 s27, v239, 37
	s_add_u32 s46, s26, s22
	s_addc_u32 s47, s27, s23
	s_and_b64 s[22:23], s[4:5], exec
	s_cselect_b32 s25, s47, s21
	s_cselect_b32 s26, s46, s20
	s_add_u32 s0, s0, 0x40080
	s_addc_u32 s1, s1, 0
	s_add_u32 s27, s20, 0x100
	s_addc_u32 s28, s21, 0
	s_mov_b32 s29, -2
	s_waitcnt lgkmcnt(0)
	ds_read_b128 v[164:167], v159
	ds_read_b128 v[168:171], v159 offset:1024
	ds_read_b128 v[172:175], v159 offset:2048
	ds_read_b128 v[176:179], v159 offset:3072
	ds_read_b128 v[180:183], v160
	ds_read_b128 v[184:187], v160 offset:1024
	ds_read_b128 v[188:191], v160 offset:2048
	ds_read_b128 v[192:195], v160 offset:3072
	s_add_u32 s20, s0, 0xfffc0080
	s_addc_u32 s21, s1, -1
	s_cmp_eq_u32 s29, 12
	s_cselect_b32 s23, s7, s21
	s_cselect_b32 s22, s24, s20
	s_cselect_b32 s21, s25, s28
	s_cselect_b32 s20, s26, s27
	v_lshl_add_u64 v[148:149], s[0:1], 0, v[140:141]
	s_add_i32 m0, s35, 0xc000
	ds_read_b128 v[196:199], v161
	ds_read_b128 v[200:203], v161 offset:1024
	ds_read_b128 v[204:207], v161 offset:2048
	ds_read_b128 v[208:211], v161 offset:3072
	ds_read_b128 v[212:215], v161 offset:4096
	ds_read_b128 v[216:219], v161 offset:5120
	ds_read_b128 v[220:223], v161 offset:6144
	ds_read_b128 v[224:227], v161 offset:7168
	global_load_lds_dwordx4 v[148:149], off
	v_lshl_add_u64 v[148:149], s[0:1], 0, v[142:143]
	s_add_i32 m0, s35, 0xe000
	s_nop 0
	global_load_lds_dwordx4 v[148:149], off
	s_waitcnt vmcnt(8)
	s_waitcnt lgkmcnt(0)
	s_barrier
	s_waitcnt lgkmcnt(0)
	v_mfma_f32_16x16x32_bf16 v[124:127], v[164:167], v[196:199], 0
	v_mfma_f32_16x16x32_bf16 v[120:123], v[172:175], v[196:199], 0
	v_mfma_f32_16x16x32_bf16 v[108:111], v[164:167], v[204:207], 0
	v_mfma_f32_16x16x32_bf16 v[104:107], v[172:175], v[204:207], 0
	v_mfma_f32_16x16x32_bf16 v[92:95], v[164:167], v[212:215], 0
	v_mfma_f32_16x16x32_bf16 v[88:91], v[172:175], v[212:215], 0
	v_mfma_f32_16x16x32_bf16 v[76:79], v[164:167], v[220:223], 0
	v_mfma_f32_16x16x32_bf16 v[72:75], v[172:175], v[220:223], 0
	v_mfma_f32_16x16x32_bf16 v[124:127], v[168:171], v[200:203], v[124:127]
	v_mfma_f32_16x16x32_bf16 v[120:123], v[176:179], v[200:203], v[120:123]
	v_mfma_f32_16x16x32_bf16 v[108:111], v[168:171], v[208:211], v[108:111]
	v_mfma_f32_16x16x32_bf16 v[104:107], v[176:179], v[208:211], v[104:107]
	v_mfma_f32_16x16x32_bf16 v[92:95], v[168:171], v[216:219], v[92:95]
	v_mfma_f32_16x16x32_bf16 v[88:91], v[176:179], v[216:219], v[88:91]
	v_mfma_f32_16x16x32_bf16 v[76:79], v[168:171], v[224:227], v[76:79]
	v_mfma_f32_16x16x32_bf16 v[72:75], v[176:179], v[224:227], v[72:75]
	v_mfma_f32_16x16x32_bf16 v[116:119], v[180:183], v[196:199], 0
	v_mfma_f32_16x16x32_bf16 v[112:115], v[188:191], v[196:199], 0
	v_mfma_f32_16x16x32_bf16 v[100:103], v[180:183], v[204:207], 0
	v_mfma_f32_16x16x32_bf16 v[96:99], v[188:191], v[204:207], 0
	v_mfma_f32_16x16x32_bf16 v[84:87], v[180:183], v[212:215], 0
	v_mfma_f32_16x16x32_bf16 v[80:83], v[188:191], v[212:215], 0
	v_mfma_f32_16x16x32_bf16 v[68:71], v[180:183], v[220:223], 0
	v_mfma_f32_16x16x32_bf16 v[64:67], v[188:191], v[220:223], 0
	v_mfma_f32_16x16x32_bf16 v[116:119], v[184:187], v[200:203], v[116:119]
	v_mfma_f32_16x16x32_bf16 v[112:115], v[192:195], v[200:203], v[112:115]
	v_mfma_f32_16x16x32_bf16 v[100:103], v[184:187], v[208:211], v[100:103]
	v_mfma_f32_16x16x32_bf16 v[96:99], v[192:195], v[208:211], v[96:99]
	v_mfma_f32_16x16x32_bf16 v[84:87], v[184:187], v[216:219], v[84:87]
	v_mfma_f32_16x16x32_bf16 v[80:83], v[192:195], v[216:219], v[80:83]
	v_mfma_f32_16x16x32_bf16 v[68:71], v[184:187], v[224:227], v[68:71]
	v_mfma_f32_16x16x32_bf16 v[64:67], v[192:195], v[224:227], v[64:67]
	s_barrier
	s_add_i32 s30, s61, s34
	v_lshl_add_u64 v[148:149], s[20:21], 0, v[130:131]
	s_mov_b32 m0, s30
	ds_read_b128 v[196:199], v161 offset:16384
	ds_read_b128 v[200:203], v161 offset:17408
	ds_read_b128 v[204:207], v161 offset:18432
	ds_read_b128 v[208:211], v161 offset:19456
	ds_read_b128 v[212:215], v161 offset:20480
	ds_read_b128 v[216:219], v161 offset:21504
	ds_read_b128 v[220:223], v161 offset:22528
	ds_read_b128 v[224:227], v161 offset:23552
	global_load_lds_dwordx4 v[148:149], off
	s_add_i32 m0, s30, 0x2000
	s_add_u32 s30, s20, 0x10000
	v_lshl_add_u64 v[228:229], s[20:21], 0, v[134:135]
	s_addc_u32 s31, s21, 0
	s_add_i32 s37, s62, s34
	global_load_lds_dwordx4 v[228:229], off
	v_lshl_add_u64 v[230:231], s[30:31], 0, v[130:131]
	s_mov_b32 m0, s37
	v_lshl_add_u64 v[232:233], s[22:23], 0, v[132:133]
	global_load_lds_dwordx4 v[230:231], off
	v_lshl_add_u64 v[230:231], s[30:31], 0, v[134:135]
	s_add_i32 m0, s37, 0x2000
	s_nop 0
	global_load_lds_dwordx4 v[230:231], off
	v_lshl_add_u64 v[230:231], s[22:23], 0, v[128:129]
	s_mov_b32 m0, s35
	s_nop 0
	global_load_lds_dwordx4 v[230:231], off
	s_mov_b32 m0, s49
	s_nop 0
	global_load_lds_dwordx4 v[232:233], off
	s_waitcnt vmcnt(8)
	s_waitcnt lgkmcnt(0)
	s_barrier
; #define PG8_STAGE(bufoff, gbase, voff) do { _Pragma("unroll") for (int _i = 0; _i < 2; ++_i) \
;         __builtin_amdgcn_global_load_lds((const unsigned*)((const char*)(gbase) + (voff)[_i]), (PG8_LAS unsigned*)(lds + (bufoff) + ldsw + _i * 8192), 16, 0, PG8_LOAD_AUX); } while (0)
; #define PG8_LDA(dst, b, h) do { _Pragma("unroll") for (int m = 0; m < 4; ++m) _Pragma("unroll") for (int k = 0; k < 2; ++k) dst[m][k] = *(const PG8_LAS bf16x8*)(lds + PG8_SA(b, h) + aoff + m * 2048 + k * 1024); } while (0)
; #define PG8_LDB(dst, b, h) do { _Pragma("unroll") for (int n = 0; n < 2; ++n) _Pragma("unroll") for (int k = 0; k < 2; ++k) dst[n][k] = *(const PG8_LAS bf16x8*)(lds + PG8_SB(b, h) + boff + n * 2048 + k * 1024); } while (0)
; #define PG8_MMA(ai, bj, At, Bt) do { __builtin_amdgcn_s_setprio(1); _Pragma("unroll") for (int m = 0; m < 4; ++m) _Pragma("unroll") for (int n = 0; n < 2; ++n) _Pragma("unroll") for (int k = 0; k < 2; ++k) \
;         acc[ai][bj][m][n] = __builtin_amdgcn_mfma_f32_16x16x32_bf16(Bt[n][k], At[m][k], acc[ai][bj][m][n], 0, 0, 0); __builtin_amdgcn_s_setprio(0); } while (0)
; #define PG8_WAIT_V(n) asm volatile("s_waitcnt vmcnt(" #n ")" ::: "memory")
; #define PG8_WAIT_L(n) asm volatile("s_waitcnt lgkmcnt(" #n ")" ::: "memory")
; #define PG8_BAR __builtin_amdgcn_s_barrier()
; #define PG8_SCHED __builtin_amdgcn_sched_barrier(0)
; template <class Epi, class Sched, bool ALIGN_EPI = false, bool SP2 = false>
; __device__ __forceinline__ void gemm_phase(PG8_LAS unsigned char* lds, const Gemm g, const Sched& S, const Epi& E) {
;     ...
;             PG8_LDB(B0, 0, 0); PG8_LDB(B1, 0, 1); PG8_SCHED; PG8_LDA(At, 0, 0); PG8_STAGE(PG8_SA(1, 1), a1 + hstepA, voffA);
;             PG8_WAIT_V(8); PG8_WAIT_L(0); PG8_BAR; PG8_MMA(0, 0, At, B0); PG8_MMA(0, 1, At, B1); PG8_BAR; PG8_SCHED;
;             PG8_LDA(At, 0, 1); PG8_STAGE(PG8_SB(0, 0), b2, voffB); PG8_STAGE(PG8_SB(0, 1), b2 + hstepB, voffB); PG8_STAGE(PG8_SA(0, 0), a2, voffA);
;             PG8_WAIT_V(8); PG8_WAIT_L(0); PG8_BAR; PG8_MMA(1, 0, At, B0); PG8_MMA(1, 1, At, B1); PG8_BAR; PG8_SCHED;
	s_waitcnt lgkmcnt(0)
	v_mfma_f32_16x16x32_bf16 v[60:63], v[164:167], v[196:199], 0
	v_mfma_f32_16x16x32_bf16 v[56:59], v[172:175], v[196:199], 0
	v_mfma_f32_16x16x32_bf16 v[44:47], v[164:167], v[204:207], 0
	v_mfma_f32_16x16x32_bf16 v[40:43], v[172:175], v[204:207], 0
	v_mfma_f32_16x16x32_bf16 v[28:31], v[164:167], v[212:215], 0
	v_mfma_f32_16x16x32_bf16 v[24:27], v[172:175], v[212:215], 0
	v_mfma_f32_16x16x32_bf16 v[12:15], v[164:167], v[220:223], 0
	v_mfma_f32_16x16x32_bf16 v[8:11], v[172:175], v[220:223], 0
	v_mfma_f32_16x16x32_bf16 v[60:63], v[168:171], v[200:203], v[60:63]
	v_mfma_f32_16x16x32_bf16 v[56:59], v[176:179], v[200:203], v[56:59]
	v_mfma_f32_16x16x32_bf16 v[44:47], v[168:171], v[208:211], v[44:47]
	v_mfma_f32_16x16x32_bf16 v[40:43], v[176:179], v[208:211], v[40:43]
	v_mfma_f32_16x16x32_bf16 v[28:31], v[168:171], v[216:219], v[28:31]
	v_mfma_f32_16x16x32_bf16 v[24:27], v[176:179], v[216:219], v[24:27]
	v_mfma_f32_16x16x32_bf16 v[12:15], v[168:171], v[224:227], v[12:15]
	v_mfma_f32_16x16x32_bf16 v[8:11], v[176:179], v[224:227], v[8:11]
	v_mfma_f32_16x16x32_bf16 v[52:55], v[180:183], v[196:199], 0
	v_mfma_f32_16x16x32_bf16 v[48:51], v[188:191], v[196:199], 0
	v_mfma_f32_16x16x32_bf16 v[36:39], v[180:183], v[204:207], 0
	v_mfma_f32_16x16x32_bf16 v[32:35], v[188:191], v[204:207], 0
	v_mfma_f32_16x16x32_bf16 v[20:23], v[180:183], v[212:215], 0
	v_mfma_f32_16x16x32_bf16 v[16:19], v[188:191], v[212:215], 0
	v_mfma_f32_16x16x32_bf16 v[4:7], v[180:183], v[220:223], 0
	v_mfma_f32_16x16x32_bf16 v[0:3], v[188:191], v[220:223], 0
	v_mfma_f32_16x16x32_bf16 v[52:55], v[184:187], v[200:203], v[52:55]
	v_mfma_f32_16x16x32_bf16 v[48:51], v[192:195], v[200:203], v[48:51]
	v_mfma_f32_16x16x32_bf16 v[36:39], v[184:187], v[208:211], v[36:39]
	v_mfma_f32_16x16x32_bf16 v[32:35], v[192:195], v[208:211], v[32:35]
	v_mfma_f32_16x16x32_bf16 v[20:23], v[184:187], v[216:219], v[20:23]
	v_mfma_f32_16x16x32_bf16 v[16:19], v[192:195], v[216:219], v[16:19]
	v_mfma_f32_16x16x32_bf16 v[4:7], v[184:187], v[224:227], v[4:7]
	v_mfma_f32_16x16x32_bf16 v[0:3], v[192:195], v[224:227], v[0:3]
	s_barrier
	s_branch .Lkmid_P9
.LBB0_850:
	ds_read_b128 v[164:167], v159
	ds_read_b128 v[168:171], v159 offset:1024
	ds_read_b128 v[172:175], v159 offset:2048
	ds_read_b128 v[176:179], v159 offset:3072
	ds_read_b128 v[180:183], v160
	ds_read_b128 v[184:187], v160 offset:1024
	ds_read_b128 v[188:191], v160 offset:2048
	ds_read_b128 v[192:195], v160 offset:3072
	s_add_u32 s20, s0, 0xfffc0080
	s_addc_u32 s21, s1, -1
	s_cmp_eq_u32 s29, 12
	s_cselect_b32 s23, s7, s21
	s_cselect_b32 s22, s24, s20
	s_cselect_b32 s21, s25, s28
	s_cselect_b32 s20, s26, s27
	v_lshl_add_u64 v[148:149], s[0:1], 0, v[140:141]
	s_add_i32 m0, s35, 0xc000
	ds_read_b128 v[196:199], v161
	ds_read_b128 v[200:203], v161 offset:1024
	ds_read_b128 v[204:207], v161 offset:2048
	ds_read_b128 v[208:211], v161 offset:3072
	ds_read_b128 v[212:215], v161 offset:4096
	ds_read_b128 v[216:219], v161 offset:5120
	ds_read_b128 v[220:223], v161 offset:6144
	ds_read_b128 v[224:227], v161 offset:7168
	global_load_lds_dwordx4 v[148:149], off
	v_lshl_add_u64 v[148:149], s[0:1], 0, v[142:143]
	s_add_i32 m0, s35, 0xe000
	s_nop 0
	global_load_lds_dwordx4 v[148:149], off
	s_waitcnt vmcnt(8)
	s_waitcnt lgkmcnt(0)
	s_barrier
	s_waitcnt lgkmcnt(0)
	v_mfma_f32_16x16x32_bf16 v[124:127], v[164:167], v[196:199], v[124:127]
	v_mfma_f32_16x16x32_bf16 v[120:123], v[172:175], v[196:199], v[120:123]
	v_mfma_f32_16x16x32_bf16 v[108:111], v[164:167], v[204:207], v[108:111]
	v_mfma_f32_16x16x32_bf16 v[104:107], v[172:175], v[204:207], v[104:107]
	v_mfma_f32_16x16x32_bf16 v[92:95], v[164:167], v[212:215], v[92:95]
	v_mfma_f32_16x16x32_bf16 v[88:91], v[172:175], v[212:215], v[88:91]
	v_mfma_f32_16x16x32_bf16 v[76:79], v[164:167], v[220:223], v[76:79]
	v_mfma_f32_16x16x32_bf16 v[72:75], v[172:175], v[220:223], v[72:75]
	v_mfma_f32_16x16x32_bf16 v[124:127], v[168:171], v[200:203], v[124:127]
	v_mfma_f32_16x16x32_bf16 v[120:123], v[176:179], v[200:203], v[120:123]
	v_mfma_f32_16x16x32_bf16 v[108:111], v[168:171], v[208:211], v[108:111]
	v_mfma_f32_16x16x32_bf16 v[104:107], v[176:179], v[208:211], v[104:107]
	v_mfma_f32_16x16x32_bf16 v[92:95], v[168:171], v[216:219], v[92:95]
	v_mfma_f32_16x16x32_bf16 v[88:91], v[176:179], v[216:219], v[88:91]
	v_mfma_f32_16x16x32_bf16 v[76:79], v[168:171], v[224:227], v[76:79]
	v_mfma_f32_16x16x32_bf16 v[72:75], v[176:179], v[224:227], v[72:75]
	v_mfma_f32_16x16x32_bf16 v[116:119], v[180:183], v[196:199], v[116:119]
	v_mfma_f32_16x16x32_bf16 v[112:115], v[188:191], v[196:199], v[112:115]
	v_mfma_f32_16x16x32_bf16 v[100:103], v[180:183], v[204:207], v[100:103]
	v_mfma_f32_16x16x32_bf16 v[96:99], v[188:191], v[204:207], v[96:99]
	v_mfma_f32_16x16x32_bf16 v[84:87], v[180:183], v[212:215], v[84:87]
	v_mfma_f32_16x16x32_bf16 v[80:83], v[188:191], v[212:215], v[80:83]
	v_mfma_f32_16x16x32_bf16 v[68:71], v[180:183], v[220:223], v[68:71]
	v_mfma_f32_16x16x32_bf16 v[64:67], v[188:191], v[220:223], v[64:67]
	v_mfma_f32_16x16x32_bf16 v[116:119], v[184:187], v[200:203], v[116:119]
	v_mfma_f32_16x16x32_bf16 v[112:115], v[192:195], v[200:203], v[112:115]
	v_mfma_f32_16x16x32_bf16 v[100:103], v[184:187], v[208:211], v[100:103]
	v_mfma_f32_16x16x32_bf16 v[96:99], v[192:195], v[208:211], v[96:99]
	v_mfma_f32_16x16x32_bf16 v[84:87], v[184:187], v[216:219], v[84:87]
	v_mfma_f32_16x16x32_bf16 v[80:83], v[192:195], v[216:219], v[80:83]
	v_mfma_f32_16x16x32_bf16 v[68:71], v[184:187], v[224:227], v[68:71]
	v_mfma_f32_16x16x32_bf16 v[64:67], v[192:195], v[224:227], v[64:67]
	s_barrier
; #define PG8_STAGE(bufoff, gbase, voff) do { _Pragma("unroll") for (int _i = 0; _i < 2; ++_i) \
;         __builtin_amdgcn_global_load_lds((const unsigned*)((const char*)(gbase) + (voff)[_i]), (PG8_LAS unsigned*)(lds + (bufoff) + ldsw + _i * 8192), 16, 0, PG8_LOAD_AUX); } while (0)
; #define PG8_LDA(dst, b, h) do { _Pragma("unroll") for (int m = 0; m < 4; ++m) _Pragma("unroll") for (int k = 0; k < 2; ++k) dst[m][k] = *(const PG8_LAS bf16x8*)(lds + PG8_SA(b, h) + aoff + m * 2048 + k * 1024); } while (0)
; #define PG8_LDB(dst, b, h) do { _Pragma("unroll") for (int n = 0; n < 2; ++n) _Pragma("unroll") for (int k = 0; k < 2; ++k) dst[n][k] = *(const PG8_LAS bf16x8*)(lds + PG8_SB(b, h) + boff + n * 2048 + k * 1024); } while (0)
; #define PG8_MMA(ai, bj, At, Bt) do { __builtin_amdgcn_s_setprio(1); _Pragma("unroll") for (int m = 0; m < 4; ++m) _Pragma("unroll") for (int n = 0; n < 2; ++n) _Pragma("unroll") for (int k = 0; k < 2; ++k) \
;         acc[ai][bj][m][n] = __builtin_amdgcn_mfma_f32_16x16x32_bf16(Bt[n][k], At[m][k], acc[ai][bj][m][n], 0, 0, 0); __builtin_amdgcn_s_setprio(0); } while (0)
; #define PG8_WAIT_V(n) asm volatile("s_waitcnt vmcnt(" #n ")" ::: "memory")
; #define PG8_WAIT_L(n) asm volatile("s_waitcnt lgkmcnt(" #n ")" ::: "memory")
; #define PG8_BAR __builtin_amdgcn_s_barrier()
; #define PG8_SCHED __builtin_amdgcn_sched_barrier(0)
; template <class Epi, class Sched, bool ALIGN_EPI = false, bool SP2 = false>
; __device__ __forceinline__ void gemm_phase(PG8_LAS unsigned char* lds, const Gemm g, const Sched& S, const Epi& E) {
;     ...
;             PG8_LDA(At, 0, 1); PG8_STAGE(PG8_SB(0, 0), b2, voffB); PG8_STAGE(PG8_SB(0, 1), b2 + hstepB, voffB); PG8_STAGE(PG8_SA(0, 0), a2, voffA);
;             PG8_WAIT_V(8); PG8_WAIT_L(0); PG8_BAR; PG8_MMA(1, 0, At, B0); PG8_MMA(1, 1, At, B1); PG8_BAR; PG8_SCHED;
;             PG8_LDB(B0, 1, 0); PG8_LDB(B1, 1, 1); PG8_SCHED; PG8_LDA(At, 1, 0); PG8_STAGE(PG8_SA(0, 1), a2 + hstepA, voffA);
;             PG8_WAIT_V(8); PG8_WAIT_L(0); PG8_BAR; PG8_MMA(0, 0, At, B0); PG8_MMA(0, 1, At, B1); PG8_BAR; PG8_SCHED;
	s_add_i32 s30, s61, s34
	v_lshl_add_u64 v[148:149], s[20:21], 0, v[130:131]
	s_mov_b32 m0, s30
	ds_read_b128 v[196:199], v161 offset:16384
	ds_read_b128 v[200:203], v161 offset:17408
	ds_read_b128 v[204:207], v161 offset:18432
	ds_read_b128 v[208:211], v161 offset:19456
	ds_read_b128 v[212:215], v161 offset:20480
	ds_read_b128 v[216:219], v161 offset:21504
	ds_read_b128 v[220:223], v161 offset:22528
	ds_read_b128 v[224:227], v161 offset:23552
	global_load_lds_dwordx4 v[148:149], off
	s_add_i32 m0, s30, 0x2000
	s_add_u32 s30, s20, 0x10000
	v_lshl_add_u64 v[228:229], s[20:21], 0, v[134:135]
	s_addc_u32 s31, s21, 0
	s_add_i32 s37, s62, s34
	global_load_lds_dwordx4 v[228:229], off
	v_lshl_add_u64 v[230:231], s[30:31], 0, v[130:131]
	s_mov_b32 m0, s37
	v_lshl_add_u64 v[232:233], s[22:23], 0, v[132:133]
	global_load_lds_dwordx4 v[230:231], off
	v_lshl_add_u64 v[230:231], s[30:31], 0, v[134:135]
	s_add_i32 m0, s37, 0x2000
	s_nop 0
	global_load_lds_dwordx4 v[230:231], off
	v_lshl_add_u64 v[230:231], s[22:23], 0, v[128:129]
	s_mov_b32 m0, s35
	s_nop 0
	global_load_lds_dwordx4 v[230:231], off
	s_mov_b32 m0, s49
	s_nop 0
	global_load_lds_dwordx4 v[232:233], off
	s_waitcnt vmcnt(8)
	s_waitcnt lgkmcnt(0)
	s_barrier
	s_waitcnt lgkmcnt(0)
	v_mfma_f32_16x16x32_bf16 v[60:63], v[164:167], v[196:199], v[60:63]
	v_mfma_f32_16x16x32_bf16 v[56:59], v[172:175], v[196:199], v[56:59]
	v_mfma_f32_16x16x32_bf16 v[44:47], v[164:167], v[204:207], v[44:47]
	v_mfma_f32_16x16x32_bf16 v[40:43], v[172:175], v[204:207], v[40:43]
	v_mfma_f32_16x16x32_bf16 v[28:31], v[164:167], v[212:215], v[28:31]
	v_mfma_f32_16x16x32_bf16 v[24:27], v[172:175], v[212:215], v[24:27]
	v_mfma_f32_16x16x32_bf16 v[12:15], v[164:167], v[220:223], v[12:15]
	v_mfma_f32_16x16x32_bf16 v[8:11], v[172:175], v[220:223], v[8:11]
	v_mfma_f32_16x16x32_bf16 v[60:63], v[168:171], v[200:203], v[60:63]
	v_mfma_f32_16x16x32_bf16 v[56:59], v[176:179], v[200:203], v[56:59]
	v_mfma_f32_16x16x32_bf16 v[44:47], v[168:171], v[208:211], v[44:47]
	v_mfma_f32_16x16x32_bf16 v[40:43], v[176:179], v[208:211], v[40:43]
	v_mfma_f32_16x16x32_bf16 v[28:31], v[168:171], v[216:219], v[28:31]
	v_mfma_f32_16x16x32_bf16 v[24:27], v[176:179], v[216:219], v[24:27]
	v_mfma_f32_16x16x32_bf16 v[12:15], v[168:171], v[224:227], v[12:15]
	v_mfma_f32_16x16x32_bf16 v[8:11], v[176:179], v[224:227], v[8:11]
	v_mfma_f32_16x16x32_bf16 v[52:55], v[180:183], v[196:199], v[52:55]
	v_mfma_f32_16x16x32_bf16 v[48:51], v[188:191], v[196:199], v[48:51]
	v_mfma_f32_16x16x32_bf16 v[36:39], v[180:183], v[204:207], v[36:39]
	v_mfma_f32_16x16x32_bf16 v[32:35], v[188:191], v[204:207], v[32:35]
	v_mfma_f32_16x16x32_bf16 v[20:23], v[180:183], v[212:215], v[20:23]
	v_mfma_f32_16x16x32_bf16 v[16:19], v[188:191], v[212:215], v[16:19]
	v_mfma_f32_16x16x32_bf16 v[4:7], v[180:183], v[220:223], v[4:7]
	v_mfma_f32_16x16x32_bf16 v[0:3], v[188:191], v[220:223], v[0:3]
	v_mfma_f32_16x16x32_bf16 v[52:55], v[184:187], v[200:203], v[52:55]
	v_mfma_f32_16x16x32_bf16 v[48:51], v[192:195], v[200:203], v[48:51]
	v_mfma_f32_16x16x32_bf16 v[36:39], v[184:187], v[208:211], v[36:39]
	v_mfma_f32_16x16x32_bf16 v[32:35], v[192:195], v[208:211], v[32:35]
	v_mfma_f32_16x16x32_bf16 v[20:23], v[184:187], v[216:219], v[20:23]
	v_mfma_f32_16x16x32_bf16 v[16:19], v[192:195], v[216:219], v[16:19]
	v_mfma_f32_16x16x32_bf16 v[4:7], v[184:187], v[224:227], v[4:7]
	v_mfma_f32_16x16x32_bf16 v[0:3], v[192:195], v[224:227], v[0:3]
	s_barrier
.Lkmid_P9:
	s_add_i32 s30, 0, 0x18000
	v_add_u32_e32 v150, s30, v157
	s_add_i32 s31, 0, 0x1c000
	ds_read_b128 v[164:167], v150
	ds_read_b128 v[168:171], v150 offset:1024
	ds_read_b128 v[172:175], v150 offset:2048
	ds_read_b128 v[176:179], v150 offset:3072
	v_add_u32_e32 v150, s31, v157
	ds_read_b128 v[180:183], v150
	ds_read_b128 v[184:187], v150 offset:1024
	ds_read_b128 v[188:191], v150 offset:2048
	ds_read_b128 v[192:195], v150 offset:3072
	s_add_u32 s22, s22, 0x40000
	s_addc_u32 s23, s23, 0
	s_mov_b32 m0, s50
	v_lshl_add_u64 v[234:235], s[22:23], 0, v[128:129]
	ds_read_b128 v[196:199], v161 offset:32768
	ds_read_b128 v[200:203], v161 offset:33792
	ds_read_b128 v[204:207], v161 offset:34816
	ds_read_b128 v[208:211], v161 offset:35840
	ds_read_b128 v[212:215], v161 offset:36864
	ds_read_b128 v[216:219], v161 offset:37888
	ds_read_b128 v[220:223], v161 offset:38912
	ds_read_b128 v[224:227], v161 offset:39936
	global_load_lds_dwordx4 v[234:235], off
	v_lshl_add_u64 v[234:235], s[22:23], 0, v[132:133]
	s_mov_b32 m0, s51
	s_nop 0
	global_load_lds_dwordx4 v[234:235], off
	s_waitcnt vmcnt(8)
	s_waitcnt lgkmcnt(0)
	s_barrier
; #define PG8_STAGE(bufoff, gbase, voff) do { _Pragma("unroll") for (int _i = 0; _i < 2; ++_i) \
;         __builtin_amdgcn_global_load_lds((const unsigned*)((const char*)(gbase) + (voff)[_i]), (PG8_LAS unsigned*)(lds + (bufoff) + ldsw + _i * 8192), 16, 0, PG8_LOAD_AUX); } while (0)
; #define PG8_LDA(dst, b, h) do { _Pragma("unroll") for (int m = 0; m < 4; ++m) _Pragma("unroll") for (int k = 0; k < 2; ++k) dst[m][k] = *(const PG8_LAS bf16x8*)(lds + PG8_SA(b, h) + aoff + m * 2048 + k * 1024); } while (0)
; #define PG8_LDB(dst, b, h) do { _Pragma("unroll") for (int n = 0; n < 2; ++n) _Pragma("unroll") for (int k = 0; k < 2; ++k) dst[n][k] = *(const PG8_LAS bf16x8*)(lds + PG8_SB(b, h) + boff + n * 2048 + k * 1024); } while (0)
; #define PG8_MMA(ai, bj, At, Bt) do { __builtin_amdgcn_s_setprio(1); _Pragma("unroll") for (int m = 0; m < 4; ++m) _Pragma("unroll") for (int n = 0; n < 2; ++n) _Pragma("unroll") for (int k = 0; k < 2; ++k) \
;         acc[ai][bj][m][n] = __builtin_amdgcn_mfma_f32_16x16x32_bf16(Bt[n][k], At[m][k], acc[ai][bj][m][n], 0, 0, 0); __builtin_amdgcn_s_setprio(0); } while (0)
; #define PG8_WAIT_V(n) asm volatile("s_waitcnt vmcnt(" #n ")" ::: "memory")
; #define PG8_WAIT_L(n) asm volatile("s_waitcnt lgkmcnt(" #n ")" ::: "memory")
; #define PG8_BAR __builtin_amdgcn_s_barrier()
; #define PG8_SCHED __builtin_amdgcn_sched_barrier(0)
; template <class Epi, class Sched, bool ALIGN_EPI = false, bool SP2 = false>
; __device__ __forceinline__ void gemm_phase(PG8_LAS unsigned char* lds, const Gemm g, const Sched& S, const Epi& E) {
;     ...
;             PG8_LDB(B0, 1, 0); PG8_LDB(B1, 1, 1); PG8_SCHED; PG8_LDA(At, 1, 0); PG8_STAGE(PG8_SA(0, 1), a2 + hstepA, voffA);
;             PG8_WAIT_V(8); PG8_WAIT_L(0); PG8_BAR; PG8_MMA(0, 0, At, B0); PG8_MMA(0, 1, At, B1); PG8_BAR; PG8_SCHED;
;             PG8_LDA(At, 1, 1); PG8_STAGE(PG8_SB(1, 0), b3, voffB); PG8_STAGE(PG8_SB(1, 1), b3 + hstepB, voffB); PG8_STAGE(PG8_SA(1, 0), a3, voffA);
;             PG8_WAIT_V(8); PG8_WAIT_L(0); PG8_BAR; PG8_MMA(1, 0, At, B0); PG8_MMA(1, 1, At, B1); PG8_BAR; PG8_SCHED;
	s_waitcnt lgkmcnt(0)
	v_mfma_f32_16x16x32_bf16 v[124:127], v[164:167], v[196:199], v[124:127]
	v_mfma_f32_16x16x32_bf16 v[120:123], v[172:175], v[196:199], v[120:123]
	v_mfma_f32_16x16x32_bf16 v[108:111], v[164:167], v[204:207], v[108:111]
	v_mfma_f32_16x16x32_bf16 v[104:107], v[172:175], v[204:207], v[104:107]
	v_mfma_f32_16x16x32_bf16 v[92:95], v[164:167], v[212:215], v[92:95]
	v_mfma_f32_16x16x32_bf16 v[88:91], v[172:175], v[212:215], v[88:91]
	v_mfma_f32_16x16x32_bf16 v[76:79], v[164:167], v[220:223], v[76:79]
	v_mfma_f32_16x16x32_bf16 v[72:75], v[172:175], v[220:223], v[72:75]
	v_mfma_f32_16x16x32_bf16 v[124:127], v[168:171], v[200:203], v[124:127]
	v_mfma_f32_16x16x32_bf16 v[120:123], v[176:179], v[200:203], v[120:123]
	v_mfma_f32_16x16x32_bf16 v[108:111], v[168:171], v[208:211], v[108:111]
	v_mfma_f32_16x16x32_bf16 v[104:107], v[176:179], v[208:211], v[104:107]
	v_mfma_f32_16x16x32_bf16 v[92:95], v[168:171], v[216:219], v[92:95]
	v_mfma_f32_16x16x32_bf16 v[88:91], v[176:179], v[216:219], v[88:91]
	v_mfma_f32_16x16x32_bf16 v[76:79], v[168:171], v[224:227], v[76:79]
	v_mfma_f32_16x16x32_bf16 v[72:75], v[176:179], v[224:227], v[72:75]
	v_mfma_f32_16x16x32_bf16 v[116:119], v[180:183], v[196:199], v[116:119]
	v_mfma_f32_16x16x32_bf16 v[112:115], v[188:191], v[196:199], v[112:115]
	v_mfma_f32_16x16x32_bf16 v[100:103], v[180:183], v[204:207], v[100:103]
	v_mfma_f32_16x16x32_bf16 v[96:99], v[188:191], v[204:207], v[96:99]
	v_mfma_f32_16x16x32_bf16 v[84:87], v[180:183], v[212:215], v[84:87]
	v_mfma_f32_16x16x32_bf16 v[80:83], v[188:191], v[212:215], v[80:83]
	v_mfma_f32_16x16x32_bf16 v[68:71], v[180:183], v[220:223], v[68:71]
	v_mfma_f32_16x16x32_bf16 v[64:67], v[188:191], v[220:223], v[64:67]
	v_mfma_f32_16x16x32_bf16 v[116:119], v[184:187], v[200:203], v[116:119]
	v_mfma_f32_16x16x32_bf16 v[112:115], v[192:195], v[200:203], v[112:115]
	v_mfma_f32_16x16x32_bf16 v[100:103], v[184:187], v[208:211], v[100:103]
	v_mfma_f32_16x16x32_bf16 v[96:99], v[192:195], v[208:211], v[96:99]
	v_mfma_f32_16x16x32_bf16 v[84:87], v[184:187], v[216:219], v[84:87]
	v_mfma_f32_16x16x32_bf16 v[80:83], v[192:195], v[216:219], v[80:83]
	v_mfma_f32_16x16x32_bf16 v[68:71], v[184:187], v[224:227], v[68:71]
	v_mfma_f32_16x16x32_bf16 v[64:67], v[192:195], v[224:227], v[64:67]
	s_barrier
	s_add_i32 s22, s30, s34
	v_lshl_add_u64 v[148:149], v[148:149], 0, s[16:17]
	s_mov_b32 m0, s22
	ds_read_b128 v[196:199], v161 offset:49152
	ds_read_b128 v[200:203], v161 offset:50176
	ds_read_b128 v[204:207], v161 offset:51200
	ds_read_b128 v[208:211], v161 offset:52224
	ds_read_b128 v[212:215], v161 offset:53248
	ds_read_b128 v[216:219], v161 offset:54272
	ds_read_b128 v[220:223], v161 offset:55296
	ds_read_b128 v[224:227], v161 offset:56320
	global_load_lds_dwordx4 v[148:149], off
	s_add_i32 m0, s22, 0x2000
	s_add_u32 s20, s20, 0x10080
	v_lshl_add_u64 v[148:149], v[228:229], 0, s[16:17]
	s_addc_u32 s21, s21, 0
	s_add_i32 s22, s31, s34
	global_load_lds_dwordx4 v[148:149], off
	v_lshl_add_u64 v[148:149], s[20:21], 0, v[130:131]
	s_mov_b32 m0, s22
	s_nop 0
	global_load_lds_dwordx4 v[148:149], off
	v_lshl_add_u64 v[148:149], s[20:21], 0, v[134:135]
	s_add_i32 m0, s22, 0x2000
	s_nop 0
	global_load_lds_dwordx4 v[148:149], off
	v_lshl_add_u64 v[148:149], v[230:231], 0, s[16:17]
	s_mov_b32 m0, s56
	s_nop 0
	global_load_lds_dwordx4 v[148:149], off
	v_lshl_add_u64 v[148:149], v[232:233], 0, s[16:17]
	s_mov_b32 m0, s57
	s_nop 0
	global_load_lds_dwordx4 v[148:149], off
	s_waitcnt vmcnt(8)
	s_waitcnt lgkmcnt(0)
	s_barrier
	s_waitcnt lgkmcnt(0)
	v_mfma_f32_16x16x32_bf16 v[60:63], v[164:167], v[196:199], v[60:63]
	v_mfma_f32_16x16x32_bf16 v[56:59], v[172:175], v[196:199], v[56:59]
	v_mfma_f32_16x16x32_bf16 v[44:47], v[164:167], v[204:207], v[44:47]
	v_mfma_f32_16x16x32_bf16 v[40:43], v[172:175], v[204:207], v[40:43]
	v_mfma_f32_16x16x32_bf16 v[28:31], v[164:167], v[212:215], v[28:31]
	v_mfma_f32_16x16x32_bf16 v[24:27], v[172:175], v[212:215], v[24:27]
	v_mfma_f32_16x16x32_bf16 v[12:15], v[164:167], v[220:223], v[12:15]
	v_mfma_f32_16x16x32_bf16 v[8:11], v[172:175], v[220:223], v[8:11]
	v_mfma_f32_16x16x32_bf16 v[60:63], v[168:171], v[200:203], v[60:63]
	v_mfma_f32_16x16x32_bf16 v[56:59], v[176:179], v[200:203], v[56:59]
	v_mfma_f32_16x16x32_bf16 v[44:47], v[168:171], v[208:211], v[44:47]
	v_mfma_f32_16x16x32_bf16 v[40:43], v[176:179], v[208:211], v[40:43]
	v_mfma_f32_16x16x32_bf16 v[28:31], v[168:171], v[216:219], v[28:31]
	v_mfma_f32_16x16x32_bf16 v[24:27], v[176:179], v[216:219], v[24:27]
	v_mfma_f32_16x16x32_bf16 v[12:15], v[168:171], v[224:227], v[12:15]
	v_mfma_f32_16x16x32_bf16 v[8:11], v[176:179], v[224:227], v[8:11]
	v_mfma_f32_16x16x32_bf16 v[52:55], v[180:183], v[196:199], v[52:55]
	v_mfma_f32_16x16x32_bf16 v[48:51], v[188:191], v[196:199], v[48:51]
	v_mfma_f32_16x16x32_bf16 v[36:39], v[180:183], v[204:207], v[36:39]
	v_mfma_f32_16x16x32_bf16 v[32:35], v[188:191], v[204:207], v[32:35]
	v_mfma_f32_16x16x32_bf16 v[20:23], v[180:183], v[212:215], v[20:23]
	v_mfma_f32_16x16x32_bf16 v[16:19], v[188:191], v[212:215], v[16:19]
	v_mfma_f32_16x16x32_bf16 v[4:7], v[180:183], v[220:223], v[4:7]
	v_mfma_f32_16x16x32_bf16 v[0:3], v[188:191], v[220:223], v[0:3]
	v_mfma_f32_16x16x32_bf16 v[52:55], v[184:187], v[200:203], v[52:55]
	v_mfma_f32_16x16x32_bf16 v[48:51], v[192:195], v[200:203], v[48:51]
	v_mfma_f32_16x16x32_bf16 v[36:39], v[184:187], v[208:211], v[36:39]
	v_mfma_f32_16x16x32_bf16 v[32:35], v[192:195], v[208:211], v[32:35]
	v_mfma_f32_16x16x32_bf16 v[20:23], v[184:187], v[216:219], v[20:23]
	v_mfma_f32_16x16x32_bf16 v[16:19], v[192:195], v[216:219], v[16:19]
	v_mfma_f32_16x16x32_bf16 v[4:7], v[184:187], v[224:227], v[4:7]
	v_mfma_f32_16x16x32_bf16 v[0:3], v[192:195], v[224:227], v[0:3]
	s_barrier
	s_add_i32 s29, s29, 2
	s_add_u32 s0, s0, 0x100
	s_addc_u32 s1, s1, 0
	s_add_u32 s27, s27, 0x100
	s_addc_u32 s28, s28, 0
	s_cmp_gt_u32 s29, 13
	s_cbranch_scc0 .LBB0_850
	s_and_b64 vcc, exec, s[18:19]
	s_cbranch_vccz .LBB0_853
	s_barrier

; #define PG8_STAGE(bufoff, gbase, voff) do { _Pragma("unroll") for (int _i = 0; _i < 2; ++_i) \
;         __builtin_amdgcn_global_load_lds((const unsigned*)((const char*)(gbase) + (voff)[_i]), (PG8_LAS unsigned*)(lds + (bufoff) + ldsw + _i * 8192), 16, 0, PG8_LOAD_AUX); } while (0)
; #define PG8_LDA(dst, b, h) do { _Pragma("unroll") for (int m = 0; m < 4; ++m) _Pragma("unroll") for (int k = 0; k < 2; ++k) dst[m][k] = *(const PG8_LAS bf16x8*)(lds + PG8_SA(b, h) + aoff + m * 2048 + k * 1024); } while (0)
; #define PG8_LDB(dst, b, h) do { _Pragma("unroll") for (int n = 0; n < 2; ++n) _Pragma("unroll") for (int k = 0; k < 2; ++k) dst[n][k] = *(const PG8_LAS bf16x8*)(lds + PG8_SB(b, h) + boff + n * 2048 + k * 1024); } while (0)
; #define PG8_WAIT_V(n) asm volatile("s_waitcnt vmcnt(" #n ")" ::: "memory")
; #define PG8_WAIT_L(n) asm volatile("s_waitcnt lgkmcnt(" #n ")" ::: "memory")
; #define PG8_BAR __builtin_amdgcn_s_barrier()
; #define PG8_SCHED __builtin_amdgcn_sched_barrier(0)
; template <class Epi, class Sched, bool ALIGN_EPI = false, bool SP2 = false>
; __device__ __forceinline__ void gemm_phase(PG8_LAS unsigned char* lds, const Gemm g, const Sched& S, const Epi& E) {
;     ...
;         const bool has_next = S.next(ui + 1, nxt);
;         const char* nA = has_next ? (const char*)g.A + (size_t)nxt.pm * tstepA + (size_t)nxt.pn * apn : cA; const char* nB = has_next ? (const char*)g.Bt + (size_t)nxt.pn * tstepB : cB;
;         for (int t = 0; t < nt; t += 2) {
;             const bool last = (t == nt - 2);
;             const char* a1 = cA + (size_t)(t + 1) * kstep;
;             const char* a2 = last ? nA : cA + (size_t)(t + 2) * kstep; const char* b2 = last ? nB : cB + (size_t)(t + 2) * kstep;
;             const char* a3 = a2 + kstep; const char* b3 = b2 + kstep;
;             if (last && has_next) S.a_ready(nxt);
;             if constexpr (SP2) {
;             PG8_LDB(B0, 0, 0); PG8_LDB(B1, 0, 1); PG8_SCHED; PG8_LDA(At, 0, 0); PG8_STAGE(PG8_SA(1, 1), a1 + hstepA, voffA);
;             PG8_WAIT_V(8); PG8_WAIT_L(0); PG8_BAR; PG8_MMA(0, 0, At, B0); PG8_MMA(0, 1, At, B1); PG8_BAR; PG8_SCHED;
;             PG8_LDA(At, 0, 1); PG8_STAGE(PG8_SB(0, 0), b2, voffB); PG8_STAGE(PG8_SB(0, 1), b2 + hstepB, voffB); PG8_STAGE(PG8_SA(0, 0), a2, voffA);
;             PG8_WAIT_V(8); PG8_WAIT_L(0); PG8_BAR; PG8_MMA(1, 0, At, B0); PG8_MMA(1, 1, At, B1); PG8_BAR; PG8_SCHED;
.LBB0_1017:
	s_lshl_b64 s[22:23], s[40:41], 17
	v_readlane_b32 s24, v239, 38
	s_add_u32 s44, s24, s22
	v_readlane_b32 s22, v239, 39
	s_addc_u32 s45, s22, s23
	s_and_b64 s[22:23], s[6:7], exec
	s_cselect_b32 s24, s45, s1
	s_cselect_b32 s25, s44, s0
	s_mov_b32 s26, 0
	s_mov_b64 s[22:23], -1
	s_mov_b64 s[34:35], 0
	s_waitcnt lgkmcnt(0)
	s_add_u32 s30, s20, s26
	s_addc_u32 s31, s21, 0
	s_add_u32 s27, s30, 0x100
	s_addc_u32 s33, s31, 0
	s_and_b64 s[28:29], s[34:35], exec
	s_cselect_b32 s51, s9, s33
	s_cselect_b32 s50, s8, s27
	s_add_u32 s26, s0, s26
	s_addc_u32 s27, s1, 0
	s_add_u32 s28, s26, 0x100
	s_addc_u32 s29, s27, 0
	s_and_b64 s[26:27], s[34:35], exec
	s_cselect_b32 s53, s24, s29
	s_cselect_b32 s52, s25, s28
	s_add_u32 s56, s30, 0x40080
	ds_read_b128 v[142:145], v150
	ds_read_b128 v[156:159], v150 offset:1024
	ds_read_b128 v[160:163], v150 offset:2048
	ds_read_b128 v[164:167], v150 offset:3072
	ds_read_b128 v[168:171], v151
	ds_read_b128 v[172:175], v151 offset:1024
	ds_read_b128 v[176:179], v151 offset:2048
	ds_read_b128 v[180:183], v151 offset:3072
	s_addc_u32 s57, s31, 0
	s_add_i32 s38, s70, s58
	s_add_i32 m0, s47, 0xc000
	s_add_i32 s43, s47, 0xe000
	s_add_i32 s30, s38, 0x2000
	s_add_u32 s54, s52, 0x4000
	s_addc_u32 s55, s53, 0
	s_add_i32 s33, s71, s58
	s_add_i32 s31, s33, 0x2000
	s_add_i32 s29, 0, 0x18000
	s_add_i32 s28, 0, 0x1c000
	s_add_u32 s48, s50, 0x40000
	s_addc_u32 s49, s51, 0
	s_add_i32 s27, s29, s58
	s_add_i32 s26, s27, 0x2000
	s_add_u32 s34, s52, 0x4080
	s_addc_u32 s35, s53, 0
	s_add_i32 s41, s28, s58
	s_add_i32 s39, s41, 0x2000
	v_lshl_add_u64 v[216:217], s[56:57], 0, v[128:129]
	ds_read_b128 v[184:187], v152
	ds_read_b128 v[188:191], v152 offset:1024
	ds_read_b128 v[192:195], v152 offset:2048
	ds_read_b128 v[196:199], v152 offset:3072
	ds_read_b128 v[200:203], v152 offset:4096
	ds_read_b128 v[204:207], v152 offset:5120
	ds_read_b128 v[208:211], v152 offset:6144
	ds_read_b128 v[212:215], v152 offset:7168
	global_load_lds_dwordx4 v[216:217], off
	v_lshl_add_u64 v[216:217], s[56:57], 0, v[132:133]
	s_mov_b32 m0, s43
	s_nop 0
	global_load_lds_dwordx4 v[216:217], off
	s_waitcnt vmcnt(8)
	s_waitcnt lgkmcnt(0)
	s_barrier
	s_waitcnt lgkmcnt(0)
	v_mfma_f32_16x16x32_bf16 v[124:127], v[142:145], v[184:187], 0
	v_mfma_f32_16x16x32_bf16 v[120:123], v[160:163], v[184:187], 0
	v_mfma_f32_16x16x32_bf16 v[108:111], v[142:145], v[192:195], 0
	v_mfma_f32_16x16x32_bf16 v[104:107], v[160:163], v[192:195], 0
	v_mfma_f32_16x16x32_bf16 v[92:95], v[142:145], v[200:203], 0
	v_mfma_f32_16x16x32_bf16 v[88:91], v[160:163], v[200:203], 0
	v_mfma_f32_16x16x32_bf16 v[76:79], v[142:145], v[208:211], 0
	v_mfma_f32_16x16x32_bf16 v[72:75], v[160:163], v[208:211], 0
	v_mfma_f32_16x16x32_bf16 v[124:127], v[156:159], v[188:191], v[124:127]
	v_mfma_f32_16x16x32_bf16 v[120:123], v[164:167], v[188:191], v[120:123]
	v_mfma_f32_16x16x32_bf16 v[108:111], v[156:159], v[196:199], v[108:111]
	v_mfma_f32_16x16x32_bf16 v[104:107], v[164:167], v[196:199], v[104:107]
	v_mfma_f32_16x16x32_bf16 v[92:95], v[156:159], v[204:207], v[92:95]
	v_mfma_f32_16x16x32_bf16 v[88:91], v[164:167], v[204:207], v[88:91]
	v_mfma_f32_16x16x32_bf16 v[76:79], v[156:159], v[212:215], v[76:79]
	v_mfma_f32_16x16x32_bf16 v[72:75], v[164:167], v[212:215], v[72:75]
	v_mfma_f32_16x16x32_bf16 v[116:119], v[168:171], v[184:187], 0
	v_mfma_f32_16x16x32_bf16 v[112:115], v[176:179], v[184:187], 0
	v_mfma_f32_16x16x32_bf16 v[100:103], v[168:171], v[192:195], 0
	v_mfma_f32_16x16x32_bf16 v[96:99], v[176:179], v[192:195], 0
	v_mfma_f32_16x16x32_bf16 v[84:87], v[168:171], v[200:203], 0
	v_mfma_f32_16x16x32_bf16 v[80:83], v[176:179], v[200:203], 0
	v_mfma_f32_16x16x32_bf16 v[68:71], v[168:171], v[208:211], 0
	v_mfma_f32_16x16x32_bf16 v[64:67], v[176:179], v[208:211], 0
	v_mfma_f32_16x16x32_bf16 v[116:119], v[172:175], v[188:191], v[116:119]
	v_mfma_f32_16x16x32_bf16 v[112:115], v[180:183], v[188:191], v[112:115]
	v_mfma_f32_16x16x32_bf16 v[100:103], v[172:175], v[196:199], v[100:103]
	v_mfma_f32_16x16x32_bf16 v[96:99], v[180:183], v[196:199], v[96:99]
	v_mfma_f32_16x16x32_bf16 v[84:87], v[172:175], v[204:207], v[84:87]
	v_mfma_f32_16x16x32_bf16 v[80:83], v[180:183], v[204:207], v[80:83]
	v_mfma_f32_16x16x32_bf16 v[68:71], v[172:175], v[212:215], v[68:71]
	v_mfma_f32_16x16x32_bf16 v[64:67], v[180:183], v[212:215], v[64:67]
	s_barrier
	s_mov_b32 m0, s38
	v_lshl_add_u64 v[216:217], s[52:53], 0, v[130:131]
	ds_read_b128 v[184:187], v152 offset:16384
	ds_read_b128 v[188:191], v152 offset:17408
	ds_read_b128 v[192:195], v152 offset:18432
	ds_read_b128 v[196:199], v152 offset:19456
	ds_read_b128 v[200:203], v152 offset:20480
	ds_read_b128 v[204:207], v152 offset:21504
	ds_read_b128 v[208:211], v152 offset:22528
	ds_read_b128 v[212:215], v152 offset:23552
	global_load_lds_dwordx4 v[216:217], off
	v_lshl_add_u64 v[218:219], s[52:53], 0, v[134:135]
	s_mov_b32 m0, s30
	v_lshl_add_u64 v[220:221], s[54:55], 0, v[130:131]
	global_load_lds_dwordx4 v[218:219], off
	s_mov_b32 m0, s33
	v_lshl_add_u64 v[222:223], s[50:51], 0, v[132:133]
	global_load_lds_dwordx4 v[220:221], off
	v_lshl_add_u64 v[220:221], s[54:55], 0, v[134:135]
	s_mov_b32 m0, s31
	s_nop 0
	global_load_lds_dwordx4 v[220:221], off
	v_lshl_add_u64 v[220:221], s[50:51], 0, v[128:129]
	s_mov_b32 m0, s47
	s_nop 0
	global_load_lds_dwordx4 v[220:221], off
	s_mov_b32 m0, s59
	s_nop 0
	global_load_lds_dwordx4 v[222:223], off
	s_waitcnt vmcnt(8)
	s_waitcnt lgkmcnt(0)
	s_barrier
; #define PG8_STAGE(bufoff, gbase, voff) do { _Pragma("unroll") for (int _i = 0; _i < 2; ++_i) \
;         __builtin_amdgcn_global_load_lds((const unsigned*)((const char*)(gbase) + (voff)[_i]), (PG8_LAS unsigned*)(lds + (bufoff) + ldsw + _i * 8192), 16, 0, PG8_LOAD_AUX); } while (0)
; #define PG8_LDA(dst, b, h) do { _Pragma("unroll") for (int m = 0; m < 4; ++m) _Pragma("unroll") for (int k = 0; k < 2; ++k) dst[m][k] = *(const PG8_LAS bf16x8*)(lds + PG8_SA(b, h) + aoff + m * 2048 + k * 1024); } while (0)
; #define PG8_LDB(dst, b, h) do { _Pragma("unroll") for (int n = 0; n < 2; ++n) _Pragma("unroll") for (int k = 0; k < 2; ++k) dst[n][k] = *(const PG8_LAS bf16x8*)(lds + PG8_SB(b, h) + boff + n * 2048 + k * 1024); } while (0)
; #define PG8_MMA(ai, bj, At, Bt) do { __builtin_amdgcn_s_setprio(1); _Pragma("unroll") for (int m = 0; m < 4; ++m) _Pragma("unroll") for (int n = 0; n < 2; ++n) _Pragma("unroll") for (int k = 0; k < 2; ++k) \
;         acc[ai][bj][m][n] = __builtin_amdgcn_mfma_f32_16x16x32_bf16(Bt[n][k], At[m][k], acc[ai][bj][m][n], 0, 0, 0); __builtin_amdgcn_s_setprio(0); } while (0)
; #define PG8_WAIT_V(n) asm volatile("s_waitcnt vmcnt(" #n ")" ::: "memory")
; #define PG8_WAIT_L(n) asm volatile("s_waitcnt lgkmcnt(" #n ")" ::: "memory")
; #define PG8_BAR __builtin_amdgcn_s_barrier()
; #define PG8_SCHED __builtin_amdgcn_sched_barrier(0)
; template <class Epi, class Sched, bool ALIGN_EPI = false, bool SP2 = false>
; __device__ __forceinline__ void gemm_phase(PG8_LAS unsigned char* lds, const Gemm g, const Sched& S, const Epi& E) {
;     ...
;             PG8_LDB(B0, 0, 0); PG8_LDB(B1, 0, 1); PG8_SCHED; PG8_LDA(At, 0, 0); PG8_STAGE(PG8_SA(1, 1), a1 + hstepA, voffA);
;             PG8_WAIT_V(8); PG8_WAIT_L(0); PG8_BAR; PG8_MMA(0, 0, At, B0); PG8_MMA(0, 1, At, B1); PG8_BAR; PG8_SCHED;
;             PG8_LDA(At, 0, 1); PG8_STAGE(PG8_SB(0, 0), b2, voffB); PG8_STAGE(PG8_SB(0, 1), b2 + hstepB, voffB); PG8_STAGE(PG8_SA(0, 0), a2, voffA);
;             PG8_WAIT_V(8); PG8_WAIT_L(0); PG8_BAR; PG8_MMA(1, 0, At, B0); PG8_MMA(1, 1, At, B1); PG8_BAR; PG8_SCHED;
	s_waitcnt lgkmcnt(0)
	v_mfma_f32_16x16x32_bf16 v[60:63], v[142:145], v[184:187], 0
	v_mfma_f32_16x16x32_bf16 v[56:59], v[160:163], v[184:187], 0
	v_mfma_f32_16x16x32_bf16 v[44:47], v[142:145], v[192:195], 0
	v_mfma_f32_16x16x32_bf16 v[40:43], v[160:163], v[192:195], 0
	v_mfma_f32_16x16x32_bf16 v[28:31], v[142:145], v[200:203], 0
	v_mfma_f32_16x16x32_bf16 v[24:27], v[160:163], v[200:203], 0
	v_mfma_f32_16x16x32_bf16 v[12:15], v[142:145], v[208:211], 0
	v_mfma_f32_16x16x32_bf16 v[8:11], v[160:163], v[208:211], 0
	v_mfma_f32_16x16x32_bf16 v[60:63], v[156:159], v[188:191], v[60:63]
	v_mfma_f32_16x16x32_bf16 v[56:59], v[164:167], v[188:191], v[56:59]
	v_mfma_f32_16x16x32_bf16 v[44:47], v[156:159], v[196:199], v[44:47]
	v_mfma_f32_16x16x32_bf16 v[40:43], v[164:167], v[196:199], v[40:43]
	v_mfma_f32_16x16x32_bf16 v[28:31], v[156:159], v[204:207], v[28:31]
	v_mfma_f32_16x16x32_bf16 v[24:27], v[164:167], v[204:207], v[24:27]
	v_mfma_f32_16x16x32_bf16 v[12:15], v[156:159], v[212:215], v[12:15]
	v_mfma_f32_16x16x32_bf16 v[8:11], v[164:167], v[212:215], v[8:11]
	v_mfma_f32_16x16x32_bf16 v[52:55], v[168:171], v[184:187], 0
	v_mfma_f32_16x16x32_bf16 v[48:51], v[176:179], v[184:187], 0
	v_mfma_f32_16x16x32_bf16 v[36:39], v[168:171], v[192:195], 0
	v_mfma_f32_16x16x32_bf16 v[32:35], v[176:179], v[192:195], 0
	v_mfma_f32_16x16x32_bf16 v[20:23], v[168:171], v[200:203], 0
	v_mfma_f32_16x16x32_bf16 v[16:19], v[176:179], v[200:203], 0
	v_mfma_f32_16x16x32_bf16 v[4:7], v[168:171], v[208:211], 0
	v_mfma_f32_16x16x32_bf16 v[0:3], v[176:179], v[208:211], 0
	v_mfma_f32_16x16x32_bf16 v[52:55], v[172:175], v[188:191], v[52:55]
	v_mfma_f32_16x16x32_bf16 v[48:51], v[180:183], v[188:191], v[48:51]
	v_mfma_f32_16x16x32_bf16 v[36:39], v[172:175], v[196:199], v[36:39]
	v_mfma_f32_16x16x32_bf16 v[32:35], v[180:183], v[196:199], v[32:35]
	v_mfma_f32_16x16x32_bf16 v[20:23], v[172:175], v[204:207], v[20:23]
	v_mfma_f32_16x16x32_bf16 v[16:19], v[180:183], v[204:207], v[16:19]
	v_mfma_f32_16x16x32_bf16 v[4:7], v[172:175], v[212:215], v[4:7]
	v_mfma_f32_16x16x32_bf16 v[0:3], v[180:183], v[212:215], v[0:3]
	s_barrier
	s_branch .Lkmid_P11
.LBB0_1018:
	s_add_u32 s30, s20, s26
	s_addc_u32 s31, s21, 0
	s_add_u32 s27, s30, 0x100
	s_addc_u32 s33, s31, 0
	s_and_b64 s[28:29], s[34:35], exec
	s_cselect_b32 s51, s9, s33
	s_cselect_b32 s50, s8, s27
	s_add_u32 s26, s0, s26
	s_addc_u32 s27, s1, 0
	s_add_u32 s28, s26, 0x100
	s_addc_u32 s29, s27, 0
	s_and_b64 s[26:27], s[34:35], exec
	s_cselect_b32 s53, s24, s29
	s_cselect_b32 s52, s25, s28
	s_add_u32 s56, s30, 0x40080
	ds_read_b128 v[142:145], v150
	ds_read_b128 v[156:159], v150 offset:1024
	ds_read_b128 v[160:163], v150 offset:2048
	ds_read_b128 v[164:167], v150 offset:3072
	ds_read_b128 v[168:171], v151
	ds_read_b128 v[172:175], v151 offset:1024
	ds_read_b128 v[176:179], v151 offset:2048
	ds_read_b128 v[180:183], v151 offset:3072
	s_addc_u32 s57, s31, 0
	s_add_i32 s38, s70, s58
	s_add_i32 m0, s47, 0xc000
	s_add_i32 s43, s47, 0xe000
	s_add_i32 s30, s38, 0x2000
	s_add_u32 s54, s52, 0x4000
	s_addc_u32 s55, s53, 0
	s_add_i32 s33, s71, s58
	s_add_i32 s31, s33, 0x2000
	s_add_i32 s29, 0, 0x18000
	s_add_i32 s28, 0, 0x1c000
	s_add_u32 s48, s50, 0x40000
	s_addc_u32 s49, s51, 0
	s_add_i32 s27, s29, s58
	s_add_i32 s26, s27, 0x2000
	s_add_u32 s34, s52, 0x4080
	s_addc_u32 s35, s53, 0
	s_add_i32 s41, s28, s58
	s_add_i32 s39, s41, 0x2000
	v_lshl_add_u64 v[216:217], s[56:57], 0, v[128:129]
	ds_read_b128 v[184:187], v152
	ds_read_b128 v[188:191], v152 offset:1024
	ds_read_b128 v[192:195], v152 offset:2048
	ds_read_b128 v[196:199], v152 offset:3072
	ds_read_b128 v[200:203], v152 offset:4096
	ds_read_b128 v[204:207], v152 offset:5120
	ds_read_b128 v[208:211], v152 offset:6144
	ds_read_b128 v[212:215], v152 offset:7168
	global_load_lds_dwordx4 v[216:217], off
	v_lshl_add_u64 v[216:217], s[56:57], 0, v[132:133]
	s_mov_b32 m0, s43
	s_nop 0
	global_load_lds_dwordx4 v[216:217], off
	s_waitcnt vmcnt(8)
	s_waitcnt lgkmcnt(0)
	s_barrier
	s_waitcnt lgkmcnt(0)
	v_mfma_f32_16x16x32_bf16 v[124:127], v[142:145], v[184:187], v[124:127]
	v_mfma_f32_16x16x32_bf16 v[120:123], v[160:163], v[184:187], v[120:123]
	v_mfma_f32_16x16x32_bf16 v[108:111], v[142:145], v[192:195], v[108:111]
	v_mfma_f32_16x16x32_bf16 v[104:107], v[160:163], v[192:195], v[104:107]
	v_mfma_f32_16x16x32_bf16 v[92:95], v[142:145], v[200:203], v[92:95]
	v_mfma_f32_16x16x32_bf16 v[88:91], v[160:163], v[200:203], v[88:91]
	v_mfma_f32_16x16x32_bf16 v[76:79], v[142:145], v[208:211], v[76:79]
	v_mfma_f32_16x16x32_bf16 v[72:75], v[160:163], v[208:211], v[72:75]
	v_mfma_f32_16x16x32_bf16 v[124:127], v[156:159], v[188:191], v[124:127]
	v_mfma_f32_16x16x32_bf16 v[120:123], v[164:167], v[188:191], v[120:123]
	v_mfma_f32_16x16x32_bf16 v[108:111], v[156:159], v[196:199], v[108:111]
	v_mfma_f32_16x16x32_bf16 v[104:107], v[164:167], v[196:199], v[104:107]
	v_mfma_f32_16x16x32_bf16 v[92:95], v[156:159], v[204:207], v[92:95]
	v_mfma_f32_16x16x32_bf16 v[88:91], v[164:167], v[204:207], v[88:91]
	v_mfma_f32_16x16x32_bf16 v[76:79], v[156:159], v[212:215], v[76:79]
	v_mfma_f32_16x16x32_bf16 v[72:75], v[164:167], v[212:215], v[72:75]
	v_mfma_f32_16x16x32_bf16 v[116:119], v[168:171], v[184:187], v[116:119]
	v_mfma_f32_16x16x32_bf16 v[112:115], v[176:179], v[184:187], v[112:115]
	v_mfma_f32_16x16x32_bf16 v[100:103], v[168:171], v[192:195], v[100:103]
	v_mfma_f32_16x16x32_bf16 v[96:99], v[176:179], v[192:195], v[96:99]
	v_mfma_f32_16x16x32_bf16 v[84:87], v[168:171], v[200:203], v[84:87]
	v_mfma_f32_16x16x32_bf16 v[80:83], v[176:179], v[200:203], v[80:83]
	v_mfma_f32_16x16x32_bf16 v[68:71], v[168:171], v[208:211], v[68:71]
	v_mfma_f32_16x16x32_bf16 v[64:67], v[176:179], v[208:211], v[64:67]
	v_mfma_f32_16x16x32_bf16 v[116:119], v[172:175], v[188:191], v[116:119]
	v_mfma_f32_16x16x32_bf16 v[112:115], v[180:183], v[188:191], v[112:115]
	v_mfma_f32_16x16x32_bf16 v[100:103], v[172:175], v[196:199], v[100:103]
	v_mfma_f32_16x16x32_bf16 v[96:99], v[180:183], v[196:199], v[96:99]
	v_mfma_f32_16x16x32_bf16 v[84:87], v[172:175], v[204:207], v[84:87]
	v_mfma_f32_16x16x32_bf16 v[80:83], v[180:183], v[204:207], v[80:83]
	v_mfma_f32_16x16x32_bf16 v[68:71], v[172:175], v[212:215], v[68:71]
	v_mfma_f32_16x16x32_bf16 v[64:67], v[180:183], v[212:215], v[64:67]
	s_barrier
; #define PG8_STAGE(bufoff, gbase, voff) do { _Pragma("unroll") for (int _i = 0; _i < 2; ++_i) \
;         __builtin_amdgcn_global_load_lds((const unsigned*)((const char*)(gbase) + (voff)[_i]), (PG8_LAS unsigned*)(lds + (bufoff) + ldsw + _i * 8192), 16, 0, PG8_LOAD_AUX); } while (0)
; #define PG8_LDA(dst, b, h) do { _Pragma("unroll") for (int m = 0; m < 4; ++m) _Pragma("unroll") for (int k = 0; k < 2; ++k) dst[m][k] = *(const PG8_LAS bf16x8*)(lds + PG8_SA(b, h) + aoff + m * 2048 + k * 1024); } while (0)
; #define PG8_MMA(ai, bj, At, Bt) do { __builtin_amdgcn_s_setprio(1); _Pragma("unroll") for (int m = 0; m < 4; ++m) _Pragma("unroll") for (int n = 0; n < 2; ++n) _Pragma("unroll") for (int k = 0; k < 2; ++k) \
;         acc[ai][bj][m][n] = __builtin_amdgcn_mfma_f32_16x16x32_bf16(Bt[n][k], At[m][k], acc[ai][bj][m][n], 0, 0, 0); __builtin_amdgcn_s_setprio(0); } while (0)
; #define PG8_WAIT_V(n) asm volatile("s_waitcnt vmcnt(" #n ")" ::: "memory")
; #define PG8_WAIT_L(n) asm volatile("s_waitcnt lgkmcnt(" #n ")" ::: "memory")
; #define PG8_BAR __builtin_amdgcn_s_barrier()
; #define PG8_SCHED __builtin_amdgcn_sched_barrier(0)
; template <class Epi, class Sched, bool ALIGN_EPI = false, bool SP2 = false>
; __device__ __forceinline__ void gemm_phase(PG8_LAS unsigned char* lds, const Gemm g, const Sched& S, const Epi& E) {
;     ...
;             PG8_LDA(At, 0, 1); PG8_STAGE(PG8_SB(0, 0), b2, voffB); PG8_STAGE(PG8_SB(0, 1), b2 + hstepB, voffB); PG8_STAGE(PG8_SA(0, 0), a2, voffA);
;             PG8_WAIT_V(8); PG8_WAIT_L(0); PG8_BAR; PG8_MMA(1, 0, At, B0); PG8_MMA(1, 1, At, B1); PG8_BAR; PG8_SCHED;
	s_mov_b32 m0, s38
	v_lshl_add_u64 v[216:217], s[52:53], 0, v[130:131]
	ds_read_b128 v[184:187], v152 offset:16384
	ds_read_b128 v[188:191], v152 offset:17408
	ds_read_b128 v[192:195], v152 offset:18432
	ds_read_b128 v[196:199], v152 offset:19456
	ds_read_b128 v[200:203], v152 offset:20480
	ds_read_b128 v[204:207], v152 offset:21504
	ds_read_b128 v[208:211], v152 offset:22528
	ds_read_b128 v[212:215], v152 offset:23552
	global_load_lds_dwordx4 v[216:217], off
	v_lshl_add_u64 v[218:219], s[52:53], 0, v[134:135]
	s_mov_b32 m0, s30
	v_lshl_add_u64 v[220:221], s[54:55], 0, v[130:131]
	global_load_lds_dwordx4 v[218:219], off
	s_mov_b32 m0, s33
	v_lshl_add_u64 v[222:223], s[50:51], 0, v[132:133]
	global_load_lds_dwordx4 v[220:221], off
	v_lshl_add_u64 v[220:221], s[54:55], 0, v[134:135]
	s_mov_b32 m0, s31
	s_nop 0
	global_load_lds_dwordx4 v[220:221], off
	v_lshl_add_u64 v[220:221], s[50:51], 0, v[128:129]
	s_mov_b32 m0, s47
	s_nop 0
	global_load_lds_dwordx4 v[220:221], off
	s_mov_b32 m0, s59
	s_nop 0
	global_load_lds_dwordx4 v[222:223], off
	s_waitcnt vmcnt(8)
	s_waitcnt lgkmcnt(0)
	s_barrier
	s_waitcnt lgkmcnt(0)
	v_mfma_f32_16x16x32_bf16 v[60:63], v[142:145], v[184:187], v[60:63]
	v_mfma_f32_16x16x32_bf16 v[56:59], v[160:163], v[184:187], v[56:59]
	v_mfma_f32_16x16x32_bf16 v[44:47], v[142:145], v[192:195], v[44:47]
	v_mfma_f32_16x16x32_bf16 v[40:43], v[160:163], v[192:195], v[40:43]
	v_mfma_f32_16x16x32_bf16 v[28:31], v[142:145], v[200:203], v[28:31]
	v_mfma_f32_16x16x32_bf16 v[24:27], v[160:163], v[200:203], v[24:27]
	v_mfma_f32_16x16x32_bf16 v[12:15], v[142:145], v[208:211], v[12:15]
	v_mfma_f32_16x16x32_bf16 v[8:11], v[160:163], v[208:211], v[8:11]
	v_mfma_f32_16x16x32_bf16 v[60:63], v[156:159], v[188:191], v[60:63]
	v_mfma_f32_16x16x32_bf16 v[56:59], v[164:167], v[188:191], v[56:59]
	v_mfma_f32_16x16x32_bf16 v[44:47], v[156:159], v[196:199], v[44:47]
	v_mfma_f32_16x16x32_bf16 v[40:43], v[164:167], v[196:199], v[40:43]
	v_mfma_f32_16x16x32_bf16 v[28:31], v[156:159], v[204:207], v[28:31]
	v_mfma_f32_16x16x32_bf16 v[24:27], v[164:167], v[204:207], v[24:27]
	v_mfma_f32_16x16x32_bf16 v[12:15], v[156:159], v[212:215], v[12:15]
	v_mfma_f32_16x16x32_bf16 v[8:11], v[164:167], v[212:215], v[8:11]
	v_mfma_f32_16x16x32_bf16 v[52:55], v[168:171], v[184:187], v[52:55]
	v_mfma_f32_16x16x32_bf16 v[48:51], v[176:179], v[184:187], v[48:51]
	v_mfma_f32_16x16x32_bf16 v[36:39], v[168:171], v[192:195], v[36:39]
	v_mfma_f32_16x16x32_bf16 v[32:35], v[176:179], v[192:195], v[32:35]
	v_mfma_f32_16x16x32_bf16 v[20:23], v[168:171], v[200:203], v[20:23]
	v_mfma_f32_16x16x32_bf16 v[16:19], v[176:179], v[200:203], v[16:19]
	v_mfma_f32_16x16x32_bf16 v[4:7], v[168:171], v[208:211], v[4:7]
	v_mfma_f32_16x16x32_bf16 v[0:3], v[176:179], v[208:211], v[0:3]
	v_mfma_f32_16x16x32_bf16 v[52:55], v[172:175], v[188:191], v[52:55]
	v_mfma_f32_16x16x32_bf16 v[48:51], v[180:183], v[188:191], v[48:51]
	v_mfma_f32_16x16x32_bf16 v[36:39], v[172:175], v[196:199], v[36:39]
	v_mfma_f32_16x16x32_bf16 v[32:35], v[180:183], v[196:199], v[32:35]
	v_mfma_f32_16x16x32_bf16 v[20:23], v[172:175], v[204:207], v[20:23]
	v_mfma_f32_16x16x32_bf16 v[16:19], v[180:183], v[204:207], v[16:19]
	v_mfma_f32_16x16x32_bf16 v[4:7], v[172:175], v[212:215], v[4:7]
	v_mfma_f32_16x16x32_bf16 v[0:3], v[180:183], v[212:215], v[0:3]
	s_barrier
; #define PG8_STAGE(bufoff, gbase, voff) do { _Pragma("unroll") for (int _i = 0; _i < 2; ++_i) \
;         __builtin_amdgcn_global_load_lds((const unsigned*)((const char*)(gbase) + (voff)[_i]), (PG8_LAS unsigned*)(lds + (bufoff) + ldsw + _i * 8192), 16, 0, PG8_LOAD_AUX); } while (0)
; #define PG8_LDA(dst, b, h) do { _Pragma("unroll") for (int m = 0; m < 4; ++m) _Pragma("unroll") for (int k = 0; k < 2; ++k) dst[m][k] = *(const PG8_LAS bf16x8*)(lds + PG8_SA(b, h) + aoff + m * 2048 + k * 1024); } while (0)
; #define PG8_LDB(dst, b, h) do { _Pragma("unroll") for (int n = 0; n < 2; ++n) _Pragma("unroll") for (int k = 0; k < 2; ++k) dst[n][k] = *(const PG8_LAS bf16x8*)(lds + PG8_SB(b, h) + boff + n * 2048 + k * 1024); } while (0)
; #define PG8_MMA(ai, bj, At, Bt) do { __builtin_amdgcn_s_setprio(1); _Pragma("unroll") for (int m = 0; m < 4; ++m) _Pragma("unroll") for (int n = 0; n < 2; ++n) _Pragma("unroll") for (int k = 0; k < 2; ++k) \
;         acc[ai][bj][m][n] = __builtin_amdgcn_mfma_f32_16x16x32_bf16(Bt[n][k], At[m][k], acc[ai][bj][m][n], 0, 0, 0); __builtin_amdgcn_s_setprio(0); } while (0)
; #define PG8_WAIT_V(n) asm volatile("s_waitcnt vmcnt(" #n ")" ::: "memory")
; #define PG8_WAIT_L(n) asm volatile("s_waitcnt lgkmcnt(" #n ")" ::: "memory")
; #define PG8_BAR __builtin_amdgcn_s_barrier()
; #define PG8_SCHED __builtin_amdgcn_sched_barrier(0)
; template <class Epi, class Sched, bool ALIGN_EPI = false, bool SP2 = false>
; __device__ __forceinline__ void gemm_phase(PG8_LAS unsigned char* lds, const Gemm g, const Sched& S, const Epi& E) {
;     ...
;             PG8_LDB(B0, 1, 0); PG8_LDB(B1, 1, 1); PG8_SCHED; PG8_LDA(At, 1, 0); PG8_STAGE(PG8_SA(0, 1), a2 + hstepA, voffA);
;             PG8_WAIT_V(8); PG8_WAIT_L(0); PG8_BAR; PG8_MMA(0, 0, At, B0); PG8_MMA(0, 1, At, B1); PG8_BAR; PG8_SCHED;
;             PG8_LDA(At, 1, 1); PG8_STAGE(PG8_SB(1, 0), b3, voffB); PG8_STAGE(PG8_SB(1, 1), b3 + hstepB, voffB); PG8_STAGE(PG8_SA(1, 0), a3, voffA);
;             PG8_WAIT_V(8); PG8_WAIT_L(0); PG8_BAR; PG8_MMA(1, 0, At, B0); PG8_MMA(1, 1, At, B1); PG8_BAR; PG8_SCHED;
.Lkmid_P11:
	v_add_u32_e32 v164, s29, v147
	v_add_u32_e32 v180, s28, v147
	ds_read_b128 v[142:145], v164
	ds_read_b128 v[156:159], v164 offset:1024
	ds_read_b128 v[160:163], v164 offset:2048
	ds_read_b128 v[164:167], v164 offset:3072
	ds_read_b128 v[168:171], v180
	ds_read_b128 v[172:175], v180 offset:1024
	ds_read_b128 v[176:179], v180 offset:2048
	ds_read_b128 v[180:183], v180 offset:3072
	s_mov_b32 m0, s60
	v_lshl_add_u64 v[224:225], s[48:49], 0, v[128:129]
	ds_read_b128 v[184:187], v152 offset:32768
	ds_read_b128 v[188:191], v152 offset:33792
	ds_read_b128 v[192:195], v152 offset:34816
	ds_read_b128 v[196:199], v152 offset:35840
	ds_read_b128 v[200:203], v152 offset:36864
	ds_read_b128 v[204:207], v152 offset:37888
	ds_read_b128 v[208:211], v152 offset:38912
	ds_read_b128 v[212:215], v152 offset:39936
	global_load_lds_dwordx4 v[224:225], off
	v_lshl_add_u64 v[224:225], s[48:49], 0, v[132:133]
	s_mov_b32 m0, s61
	s_nop 0
	global_load_lds_dwordx4 v[224:225], off
	s_waitcnt vmcnt(8)
	s_waitcnt lgkmcnt(0)
	s_barrier
	s_waitcnt lgkmcnt(0)
	v_mfma_f32_16x16x32_bf16 v[124:127], v[142:145], v[184:187], v[124:127]
	v_mfma_f32_16x16x32_bf16 v[120:123], v[160:163], v[184:187], v[120:123]
	v_mfma_f32_16x16x32_bf16 v[108:111], v[142:145], v[192:195], v[108:111]
	v_mfma_f32_16x16x32_bf16 v[104:107], v[160:163], v[192:195], v[104:107]
	v_mfma_f32_16x16x32_bf16 v[92:95], v[142:145], v[200:203], v[92:95]
	v_mfma_f32_16x16x32_bf16 v[88:91], v[160:163], v[200:203], v[88:91]
	v_mfma_f32_16x16x32_bf16 v[76:79], v[142:145], v[208:211], v[76:79]
	v_mfma_f32_16x16x32_bf16 v[72:75], v[160:163], v[208:211], v[72:75]
	v_mfma_f32_16x16x32_bf16 v[124:127], v[156:159], v[188:191], v[124:127]
	v_mfma_f32_16x16x32_bf16 v[120:123], v[164:167], v[188:191], v[120:123]
	v_mfma_f32_16x16x32_bf16 v[108:111], v[156:159], v[196:199], v[108:111]
	v_mfma_f32_16x16x32_bf16 v[104:107], v[164:167], v[196:199], v[104:107]
	v_mfma_f32_16x16x32_bf16 v[92:95], v[156:159], v[204:207], v[92:95]
	v_mfma_f32_16x16x32_bf16 v[88:91], v[164:167], v[204:207], v[88:91]
	v_mfma_f32_16x16x32_bf16 v[76:79], v[156:159], v[212:215], v[76:79]
	v_mfma_f32_16x16x32_bf16 v[72:75], v[164:167], v[212:215], v[72:75]
	v_mfma_f32_16x16x32_bf16 v[116:119], v[168:171], v[184:187], v[116:119]
	v_mfma_f32_16x16x32_bf16 v[112:115], v[176:179], v[184:187], v[112:115]
	v_mfma_f32_16x16x32_bf16 v[100:103], v[168:171], v[192:195], v[100:103]
	v_mfma_f32_16x16x32_bf16 v[96:99], v[176:179], v[192:195], v[96:99]
	v_mfma_f32_16x16x32_bf16 v[84:87], v[168:171], v[200:203], v[84:87]
	v_mfma_f32_16x16x32_bf16 v[80:83], v[176:179], v[200:203], v[80:83]
	v_mfma_f32_16x16x32_bf16 v[68:71], v[168:171], v[208:211], v[68:71]
	v_mfma_f32_16x16x32_bf16 v[64:67], v[176:179], v[208:211], v[64:67]
	v_mfma_f32_16x16x32_bf16 v[116:119], v[172:175], v[188:191], v[116:119]
	v_mfma_f32_16x16x32_bf16 v[112:115], v[180:183], v[188:191], v[112:115]
	v_mfma_f32_16x16x32_bf16 v[100:103], v[172:175], v[196:199], v[100:103]
	v_mfma_f32_16x16x32_bf16 v[96:99], v[180:183], v[196:199], v[96:99]
	v_mfma_f32_16x16x32_bf16 v[84:87], v[172:175], v[204:207], v[84:87]
	v_mfma_f32_16x16x32_bf16 v[80:83], v[180:183], v[204:207], v[80:83]
	v_mfma_f32_16x16x32_bf16 v[68:71], v[172:175], v[212:215], v[68:71]
	v_mfma_f32_16x16x32_bf16 v[64:67], v[180:183], v[212:215], v[64:67]
	s_barrier
	s_mov_b32 m0, s27
	v_lshl_add_u64 v[216:217], v[216:217], 0, s[18:19]
	ds_read_b128 v[184:187], v152 offset:49152
	ds_read_b128 v[188:191], v152 offset:50176
	ds_read_b128 v[192:195], v152 offset:51200
	ds_read_b128 v[196:199], v152 offset:52224
	ds_read_b128 v[200:203], v152 offset:53248
	ds_read_b128 v[204:207], v152 offset:54272
	ds_read_b128 v[208:211], v152 offset:55296
	ds_read_b128 v[212:215], v152 offset:56320
	global_load_lds_dwordx4 v[216:217], off
	v_lshl_add_u64 v[216:217], v[218:219], 0, s[18:19]
	s_mov_b32 m0, s26
	s_nop 0
	global_load_lds_dwordx4 v[216:217], off
	v_lshl_add_u64 v[216:217], s[34:35], 0, v[130:131]
	s_mov_b32 m0, s41
	s_nop 0
	global_load_lds_dwordx4 v[216:217], off
	v_lshl_add_u64 v[216:217], s[34:35], 0, v[134:135]
	s_mov_b32 m0, s39
	s_nop 0
	global_load_lds_dwordx4 v[216:217], off
	v_lshl_add_u64 v[216:217], v[220:221], 0, s[18:19]
	s_mov_b32 m0, s65
	s_nop 0
	global_load_lds_dwordx4 v[216:217], off
	v_lshl_add_u64 v[216:217], v[222:223], 0, s[18:19]
	s_mov_b32 m0, s66
	s_nop 0
	global_load_lds_dwordx4 v[216:217], off
	s_waitcnt vmcnt(8)
	s_waitcnt lgkmcnt(0)
	s_barrier
	s_waitcnt lgkmcnt(0)
	v_mfma_f32_16x16x32_bf16 v[60:63], v[142:145], v[184:187], v[60:63]
	v_mfma_f32_16x16x32_bf16 v[56:59], v[160:163], v[184:187], v[56:59]
	v_mfma_f32_16x16x32_bf16 v[44:47], v[142:145], v[192:195], v[44:47]
	v_mfma_f32_16x16x32_bf16 v[40:43], v[160:163], v[192:195], v[40:43]
	v_mfma_f32_16x16x32_bf16 v[28:31], v[142:145], v[200:203], v[28:31]
	v_mfma_f32_16x16x32_bf16 v[24:27], v[160:163], v[200:203], v[24:27]
	v_mfma_f32_16x16x32_bf16 v[12:15], v[142:145], v[208:211], v[12:15]
	v_mfma_f32_16x16x32_bf16 v[8:11], v[160:163], v[208:211], v[8:11]
	v_mfma_f32_16x16x32_bf16 v[60:63], v[156:159], v[188:191], v[60:63]
	v_mfma_f32_16x16x32_bf16 v[56:59], v[164:167], v[188:191], v[56:59]
	v_mfma_f32_16x16x32_bf16 v[44:47], v[156:159], v[196:199], v[44:47]
	v_mfma_f32_16x16x32_bf16 v[40:43], v[164:167], v[196:199], v[40:43]
	v_mfma_f32_16x16x32_bf16 v[28:31], v[156:159], v[204:207], v[28:31]
	v_mfma_f32_16x16x32_bf16 v[24:27], v[164:167], v[204:207], v[24:27]
	v_mfma_f32_16x16x32_bf16 v[12:15], v[156:159], v[212:215], v[12:15]
	v_mfma_f32_16x16x32_bf16 v[8:11], v[164:167], v[212:215], v[8:11]
	v_mfma_f32_16x16x32_bf16 v[52:55], v[168:171], v[184:187], v[52:55]
	v_mfma_f32_16x16x32_bf16 v[48:51], v[176:179], v[184:187], v[48:51]
	v_mfma_f32_16x16x32_bf16 v[36:39], v[168:171], v[192:195], v[36:39]
	v_mfma_f32_16x16x32_bf16 v[32:35], v[176:179], v[192:195], v[32:35]
	v_mfma_f32_16x16x32_bf16 v[20:23], v[168:171], v[200:203], v[20:23]
	v_mfma_f32_16x16x32_bf16 v[16:19], v[176:179], v[200:203], v[16:19]
	v_mfma_f32_16x16x32_bf16 v[4:7], v[168:171], v[208:211], v[4:7]
	v_mfma_f32_16x16x32_bf16 v[0:3], v[176:179], v[208:211], v[0:3]
	v_mfma_f32_16x16x32_bf16 v[52:55], v[172:175], v[188:191], v[52:55]
	v_mfma_f32_16x16x32_bf16 v[48:51], v[180:183], v[188:191], v[48:51]
	v_mfma_f32_16x16x32_bf16 v[36:39], v[172:175], v[196:199], v[36:39]
	v_mfma_f32_16x16x32_bf16 v[32:35], v[180:183], v[196:199], v[32:35]
	v_mfma_f32_16x16x32_bf16 v[20:23], v[172:175], v[204:207], v[20:23]
	v_mfma_f32_16x16x32_bf16 v[16:19], v[180:183], v[204:207], v[16:19]
	v_mfma_f32_16x16x32_bf16 v[4:7], v[172:175], v[212:215], v[4:7]
	v_mfma_f32_16x16x32_bf16 v[0:3], v[180:183], v[212:215], v[0:3]
	s_barrier
	s_movk_i32 s26, 0x100
	s_andn2_b64 vcc, exec, s[22:23]
	s_mov_b64 s[34:35], -1
	s_mov_b64 s[22:23], 0
	s_cbranch_vccz .LBB0_1018
	s_and_b64 vcc, exec, s[36:37]
	s_cbranch_vccz .LBB0_1021
	s_barrier

; #define PG8_STAGE(bufoff, gbase, voff) do { _Pragma("unroll") for (int _i = 0; _i < 2; ++_i) \
;         __builtin_amdgcn_global_load_lds((const unsigned*)((const char*)(gbase) + (voff)[_i]), (PG8_LAS unsigned*)(lds + (bufoff) + ldsw + _i * 8192), 16, 0, PG8_LOAD_AUX); } while (0)
; #define PG8_LDA(dst, b, h) do { _Pragma("unroll") for (int m = 0; m < 4; ++m) _Pragma("unroll") for (int k = 0; k < 2; ++k) dst[m][k] = *(const PG8_LAS bf16x8*)(lds + PG8_SA(b, h) + aoff + m * 2048 + k * 1024); } while (0)
; #define PG8_LDB(dst, b, h) do { _Pragma("unroll") for (int n = 0; n < 2; ++n) _Pragma("unroll") for (int k = 0; k < 2; ++k) dst[n][k] = *(const PG8_LAS bf16x8*)(lds + PG8_SB(b, h) + boff + n * 2048 + k * 1024); } while (0)
; #define PG8_WAIT_V(n) asm volatile("s_waitcnt vmcnt(" #n ")" ::: "memory")
; #define PG8_WAIT_L(n) asm volatile("s_waitcnt lgkmcnt(" #n ")" ::: "memory")
; #define PG8_BAR __builtin_amdgcn_s_barrier()
; #define PG8_SCHED __builtin_amdgcn_sched_barrier(0)
; template <class Epi, class Sched, bool ALIGN_EPI = false, bool SP2 = false>
; __device__ __forceinline__ void gemm_phase(PG8_LAS unsigned char* lds, const Gemm g, const Sched& S, const Epi& E) {
;     ...
;         const char* nA = has_next ? (const char*)g.A + (size_t)nxt.pm * tstepA + (size_t)nxt.pn * apn : cA; const char* nB = has_next ? (const char*)g.Bt + (size_t)nxt.pn * tstepB : cB;
;         for (int t = 0; t < nt; t += 2) {
;             const bool last = (t == nt - 2);
;             const char* a1 = cA + (size_t)(t + 1) * kstep;
;             const char* a2 = last ? nA : cA + (size_t)(t + 2) * kstep; const char* b2 = last ? nB : cB + (size_t)(t + 2) * kstep;
;             const char* a3 = a2 + kstep; const char* b3 = b2 + kstep;
;             if (last && has_next) S.a_ready(nxt);
;             if constexpr (SP2) {
;             PG8_LDB(B0, 0, 0); PG8_LDB(B1, 0, 1); PG8_SCHED; PG8_LDA(At, 0, 0); PG8_STAGE(PG8_SA(1, 1), a1 + hstepA, voffA);
;             PG8_WAIT_V(8); PG8_WAIT_L(0); PG8_BAR; PG8_MMA(0, 0, At, B0); PG8_MMA(0, 1, At, B1); PG8_BAR; PG8_SCHED;
;             PG8_LDA(At, 0, 1); PG8_STAGE(PG8_SB(0, 0), b2, voffB); PG8_STAGE(PG8_SB(0, 1), b2 + hstepB, voffB); PG8_STAGE(PG8_SA(0, 0), a2, voffA);
;             PG8_WAIT_V(8); PG8_WAIT_L(0); PG8_BAR; PG8_MMA(1, 0, At, B0); PG8_MMA(1, 1, At, B1); PG8_BAR; PG8_SCHED;
.LBB0_1110:
	s_ashr_i32 s17, s16, 31
	s_lshl_b64 s[18:19], s[16:17], 19
	s_add_u32 s18, s30, s18
	s_addc_u32 s19, s31, s19
	s_and_b64 s[24:25], s[2:3], exec
	s_cselect_b32 s17, s19, s21
	s_cselect_b32 s24, s18, s20
	s_ashr_i32 s15, s14, 31
	s_lshl_b64 s[26:27], s[14:15], 19
	s_add_u32 s36, s40, s26
	s_addc_u32 s37, s41, s27
	s_and_b64 s[26:27], s[2:3], exec
	s_cselect_b32 s15, s37, s23
	s_cselect_b32 s25, s36, s22
	s_add_u32 s20, s20, 0x40080
	s_addc_u32 s21, s21, 0
	s_add_u32 s26, s22, 0x100
	s_addc_u32 s27, s23, 0
	s_mov_b32 s28, -2
	ds_read_b128 v[146:149], v157
	ds_read_b128 v[162:165], v157 offset:1024
	ds_read_b128 v[166:169], v157 offset:2048
	ds_read_b128 v[170:173], v157 offset:3072
	ds_read_b128 v[174:177], v158
	ds_read_b128 v[178:181], v158 offset:1024
	ds_read_b128 v[182:185], v158 offset:2048
	ds_read_b128 v[186:189], v158 offset:3072
	s_add_u32 s22, s20, 0xfffc0080
	s_addc_u32 s23, s21, -1
	s_cmp_eq_u32 s28, 12
	s_cselect_b32 s35, s17, s23
	s_cselect_b32 s34, s24, s22
	s_cselect_b32 s23, s15, s27
	s_cselect_b32 s22, s25, s26
	v_lshl_add_u64 v[150:151], s[20:21], 0, v[138:139]
	s_add_i32 m0, s45, 0xc000
	ds_read_b128 v[190:193], v159
	ds_read_b128 v[194:197], v159 offset:1024
	ds_read_b128 v[198:201], v159 offset:2048
	ds_read_b128 v[202:205], v159 offset:3072
	ds_read_b128 v[206:209], v159 offset:4096
	ds_read_b128 v[210:213], v159 offset:5120
	ds_read_b128 v[214:217], v159 offset:6144
	ds_read_b128 v[218:221], v159 offset:7168
	global_load_lds_dwordx4 v[150:151], off
	v_lshl_add_u64 v[150:151], s[20:21], 0, v[140:141]
	s_add_i32 m0, s45, 0xe000
	s_nop 0
	global_load_lds_dwordx4 v[150:151], off
	s_waitcnt vmcnt(8)
	s_waitcnt lgkmcnt(0)
	s_barrier
	s_waitcnt lgkmcnt(0)
	v_mfma_f32_16x16x32_bf16 v[124:127], v[146:149], v[190:193], 0
	v_mfma_f32_16x16x32_bf16 v[120:123], v[166:169], v[190:193], 0
	v_mfma_f32_16x16x32_bf16 v[108:111], v[146:149], v[198:201], 0
	v_mfma_f32_16x16x32_bf16 v[104:107], v[166:169], v[198:201], 0
	v_mfma_f32_16x16x32_bf16 v[92:95], v[146:149], v[206:209], 0
	v_mfma_f32_16x16x32_bf16 v[88:91], v[166:169], v[206:209], 0
	v_mfma_f32_16x16x32_bf16 v[76:79], v[146:149], v[214:217], 0
	v_mfma_f32_16x16x32_bf16 v[72:75], v[166:169], v[214:217], 0
	v_mfma_f32_16x16x32_bf16 v[124:127], v[162:165], v[194:197], v[124:127]
	v_mfma_f32_16x16x32_bf16 v[120:123], v[170:173], v[194:197], v[120:123]
	v_mfma_f32_16x16x32_bf16 v[108:111], v[162:165], v[202:205], v[108:111]
	v_mfma_f32_16x16x32_bf16 v[104:107], v[170:173], v[202:205], v[104:107]
	v_mfma_f32_16x16x32_bf16 v[92:95], v[162:165], v[210:213], v[92:95]
	v_mfma_f32_16x16x32_bf16 v[88:91], v[170:173], v[210:213], v[88:91]
	v_mfma_f32_16x16x32_bf16 v[76:79], v[162:165], v[218:221], v[76:79]
	v_mfma_f32_16x16x32_bf16 v[72:75], v[170:173], v[218:221], v[72:75]
	v_mfma_f32_16x16x32_bf16 v[116:119], v[174:177], v[190:193], 0
	v_mfma_f32_16x16x32_bf16 v[112:115], v[182:185], v[190:193], 0
	v_mfma_f32_16x16x32_bf16 v[100:103], v[174:177], v[198:201], 0
	v_mfma_f32_16x16x32_bf16 v[96:99], v[182:185], v[198:201], 0
	v_mfma_f32_16x16x32_bf16 v[84:87], v[174:177], v[206:209], 0
	v_mfma_f32_16x16x32_bf16 v[80:83], v[182:185], v[206:209], 0
	v_mfma_f32_16x16x32_bf16 v[68:71], v[174:177], v[214:217], 0
	v_mfma_f32_16x16x32_bf16 v[64:67], v[182:185], v[214:217], 0
	v_mfma_f32_16x16x32_bf16 v[116:119], v[178:181], v[194:197], v[116:119]
	v_mfma_f32_16x16x32_bf16 v[112:115], v[186:189], v[194:197], v[112:115]
	v_mfma_f32_16x16x32_bf16 v[100:103], v[178:181], v[202:205], v[100:103]
	v_mfma_f32_16x16x32_bf16 v[96:99], v[186:189], v[202:205], v[96:99]
	v_mfma_f32_16x16x32_bf16 v[84:87], v[178:181], v[210:213], v[84:87]
	v_mfma_f32_16x16x32_bf16 v[80:83], v[186:189], v[210:213], v[80:83]
	v_mfma_f32_16x16x32_bf16 v[68:71], v[178:181], v[218:221], v[68:71]
	v_mfma_f32_16x16x32_bf16 v[64:67], v[186:189], v[218:221], v[64:67]
	s_barrier
	s_add_i32 s29, s54, s42
	v_lshl_add_u64 v[150:151], s[22:23], 0, v[132:133]
	s_mov_b32 m0, s29
	ds_read_b128 v[190:193], v159 offset:16384
	ds_read_b128 v[194:197], v159 offset:17408
	ds_read_b128 v[198:201], v159 offset:18432
	ds_read_b128 v[202:205], v159 offset:19456
	ds_read_b128 v[206:209], v159 offset:20480
	ds_read_b128 v[210:213], v159 offset:21504
	ds_read_b128 v[214:217], v159 offset:22528
	ds_read_b128 v[218:221], v159 offset:23552
	global_load_lds_dwordx4 v[150:151], off
	s_add_i32 m0, s29, 0x2000
	s_add_u32 s30, s22, 0x40000
	v_lshl_add_u64 v[222:223], s[22:23], 0, v[128:129]
	s_addc_u32 s31, s23, 0
	s_add_i32 s29, s55, s42
	global_load_lds_dwordx4 v[222:223], off
	v_lshl_add_u64 v[224:225], s[30:31], 0, v[132:133]
	s_mov_b32 m0, s29
	v_lshl_add_u64 v[226:227], s[34:35], 0, v[130:131]
	global_load_lds_dwordx4 v[224:225], off
	v_lshl_add_u64 v[224:225], s[30:31], 0, v[128:129]
	s_add_i32 m0, s29, 0x2000
	s_nop 0
	global_load_lds_dwordx4 v[224:225], off
	v_lshl_add_u64 v[224:225], s[34:35], 0, v[134:135]
	s_mov_b32 m0, s45
	s_nop 0
	global_load_lds_dwordx4 v[224:225], off
	s_mov_b32 m0, s46
	s_nop 0
	global_load_lds_dwordx4 v[226:227], off
	s_waitcnt vmcnt(8)
	s_waitcnt lgkmcnt(0)
	s_barrier
; #define PG8_STAGE(bufoff, gbase, voff) do { _Pragma("unroll") for (int _i = 0; _i < 2; ++_i) \
;         __builtin_amdgcn_global_load_lds((const unsigned*)((const char*)(gbase) + (voff)[_i]), (PG8_LAS unsigned*)(lds + (bufoff) + ldsw + _i * 8192), 16, 0, PG8_LOAD_AUX); } while (0)
; #define PG8_LDA(dst, b, h) do { _Pragma("unroll") for (int m = 0; m < 4; ++m) _Pragma("unroll") for (int k = 0; k < 2; ++k) dst[m][k] = *(const PG8_LAS bf16x8*)(lds + PG8_SA(b, h) + aoff + m * 2048 + k * 1024); } while (0)
; #define PG8_LDB(dst, b, h) do { _Pragma("unroll") for (int n = 0; n < 2; ++n) _Pragma("unroll") for (int k = 0; k < 2; ++k) dst[n][k] = *(const PG8_LAS bf16x8*)(lds + PG8_SB(b, h) + boff + n * 2048 + k * 1024); } while (0)
; #define PG8_MMA(ai, bj, At, Bt) do { __builtin_amdgcn_s_setprio(1); _Pragma("unroll") for (int m = 0; m < 4; ++m) _Pragma("unroll") for (int n = 0; n < 2; ++n) _Pragma("unroll") for (int k = 0; k < 2; ++k) \
;         acc[ai][bj][m][n] = __builtin_amdgcn_mfma_f32_16x16x32_bf16(Bt[n][k], At[m][k], acc[ai][bj][m][n], 0, 0, 0); __builtin_amdgcn_s_setprio(0); } while (0)
; #define PG8_WAIT_V(n) asm volatile("s_waitcnt vmcnt(" #n ")" ::: "memory")
; #define PG8_WAIT_L(n) asm volatile("s_waitcnt lgkmcnt(" #n ")" ::: "memory")
; #define PG8_BAR __builtin_amdgcn_s_barrier()
; #define PG8_SCHED __builtin_amdgcn_sched_barrier(0)
; template <class Epi, class Sched, bool ALIGN_EPI = false, bool SP2 = false>
; __device__ __forceinline__ void gemm_phase(PG8_LAS unsigned char* lds, const Gemm g, const Sched& S, const Epi& E) {
;     ...
;             PG8_LDB(B0, 0, 0); PG8_LDB(B1, 0, 1); PG8_SCHED; PG8_LDA(At, 0, 0); PG8_STAGE(PG8_SA(1, 1), a1 + hstepA, voffA);
;             PG8_WAIT_V(8); PG8_WAIT_L(0); PG8_BAR; PG8_MMA(0, 0, At, B0); PG8_MMA(0, 1, At, B1); PG8_BAR; PG8_SCHED;
;             PG8_LDA(At, 0, 1); PG8_STAGE(PG8_SB(0, 0), b2, voffB); PG8_STAGE(PG8_SB(0, 1), b2 + hstepB, voffB); PG8_STAGE(PG8_SA(0, 0), a2, voffA);
;             PG8_WAIT_V(8); PG8_WAIT_L(0); PG8_BAR; PG8_MMA(1, 0, At, B0); PG8_MMA(1, 1, At, B1); PG8_BAR; PG8_SCHED;
	s_waitcnt lgkmcnt(0)
	v_mfma_f32_16x16x32_bf16 v[60:63], v[146:149], v[190:193], 0
	v_mfma_f32_16x16x32_bf16 v[56:59], v[166:169], v[190:193], 0
	v_mfma_f32_16x16x32_bf16 v[44:47], v[146:149], v[198:201], 0
	v_mfma_f32_16x16x32_bf16 v[40:43], v[166:169], v[198:201], 0
	v_mfma_f32_16x16x32_bf16 v[28:31], v[146:149], v[206:209], 0
	v_mfma_f32_16x16x32_bf16 v[24:27], v[166:169], v[206:209], 0
	v_mfma_f32_16x16x32_bf16 v[12:15], v[146:149], v[214:217], 0
	v_mfma_f32_16x16x32_bf16 v[8:11], v[166:169], v[214:217], 0
	v_mfma_f32_16x16x32_bf16 v[60:63], v[162:165], v[194:197], v[60:63]
	v_mfma_f32_16x16x32_bf16 v[56:59], v[170:173], v[194:197], v[56:59]
	v_mfma_f32_16x16x32_bf16 v[44:47], v[162:165], v[202:205], v[44:47]
	v_mfma_f32_16x16x32_bf16 v[40:43], v[170:173], v[202:205], v[40:43]
	v_mfma_f32_16x16x32_bf16 v[28:31], v[162:165], v[210:213], v[28:31]
	v_mfma_f32_16x16x32_bf16 v[24:27], v[170:173], v[210:213], v[24:27]
	v_mfma_f32_16x16x32_bf16 v[12:15], v[162:165], v[218:221], v[12:15]
	v_mfma_f32_16x16x32_bf16 v[8:11], v[170:173], v[218:221], v[8:11]
	v_mfma_f32_16x16x32_bf16 v[52:55], v[174:177], v[190:193], 0
	v_mfma_f32_16x16x32_bf16 v[48:51], v[182:185], v[190:193], 0
	v_mfma_f32_16x16x32_bf16 v[36:39], v[174:177], v[198:201], 0
	v_mfma_f32_16x16x32_bf16 v[32:35], v[182:185], v[198:201], 0
	v_mfma_f32_16x16x32_bf16 v[20:23], v[174:177], v[206:209], 0
	v_mfma_f32_16x16x32_bf16 v[16:19], v[182:185], v[206:209], 0
	v_mfma_f32_16x16x32_bf16 v[4:7], v[174:177], v[214:217], 0
	v_mfma_f32_16x16x32_bf16 v[0:3], v[182:185], v[214:217], 0
	v_mfma_f32_16x16x32_bf16 v[52:55], v[178:181], v[194:197], v[52:55]
	v_mfma_f32_16x16x32_bf16 v[48:51], v[186:189], v[194:197], v[48:51]
	v_mfma_f32_16x16x32_bf16 v[36:39], v[178:181], v[202:205], v[36:39]
	v_mfma_f32_16x16x32_bf16 v[32:35], v[186:189], v[202:205], v[32:35]
	v_mfma_f32_16x16x32_bf16 v[20:23], v[178:181], v[210:213], v[20:23]
	v_mfma_f32_16x16x32_bf16 v[16:19], v[186:189], v[210:213], v[16:19]
	v_mfma_f32_16x16x32_bf16 v[4:7], v[178:181], v[218:221], v[4:7]
	v_mfma_f32_16x16x32_bf16 v[0:3], v[186:189], v[218:221], v[0:3]
	s_barrier
	s_branch .Lkmid_P12
.LBB0_1111:
	ds_read_b128 v[146:149], v157
	ds_read_b128 v[162:165], v157 offset:1024
	ds_read_b128 v[166:169], v157 offset:2048
	ds_read_b128 v[170:173], v157 offset:3072
	ds_read_b128 v[174:177], v158
	ds_read_b128 v[178:181], v158 offset:1024
	ds_read_b128 v[182:185], v158 offset:2048
	ds_read_b128 v[186:189], v158 offset:3072
	s_add_u32 s22, s20, 0xfffc0080
	s_addc_u32 s23, s21, -1
	s_cmp_eq_u32 s28, 12
	s_cselect_b32 s35, s17, s23
	s_cselect_b32 s34, s24, s22
	s_cselect_b32 s23, s15, s27
	s_cselect_b32 s22, s25, s26
	v_lshl_add_u64 v[150:151], s[20:21], 0, v[138:139]
	s_add_i32 m0, s45, 0xc000
	ds_read_b128 v[190:193], v159
	ds_read_b128 v[194:197], v159 offset:1024
	ds_read_b128 v[198:201], v159 offset:2048
	ds_read_b128 v[202:205], v159 offset:3072
	ds_read_b128 v[206:209], v159 offset:4096
	ds_read_b128 v[210:213], v159 offset:5120
	ds_read_b128 v[214:217], v159 offset:6144
	ds_read_b128 v[218:221], v159 offset:7168
	global_load_lds_dwordx4 v[150:151], off
	v_lshl_add_u64 v[150:151], s[20:21], 0, v[140:141]
	s_add_i32 m0, s45, 0xe000
	s_nop 0
	global_load_lds_dwordx4 v[150:151], off
	s_waitcnt vmcnt(8)
	s_waitcnt lgkmcnt(0)
	s_barrier
	s_waitcnt lgkmcnt(0)
	v_mfma_f32_16x16x32_bf16 v[124:127], v[146:149], v[190:193], v[124:127]
	v_mfma_f32_16x16x32_bf16 v[120:123], v[166:169], v[190:193], v[120:123]
	v_mfma_f32_16x16x32_bf16 v[108:111], v[146:149], v[198:201], v[108:111]
	v_mfma_f32_16x16x32_bf16 v[104:107], v[166:169], v[198:201], v[104:107]
	v_mfma_f32_16x16x32_bf16 v[92:95], v[146:149], v[206:209], v[92:95]
	v_mfma_f32_16x16x32_bf16 v[88:91], v[166:169], v[206:209], v[88:91]
	v_mfma_f32_16x16x32_bf16 v[76:79], v[146:149], v[214:217], v[76:79]
	v_mfma_f32_16x16x32_bf16 v[72:75], v[166:169], v[214:217], v[72:75]
	v_mfma_f32_16x16x32_bf16 v[124:127], v[162:165], v[194:197], v[124:127]
	v_mfma_f32_16x16x32_bf16 v[120:123], v[170:173], v[194:197], v[120:123]
	v_mfma_f32_16x16x32_bf16 v[108:111], v[162:165], v[202:205], v[108:111]
	v_mfma_f32_16x16x32_bf16 v[104:107], v[170:173], v[202:205], v[104:107]
	v_mfma_f32_16x16x32_bf16 v[92:95], v[162:165], v[210:213], v[92:95]
	v_mfma_f32_16x16x32_bf16 v[88:91], v[170:173], v[210:213], v[88:91]
	v_mfma_f32_16x16x32_bf16 v[76:79], v[162:165], v[218:221], v[76:79]
	v_mfma_f32_16x16x32_bf16 v[72:75], v[170:173], v[218:221], v[72:75]
	v_mfma_f32_16x16x32_bf16 v[116:119], v[174:177], v[190:193], v[116:119]
	v_mfma_f32_16x16x32_bf16 v[112:115], v[182:185], v[190:193], v[112:115]
	v_mfma_f32_16x16x32_bf16 v[100:103], v[174:177], v[198:201], v[100:103]
	v_mfma_f32_16x16x32_bf16 v[96:99], v[182:185], v[198:201], v[96:99]
	v_mfma_f32_16x16x32_bf16 v[84:87], v[174:177], v[206:209], v[84:87]
	v_mfma_f32_16x16x32_bf16 v[80:83], v[182:185], v[206:209], v[80:83]
	v_mfma_f32_16x16x32_bf16 v[68:71], v[174:177], v[214:217], v[68:71]
	v_mfma_f32_16x16x32_bf16 v[64:67], v[182:185], v[214:217], v[64:67]
	v_mfma_f32_16x16x32_bf16 v[116:119], v[178:181], v[194:197], v[116:119]
	v_mfma_f32_16x16x32_bf16 v[112:115], v[186:189], v[194:197], v[112:115]
	v_mfma_f32_16x16x32_bf16 v[100:103], v[178:181], v[202:205], v[100:103]
	v_mfma_f32_16x16x32_bf16 v[96:99], v[186:189], v[202:205], v[96:99]
	v_mfma_f32_16x16x32_bf16 v[84:87], v[178:181], v[210:213], v[84:87]
	v_mfma_f32_16x16x32_bf16 v[80:83], v[186:189], v[210:213], v[80:83]
	v_mfma_f32_16x16x32_bf16 v[68:71], v[178:181], v[218:221], v[68:71]
	v_mfma_f32_16x16x32_bf16 v[64:67], v[186:189], v[218:221], v[64:67]
	s_barrier
; #define PG8_STAGE(bufoff, gbase, voff) do { _Pragma("unroll") for (int _i = 0; _i < 2; ++_i) \
;         __builtin_amdgcn_global_load_lds((const unsigned*)((const char*)(gbase) + (voff)[_i]), (PG8_LAS unsigned*)(lds + (bufoff) + ldsw + _i * 8192), 16, 0, PG8_LOAD_AUX); } while (0)
; #define PG8_LDA(dst, b, h) do { _Pragma("unroll") for (int m = 0; m < 4; ++m) _Pragma("unroll") for (int k = 0; k < 2; ++k) dst[m][k] = *(const PG8_LAS bf16x8*)(lds + PG8_SA(b, h) + aoff + m * 2048 + k * 1024); } while (0)
; #define PG8_LDB(dst, b, h) do { _Pragma("unroll") for (int n = 0; n < 2; ++n) _Pragma("unroll") for (int k = 0; k < 2; ++k) dst[n][k] = *(const PG8_LAS bf16x8*)(lds + PG8_SB(b, h) + boff + n * 2048 + k * 1024); } while (0)
; #define PG8_MMA(ai, bj, At, Bt) do { __builtin_amdgcn_s_setprio(1); _Pragma("unroll") for (int m = 0; m < 4; ++m) _Pragma("unroll") for (int n = 0; n < 2; ++n) _Pragma("unroll") for (int k = 0; k < 2; ++k) \
;         acc[ai][bj][m][n] = __builtin_amdgcn_mfma_f32_16x16x32_bf16(Bt[n][k], At[m][k], acc[ai][bj][m][n], 0, 0, 0); __builtin_amdgcn_s_setprio(0); } while (0)
; #define PG8_WAIT_V(n) asm volatile("s_waitcnt vmcnt(" #n ")" ::: "memory")
; #define PG8_WAIT_L(n) asm volatile("s_waitcnt lgkmcnt(" #n ")" ::: "memory")
; #define PG8_BAR __builtin_amdgcn_s_barrier()
; #define PG8_SCHED __builtin_amdgcn_sched_barrier(0)
; template <class Epi, class Sched, bool ALIGN_EPI = false, bool SP2 = false>
; __device__ __forceinline__ void gemm_phase(PG8_LAS unsigned char* lds, const Gemm g, const Sched& S, const Epi& E) {
;     ...
;             PG8_LDA(At, 0, 1); PG8_STAGE(PG8_SB(0, 0), b2, voffB); PG8_STAGE(PG8_SB(0, 1), b2 + hstepB, voffB); PG8_STAGE(PG8_SA(0, 0), a2, voffA);
;             PG8_WAIT_V(8); PG8_WAIT_L(0); PG8_BAR; PG8_MMA(1, 0, At, B0); PG8_MMA(1, 1, At, B1); PG8_BAR; PG8_SCHED;
;             PG8_LDB(B0, 1, 0); PG8_LDB(B1, 1, 1); PG8_SCHED; PG8_LDA(At, 1, 0); PG8_STAGE(PG8_SA(0, 1), a2 + hstepA, voffA);
;             PG8_WAIT_V(8); PG8_WAIT_L(0); PG8_BAR; PG8_MMA(0, 0, At, B0); PG8_MMA(0, 1, At, B1); PG8_BAR; PG8_SCHED;
	s_add_i32 s29, s54, s42
	v_lshl_add_u64 v[150:151], s[22:23], 0, v[132:133]
	s_mov_b32 m0, s29
	ds_read_b128 v[190:193], v159 offset:16384
	ds_read_b128 v[194:197], v159 offset:17408
	ds_read_b128 v[198:201], v159 offset:18432
	ds_read_b128 v[202:205], v159 offset:19456
	ds_read_b128 v[206:209], v159 offset:20480
	ds_read_b128 v[210:213], v159 offset:21504
	ds_read_b128 v[214:217], v159 offset:22528
	ds_read_b128 v[218:221], v159 offset:23552
	global_load_lds_dwordx4 v[150:151], off
	s_add_i32 m0, s29, 0x2000
	s_add_u32 s30, s22, 0x40000
	v_lshl_add_u64 v[222:223], s[22:23], 0, v[128:129]
	s_addc_u32 s31, s23, 0
	s_add_i32 s29, s55, s42
	global_load_lds_dwordx4 v[222:223], off
	v_lshl_add_u64 v[224:225], s[30:31], 0, v[132:133]
	s_mov_b32 m0, s29
	v_lshl_add_u64 v[226:227], s[34:35], 0, v[130:131]
	global_load_lds_dwordx4 v[224:225], off
	v_lshl_add_u64 v[224:225], s[30:31], 0, v[128:129]
	s_add_i32 m0, s29, 0x2000
	s_nop 0
	global_load_lds_dwordx4 v[224:225], off
	v_lshl_add_u64 v[224:225], s[34:35], 0, v[134:135]
	s_mov_b32 m0, s45
	s_nop 0
	global_load_lds_dwordx4 v[224:225], off
	s_mov_b32 m0, s46
	s_nop 0
	global_load_lds_dwordx4 v[226:227], off
	s_waitcnt vmcnt(8)
	s_waitcnt lgkmcnt(0)
	s_barrier
	s_waitcnt lgkmcnt(0)
	v_mfma_f32_16x16x32_bf16 v[60:63], v[146:149], v[190:193], v[60:63]
	v_mfma_f32_16x16x32_bf16 v[56:59], v[166:169], v[190:193], v[56:59]
	v_mfma_f32_16x16x32_bf16 v[44:47], v[146:149], v[198:201], v[44:47]
	v_mfma_f32_16x16x32_bf16 v[40:43], v[166:169], v[198:201], v[40:43]
	v_mfma_f32_16x16x32_bf16 v[28:31], v[146:149], v[206:209], v[28:31]
	v_mfma_f32_16x16x32_bf16 v[24:27], v[166:169], v[206:209], v[24:27]
	v_mfma_f32_16x16x32_bf16 v[12:15], v[146:149], v[214:217], v[12:15]
	v_mfma_f32_16x16x32_bf16 v[8:11], v[166:169], v[214:217], v[8:11]
	v_mfma_f32_16x16x32_bf16 v[60:63], v[162:165], v[194:197], v[60:63]
	v_mfma_f32_16x16x32_bf16 v[56:59], v[170:173], v[194:197], v[56:59]
	v_mfma_f32_16x16x32_bf16 v[44:47], v[162:165], v[202:205], v[44:47]
	v_mfma_f32_16x16x32_bf16 v[40:43], v[170:173], v[202:205], v[40:43]
	v_mfma_f32_16x16x32_bf16 v[28:31], v[162:165], v[210:213], v[28:31]
	v_mfma_f32_16x16x32_bf16 v[24:27], v[170:173], v[210:213], v[24:27]
	v_mfma_f32_16x16x32_bf16 v[12:15], v[162:165], v[218:221], v[12:15]
	v_mfma_f32_16x16x32_bf16 v[8:11], v[170:173], v[218:221], v[8:11]
	v_mfma_f32_16x16x32_bf16 v[52:55], v[174:177], v[190:193], v[52:55]
	v_mfma_f32_16x16x32_bf16 v[48:51], v[182:185], v[190:193], v[48:51]
	v_mfma_f32_16x16x32_bf16 v[36:39], v[174:177], v[198:201], v[36:39]
	v_mfma_f32_16x16x32_bf16 v[32:35], v[182:185], v[198:201], v[32:35]
	v_mfma_f32_16x16x32_bf16 v[20:23], v[174:177], v[206:209], v[20:23]
	v_mfma_f32_16x16x32_bf16 v[16:19], v[182:185], v[206:209], v[16:19]
	v_mfma_f32_16x16x32_bf16 v[4:7], v[174:177], v[214:217], v[4:7]
	v_mfma_f32_16x16x32_bf16 v[0:3], v[182:185], v[214:217], v[0:3]
	v_mfma_f32_16x16x32_bf16 v[52:55], v[178:181], v[194:197], v[52:55]
	v_mfma_f32_16x16x32_bf16 v[48:51], v[186:189], v[194:197], v[48:51]
	v_mfma_f32_16x16x32_bf16 v[36:39], v[178:181], v[202:205], v[36:39]
	v_mfma_f32_16x16x32_bf16 v[32:35], v[186:189], v[202:205], v[32:35]
	v_mfma_f32_16x16x32_bf16 v[20:23], v[178:181], v[210:213], v[20:23]
	v_mfma_f32_16x16x32_bf16 v[16:19], v[186:189], v[210:213], v[16:19]
	v_mfma_f32_16x16x32_bf16 v[4:7], v[178:181], v[218:221], v[4:7]
	v_mfma_f32_16x16x32_bf16 v[0:3], v[186:189], v[218:221], v[0:3]
	s_barrier
.Lkmid_P12:
	s_add_i32 s29, 0, 0x18000
	s_add_i32 s33, 0, 0x1c000
	v_add_u32_e32 v170, s29, v155
	v_add_u32_e32 v186, s33, v155
	ds_read_b128 v[146:149], v170
	ds_read_b128 v[162:165], v170 offset:1024
	ds_read_b128 v[166:169], v170 offset:2048
	ds_read_b128 v[170:173], v170 offset:3072
	ds_read_b128 v[174:177], v186
	ds_read_b128 v[178:181], v186 offset:1024
	ds_read_b128 v[182:185], v186 offset:2048
	ds_read_b128 v[186:189], v186 offset:3072
	s_add_u32 s30, s34, 0x40000
	s_addc_u32 s31, s35, 0
	s_mov_b32 m0, s47
	v_lshl_add_u64 v[228:229], s[30:31], 0, v[134:135]
	ds_read_b128 v[190:193], v159 offset:32768
	ds_read_b128 v[194:197], v159 offset:33792
	ds_read_b128 v[198:201], v159 offset:34816
	ds_read_b128 v[202:205], v159 offset:35840
	ds_read_b128 v[206:209], v159 offset:36864
	ds_read_b128 v[210:213], v159 offset:37888
	ds_read_b128 v[214:217], v159 offset:38912
	ds_read_b128 v[218:221], v159 offset:39936
	global_load_lds_dwordx4 v[228:229], off
	v_lshl_add_u64 v[228:229], s[30:31], 0, v[130:131]
	s_mov_b32 m0, s48
	s_nop 0
	global_load_lds_dwordx4 v[228:229], off
	s_waitcnt vmcnt(8)
	s_waitcnt lgkmcnt(0)
	s_barrier
; #define PG8_STAGE(bufoff, gbase, voff) do { _Pragma("unroll") for (int _i = 0; _i < 2; ++_i) \
;         __builtin_amdgcn_global_load_lds((const unsigned*)((const char*)(gbase) + (voff)[_i]), (PG8_LAS unsigned*)(lds + (bufoff) + ldsw + _i * 8192), 16, 0, PG8_LOAD_AUX); } while (0)
; #define PG8_LDA(dst, b, h) do { _Pragma("unroll") for (int m = 0; m < 4; ++m) _Pragma("unroll") for (int k = 0; k < 2; ++k) dst[m][k] = *(const PG8_LAS bf16x8*)(lds + PG8_SA(b, h) + aoff + m * 2048 + k * 1024); } while (0)
; #define PG8_LDB(dst, b, h) do { _Pragma("unroll") for (int n = 0; n < 2; ++n) _Pragma("unroll") for (int k = 0; k < 2; ++k) dst[n][k] = *(const PG8_LAS bf16x8*)(lds + PG8_SB(b, h) + boff + n * 2048 + k * 1024); } while (0)
; #define PG8_MMA(ai, bj, At, Bt) do { __builtin_amdgcn_s_setprio(1); _Pragma("unroll") for (int m = 0; m < 4; ++m) _Pragma("unroll") for (int n = 0; n < 2; ++n) _Pragma("unroll") for (int k = 0; k < 2; ++k) \
;         acc[ai][bj][m][n] = __builtin_amdgcn_mfma_f32_16x16x32_bf16(Bt[n][k], At[m][k], acc[ai][bj][m][n], 0, 0, 0); __builtin_amdgcn_s_setprio(0); } while (0)
; #define PG8_WAIT_V(n) asm volatile("s_waitcnt vmcnt(" #n ")" ::: "memory")
; #define PG8_WAIT_L(n) asm volatile("s_waitcnt lgkmcnt(" #n ")" ::: "memory")
; #define PG8_BAR __builtin_amdgcn_s_barrier()
; #define PG8_SCHED __builtin_amdgcn_sched_barrier(0)
; __device__ __forceinline__ float rstd_from_slots(const float* slots, int row, int fq) {
;     const f32x4 s4 = *(const f32x4*)(slots + (size_t)row * 16 + 4 * fq);
; template <class Epi, class Sched, bool ALIGN_EPI = false, bool SP2 = false>
; __device__ __forceinline__ void gemm_phase(PG8_LAS unsigned char* lds, const Gemm g, const Sched& S, const Epi& E) {
;     ...
;             PG8_LDB(B0, 1, 0); PG8_LDB(B1, 1, 1); PG8_SCHED; PG8_LDA(At, 1, 0); PG8_STAGE(PG8_SA(0, 1), a2 + hstepA, voffA);
;             PG8_WAIT_V(8); PG8_WAIT_L(0); PG8_BAR; PG8_MMA(0, 0, At, B0); PG8_MMA(0, 1, At, B1); PG8_BAR; PG8_SCHED;
;             PG8_LDA(At, 1, 1); PG8_STAGE(PG8_SB(1, 0), b3, voffB); PG8_STAGE(PG8_SB(1, 1), b3 + hstepB, voffB); PG8_STAGE(PG8_SA(1, 0), a3, voffA);
;             PG8_WAIT_V(8); PG8_WAIT_L(0); PG8_BAR; PG8_MMA(1, 0, At, B0); PG8_MMA(1, 1, At, B1); PG8_BAR; PG8_SCHED;
	s_waitcnt lgkmcnt(0)
	v_mfma_f32_16x16x32_bf16 v[124:127], v[146:149], v[190:193], v[124:127]
	v_mfma_f32_16x16x32_bf16 v[120:123], v[166:169], v[190:193], v[120:123]
	v_mfma_f32_16x16x32_bf16 v[108:111], v[146:149], v[198:201], v[108:111]
	v_mfma_f32_16x16x32_bf16 v[104:107], v[166:169], v[198:201], v[104:107]
	v_mfma_f32_16x16x32_bf16 v[92:95], v[146:149], v[206:209], v[92:95]
	v_mfma_f32_16x16x32_bf16 v[88:91], v[166:169], v[206:209], v[88:91]
	v_mfma_f32_16x16x32_bf16 v[76:79], v[146:149], v[214:217], v[76:79]
	v_mfma_f32_16x16x32_bf16 v[72:75], v[166:169], v[214:217], v[72:75]
	v_mfma_f32_16x16x32_bf16 v[124:127], v[162:165], v[194:197], v[124:127]
	v_mfma_f32_16x16x32_bf16 v[120:123], v[170:173], v[194:197], v[120:123]
	v_mfma_f32_16x16x32_bf16 v[108:111], v[162:165], v[202:205], v[108:111]
	v_mfma_f32_16x16x32_bf16 v[104:107], v[170:173], v[202:205], v[104:107]
	v_mfma_f32_16x16x32_bf16 v[92:95], v[162:165], v[210:213], v[92:95]
	v_mfma_f32_16x16x32_bf16 v[88:91], v[170:173], v[210:213], v[88:91]
	v_mfma_f32_16x16x32_bf16 v[76:79], v[162:165], v[218:221], v[76:79]
	v_mfma_f32_16x16x32_bf16 v[72:75], v[170:173], v[218:221], v[72:75]
	v_mfma_f32_16x16x32_bf16 v[116:119], v[174:177], v[190:193], v[116:119]
	v_mfma_f32_16x16x32_bf16 v[112:115], v[182:185], v[190:193], v[112:115]
	v_mfma_f32_16x16x32_bf16 v[100:103], v[174:177], v[198:201], v[100:103]
	v_mfma_f32_16x16x32_bf16 v[96:99], v[182:185], v[198:201], v[96:99]
	v_mfma_f32_16x16x32_bf16 v[84:87], v[174:177], v[206:209], v[84:87]
	v_mfma_f32_16x16x32_bf16 v[80:83], v[182:185], v[206:209], v[80:83]
	v_mfma_f32_16x16x32_bf16 v[68:71], v[174:177], v[214:217], v[68:71]
	v_mfma_f32_16x16x32_bf16 v[64:67], v[182:185], v[214:217], v[64:67]
	v_mfma_f32_16x16x32_bf16 v[116:119], v[178:181], v[194:197], v[116:119]
	v_mfma_f32_16x16x32_bf16 v[112:115], v[186:189], v[194:197], v[112:115]
	v_mfma_f32_16x16x32_bf16 v[100:103], v[178:181], v[202:205], v[100:103]
	v_mfma_f32_16x16x32_bf16 v[96:99], v[186:189], v[202:205], v[96:99]
	v_mfma_f32_16x16x32_bf16 v[84:87], v[178:181], v[210:213], v[84:87]
	v_mfma_f32_16x16x32_bf16 v[80:83], v[186:189], v[210:213], v[80:83]
	v_mfma_f32_16x16x32_bf16 v[68:71], v[178:181], v[218:221], v[68:71]
	v_mfma_f32_16x16x32_bf16 v[64:67], v[186:189], v[218:221], v[64:67]
	s_barrier
	s_add_i32 s29, s29, s42
	v_lshl_add_u64 v[150:151], v[150:151], 0, s[8:9]
	s_mov_b32 m0, s29
	ds_read_b128 v[190:193], v159 offset:49152
	ds_read_b128 v[194:197], v159 offset:50176
	ds_read_b128 v[198:201], v159 offset:51200
	ds_read_b128 v[202:205], v159 offset:52224
	ds_read_b128 v[206:209], v159 offset:53248
	ds_read_b128 v[210:213], v159 offset:54272
	ds_read_b128 v[214:217], v159 offset:55296
	ds_read_b128 v[218:221], v159 offset:56320
	global_load_lds_dwordx4 v[150:151], off
	s_add_i32 m0, s29, 0x2000
	s_add_u32 s22, s22, 0x40080
	v_lshl_add_u64 v[150:151], v[222:223], 0, s[8:9]
	s_addc_u32 s23, s23, 0
	s_add_i32 s29, s33, s42
	global_load_lds_dwordx4 v[150:151], off
	v_lshl_add_u64 v[150:151], s[22:23], 0, v[132:133]
	s_mov_b32 m0, s29
	s_nop 0
	global_load_lds_dwordx4 v[150:151], off
	v_lshl_add_u64 v[150:151], s[22:23], 0, v[128:129]
	s_add_i32 m0, s29, 0x2000
	s_nop 0
	global_load_lds_dwordx4 v[150:151], off
	v_lshl_add_u64 v[150:151], v[224:225], 0, s[8:9]
	s_mov_b32 m0, s50
	s_nop 0
	global_load_lds_dwordx4 v[150:151], off
	v_lshl_add_u64 v[150:151], v[226:227], 0, s[8:9]
	s_mov_b32 m0, s51
	s_nop 0
	global_load_lds_dwordx4 v[150:151], off
	s_waitcnt vmcnt(8)
	s_waitcnt lgkmcnt(0)
	s_barrier
	s_waitcnt lgkmcnt(0)
	v_mfma_f32_16x16x32_bf16 v[60:63], v[146:149], v[190:193], v[60:63]
	v_mfma_f32_16x16x32_bf16 v[56:59], v[166:169], v[190:193], v[56:59]
	v_mfma_f32_16x16x32_bf16 v[44:47], v[146:149], v[198:201], v[44:47]
	v_mfma_f32_16x16x32_bf16 v[40:43], v[166:169], v[198:201], v[40:43]
	v_mfma_f32_16x16x32_bf16 v[28:31], v[146:149], v[206:209], v[28:31]
	v_mfma_f32_16x16x32_bf16 v[24:27], v[166:169], v[206:209], v[24:27]
	v_mfma_f32_16x16x32_bf16 v[12:15], v[146:149], v[214:217], v[12:15]
	v_mfma_f32_16x16x32_bf16 v[8:11], v[166:169], v[214:217], v[8:11]
	v_mfma_f32_16x16x32_bf16 v[60:63], v[162:165], v[194:197], v[60:63]
	v_mfma_f32_16x16x32_bf16 v[56:59], v[170:173], v[194:197], v[56:59]
	v_mfma_f32_16x16x32_bf16 v[44:47], v[162:165], v[202:205], v[44:47]
	v_mfma_f32_16x16x32_bf16 v[40:43], v[170:173], v[202:205], v[40:43]
	v_mfma_f32_16x16x32_bf16 v[28:31], v[162:165], v[210:213], v[28:31]
	v_mfma_f32_16x16x32_bf16 v[24:27], v[170:173], v[210:213], v[24:27]
	v_mfma_f32_16x16x32_bf16 v[12:15], v[162:165], v[218:221], v[12:15]
	v_mfma_f32_16x16x32_bf16 v[8:11], v[170:173], v[218:221], v[8:11]
	v_mfma_f32_16x16x32_bf16 v[52:55], v[174:177], v[190:193], v[52:55]
	v_mfma_f32_16x16x32_bf16 v[48:51], v[182:185], v[190:193], v[48:51]
	v_mfma_f32_16x16x32_bf16 v[36:39], v[174:177], v[198:201], v[36:39]
	v_mfma_f32_16x16x32_bf16 v[32:35], v[182:185], v[198:201], v[32:35]
	v_mfma_f32_16x16x32_bf16 v[20:23], v[174:177], v[206:209], v[20:23]
	v_mfma_f32_16x16x32_bf16 v[16:19], v[182:185], v[206:209], v[16:19]
	v_mfma_f32_16x16x32_bf16 v[4:7], v[174:177], v[214:217], v[4:7]
	v_mfma_f32_16x16x32_bf16 v[0:3], v[182:185], v[214:217], v[0:3]
	v_mfma_f32_16x16x32_bf16 v[52:55], v[178:181], v[194:197], v[52:55]
	v_mfma_f32_16x16x32_bf16 v[48:51], v[186:189], v[194:197], v[48:51]
	v_mfma_f32_16x16x32_bf16 v[36:39], v[178:181], v[202:205], v[36:39]
	v_mfma_f32_16x16x32_bf16 v[32:35], v[186:189], v[202:205], v[32:35]
	v_mfma_f32_16x16x32_bf16 v[20:23], v[178:181], v[210:213], v[20:23]
	v_mfma_f32_16x16x32_bf16 v[16:19], v[186:189], v[210:213], v[16:19]
	v_mfma_f32_16x16x32_bf16 v[4:7], v[178:181], v[218:221], v[4:7]
	v_mfma_f32_16x16x32_bf16 v[0:3], v[186:189], v[218:221], v[0:3]
	s_barrier
	s_add_i32 s28, s28, 2
	s_add_u32 s20, s20, 0x100
	s_addc_u32 s21, s21, 0
	s_add_u32 s26, s26, 0x100
	s_addc_u32 s27, s27, 0
	s_cmp_gt_u32 s28, 13
	s_cbranch_scc0 .LBB0_1111
	v_lshl_add_u32 v204, s0, 8, v152
	v_ashrrev_i32_e32 v205, 31, v204
	v_lshlrev_b64 v[204:205], 6, v[204:205]
	v_lshl_add_u64 v[204:205], v[136:137], 0, v[204:205]
	v_add_co_u32_e32 v206, vcc, 0x2000, v204
	s_nop 1
	v_addc_co_u32_e32 v207, vcc, 0, v205, vcc
	global_load_dwordx4 v[172:175], v[204:205], off
	global_load_dwordx4 v[176:179], v[204:205], off offset:1024
	global_load_dwordx4 v[180:183], v[204:205], off offset:2048
	global_load_dwordx4 v[184:187], v[204:205], off offset:3072
	global_load_dwordx4 v[188:191], v[206:207], off
	global_load_dwordx4 v[192:195], v[206:207], off offset:1024
	global_load_dwordx4 v[196:199], v[206:207], off offset:2048
	global_load_dwordx4 v[200:203], v[206:207], off offset:3072
	s_and_b64 vcc, exec, s[12:13]
	s_cbranch_vccz .LBB0_1114
	s_barrier

; #define PG8_STAGE(bufoff, gbase, voff) do { _Pragma("unroll") for (int _i = 0; _i < 2; ++_i) \
;         __builtin_amdgcn_global_load_lds((const unsigned*)((const char*)(gbase) + (voff)[_i]), (PG8_LAS unsigned*)(lds + (bufoff) + ldsw + _i * 8192), 16, 0, PG8_LOAD_AUX); } while (0)
; #define PG8_LDA(dst, b, h) do { _Pragma("unroll") for (int m = 0; m < 4; ++m) _Pragma("unroll") for (int k = 0; k < 2; ++k) dst[m][k] = *(const PG8_LAS bf16x8*)(lds + PG8_SA(b, h) + aoff + m * 2048 + k * 1024); } while (0)
; #define PG8_LDB(dst, b, h) do { _Pragma("unroll") for (int n = 0; n < 2; ++n) _Pragma("unroll") for (int k = 0; k < 2; ++k) dst[n][k] = *(const PG8_LAS bf16x8*)(lds + PG8_SB(b, h) + boff + n * 2048 + k * 1024); } while (0)
; #define PG8_MMA(ai, bj, At, Bt) do { __builtin_amdgcn_s_setprio(1); _Pragma("unroll") for (int m = 0; m < 4; ++m) _Pragma("unroll") for (int n = 0; n < 2; ++n) _Pragma("unroll") for (int k = 0; k < 2; ++k) \
;         acc[ai][bj][m][n] = __builtin_amdgcn_mfma_f32_16x16x32_bf16(Bt[n][k], At[m][k], acc[ai][bj][m][n], 0, 0, 0); __builtin_amdgcn_s_setprio(0); } while (0)
; #define PG8_WAIT_V(n) asm volatile("s_waitcnt vmcnt(" #n ")" ::: "memory")
; #define PG8_WAIT_L(n) asm volatile("s_waitcnt lgkmcnt(" #n ")" ::: "memory")
; #define PG8_BAR __builtin_amdgcn_s_barrier()
; template <class Epi, class Sched, bool ALIGN_EPI = false, bool SP2 = false>
; __device__ __forceinline__ void gemm_phase(PG8_LAS unsigned char* lds, const Gemm g, const Sched& S, const Epi& E) {
;     ...
;             const char* a1 = cA + (size_t)(t + 1) * kstep;
;             const char* a2 = last ? nA : cA + (size_t)(t + 2) * kstep; const char* b2 = last ? nB : cB + (size_t)(t + 2) * kstep;
;             const char* a3 = a2 + kstep; const char* b3 = b2 + kstep;
;             if (last && has_next) S.a_ready(nxt);
;             if constexpr (SP2) {
;             PG8_LDB(B0, 0, 0); PG8_LDB(B1, 0, 1); PG8_SCHED; PG8_LDA(At, 0, 0); PG8_STAGE(PG8_SA(1, 1), a1 + hstepA, voffA);
;             PG8_WAIT_V(8); PG8_WAIT_L(0); PG8_BAR; PG8_MMA(0, 0, At, B0); PG8_MMA(0, 1, At, B1); PG8_BAR; PG8_SCHED;
;             PG8_LDA(At, 0, 1); PG8_STAGE(PG8_SB(0, 0), b2, voffB); PG8_STAGE(PG8_SB(0, 1), b2 + hstepB, voffB); PG8_STAGE(PG8_SA(0, 0), a2, voffA);
;             PG8_WAIT_V(8); PG8_WAIT_L(0); PG8_BAR; PG8_MMA(1, 0, At, B0); PG8_MMA(1, 1, At, B1); PG8_BAR; PG8_SCHED;
.LBB0_1195:
	s_add_u32 s0, s0, 0xb0080
	s_addc_u32 s1, s1, 0
	s_add_u32 s25, s20, 0x100
	s_addc_u32 s26, s21, 0
	s_mov_b32 s27, -2
	s_waitcnt lgkmcnt(0)
	ds_read_b128 v[146:149], v155
	ds_read_b128 v[160:163], v155 offset:1024
	ds_read_b128 v[164:167], v155 offset:2048
	ds_read_b128 v[168:171], v155 offset:3072
	ds_read_b128 v[172:175], v156
	ds_read_b128 v[176:179], v156 offset:1024
	ds_read_b128 v[180:183], v156 offset:2048
	ds_read_b128 v[184:187], v156 offset:3072
	s_add_u32 s20, s0, 0xfff50080
	s_addc_u32 s21, s1, -1
	s_cmp_eq_u32 s27, 40
	s_cselect_b32 s23, s9, s21
	s_cselect_b32 s22, s8, s20
	s_cselect_b32 s21, s41, s26
	s_cselect_b32 s20, s40, s25
	v_lshl_add_u64 v[220:221], s[0:1], 0, v[138:139]
	s_add_i32 m0, s43, 0xc000
	ds_read_b128 v[188:191], v157
	ds_read_b128 v[192:195], v157 offset:1024
	ds_read_b128 v[196:199], v157 offset:2048
	ds_read_b128 v[200:203], v157 offset:3072
	ds_read_b128 v[204:207], v157 offset:4096
	ds_read_b128 v[208:211], v157 offset:5120
	ds_read_b128 v[212:215], v157 offset:6144
	ds_read_b128 v[216:219], v157 offset:7168
	global_load_lds_dwordx4 v[220:221], off
	v_lshl_add_u64 v[220:221], s[0:1], 0, v[140:141]
	s_add_i32 m0, s43, 0xe000
	s_nop 0
	global_load_lds_dwordx4 v[220:221], off
	s_waitcnt vmcnt(8)
	s_waitcnt lgkmcnt(0)
	s_barrier
	s_waitcnt lgkmcnt(0)
	v_mfma_f32_16x16x32_bf16 v[124:127], v[146:149], v[188:191], 0
	v_mfma_f32_16x16x32_bf16 v[120:123], v[164:167], v[188:191], 0
	v_mfma_f32_16x16x32_bf16 v[108:111], v[146:149], v[196:199], 0
	v_mfma_f32_16x16x32_bf16 v[104:107], v[164:167], v[196:199], 0
	v_mfma_f32_16x16x32_bf16 v[92:95], v[146:149], v[204:207], 0
	v_mfma_f32_16x16x32_bf16 v[88:91], v[164:167], v[204:207], 0
	v_mfma_f32_16x16x32_bf16 v[76:79], v[146:149], v[212:215], 0
	v_mfma_f32_16x16x32_bf16 v[72:75], v[164:167], v[212:215], 0
	v_mfma_f32_16x16x32_bf16 v[124:127], v[160:163], v[192:195], v[124:127]
	v_mfma_f32_16x16x32_bf16 v[120:123], v[168:171], v[192:195], v[120:123]
	v_mfma_f32_16x16x32_bf16 v[108:111], v[160:163], v[200:203], v[108:111]
	v_mfma_f32_16x16x32_bf16 v[104:107], v[168:171], v[200:203], v[104:107]
	v_mfma_f32_16x16x32_bf16 v[92:95], v[160:163], v[208:211], v[92:95]
	v_mfma_f32_16x16x32_bf16 v[88:91], v[168:171], v[208:211], v[88:91]
	v_mfma_f32_16x16x32_bf16 v[76:79], v[160:163], v[216:219], v[76:79]
	v_mfma_f32_16x16x32_bf16 v[72:75], v[168:171], v[216:219], v[72:75]
	v_mfma_f32_16x16x32_bf16 v[116:119], v[172:175], v[188:191], 0
	v_mfma_f32_16x16x32_bf16 v[112:115], v[180:183], v[188:191], 0
	v_mfma_f32_16x16x32_bf16 v[100:103], v[172:175], v[196:199], 0
	v_mfma_f32_16x16x32_bf16 v[96:99], v[180:183], v[196:199], 0
	v_mfma_f32_16x16x32_bf16 v[84:87], v[172:175], v[204:207], 0
	v_mfma_f32_16x16x32_bf16 v[80:83], v[180:183], v[204:207], 0
	v_mfma_f32_16x16x32_bf16 v[68:71], v[172:175], v[212:215], 0
	v_mfma_f32_16x16x32_bf16 v[64:67], v[180:183], v[212:215], 0
	v_mfma_f32_16x16x32_bf16 v[116:119], v[176:179], v[192:195], v[116:119]
	v_mfma_f32_16x16x32_bf16 v[112:115], v[184:187], v[192:195], v[112:115]
	v_mfma_f32_16x16x32_bf16 v[100:103], v[176:179], v[200:203], v[100:103]
	v_mfma_f32_16x16x32_bf16 v[96:99], v[184:187], v[200:203], v[96:99]
	v_mfma_f32_16x16x32_bf16 v[84:87], v[176:179], v[208:211], v[84:87]
	v_mfma_f32_16x16x32_bf16 v[80:83], v[184:187], v[208:211], v[80:83]
	v_mfma_f32_16x16x32_bf16 v[68:71], v[176:179], v[216:219], v[68:71]
	v_mfma_f32_16x16x32_bf16 v[64:67], v[184:187], v[216:219], v[64:67]
	s_barrier
	s_add_i32 s28, s55, s42
	v_lshl_add_u64 v[220:221], s[20:21], 0, v[130:131]
	s_mov_b32 m0, s28
	ds_read_b128 v[188:191], v157 offset:16384
	ds_read_b128 v[192:195], v157 offset:17408
	ds_read_b128 v[196:199], v157 offset:18432
	ds_read_b128 v[200:203], v157 offset:19456
	ds_read_b128 v[204:207], v157 offset:20480
	ds_read_b128 v[208:211], v157 offset:21504
	ds_read_b128 v[212:215], v157 offset:22528
	ds_read_b128 v[216:219], v157 offset:23552
	global_load_lds_dwordx4 v[220:221], off
	s_add_i32 m0, s28, 0x2000
	s_add_u32 s28, s20, 0x2c000
	v_lshl_add_u64 v[222:223], s[20:21], 0, v[134:135]
	s_addc_u32 s29, s21, 0
	s_add_i32 s30, s56, s42
	global_load_lds_dwordx4 v[222:223], off
	v_lshl_add_u64 v[224:225], s[28:29], 0, v[130:131]
	s_mov_b32 m0, s30
	v_lshl_add_u64 v[226:227], s[22:23], 0, v[132:133]
	global_load_lds_dwordx4 v[224:225], off
	v_lshl_add_u64 v[224:225], s[28:29], 0, v[134:135]
	s_add_i32 m0, s30, 0x2000
	s_nop 0
	global_load_lds_dwordx4 v[224:225], off
	v_lshl_add_u64 v[224:225], s[22:23], 0, v[128:129]
	s_mov_b32 m0, s43
	s_nop 0
	global_load_lds_dwordx4 v[224:225], off
	s_mov_b32 m0, s44
	s_nop 0
	global_load_lds_dwordx4 v[226:227], off
	s_waitcnt vmcnt(8)
	s_waitcnt lgkmcnt(0)
	s_barrier
	s_waitcnt lgkmcnt(0)
	v_mfma_f32_16x16x32_bf16 v[60:63], v[146:149], v[188:191], 0
	v_mfma_f32_16x16x32_bf16 v[56:59], v[164:167], v[188:191], 0
	v_mfma_f32_16x16x32_bf16 v[44:47], v[146:149], v[196:199], 0
	v_mfma_f32_16x16x32_bf16 v[40:43], v[164:167], v[196:199], 0
	v_mfma_f32_16x16x32_bf16 v[28:31], v[146:149], v[204:207], 0
	v_mfma_f32_16x16x32_bf16 v[24:27], v[164:167], v[204:207], 0
	v_mfma_f32_16x16x32_bf16 v[12:15], v[146:149], v[212:215], 0
	v_mfma_f32_16x16x32_bf16 v[8:11], v[164:167], v[212:215], 0
	v_mfma_f32_16x16x32_bf16 v[60:63], v[160:163], v[192:195], v[60:63]
	v_mfma_f32_16x16x32_bf16 v[56:59], v[168:171], v[192:195], v[56:59]
	v_mfma_f32_16x16x32_bf16 v[44:47], v[160:163], v[200:203], v[44:47]
	v_mfma_f32_16x16x32_bf16 v[40:43], v[168:171], v[200:203], v[40:43]
	v_mfma_f32_16x16x32_bf16 v[28:31], v[160:163], v[208:211], v[28:31]
	v_mfma_f32_16x16x32_bf16 v[24:27], v[168:171], v[208:211], v[24:27]
	v_mfma_f32_16x16x32_bf16 v[12:15], v[160:163], v[216:219], v[12:15]
	v_mfma_f32_16x16x32_bf16 v[8:11], v[168:171], v[216:219], v[8:11]
	v_mfma_f32_16x16x32_bf16 v[52:55], v[172:175], v[188:191], 0
	v_mfma_f32_16x16x32_bf16 v[48:51], v[180:183], v[188:191], 0
	v_mfma_f32_16x16x32_bf16 v[36:39], v[172:175], v[196:199], 0
	v_mfma_f32_16x16x32_bf16 v[32:35], v[180:183], v[196:199], 0
	v_mfma_f32_16x16x32_bf16 v[20:23], v[172:175], v[204:207], 0
	v_mfma_f32_16x16x32_bf16 v[16:19], v[180:183], v[204:207], 0
	v_mfma_f32_16x16x32_bf16 v[4:7], v[172:175], v[212:215], 0
	v_mfma_f32_16x16x32_bf16 v[0:3], v[180:183], v[212:215], 0
	v_mfma_f32_16x16x32_bf16 v[52:55], v[176:179], v[192:195], v[52:55]
	v_mfma_f32_16x16x32_bf16 v[48:51], v[184:187], v[192:195], v[48:51]
	v_mfma_f32_16x16x32_bf16 v[36:39], v[176:179], v[200:203], v[36:39]
	v_mfma_f32_16x16x32_bf16 v[32:35], v[184:187], v[200:203], v[32:35]
	v_mfma_f32_16x16x32_bf16 v[20:23], v[176:179], v[208:211], v[20:23]
	v_mfma_f32_16x16x32_bf16 v[16:19], v[184:187], v[208:211], v[16:19]
	v_mfma_f32_16x16x32_bf16 v[4:7], v[176:179], v[216:219], v[4:7]
	v_mfma_f32_16x16x32_bf16 v[0:3], v[184:187], v[216:219], v[0:3]
	s_barrier
	s_branch .Lkmid_P13
; #define PG8_STAGE(bufoff, gbase, voff) do { _Pragma("unroll") for (int _i = 0; _i < 2; ++_i) \
;         __builtin_amdgcn_global_load_lds((const unsigned*)((const char*)(gbase) + (voff)[_i]), (PG8_LAS unsigned*)(lds + (bufoff) + ldsw + _i * 8192), 16, 0, PG8_LOAD_AUX); } while (0)
; #define PG8_LDA(dst, b, h) do { _Pragma("unroll") for (int m = 0; m < 4; ++m) _Pragma("unroll") for (int k = 0; k < 2; ++k) dst[m][k] = *(const PG8_LAS bf16x8*)(lds + PG8_SA(b, h) + aoff + m * 2048 + k * 1024); } while (0)
; #define PG8_LDB(dst, b, h) do { _Pragma("unroll") for (int n = 0; n < 2; ++n) _Pragma("unroll") for (int k = 0; k < 2; ++k) dst[n][k] = *(const PG8_LAS bf16x8*)(lds + PG8_SB(b, h) + boff + n * 2048 + k * 1024); } while (0)
; #define PG8_MMA(ai, bj, At, Bt) do { __builtin_amdgcn_s_setprio(1); _Pragma("unroll") for (int m = 0; m < 4; ++m) _Pragma("unroll") for (int n = 0; n < 2; ++n) _Pragma("unroll") for (int k = 0; k < 2; ++k) \
;         acc[ai][bj][m][n] = __builtin_amdgcn_mfma_f32_16x16x32_bf16(Bt[n][k], At[m][k], acc[ai][bj][m][n], 0, 0, 0); __builtin_amdgcn_s_setprio(0); } while (0)
; #define PG8_WAIT_V(n) asm volatile("s_waitcnt vmcnt(" #n ")" ::: "memory")
; #define PG8_WAIT_L(n) asm volatile("s_waitcnt lgkmcnt(" #n ")" ::: "memory")
; #define PG8_BAR __builtin_amdgcn_s_barrier()
; #define PG8_SCHED __builtin_amdgcn_sched_barrier(0)
; template <class Epi, class Sched, bool ALIGN_EPI = false, bool SP2 = false>
; __device__ __forceinline__ void gemm_phase(PG8_LAS unsigned char* lds, const Gemm g, const Sched& S, const Epi& E) {
;     ...
;             PG8_LDB(B0, 0, 0); PG8_LDB(B1, 0, 1); PG8_SCHED; PG8_LDA(At, 0, 0); PG8_STAGE(PG8_SA(1, 1), a1 + hstepA, voffA);
;             PG8_WAIT_V(8); PG8_WAIT_L(0); PG8_BAR; PG8_MMA(0, 0, At, B0); PG8_MMA(0, 1, At, B1); PG8_BAR; PG8_SCHED;
;             PG8_LDA(At, 0, 1); PG8_STAGE(PG8_SB(0, 0), b2, voffB); PG8_STAGE(PG8_SB(0, 1), b2 + hstepB, voffB); PG8_STAGE(PG8_SA(0, 0), a2, voffA);
;             PG8_WAIT_V(8); PG8_WAIT_L(0); PG8_BAR; PG8_MMA(1, 0, At, B0); PG8_MMA(1, 1, At, B1); PG8_BAR; PG8_SCHED;
.LBB0_1196:
	ds_read_b128 v[146:149], v155
	ds_read_b128 v[160:163], v155 offset:1024
	ds_read_b128 v[164:167], v155 offset:2048
	ds_read_b128 v[168:171], v155 offset:3072
	ds_read_b128 v[172:175], v156
	ds_read_b128 v[176:179], v156 offset:1024
	ds_read_b128 v[180:183], v156 offset:2048
	ds_read_b128 v[184:187], v156 offset:3072
	s_add_u32 s20, s0, 0xfff50080
	s_addc_u32 s21, s1, -1
	s_cmp_eq_u32 s27, 40
	s_cselect_b32 s23, s9, s21
	s_cselect_b32 s22, s8, s20
	s_cselect_b32 s21, s41, s26
	s_cselect_b32 s20, s40, s25
	v_lshl_add_u64 v[220:221], s[0:1], 0, v[138:139]
	s_add_i32 m0, s43, 0xc000
	ds_read_b128 v[188:191], v157
	ds_read_b128 v[192:195], v157 offset:1024
	ds_read_b128 v[196:199], v157 offset:2048
	ds_read_b128 v[200:203], v157 offset:3072
	ds_read_b128 v[204:207], v157 offset:4096
	ds_read_b128 v[208:211], v157 offset:5120
	ds_read_b128 v[212:215], v157 offset:6144
	ds_read_b128 v[216:219], v157 offset:7168
	global_load_lds_dwordx4 v[220:221], off
	v_lshl_add_u64 v[220:221], s[0:1], 0, v[140:141]
	s_add_i32 m0, s43, 0xe000
	s_nop 0
	global_load_lds_dwordx4 v[220:221], off
	s_waitcnt vmcnt(8)
	s_waitcnt lgkmcnt(0)
	s_barrier
	s_waitcnt lgkmcnt(0)
	v_mfma_f32_16x16x32_bf16 v[124:127], v[146:149], v[188:191], v[124:127]
	v_mfma_f32_16x16x32_bf16 v[120:123], v[164:167], v[188:191], v[120:123]
	v_mfma_f32_16x16x32_bf16 v[108:111], v[146:149], v[196:199], v[108:111]
	v_mfma_f32_16x16x32_bf16 v[104:107], v[164:167], v[196:199], v[104:107]
	v_mfma_f32_16x16x32_bf16 v[92:95], v[146:149], v[204:207], v[92:95]
	v_mfma_f32_16x16x32_bf16 v[88:91], v[164:167], v[204:207], v[88:91]
	v_mfma_f32_16x16x32_bf16 v[76:79], v[146:149], v[212:215], v[76:79]
	v_mfma_f32_16x16x32_bf16 v[72:75], v[164:167], v[212:215], v[72:75]
	v_mfma_f32_16x16x32_bf16 v[124:127], v[160:163], v[192:195], v[124:127]
	v_mfma_f32_16x16x32_bf16 v[120:123], v[168:171], v[192:195], v[120:123]
	v_mfma_f32_16x16x32_bf16 v[108:111], v[160:163], v[200:203], v[108:111]
	v_mfma_f32_16x16x32_bf16 v[104:107], v[168:171], v[200:203], v[104:107]
	v_mfma_f32_16x16x32_bf16 v[92:95], v[160:163], v[208:211], v[92:95]
	v_mfma_f32_16x16x32_bf16 v[88:91], v[168:171], v[208:211], v[88:91]
	v_mfma_f32_16x16x32_bf16 v[76:79], v[160:163], v[216:219], v[76:79]
	v_mfma_f32_16x16x32_bf16 v[72:75], v[168:171], v[216:219], v[72:75]
	v_mfma_f32_16x16x32_bf16 v[116:119], v[172:175], v[188:191], v[116:119]
	v_mfma_f32_16x16x32_bf16 v[112:115], v[180:183], v[188:191], v[112:115]
	v_mfma_f32_16x16x32_bf16 v[100:103], v[172:175], v[196:199], v[100:103]
	v_mfma_f32_16x16x32_bf16 v[96:99], v[180:183], v[196:199], v[96:99]
	v_mfma_f32_16x16x32_bf16 v[84:87], v[172:175], v[204:207], v[84:87]
	v_mfma_f32_16x16x32_bf16 v[80:83], v[180:183], v[204:207], v[80:83]
	v_mfma_f32_16x16x32_bf16 v[68:71], v[172:175], v[212:215], v[68:71]
	v_mfma_f32_16x16x32_bf16 v[64:67], v[180:183], v[212:215], v[64:67]
	v_mfma_f32_16x16x32_bf16 v[116:119], v[176:179], v[192:195], v[116:119]
	v_mfma_f32_16x16x32_bf16 v[112:115], v[184:187], v[192:195], v[112:115]
	v_mfma_f32_16x16x32_bf16 v[100:103], v[176:179], v[200:203], v[100:103]
	v_mfma_f32_16x16x32_bf16 v[96:99], v[184:187], v[200:203], v[96:99]
	v_mfma_f32_16x16x32_bf16 v[84:87], v[176:179], v[208:211], v[84:87]
	v_mfma_f32_16x16x32_bf16 v[80:83], v[184:187], v[208:211], v[80:83]
	v_mfma_f32_16x16x32_bf16 v[68:71], v[176:179], v[216:219], v[68:71]
	v_mfma_f32_16x16x32_bf16 v[64:67], v[184:187], v[216:219], v[64:67]
	s_barrier
	s_add_i32 s28, s55, s42
	v_lshl_add_u64 v[220:221], s[20:21], 0, v[130:131]
	s_mov_b32 m0, s28
	ds_read_b128 v[188:191], v157 offset:16384
	ds_read_b128 v[192:195], v157 offset:17408
	ds_read_b128 v[196:199], v157 offset:18432
	ds_read_b128 v[200:203], v157 offset:19456
	ds_read_b128 v[204:207], v157 offset:20480
	ds_read_b128 v[208:211], v157 offset:21504
	ds_read_b128 v[212:215], v157 offset:22528
	ds_read_b128 v[216:219], v157 offset:23552
	global_load_lds_dwordx4 v[220:221], off
	s_add_i32 m0, s28, 0x2000
	s_add_u32 s28, s20, 0x2c000
	v_lshl_add_u64 v[222:223], s[20:21], 0, v[134:135]
	s_addc_u32 s29, s21, 0
	s_add_i32 s30, s56, s42
	global_load_lds_dwordx4 v[222:223], off
	v_lshl_add_u64 v[224:225], s[28:29], 0, v[130:131]
	s_mov_b32 m0, s30
	v_lshl_add_u64 v[226:227], s[22:23], 0, v[132:133]
	global_load_lds_dwordx4 v[224:225], off
	v_lshl_add_u64 v[224:225], s[28:29], 0, v[134:135]
	s_add_i32 m0, s30, 0x2000
	s_nop 0
	global_load_lds_dwordx4 v[224:225], off
	v_lshl_add_u64 v[224:225], s[22:23], 0, v[128:129]
	s_mov_b32 m0, s43
	s_nop 0
	global_load_lds_dwordx4 v[224:225], off
	s_mov_b32 m0, s44
	s_nop 0
	global_load_lds_dwordx4 v[226:227], off
	s_waitcnt vmcnt(8)
	s_waitcnt lgkmcnt(0)
	s_barrier
	s_waitcnt lgkmcnt(0)
	v_mfma_f32_16x16x32_bf16 v[60:63], v[146:149], v[188:191], v[60:63]
	v_mfma_f32_16x16x32_bf16 v[56:59], v[164:167], v[188:191], v[56:59]
	v_mfma_f32_16x16x32_bf16 v[44:47], v[146:149], v[196:199], v[44:47]
	v_mfma_f32_16x16x32_bf16 v[40:43], v[164:167], v[196:199], v[40:43]
	v_mfma_f32_16x16x32_bf16 v[28:31], v[146:149], v[204:207], v[28:31]
	v_mfma_f32_16x16x32_bf16 v[24:27], v[164:167], v[204:207], v[24:27]
	v_mfma_f32_16x16x32_bf16 v[12:15], v[146:149], v[212:215], v[12:15]
	v_mfma_f32_16x16x32_bf16 v[8:11], v[164:167], v[212:215], v[8:11]
	v_mfma_f32_16x16x32_bf16 v[60:63], v[160:163], v[192:195], v[60:63]
	v_mfma_f32_16x16x32_bf16 v[56:59], v[168:171], v[192:195], v[56:59]
	v_mfma_f32_16x16x32_bf16 v[44:47], v[160:163], v[200:203], v[44:47]
	v_mfma_f32_16x16x32_bf16 v[40:43], v[168:171], v[200:203], v[40:43]
	v_mfma_f32_16x16x32_bf16 v[28:31], v[160:163], v[208:211], v[28:31]
	v_mfma_f32_16x16x32_bf16 v[24:27], v[168:171], v[208:211], v[24:27]
	v_mfma_f32_16x16x32_bf16 v[12:15], v[160:163], v[216:219], v[12:15]
	v_mfma_f32_16x16x32_bf16 v[8:11], v[168:171], v[216:219], v[8:11]
	v_mfma_f32_16x16x32_bf16 v[52:55], v[172:175], v[188:191], v[52:55]
	v_mfma_f32_16x16x32_bf16 v[48:51], v[180:183], v[188:191], v[48:51]
	v_mfma_f32_16x16x32_bf16 v[36:39], v[172:175], v[196:199], v[36:39]
	v_mfma_f32_16x16x32_bf16 v[32:35], v[180:183], v[196:199], v[32:35]
	v_mfma_f32_16x16x32_bf16 v[20:23], v[172:175], v[204:207], v[20:23]
	v_mfma_f32_16x16x32_bf16 v[16:19], v[180:183], v[204:207], v[16:19]
	v_mfma_f32_16x16x32_bf16 v[4:7], v[172:175], v[212:215], v[4:7]
	v_mfma_f32_16x16x32_bf16 v[0:3], v[180:183], v[212:215], v[0:3]
	v_mfma_f32_16x16x32_bf16 v[52:55], v[176:179], v[192:195], v[52:55]
	v_mfma_f32_16x16x32_bf16 v[48:51], v[184:187], v[192:195], v[48:51]
	v_mfma_f32_16x16x32_bf16 v[36:39], v[176:179], v[200:203], v[36:39]
	v_mfma_f32_16x16x32_bf16 v[32:35], v[184:187], v[200:203], v[32:35]
	v_mfma_f32_16x16x32_bf16 v[20:23], v[176:179], v[208:211], v[20:23]
	v_mfma_f32_16x16x32_bf16 v[16:19], v[184:187], v[208:211], v[16:19]
	v_mfma_f32_16x16x32_bf16 v[4:7], v[176:179], v[216:219], v[4:7]
	v_mfma_f32_16x16x32_bf16 v[0:3], v[184:187], v[216:219], v[0:3]
	s_barrier
; #define PG8_STAGE(bufoff, gbase, voff) do { _Pragma("unroll") for (int _i = 0; _i < 2; ++_i) \
;         __builtin_amdgcn_global_load_lds((const unsigned*)((const char*)(gbase) + (voff)[_i]), (PG8_LAS unsigned*)(lds + (bufoff) + ldsw + _i * 8192), 16, 0, PG8_LOAD_AUX); } while (0)
; #define PG8_LDA(dst, b, h) do { _Pragma("unroll") for (int m = 0; m < 4; ++m) _Pragma("unroll") for (int k = 0; k < 2; ++k) dst[m][k] = *(const PG8_LAS bf16x8*)(lds + PG8_SA(b, h) + aoff + m * 2048 + k * 1024); } while (0)
; #define PG8_LDB(dst, b, h) do { _Pragma("unroll") for (int n = 0; n < 2; ++n) _Pragma("unroll") for (int k = 0; k < 2; ++k) dst[n][k] = *(const PG8_LAS bf16x8*)(lds + PG8_SB(b, h) + boff + n * 2048 + k * 1024); } while (0)
; #define PG8_MMA(ai, bj, At, Bt) do { __builtin_amdgcn_s_setprio(1); _Pragma("unroll") for (int m = 0; m < 4; ++m) _Pragma("unroll") for (int n = 0; n < 2; ++n) _Pragma("unroll") for (int k = 0; k < 2; ++k) \
;         acc[ai][bj][m][n] = __builtin_amdgcn_mfma_f32_16x16x32_bf16(Bt[n][k], At[m][k], acc[ai][bj][m][n], 0, 0, 0); __builtin_amdgcn_s_setprio(0); } while (0)
; #define PG8_WAIT_V(n) asm volatile("s_waitcnt vmcnt(" #n ")" ::: "memory")
; #define PG8_WAIT_L(n) asm volatile("s_waitcnt lgkmcnt(" #n ")" ::: "memory")
; #define PG8_BAR __builtin_amdgcn_s_barrier()
; #define PG8_SCHED __builtin_amdgcn_sched_barrier(0)
; template <class Epi, class Sched, bool ALIGN_EPI = false, bool SP2 = false>
; __device__ __forceinline__ void gemm_phase(PG8_LAS unsigned char* lds, const Gemm g, const Sched& S, const Epi& E) {
;     ...
;             PG8_LDB(B0, 1, 0); PG8_LDB(B1, 1, 1); PG8_SCHED; PG8_LDA(At, 1, 0); PG8_STAGE(PG8_SA(0, 1), a2 + hstepA, voffA);
;             PG8_WAIT_V(8); PG8_WAIT_L(0); PG8_BAR; PG8_MMA(0, 0, At, B0); PG8_MMA(0, 1, At, B1); PG8_BAR; PG8_SCHED;
.Lkmid_P13:
	s_add_i32 s28, 0, 0x18000
	v_add_u32_e32 v159, s28, v151
	s_add_i32 s29, 0, 0x1c000
	ds_read_b128 v[146:149], v159
	ds_read_b128 v[160:163], v159 offset:1024
	ds_read_b128 v[164:167], v159 offset:2048
	ds_read_b128 v[168:171], v159 offset:3072
	v_add_u32_e32 v159, s29, v151
	ds_read_b128 v[172:175], v159
	ds_read_b128 v[176:179], v159 offset:1024
	ds_read_b128 v[180:183], v159 offset:2048
	ds_read_b128 v[184:187], v159 offset:3072
	s_add_u32 s22, s22, 0xb0000
	s_addc_u32 s23, s23, 0
	s_mov_b32 m0, s45
	v_lshl_add_u64 v[228:229], s[22:23], 0, v[128:129]
	ds_read_b128 v[188:191], v157 offset:32768
	ds_read_b128 v[192:195], v157 offset:33792
	ds_read_b128 v[196:199], v157 offset:34816
	ds_read_b128 v[200:203], v157 offset:35840
	ds_read_b128 v[204:207], v157 offset:36864
	ds_read_b128 v[208:211], v157 offset:37888
	ds_read_b128 v[212:215], v157 offset:38912
	ds_read_b128 v[216:219], v157 offset:39936
	global_load_lds_dwordx4 v[228:229], off
	v_lshl_add_u64 v[228:229], s[22:23], 0, v[132:133]
	s_mov_b32 m0, s46
	s_nop 0
	global_load_lds_dwordx4 v[228:229], off
	s_waitcnt vmcnt(8)
	s_waitcnt lgkmcnt(0)
	s_barrier
	s_waitcnt lgkmcnt(0)
	v_mfma_f32_16x16x32_bf16 v[124:127], v[146:149], v[188:191], v[124:127]
	v_mfma_f32_16x16x32_bf16 v[120:123], v[164:167], v[188:191], v[120:123]
	v_mfma_f32_16x16x32_bf16 v[108:111], v[146:149], v[196:199], v[108:111]
	v_mfma_f32_16x16x32_bf16 v[104:107], v[164:167], v[196:199], v[104:107]
	v_mfma_f32_16x16x32_bf16 v[92:95], v[146:149], v[204:207], v[92:95]
	v_mfma_f32_16x16x32_bf16 v[88:91], v[164:167], v[204:207], v[88:91]
	v_mfma_f32_16x16x32_bf16 v[76:79], v[146:149], v[212:215], v[76:79]
	v_mfma_f32_16x16x32_bf16 v[72:75], v[164:167], v[212:215], v[72:75]
	v_mfma_f32_16x16x32_bf16 v[124:127], v[160:163], v[192:195], v[124:127]
	v_mfma_f32_16x16x32_bf16 v[120:123], v[168:171], v[192:195], v[120:123]
	v_mfma_f32_16x16x32_bf16 v[108:111], v[160:163], v[200:203], v[108:111]
	v_mfma_f32_16x16x32_bf16 v[104:107], v[168:171], v[200:203], v[104:107]
	v_mfma_f32_16x16x32_bf16 v[92:95], v[160:163], v[208:211], v[92:95]
	v_mfma_f32_16x16x32_bf16 v[88:91], v[168:171], v[208:211], v[88:91]
	v_mfma_f32_16x16x32_bf16 v[76:79], v[160:163], v[216:219], v[76:79]
	v_mfma_f32_16x16x32_bf16 v[72:75], v[168:171], v[216:219], v[72:75]
	v_mfma_f32_16x16x32_bf16 v[116:119], v[172:175], v[188:191], v[116:119]
	v_mfma_f32_16x16x32_bf16 v[112:115], v[180:183], v[188:191], v[112:115]
	v_mfma_f32_16x16x32_bf16 v[100:103], v[172:175], v[196:199], v[100:103]
	v_mfma_f32_16x16x32_bf16 v[96:99], v[180:183], v[196:199], v[96:99]
	v_mfma_f32_16x16x32_bf16 v[84:87], v[172:175], v[204:207], v[84:87]
	v_mfma_f32_16x16x32_bf16 v[80:83], v[180:183], v[204:207], v[80:83]
	v_mfma_f32_16x16x32_bf16 v[68:71], v[172:175], v[212:215], v[68:71]
	v_mfma_f32_16x16x32_bf16 v[64:67], v[180:183], v[212:215], v[64:67]
	v_mfma_f32_16x16x32_bf16 v[116:119], v[176:179], v[192:195], v[116:119]
	v_mfma_f32_16x16x32_bf16 v[112:115], v[184:187], v[192:195], v[112:115]
	v_mfma_f32_16x16x32_bf16 v[100:103], v[176:179], v[200:203], v[100:103]
	v_mfma_f32_16x16x32_bf16 v[96:99], v[184:187], v[200:203], v[96:99]
	v_mfma_f32_16x16x32_bf16 v[84:87], v[176:179], v[208:211], v[84:87]
	v_mfma_f32_16x16x32_bf16 v[80:83], v[184:187], v[208:211], v[80:83]
	v_mfma_f32_16x16x32_bf16 v[68:71], v[176:179], v[216:219], v[68:71]
	v_mfma_f32_16x16x32_bf16 v[64:67], v[184:187], v[216:219], v[64:67]
	s_barrier
; #define PG8_STAGE(bufoff, gbase, voff) do { _Pragma("unroll") for (int _i = 0; _i < 2; ++_i) \
;         __builtin_amdgcn_global_load_lds((const unsigned*)((const char*)(gbase) + (voff)[_i]), (PG8_LAS unsigned*)(lds + (bufoff) + ldsw + _i * 8192), 16, 0, PG8_LOAD_AUX); } while (0)
; #define PG8_LDA(dst, b, h) do { _Pragma("unroll") for (int m = 0; m < 4; ++m) _Pragma("unroll") for (int k = 0; k < 2; ++k) dst[m][k] = *(const PG8_LAS bf16x8*)(lds + PG8_SA(b, h) + aoff + m * 2048 + k * 1024); } while (0)
; #define PG8_MMA(ai, bj, At, Bt) do { __builtin_amdgcn_s_setprio(1); _Pragma("unroll") for (int m = 0; m < 4; ++m) _Pragma("unroll") for (int n = 0; n < 2; ++n) _Pragma("unroll") for (int k = 0; k < 2; ++k) \
;         acc[ai][bj][m][n] = __builtin_amdgcn_mfma_f32_16x16x32_bf16(Bt[n][k], At[m][k], acc[ai][bj][m][n], 0, 0, 0); __builtin_amdgcn_s_setprio(0); } while (0)
; #define PG8_WAIT_V(n) asm volatile("s_waitcnt vmcnt(" #n ")" ::: "memory")
; #define PG8_WAIT_L(n) asm volatile("s_waitcnt lgkmcnt(" #n ")" ::: "memory")
; #define PG8_BAR __builtin_amdgcn_s_barrier()
; #define PG8_SCHED __builtin_amdgcn_sched_barrier(0)
; template <class Epi, class Sched, bool ALIGN_EPI = false, bool SP2 = false>
; __device__ __forceinline__ void gemm_phase(PG8_LAS unsigned char* lds, const Gemm g, const Sched& S, const Epi& E) {
;     ...
;             PG8_LDA(At, 1, 1); PG8_STAGE(PG8_SB(1, 0), b3, voffB); PG8_STAGE(PG8_SB(1, 1), b3 + hstepB, voffB); PG8_STAGE(PG8_SA(1, 0), a3, voffA);
;             PG8_WAIT_V(8); PG8_WAIT_L(0); PG8_BAR; PG8_MMA(1, 0, At, B0); PG8_MMA(1, 1, At, B1); PG8_BAR; PG8_SCHED;
	s_add_i32 s22, s28, s42
	v_lshl_add_u64 v[220:221], v[220:221], 0, s[18:19]
	s_mov_b32 m0, s22
	ds_read_b128 v[188:191], v157 offset:49152
	ds_read_b128 v[192:195], v157 offset:50176
	ds_read_b128 v[196:199], v157 offset:51200
	ds_read_b128 v[200:203], v157 offset:52224
	ds_read_b128 v[204:207], v157 offset:53248
	ds_read_b128 v[208:211], v157 offset:54272
	ds_read_b128 v[212:215], v157 offset:55296
	ds_read_b128 v[216:219], v157 offset:56320
	global_load_lds_dwordx4 v[220:221], off
	s_add_i32 m0, s22, 0x2000
	s_add_u32 s20, s20, 0x2c080
	v_lshl_add_u64 v[220:221], v[222:223], 0, s[18:19]
	s_addc_u32 s21, s21, 0
	s_add_i32 s22, s29, s42
	global_load_lds_dwordx4 v[220:221], off
	v_lshl_add_u64 v[220:221], s[20:21], 0, v[130:131]
	s_mov_b32 m0, s22
	s_nop 0
	global_load_lds_dwordx4 v[220:221], off
	v_lshl_add_u64 v[220:221], s[20:21], 0, v[134:135]
	s_add_i32 m0, s22, 0x2000
	s_nop 0
	global_load_lds_dwordx4 v[220:221], off
	v_lshl_add_u64 v[220:221], v[224:225], 0, s[18:19]
	s_mov_b32 m0, s50
	s_nop 0
	global_load_lds_dwordx4 v[220:221], off
	v_lshl_add_u64 v[220:221], v[226:227], 0, s[18:19]
	s_mov_b32 m0, s51
	s_nop 0
	global_load_lds_dwordx4 v[220:221], off
	s_waitcnt vmcnt(8)
	s_waitcnt lgkmcnt(0)
	s_barrier
	s_waitcnt lgkmcnt(0)
	v_mfma_f32_16x16x32_bf16 v[60:63], v[146:149], v[188:191], v[60:63]
	v_mfma_f32_16x16x32_bf16 v[56:59], v[164:167], v[188:191], v[56:59]
	v_mfma_f32_16x16x32_bf16 v[44:47], v[146:149], v[196:199], v[44:47]
	v_mfma_f32_16x16x32_bf16 v[40:43], v[164:167], v[196:199], v[40:43]
	v_mfma_f32_16x16x32_bf16 v[28:31], v[146:149], v[204:207], v[28:31]
	v_mfma_f32_16x16x32_bf16 v[24:27], v[164:167], v[204:207], v[24:27]
	v_mfma_f32_16x16x32_bf16 v[12:15], v[146:149], v[212:215], v[12:15]
	v_mfma_f32_16x16x32_bf16 v[8:11], v[164:167], v[212:215], v[8:11]
	v_mfma_f32_16x16x32_bf16 v[60:63], v[160:163], v[192:195], v[60:63]
	v_mfma_f32_16x16x32_bf16 v[56:59], v[168:171], v[192:195], v[56:59]
	v_mfma_f32_16x16x32_bf16 v[44:47], v[160:163], v[200:203], v[44:47]
	v_mfma_f32_16x16x32_bf16 v[40:43], v[168:171], v[200:203], v[40:43]
	v_mfma_f32_16x16x32_bf16 v[28:31], v[160:163], v[208:211], v[28:31]
	v_mfma_f32_16x16x32_bf16 v[24:27], v[168:171], v[208:211], v[24:27]
	v_mfma_f32_16x16x32_bf16 v[12:15], v[160:163], v[216:219], v[12:15]
	v_mfma_f32_16x16x32_bf16 v[8:11], v[168:171], v[216:219], v[8:11]
	v_mfma_f32_16x16x32_bf16 v[52:55], v[172:175], v[188:191], v[52:55]
	v_mfma_f32_16x16x32_bf16 v[48:51], v[180:183], v[188:191], v[48:51]
	v_mfma_f32_16x16x32_bf16 v[36:39], v[172:175], v[196:199], v[36:39]
	v_mfma_f32_16x16x32_bf16 v[32:35], v[180:183], v[196:199], v[32:35]
	v_mfma_f32_16x16x32_bf16 v[20:23], v[172:175], v[204:207], v[20:23]
	v_mfma_f32_16x16x32_bf16 v[16:19], v[180:183], v[204:207], v[16:19]
	v_mfma_f32_16x16x32_bf16 v[4:7], v[172:175], v[212:215], v[4:7]
	v_mfma_f32_16x16x32_bf16 v[0:3], v[180:183], v[212:215], v[0:3]
	v_mfma_f32_16x16x32_bf16 v[52:55], v[176:179], v[192:195], v[52:55]
	v_mfma_f32_16x16x32_bf16 v[48:51], v[184:187], v[192:195], v[48:51]
	v_mfma_f32_16x16x32_bf16 v[36:39], v[176:179], v[200:203], v[36:39]
	v_mfma_f32_16x16x32_bf16 v[32:35], v[184:187], v[200:203], v[32:35]
	v_mfma_f32_16x16x32_bf16 v[20:23], v[176:179], v[208:211], v[20:23]
	v_mfma_f32_16x16x32_bf16 v[16:19], v[184:187], v[208:211], v[16:19]
	v_mfma_f32_16x16x32_bf16 v[4:7], v[176:179], v[216:219], v[4:7]
	v_mfma_f32_16x16x32_bf16 v[0:3], v[184:187], v[216:219], v[0:3]
	s_barrier
	s_add_i32 s27, s27, 2
	s_add_u32 s0, s0, 0x100
	s_addc_u32 s1, s1, 0
	s_add_u32 s25, s25, 0x100
	s_addc_u32 s26, s26, 0
	s_cmp_gt_u32 s27, 41
	s_cbranch_scc0 .LBB0_1196
	s_and_b64 vcc, exec, s[36:37]
	s_cbranch_vccz .LBB0_1199
	s_barrier
